# first K-loop trip after an epilogue waits with vmcnt(8+stores) so the epilogue stores need not drain before the first two super-phases; zero-init kept
# speedup vs baseline: 1.0143x; 1.0014x over previous
.LBB0_74:
	s_ashr_i32 s27, s26, 31
	s_lshl_b64 s[28:29], s[26:27], 19
	s_add_u32 s28, s3, s28
	s_addc_u32 s29, s35, s29
	s_and_b64 s[30:31], s[4:5], exec
	s_cselect_b32 s27, s29, s49
	s_cselect_b32 s68, s28, s48
	s_ashr_i32 s23, s22, 31
	s_lshl_b64 s[30:31], s[22:23], 19
	s_add_u32 s30, s50, s30
	s_addc_u32 s31, s51, s31
	s_and_b64 s[70:71], s[4:5], exec
	s_cselect_b32 s69, s31, s47
	s_cselect_b32 s70, s30, s46
	s_lshl_b32 s23, s44, 8
	v_add_u32_e32 v0, s23, v148
	s_add_u32 s71, s46, 0x100
	v_ashrrev_i32_e32 v1, 31, v0
	s_addc_u32 s74, s47, 0
	v_lshl_add_u64 v[144:145], v[0:1], 4, s[12:13]
	s_add_u32 s44, s48, 0x40080
	s_addc_u32 s45, s49, 0
	s_mov_b32 s75, -2
	s_mov_b64 s[46:47], 0
	s_cmp_eq_u32 s59, 1
	s_cbranch_scc1 .Lfa_0
	v_add_u32_e32 v153, s64, v147
	ds_read_b128 v[160:163], v153
	ds_read_b128 v[164:167], v153 offset:1024
	ds_read_b128 v[168:171], v153 offset:2048
	ds_read_b128 v[172:175], v153 offset:3072
	v_add_u32_e32 v153, s65, v147
	ds_read_b128 v[176:179], v153
	ds_read_b128 v[180:183], v153 offset:1024
	ds_read_b128 v[186:189], v153 offset:2048
	ds_read_b128 v[190:193], v153 offset:3072
	s_add_u32 s48, s44, 0xfffc0080
	s_addc_u32 s49, s45, -1
	s_and_b64 s[46:47], s[46:47], exec
	s_cselect_b32 s49, s27, s49
	s_cselect_b32 s48, s68, s48
	s_cselect_b32 s47, s69, s74
	s_cselect_b32 s46, s70, s71
	v_lshl_add_u64 v[154:155], s[44:45], 0, v[138:139]
	s_add_i32 m0, s55, 0xc000
	ds_read_b128 v[194:197], v150
	ds_read_b128 v[198:201], v150 offset:1024
	ds_read_b128 v[202:205], v150 offset:2048
	ds_read_b128 v[206:209], v150 offset:3072
	ds_read_b128 v[210:213], v150 offset:4096
	ds_read_b128 v[214:217], v150 offset:5120
	ds_read_b128 v[218:221], v150 offset:6144
	ds_read_b128 v[222:225], v150 offset:7168
	global_load_lds_dwordx4 v[154:155], off
	v_lshl_add_u64 v[154:155], s[44:45], 0, v[136:137]
	s_add_i32 m0, s55, 0xe000
	s_nop 0
	global_load_lds_dwordx4 v[154:155], off
	s_waitcnt vmcnt(16)
	s_waitcnt lgkmcnt(0)
	s_barrier
	s_setprio 1
	s_waitcnt lgkmcnt(0)
	v_mfma_f32_16x16x32_bf16 v[124:127], v[160:163], v[194:197], 0
	v_mfma_f32_16x16x32_bf16 v[116:119], v[168:171], v[194:197], 0
	v_mfma_f32_16x16x32_bf16 v[108:111], v[160:163], v[202:205], 0
	v_mfma_f32_16x16x32_bf16 v[100:103], v[168:171], v[202:205], 0
	v_mfma_f32_16x16x32_bf16 v[92:95], v[160:163], v[210:213], 0
	v_mfma_f32_16x16x32_bf16 v[84:87], v[168:171], v[210:213], 0
	v_mfma_f32_16x16x32_bf16 v[76:79], v[160:163], v[218:221], 0
	v_mfma_f32_16x16x32_bf16 v[68:71], v[168:171], v[218:221], 0
	v_mfma_f32_16x16x32_bf16 v[124:127], v[164:167], v[198:201], v[124:127]
	v_mfma_f32_16x16x32_bf16 v[116:119], v[172:175], v[198:201], v[116:119]
	v_mfma_f32_16x16x32_bf16 v[108:111], v[164:167], v[206:209], v[108:111]
	v_mfma_f32_16x16x32_bf16 v[100:103], v[172:175], v[206:209], v[100:103]
	v_mfma_f32_16x16x32_bf16 v[92:95], v[164:167], v[214:217], v[92:95]
	v_mfma_f32_16x16x32_bf16 v[84:87], v[172:175], v[214:217], v[84:87]
	v_mfma_f32_16x16x32_bf16 v[76:79], v[164:167], v[222:225], v[76:79]
	v_mfma_f32_16x16x32_bf16 v[68:71], v[172:175], v[222:225], v[68:71]
	s_setprio 0
	s_setprio 1
	v_mfma_f32_16x16x32_bf16 v[120:123], v[176:179], v[194:197], 0
	v_mfma_f32_16x16x32_bf16 v[112:115], v[186:189], v[194:197], 0
	v_mfma_f32_16x16x32_bf16 v[104:107], v[176:179], v[202:205], 0
	v_mfma_f32_16x16x32_bf16 v[96:99], v[186:189], v[202:205], 0
	v_mfma_f32_16x16x32_bf16 v[88:91], v[176:179], v[210:213], 0
	v_mfma_f32_16x16x32_bf16 v[80:83], v[186:189], v[210:213], 0
	v_mfma_f32_16x16x32_bf16 v[72:75], v[176:179], v[218:221], 0
	v_mfma_f32_16x16x32_bf16 v[64:67], v[186:189], v[218:221], 0
	v_mfma_f32_16x16x32_bf16 v[120:123], v[180:183], v[198:201], v[120:123]
	v_mfma_f32_16x16x32_bf16 v[112:115], v[190:193], v[198:201], v[112:115]
	v_mfma_f32_16x16x32_bf16 v[104:107], v[180:183], v[206:209], v[104:107]
	v_mfma_f32_16x16x32_bf16 v[96:99], v[190:193], v[206:209], v[96:99]
	v_mfma_f32_16x16x32_bf16 v[88:91], v[180:183], v[214:217], v[88:91]
	v_mfma_f32_16x16x32_bf16 v[80:83], v[190:193], v[214:217], v[80:83]
	v_mfma_f32_16x16x32_bf16 v[72:75], v[180:183], v[222:225], v[72:75]
	v_mfma_f32_16x16x32_bf16 v[64:67], v[190:193], v[222:225], v[64:67]
	s_setprio 0
	s_barrier
	s_add_i32 s76, s64, s52
	v_lshl_add_u64 v[154:155], s[46:47], 0, v[132:133]
	s_mov_b32 m0, s76
	ds_read_b128 v[194:197], v150 offset:16384
	ds_read_b128 v[198:201], v150 offset:17408
	ds_read_b128 v[202:205], v150 offset:18432
	ds_read_b128 v[206:209], v150 offset:19456
	ds_read_b128 v[210:213], v150 offset:20480
	ds_read_b128 v[214:217], v150 offset:21504
	ds_read_b128 v[218:221], v150 offset:22528
	ds_read_b128 v[222:225], v150 offset:23552
	global_load_lds_dwordx4 v[154:155], off
	s_add_i32 m0, s76, 0x2000
	s_add_u32 s76, s46, 0x40000
	v_lshl_add_u64 v[226:227], s[46:47], 0, v[128:129]
	s_addc_u32 s77, s47, 0
	s_add_i32 s78, s65, s52
	global_load_lds_dwordx4 v[226:227], off
	v_lshl_add_u64 v[228:229], s[76:77], 0, v[132:133]
	s_mov_b32 m0, s78
	v_lshl_add_u64 v[230:231], s[48:49], 0, v[130:131]
	global_load_lds_dwordx4 v[228:229], off
	v_lshl_add_u64 v[228:229], s[76:77], 0, v[128:129]
	s_add_i32 m0, s78, 0x2000
	s_nop 0
	global_load_lds_dwordx4 v[228:229], off
	v_lshl_add_u64 v[228:229], s[48:49], 0, v[134:135]
	s_mov_b32 m0, s55
	s_nop 0
	global_load_lds_dwordx4 v[228:229], off
	s_mov_b32 m0, s56
	s_nop 0
	global_load_lds_dwordx4 v[230:231], off
	s_waitcnt vmcnt(16)
	s_waitcnt lgkmcnt(0)
	s_barrier
	s_setprio 1
	s_waitcnt lgkmcnt(0)
	v_mfma_f32_16x16x32_bf16 v[60:63], v[160:163], v[194:197], 0
	v_mfma_f32_16x16x32_bf16 v[52:55], v[168:171], v[194:197], 0
	v_mfma_f32_16x16x32_bf16 v[44:47], v[160:163], v[202:205], 0
	v_mfma_f32_16x16x32_bf16 v[36:39], v[168:171], v[202:205], 0
	v_mfma_f32_16x16x32_bf16 v[28:31], v[160:163], v[210:213], 0
	v_mfma_f32_16x16x32_bf16 v[20:23], v[168:171], v[210:213], 0
	v_mfma_f32_16x16x32_bf16 v[12:15], v[160:163], v[218:221], 0
	v_mfma_f32_16x16x32_bf16 v[4:7], v[168:171], v[218:221], 0
	v_mfma_f32_16x16x32_bf16 v[60:63], v[164:167], v[198:201], v[60:63]
	v_mfma_f32_16x16x32_bf16 v[52:55], v[172:175], v[198:201], v[52:55]
	v_mfma_f32_16x16x32_bf16 v[44:47], v[164:167], v[206:209], v[44:47]
	v_mfma_f32_16x16x32_bf16 v[36:39], v[172:175], v[206:209], v[36:39]
	v_mfma_f32_16x16x32_bf16 v[28:31], v[164:167], v[214:217], v[28:31]
	v_mfma_f32_16x16x32_bf16 v[20:23], v[172:175], v[214:217], v[20:23]
	v_mfma_f32_16x16x32_bf16 v[12:15], v[164:167], v[222:225], v[12:15]
	v_mfma_f32_16x16x32_bf16 v[4:7], v[172:175], v[222:225], v[4:7]
	s_setprio 0
	s_setprio 1
	v_mfma_f32_16x16x32_bf16 v[56:59], v[176:179], v[194:197], 0
	v_mfma_f32_16x16x32_bf16 v[48:51], v[186:189], v[194:197], 0
	v_mfma_f32_16x16x32_bf16 v[40:43], v[176:179], v[202:205], 0
	v_mfma_f32_16x16x32_bf16 v[32:35], v[186:189], v[202:205], 0
	v_mfma_f32_16x16x32_bf16 v[24:27], v[176:179], v[210:213], 0
	v_mfma_f32_16x16x32_bf16 v[16:19], v[186:189], v[210:213], 0
	v_mfma_f32_16x16x32_bf16 v[8:11], v[176:179], v[218:221], 0
	v_mfma_f32_16x16x32_bf16 v[0:3], v[186:189], v[218:221], 0
	v_mfma_f32_16x16x32_bf16 v[56:59], v[180:183], v[198:201], v[56:59]
	v_mfma_f32_16x16x32_bf16 v[48:51], v[190:193], v[198:201], v[48:51]
	v_mfma_f32_16x16x32_bf16 v[40:43], v[180:183], v[206:209], v[40:43]
	v_mfma_f32_16x16x32_bf16 v[32:35], v[190:193], v[206:209], v[32:35]
	v_mfma_f32_16x16x32_bf16 v[24:27], v[180:183], v[214:217], v[24:27]
	v_mfma_f32_16x16x32_bf16 v[16:19], v[190:193], v[214:217], v[16:19]
	v_mfma_f32_16x16x32_bf16 v[8:11], v[180:183], v[222:225], v[8:11]
	v_mfma_f32_16x16x32_bf16 v[0:3], v[190:193], v[222:225], v[0:3]
	s_setprio 0
	s_barrier
	s_add_i32 s76, 0, 0x18000
	v_add_u32_e32 v153, s76, v147
	s_add_i32 s77, 0, 0x1c000
	ds_read_b128 v[160:163], v153
	ds_read_b128 v[164:167], v153 offset:1024
	ds_read_b128 v[168:171], v153 offset:2048
	ds_read_b128 v[172:175], v153 offset:3072
	v_add_u32_e32 v153, s77, v147
	ds_read_b128 v[176:179], v153
	ds_read_b128 v[180:183], v153 offset:1024
	ds_read_b128 v[186:189], v153 offset:2048
	ds_read_b128 v[190:193], v153 offset:3072
	s_add_u32 s48, s48, 0x40000
	s_addc_u32 s49, s49, 0
	s_mov_b32 m0, s57
	v_lshl_add_u64 v[232:233], s[48:49], 0, v[134:135]
	ds_read_b128 v[194:197], v150 offset:32768
	ds_read_b128 v[198:201], v150 offset:33792
	ds_read_b128 v[202:205], v150 offset:34816
	ds_read_b128 v[206:209], v150 offset:35840
	ds_read_b128 v[210:213], v150 offset:36864
	ds_read_b128 v[214:217], v150 offset:37888
	ds_read_b128 v[218:221], v150 offset:38912
	ds_read_b128 v[222:225], v150 offset:39936
	global_load_lds_dwordx4 v[232:233], off
	v_lshl_add_u64 v[232:233], s[48:49], 0, v[130:131]
	s_mov_b32 m0, s58
	s_nop 0
	global_load_lds_dwordx4 v[232:233], off
	s_waitcnt vmcnt(8)
	s_waitcnt lgkmcnt(0)
	s_barrier
	s_setprio 1
	s_waitcnt lgkmcnt(0)
	v_mfma_f32_16x16x32_bf16 v[124:127], v[160:163], v[194:197], v[124:127]
	v_mfma_f32_16x16x32_bf16 v[116:119], v[168:171], v[194:197], v[116:119]
	v_mfma_f32_16x16x32_bf16 v[108:111], v[160:163], v[202:205], v[108:111]
	v_mfma_f32_16x16x32_bf16 v[100:103], v[168:171], v[202:205], v[100:103]
	v_mfma_f32_16x16x32_bf16 v[92:95], v[160:163], v[210:213], v[92:95]
	v_mfma_f32_16x16x32_bf16 v[84:87], v[168:171], v[210:213], v[84:87]
	v_mfma_f32_16x16x32_bf16 v[76:79], v[160:163], v[218:221], v[76:79]
	v_mfma_f32_16x16x32_bf16 v[68:71], v[168:171], v[218:221], v[68:71]
	v_mfma_f32_16x16x32_bf16 v[124:127], v[164:167], v[198:201], v[124:127]
	v_mfma_f32_16x16x32_bf16 v[116:119], v[172:175], v[198:201], v[116:119]
	v_mfma_f32_16x16x32_bf16 v[108:111], v[164:167], v[206:209], v[108:111]
	v_mfma_f32_16x16x32_bf16 v[100:103], v[172:175], v[206:209], v[100:103]
	v_mfma_f32_16x16x32_bf16 v[92:95], v[164:167], v[214:217], v[92:95]
	v_mfma_f32_16x16x32_bf16 v[84:87], v[172:175], v[214:217], v[84:87]
	v_mfma_f32_16x16x32_bf16 v[76:79], v[164:167], v[222:225], v[76:79]
	v_mfma_f32_16x16x32_bf16 v[68:71], v[172:175], v[222:225], v[68:71]
	s_setprio 0
	s_setprio 1
	v_mfma_f32_16x16x32_bf16 v[120:123], v[176:179], v[194:197], v[120:123]
	v_mfma_f32_16x16x32_bf16 v[112:115], v[186:189], v[194:197], v[112:115]
	v_mfma_f32_16x16x32_bf16 v[104:107], v[176:179], v[202:205], v[104:107]
	v_mfma_f32_16x16x32_bf16 v[96:99], v[186:189], v[202:205], v[96:99]
	v_mfma_f32_16x16x32_bf16 v[88:91], v[176:179], v[210:213], v[88:91]
	v_mfma_f32_16x16x32_bf16 v[80:83], v[186:189], v[210:213], v[80:83]
	v_mfma_f32_16x16x32_bf16 v[72:75], v[176:179], v[218:221], v[72:75]
	v_mfma_f32_16x16x32_bf16 v[64:67], v[186:189], v[218:221], v[64:67]
	v_mfma_f32_16x16x32_bf16 v[120:123], v[180:183], v[198:201], v[120:123]
	v_mfma_f32_16x16x32_bf16 v[112:115], v[190:193], v[198:201], v[112:115]
	v_mfma_f32_16x16x32_bf16 v[104:107], v[180:183], v[206:209], v[104:107]
	v_mfma_f32_16x16x32_bf16 v[96:99], v[190:193], v[206:209], v[96:99]
	v_mfma_f32_16x16x32_bf16 v[88:91], v[180:183], v[214:217], v[88:91]
	v_mfma_f32_16x16x32_bf16 v[80:83], v[190:193], v[214:217], v[80:83]
	v_mfma_f32_16x16x32_bf16 v[72:75], v[180:183], v[222:225], v[72:75]
	v_mfma_f32_16x16x32_bf16 v[64:67], v[190:193], v[222:225], v[64:67]
	s_setprio 0
	s_barrier
	s_add_i32 s48, s76, s52
	v_lshl_add_u64 v[154:155], v[154:155], 0, s[14:15]
	s_mov_b32 m0, s48
	ds_read_b128 v[194:197], v150 offset:49152
	ds_read_b128 v[198:201], v150 offset:50176
	ds_read_b128 v[202:205], v150 offset:51200
	ds_read_b128 v[206:209], v150 offset:52224
	ds_read_b128 v[210:213], v150 offset:53248
	ds_read_b128 v[214:217], v150 offset:54272
	ds_read_b128 v[218:221], v150 offset:55296
	ds_read_b128 v[222:225], v150 offset:56320
	global_load_lds_dwordx4 v[154:155], off
	s_add_i32 m0, s48, 0x2000
	s_add_u32 s46, s46, 0x40080
	v_lshl_add_u64 v[154:155], v[226:227], 0, s[14:15]
	s_addc_u32 s47, s47, 0
	s_add_i32 s48, s77, s52
	global_load_lds_dwordx4 v[154:155], off
	v_lshl_add_u64 v[154:155], s[46:47], 0, v[132:133]
	s_mov_b32 m0, s48
	s_nop 0
	global_load_lds_dwordx4 v[154:155], off
	v_lshl_add_u64 v[154:155], s[46:47], 0, v[128:129]
	s_add_i32 m0, s48, 0x2000
	s_nop 0
	global_load_lds_dwordx4 v[154:155], off
	v_lshl_add_u64 v[154:155], v[228:229], 0, s[14:15]
	s_mov_b32 m0, s60
	s_nop 0
	global_load_lds_dwordx4 v[154:155], off
	v_lshl_add_u64 v[154:155], v[230:231], 0, s[14:15]
	s_mov_b32 m0, s61
	s_nop 0
	global_load_lds_dwordx4 v[154:155], off
	s_waitcnt vmcnt(8)
	s_waitcnt lgkmcnt(0)
	s_barrier
	s_setprio 1
	s_waitcnt lgkmcnt(0)
	v_mfma_f32_16x16x32_bf16 v[60:63], v[160:163], v[194:197], v[60:63]
	v_mfma_f32_16x16x32_bf16 v[52:55], v[168:171], v[194:197], v[52:55]
	v_mfma_f32_16x16x32_bf16 v[44:47], v[160:163], v[202:205], v[44:47]
	v_mfma_f32_16x16x32_bf16 v[36:39], v[168:171], v[202:205], v[36:39]
	v_mfma_f32_16x16x32_bf16 v[28:31], v[160:163], v[210:213], v[28:31]
	v_mfma_f32_16x16x32_bf16 v[20:23], v[168:171], v[210:213], v[20:23]
	v_mfma_f32_16x16x32_bf16 v[12:15], v[160:163], v[218:221], v[12:15]
	v_mfma_f32_16x16x32_bf16 v[4:7], v[168:171], v[218:221], v[4:7]
	v_mfma_f32_16x16x32_bf16 v[60:63], v[164:167], v[198:201], v[60:63]
	v_mfma_f32_16x16x32_bf16 v[52:55], v[172:175], v[198:201], v[52:55]
	v_mfma_f32_16x16x32_bf16 v[44:47], v[164:167], v[206:209], v[44:47]
	v_mfma_f32_16x16x32_bf16 v[36:39], v[172:175], v[206:209], v[36:39]
	v_mfma_f32_16x16x32_bf16 v[28:31], v[164:167], v[214:217], v[28:31]
	v_mfma_f32_16x16x32_bf16 v[20:23], v[172:175], v[214:217], v[20:23]
	v_mfma_f32_16x16x32_bf16 v[12:15], v[164:167], v[222:225], v[12:15]
	v_mfma_f32_16x16x32_bf16 v[4:7], v[172:175], v[222:225], v[4:7]
	s_setprio 0
	s_setprio 1
	v_mfma_f32_16x16x32_bf16 v[56:59], v[176:179], v[194:197], v[56:59]
	v_mfma_f32_16x16x32_bf16 v[48:51], v[186:189], v[194:197], v[48:51]
	v_mfma_f32_16x16x32_bf16 v[40:43], v[176:179], v[202:205], v[40:43]
	v_mfma_f32_16x16x32_bf16 v[32:35], v[186:189], v[202:205], v[32:35]
	v_mfma_f32_16x16x32_bf16 v[24:27], v[176:179], v[210:213], v[24:27]
	v_mfma_f32_16x16x32_bf16 v[16:19], v[186:189], v[210:213], v[16:19]
	v_mfma_f32_16x16x32_bf16 v[8:11], v[176:179], v[218:221], v[8:11]
	v_mfma_f32_16x16x32_bf16 v[0:3], v[186:189], v[218:221], v[0:3]
	v_mfma_f32_16x16x32_bf16 v[56:59], v[180:183], v[198:201], v[56:59]
	v_mfma_f32_16x16x32_bf16 v[48:51], v[190:193], v[198:201], v[48:51]
	v_mfma_f32_16x16x32_bf16 v[40:43], v[180:183], v[206:209], v[40:43]
	v_mfma_f32_16x16x32_bf16 v[32:35], v[190:193], v[206:209], v[32:35]
	v_mfma_f32_16x16x32_bf16 v[24:27], v[180:183], v[214:217], v[24:27]
	v_mfma_f32_16x16x32_bf16 v[16:19], v[190:193], v[214:217], v[16:19]
	v_mfma_f32_16x16x32_bf16 v[8:11], v[180:183], v[222:225], v[8:11]
	v_mfma_f32_16x16x32_bf16 v[0:3], v[190:193], v[222:225], v[0:3]
	s_setprio 0
	s_barrier
	s_add_i32 s75, s75, 2
	s_add_u32 s71, s71, 0x100
	s_addc_u32 s74, s74, 0
	s_add_u32 s44, s44, 0x100
	s_addc_u32 s45, s45, 0
	s_branch .LBB0_76
.Lfa_0:
	v_add_u32_e32 v153, s64, v147
	ds_read_b128 v[160:163], v153
	ds_read_b128 v[164:167], v153 offset:1024
	ds_read_b128 v[168:171], v153 offset:2048
	ds_read_b128 v[172:175], v153 offset:3072
	v_add_u32_e32 v153, s65, v147
	ds_read_b128 v[176:179], v153
	ds_read_b128 v[180:183], v153 offset:1024
	ds_read_b128 v[186:189], v153 offset:2048
	ds_read_b128 v[190:193], v153 offset:3072
	s_add_u32 s48, s44, 0xfffc0080
	s_addc_u32 s49, s45, -1
	s_and_b64 s[46:47], s[46:47], exec
	s_cselect_b32 s49, s27, s49
	s_cselect_b32 s48, s68, s48
	s_cselect_b32 s47, s69, s74
	s_cselect_b32 s46, s70, s71
	v_lshl_add_u64 v[154:155], s[44:45], 0, v[138:139]
	s_add_i32 m0, s55, 0xc000
	ds_read_b128 v[194:197], v150
	ds_read_b128 v[198:201], v150 offset:1024
	ds_read_b128 v[202:205], v150 offset:2048
	ds_read_b128 v[206:209], v150 offset:3072
	ds_read_b128 v[210:213], v150 offset:4096
	ds_read_b128 v[214:217], v150 offset:5120
	ds_read_b128 v[218:221], v150 offset:6144
	ds_read_b128 v[222:225], v150 offset:7168
	global_load_lds_dwordx4 v[154:155], off
	v_lshl_add_u64 v[154:155], s[44:45], 0, v[136:137]
	s_add_i32 m0, s55, 0xe000
	s_nop 0
	global_load_lds_dwordx4 v[154:155], off
	s_waitcnt vmcnt(8)
	s_waitcnt lgkmcnt(0)
	s_barrier
	s_setprio 1
	s_waitcnt lgkmcnt(0)
	v_mfma_f32_16x16x32_bf16 v[124:127], v[160:163], v[194:197], 0
	v_mfma_f32_16x16x32_bf16 v[116:119], v[168:171], v[194:197], 0
	v_mfma_f32_16x16x32_bf16 v[108:111], v[160:163], v[202:205], 0
	v_mfma_f32_16x16x32_bf16 v[100:103], v[168:171], v[202:205], 0
	v_mfma_f32_16x16x32_bf16 v[92:95], v[160:163], v[210:213], 0
	v_mfma_f32_16x16x32_bf16 v[84:87], v[168:171], v[210:213], 0
	v_mfma_f32_16x16x32_bf16 v[76:79], v[160:163], v[218:221], 0
	v_mfma_f32_16x16x32_bf16 v[68:71], v[168:171], v[218:221], 0
	v_mfma_f32_16x16x32_bf16 v[124:127], v[164:167], v[198:201], v[124:127]
	v_mfma_f32_16x16x32_bf16 v[116:119], v[172:175], v[198:201], v[116:119]
	v_mfma_f32_16x16x32_bf16 v[108:111], v[164:167], v[206:209], v[108:111]
	v_mfma_f32_16x16x32_bf16 v[100:103], v[172:175], v[206:209], v[100:103]
	v_mfma_f32_16x16x32_bf16 v[92:95], v[164:167], v[214:217], v[92:95]
	v_mfma_f32_16x16x32_bf16 v[84:87], v[172:175], v[214:217], v[84:87]
	v_mfma_f32_16x16x32_bf16 v[76:79], v[164:167], v[222:225], v[76:79]
	v_mfma_f32_16x16x32_bf16 v[68:71], v[172:175], v[222:225], v[68:71]
	s_setprio 0
	s_setprio 1
	v_mfma_f32_16x16x32_bf16 v[120:123], v[176:179], v[194:197], 0
	v_mfma_f32_16x16x32_bf16 v[112:115], v[186:189], v[194:197], 0
	v_mfma_f32_16x16x32_bf16 v[104:107], v[176:179], v[202:205], 0
	v_mfma_f32_16x16x32_bf16 v[96:99], v[186:189], v[202:205], 0
	v_mfma_f32_16x16x32_bf16 v[88:91], v[176:179], v[210:213], 0
	v_mfma_f32_16x16x32_bf16 v[80:83], v[186:189], v[210:213], 0
	v_mfma_f32_16x16x32_bf16 v[72:75], v[176:179], v[218:221], 0
	v_mfma_f32_16x16x32_bf16 v[64:67], v[186:189], v[218:221], 0
	v_mfma_f32_16x16x32_bf16 v[120:123], v[180:183], v[198:201], v[120:123]
	v_mfma_f32_16x16x32_bf16 v[112:115], v[190:193], v[198:201], v[112:115]
	v_mfma_f32_16x16x32_bf16 v[104:107], v[180:183], v[206:209], v[104:107]
	v_mfma_f32_16x16x32_bf16 v[96:99], v[190:193], v[206:209], v[96:99]
	v_mfma_f32_16x16x32_bf16 v[88:91], v[180:183], v[214:217], v[88:91]
	v_mfma_f32_16x16x32_bf16 v[80:83], v[190:193], v[214:217], v[80:83]
	v_mfma_f32_16x16x32_bf16 v[72:75], v[180:183], v[222:225], v[72:75]
	v_mfma_f32_16x16x32_bf16 v[64:67], v[190:193], v[222:225], v[64:67]
	s_setprio 0
	s_barrier
	s_add_i32 s76, s64, s52
	v_lshl_add_u64 v[154:155], s[46:47], 0, v[132:133]
	s_mov_b32 m0, s76
	ds_read_b128 v[194:197], v150 offset:16384
	ds_read_b128 v[198:201], v150 offset:17408
	ds_read_b128 v[202:205], v150 offset:18432
	ds_read_b128 v[206:209], v150 offset:19456
	ds_read_b128 v[210:213], v150 offset:20480
	ds_read_b128 v[214:217], v150 offset:21504
	ds_read_b128 v[218:221], v150 offset:22528
	ds_read_b128 v[222:225], v150 offset:23552
	global_load_lds_dwordx4 v[154:155], off
	s_add_i32 m0, s76, 0x2000
	s_add_u32 s76, s46, 0x40000
	v_lshl_add_u64 v[226:227], s[46:47], 0, v[128:129]
	s_addc_u32 s77, s47, 0
	s_add_i32 s78, s65, s52
	global_load_lds_dwordx4 v[226:227], off
	v_lshl_add_u64 v[228:229], s[76:77], 0, v[132:133]
	s_mov_b32 m0, s78
	v_lshl_add_u64 v[230:231], s[48:49], 0, v[130:131]
	global_load_lds_dwordx4 v[228:229], off
	v_lshl_add_u64 v[228:229], s[76:77], 0, v[128:129]
	s_add_i32 m0, s78, 0x2000
	s_nop 0
	global_load_lds_dwordx4 v[228:229], off
	v_lshl_add_u64 v[228:229], s[48:49], 0, v[134:135]
	s_mov_b32 m0, s55
	s_nop 0
	global_load_lds_dwordx4 v[228:229], off
	s_mov_b32 m0, s56
	s_nop 0
	global_load_lds_dwordx4 v[230:231], off
	s_waitcnt vmcnt(8)
	s_waitcnt lgkmcnt(0)
	s_barrier
	s_setprio 1
	s_waitcnt lgkmcnt(0)
	v_mfma_f32_16x16x32_bf16 v[60:63], v[160:163], v[194:197], 0
	v_mfma_f32_16x16x32_bf16 v[52:55], v[168:171], v[194:197], 0
	v_mfma_f32_16x16x32_bf16 v[44:47], v[160:163], v[202:205], 0
	v_mfma_f32_16x16x32_bf16 v[36:39], v[168:171], v[202:205], 0
	v_mfma_f32_16x16x32_bf16 v[28:31], v[160:163], v[210:213], 0
	v_mfma_f32_16x16x32_bf16 v[20:23], v[168:171], v[210:213], 0
	v_mfma_f32_16x16x32_bf16 v[12:15], v[160:163], v[218:221], 0
	v_mfma_f32_16x16x32_bf16 v[4:7], v[168:171], v[218:221], 0
	v_mfma_f32_16x16x32_bf16 v[60:63], v[164:167], v[198:201], v[60:63]
	v_mfma_f32_16x16x32_bf16 v[52:55], v[172:175], v[198:201], v[52:55]
	v_mfma_f32_16x16x32_bf16 v[44:47], v[164:167], v[206:209], v[44:47]
	v_mfma_f32_16x16x32_bf16 v[36:39], v[172:175], v[206:209], v[36:39]
	v_mfma_f32_16x16x32_bf16 v[28:31], v[164:167], v[214:217], v[28:31]
	v_mfma_f32_16x16x32_bf16 v[20:23], v[172:175], v[214:217], v[20:23]
	v_mfma_f32_16x16x32_bf16 v[12:15], v[164:167], v[222:225], v[12:15]
	v_mfma_f32_16x16x32_bf16 v[4:7], v[172:175], v[222:225], v[4:7]
	s_setprio 0
	s_setprio 1
	v_mfma_f32_16x16x32_bf16 v[56:59], v[176:179], v[194:197], 0
	v_mfma_f32_16x16x32_bf16 v[48:51], v[186:189], v[194:197], 0
	v_mfma_f32_16x16x32_bf16 v[40:43], v[176:179], v[202:205], 0
	v_mfma_f32_16x16x32_bf16 v[32:35], v[186:189], v[202:205], 0
	v_mfma_f32_16x16x32_bf16 v[24:27], v[176:179], v[210:213], 0
	v_mfma_f32_16x16x32_bf16 v[16:19], v[186:189], v[210:213], 0
	v_mfma_f32_16x16x32_bf16 v[8:11], v[176:179], v[218:221], 0
	v_mfma_f32_16x16x32_bf16 v[0:3], v[186:189], v[218:221], 0
	v_mfma_f32_16x16x32_bf16 v[56:59], v[180:183], v[198:201], v[56:59]
	v_mfma_f32_16x16x32_bf16 v[48:51], v[190:193], v[198:201], v[48:51]
	v_mfma_f32_16x16x32_bf16 v[40:43], v[180:183], v[206:209], v[40:43]
	v_mfma_f32_16x16x32_bf16 v[32:35], v[190:193], v[206:209], v[32:35]
	v_mfma_f32_16x16x32_bf16 v[24:27], v[180:183], v[214:217], v[24:27]
	v_mfma_f32_16x16x32_bf16 v[16:19], v[190:193], v[214:217], v[16:19]
	v_mfma_f32_16x16x32_bf16 v[8:11], v[180:183], v[222:225], v[8:11]
	v_mfma_f32_16x16x32_bf16 v[0:3], v[190:193], v[222:225], v[0:3]
	s_setprio 0
	s_barrier
	s_add_i32 s76, 0, 0x18000
	v_add_u32_e32 v153, s76, v147
	s_add_i32 s77, 0, 0x1c000
	ds_read_b128 v[160:163], v153
	ds_read_b128 v[164:167], v153 offset:1024
	ds_read_b128 v[168:171], v153 offset:2048
	ds_read_b128 v[172:175], v153 offset:3072
	v_add_u32_e32 v153, s77, v147
	ds_read_b128 v[176:179], v153
	ds_read_b128 v[180:183], v153 offset:1024
	ds_read_b128 v[186:189], v153 offset:2048
	ds_read_b128 v[190:193], v153 offset:3072
	s_add_u32 s48, s48, 0x40000
	s_addc_u32 s49, s49, 0
	s_mov_b32 m0, s57
	v_lshl_add_u64 v[232:233], s[48:49], 0, v[134:135]
	ds_read_b128 v[194:197], v150 offset:32768
	ds_read_b128 v[198:201], v150 offset:33792
	ds_read_b128 v[202:205], v150 offset:34816
	ds_read_b128 v[206:209], v150 offset:35840
	ds_read_b128 v[210:213], v150 offset:36864
	ds_read_b128 v[214:217], v150 offset:37888
	ds_read_b128 v[218:221], v150 offset:38912
	ds_read_b128 v[222:225], v150 offset:39936
	global_load_lds_dwordx4 v[232:233], off
	v_lshl_add_u64 v[232:233], s[48:49], 0, v[130:131]
	s_mov_b32 m0, s58
	s_nop 0
	global_load_lds_dwordx4 v[232:233], off
	s_waitcnt vmcnt(8)
	s_waitcnt lgkmcnt(0)
	s_barrier
	s_setprio 1
	s_waitcnt lgkmcnt(0)
	v_mfma_f32_16x16x32_bf16 v[124:127], v[160:163], v[194:197], v[124:127]
	v_mfma_f32_16x16x32_bf16 v[116:119], v[168:171], v[194:197], v[116:119]
	v_mfma_f32_16x16x32_bf16 v[108:111], v[160:163], v[202:205], v[108:111]
	v_mfma_f32_16x16x32_bf16 v[100:103], v[168:171], v[202:205], v[100:103]
	v_mfma_f32_16x16x32_bf16 v[92:95], v[160:163], v[210:213], v[92:95]
	v_mfma_f32_16x16x32_bf16 v[84:87], v[168:171], v[210:213], v[84:87]
	v_mfma_f32_16x16x32_bf16 v[76:79], v[160:163], v[218:221], v[76:79]
	v_mfma_f32_16x16x32_bf16 v[68:71], v[168:171], v[218:221], v[68:71]
	v_mfma_f32_16x16x32_bf16 v[124:127], v[164:167], v[198:201], v[124:127]
	v_mfma_f32_16x16x32_bf16 v[116:119], v[172:175], v[198:201], v[116:119]
	v_mfma_f32_16x16x32_bf16 v[108:111], v[164:167], v[206:209], v[108:111]
	v_mfma_f32_16x16x32_bf16 v[100:103], v[172:175], v[206:209], v[100:103]
	v_mfma_f32_16x16x32_bf16 v[92:95], v[164:167], v[214:217], v[92:95]
	v_mfma_f32_16x16x32_bf16 v[84:87], v[172:175], v[214:217], v[84:87]
	v_mfma_f32_16x16x32_bf16 v[76:79], v[164:167], v[222:225], v[76:79]
	v_mfma_f32_16x16x32_bf16 v[68:71], v[172:175], v[222:225], v[68:71]
	s_setprio 0
	s_setprio 1
	v_mfma_f32_16x16x32_bf16 v[120:123], v[176:179], v[194:197], v[120:123]
	v_mfma_f32_16x16x32_bf16 v[112:115], v[186:189], v[194:197], v[112:115]
	v_mfma_f32_16x16x32_bf16 v[104:107], v[176:179], v[202:205], v[104:107]
	v_mfma_f32_16x16x32_bf16 v[96:99], v[186:189], v[202:205], v[96:99]
	v_mfma_f32_16x16x32_bf16 v[88:91], v[176:179], v[210:213], v[88:91]
	v_mfma_f32_16x16x32_bf16 v[80:83], v[186:189], v[210:213], v[80:83]
	v_mfma_f32_16x16x32_bf16 v[72:75], v[176:179], v[218:221], v[72:75]
	v_mfma_f32_16x16x32_bf16 v[64:67], v[186:189], v[218:221], v[64:67]
	v_mfma_f32_16x16x32_bf16 v[120:123], v[180:183], v[198:201], v[120:123]
	v_mfma_f32_16x16x32_bf16 v[112:115], v[190:193], v[198:201], v[112:115]
	v_mfma_f32_16x16x32_bf16 v[104:107], v[180:183], v[206:209], v[104:107]
	v_mfma_f32_16x16x32_bf16 v[96:99], v[190:193], v[206:209], v[96:99]
	v_mfma_f32_16x16x32_bf16 v[88:91], v[180:183], v[214:217], v[88:91]
	v_mfma_f32_16x16x32_bf16 v[80:83], v[190:193], v[214:217], v[80:83]
	v_mfma_f32_16x16x32_bf16 v[72:75], v[180:183], v[222:225], v[72:75]
	v_mfma_f32_16x16x32_bf16 v[64:67], v[190:193], v[222:225], v[64:67]
	s_setprio 0
	s_barrier
	s_add_i32 s48, s76, s52
	v_lshl_add_u64 v[154:155], v[154:155], 0, s[14:15]
	s_mov_b32 m0, s48
	ds_read_b128 v[194:197], v150 offset:49152
	ds_read_b128 v[198:201], v150 offset:50176
	ds_read_b128 v[202:205], v150 offset:51200
	ds_read_b128 v[206:209], v150 offset:52224
	ds_read_b128 v[210:213], v150 offset:53248
	ds_read_b128 v[214:217], v150 offset:54272
	ds_read_b128 v[218:221], v150 offset:55296
	ds_read_b128 v[222:225], v150 offset:56320
	global_load_lds_dwordx4 v[154:155], off
	s_add_i32 m0, s48, 0x2000
	s_add_u32 s46, s46, 0x40080
	v_lshl_add_u64 v[154:155], v[226:227], 0, s[14:15]
	s_addc_u32 s47, s47, 0
	s_add_i32 s48, s77, s52
	global_load_lds_dwordx4 v[154:155], off
	v_lshl_add_u64 v[154:155], s[46:47], 0, v[132:133]
	s_mov_b32 m0, s48
	s_nop 0
	global_load_lds_dwordx4 v[154:155], off
	v_lshl_add_u64 v[154:155], s[46:47], 0, v[128:129]
	s_add_i32 m0, s48, 0x2000
	s_nop 0
	global_load_lds_dwordx4 v[154:155], off
	v_lshl_add_u64 v[154:155], v[228:229], 0, s[14:15]
	s_mov_b32 m0, s60
	s_nop 0
	global_load_lds_dwordx4 v[154:155], off
	v_lshl_add_u64 v[154:155], v[230:231], 0, s[14:15]
	s_mov_b32 m0, s61
	s_nop 0
	global_load_lds_dwordx4 v[154:155], off
	s_waitcnt vmcnt(8)
	s_waitcnt lgkmcnt(0)
	s_barrier
	s_setprio 1
	s_waitcnt lgkmcnt(0)
	v_mfma_f32_16x16x32_bf16 v[60:63], v[160:163], v[194:197], v[60:63]
	v_mfma_f32_16x16x32_bf16 v[52:55], v[168:171], v[194:197], v[52:55]
	v_mfma_f32_16x16x32_bf16 v[44:47], v[160:163], v[202:205], v[44:47]
	v_mfma_f32_16x16x32_bf16 v[36:39], v[168:171], v[202:205], v[36:39]
	v_mfma_f32_16x16x32_bf16 v[28:31], v[160:163], v[210:213], v[28:31]
	v_mfma_f32_16x16x32_bf16 v[20:23], v[168:171], v[210:213], v[20:23]
	v_mfma_f32_16x16x32_bf16 v[12:15], v[160:163], v[218:221], v[12:15]
	v_mfma_f32_16x16x32_bf16 v[4:7], v[168:171], v[218:221], v[4:7]
	v_mfma_f32_16x16x32_bf16 v[60:63], v[164:167], v[198:201], v[60:63]
	v_mfma_f32_16x16x32_bf16 v[52:55], v[172:175], v[198:201], v[52:55]
	v_mfma_f32_16x16x32_bf16 v[44:47], v[164:167], v[206:209], v[44:47]
	v_mfma_f32_16x16x32_bf16 v[36:39], v[172:175], v[206:209], v[36:39]
	v_mfma_f32_16x16x32_bf16 v[28:31], v[164:167], v[214:217], v[28:31]
	v_mfma_f32_16x16x32_bf16 v[20:23], v[172:175], v[214:217], v[20:23]
	v_mfma_f32_16x16x32_bf16 v[12:15], v[164:167], v[222:225], v[12:15]
	v_mfma_f32_16x16x32_bf16 v[4:7], v[172:175], v[222:225], v[4:7]
	s_setprio 0
	s_setprio 1
	v_mfma_f32_16x16x32_bf16 v[56:59], v[176:179], v[194:197], v[56:59]
	v_mfma_f32_16x16x32_bf16 v[48:51], v[186:189], v[194:197], v[48:51]
	v_mfma_f32_16x16x32_bf16 v[40:43], v[176:179], v[202:205], v[40:43]
	v_mfma_f32_16x16x32_bf16 v[32:35], v[186:189], v[202:205], v[32:35]
	v_mfma_f32_16x16x32_bf16 v[24:27], v[176:179], v[210:213], v[24:27]
	v_mfma_f32_16x16x32_bf16 v[16:19], v[186:189], v[210:213], v[16:19]
	v_mfma_f32_16x16x32_bf16 v[8:11], v[176:179], v[218:221], v[8:11]
	v_mfma_f32_16x16x32_bf16 v[0:3], v[186:189], v[218:221], v[0:3]
	v_mfma_f32_16x16x32_bf16 v[56:59], v[180:183], v[198:201], v[56:59]
	v_mfma_f32_16x16x32_bf16 v[48:51], v[190:193], v[198:201], v[48:51]
	v_mfma_f32_16x16x32_bf16 v[40:43], v[180:183], v[206:209], v[40:43]
	v_mfma_f32_16x16x32_bf16 v[32:35], v[190:193], v[206:209], v[32:35]
	v_mfma_f32_16x16x32_bf16 v[24:27], v[180:183], v[214:217], v[24:27]
	v_mfma_f32_16x16x32_bf16 v[16:19], v[190:193], v[214:217], v[16:19]
	v_mfma_f32_16x16x32_bf16 v[8:11], v[180:183], v[222:225], v[8:11]
	v_mfma_f32_16x16x32_bf16 v[0:3], v[190:193], v[222:225], v[0:3]
	s_setprio 0
	s_barrier
	s_add_i32 s75, s75, 2
	s_add_u32 s71, s71, 0x100
	s_addc_u32 s74, s74, 0
	s_add_u32 s44, s44, 0x100
	s_addc_u32 s45, s45, 0
	s_branch .LBB0_76

.LBB0_158:
	s_add_u32 s81, s56, 0x100
	s_addc_u32 s82, s57, 0
	s_mov_b32 s83, -2
	s_waitcnt lgkmcnt(0)
	s_cmp_eq_u32 s70, 1
	s_cbranch_scc1 .Lfa_1
	ds_read_b128 v[128:131], v189
	ds_read_b128 v[132:135], v189 offset:1024
	ds_read_b128 v[136:139], v189 offset:2048
	ds_read_b128 v[140:143], v189 offset:3072
	ds_read_b128 v[144:147], v190
	ds_read_b128 v[148:151], v190 offset:1024
	ds_read_b128 v[172:175], v190 offset:2048
	ds_read_b128 v[176:179], v190 offset:3072
	s_add_u32 s56, s54, 0x100
	s_addc_u32 s57, s55, 0
	s_cmp_eq_u32 s83, 40
	s_cselect_b32 s61, s15, s57
	s_cselect_b32 s60, s14, s56
	s_cselect_b32 s59, s53, s82
	s_cselect_b32 s58, s52, s81
	v_lshl_add_u64 v[222:223], s[54:55], 0, v[166:167]
	s_add_i32 m0, s66, 0xc000
	ds_read_b128 v[180:183], v191
	ds_read_b128 v[194:197], v191 offset:1024
	ds_read_b128 v[198:201], v191 offset:2048
	ds_read_b128 v[202:205], v191 offset:3072
	ds_read_b128 v[206:209], v191 offset:4096
	ds_read_b128 v[210:213], v191 offset:5120
	ds_read_b128 v[214:217], v191 offset:6144
	ds_read_b128 v[218:221], v191 offset:7168
	global_load_lds_dwordx4 v[222:223], off
	v_lshl_add_u64 v[222:223], s[54:55], 0, v[164:165]
	s_add_i32 m0, s66, 0xe000
	s_nop 0
	global_load_lds_dwordx4 v[222:223], off
	s_waitcnt vmcnt(24)
	s_waitcnt lgkmcnt(0)
	s_barrier
	s_setprio 1
	s_waitcnt lgkmcnt(0)
	v_mfma_f32_16x16x32_bf16 v[124:127], v[128:131], v[180:183], 0
	v_mfma_f32_16x16x32_bf16 v[120:123], v[136:139], v[180:183], 0
	v_mfma_f32_16x16x32_bf16 v[108:111], v[128:131], v[198:201], 0
	v_mfma_f32_16x16x32_bf16 v[104:107], v[136:139], v[198:201], 0
	v_mfma_f32_16x16x32_bf16 v[92:95], v[128:131], v[206:209], 0
	v_mfma_f32_16x16x32_bf16 v[88:91], v[136:139], v[206:209], 0
	v_mfma_f32_16x16x32_bf16 v[76:79], v[128:131], v[214:217], 0
	v_mfma_f32_16x16x32_bf16 v[72:75], v[136:139], v[214:217], 0
	v_mfma_f32_16x16x32_bf16 v[124:127], v[132:135], v[194:197], v[124:127]
	v_mfma_f32_16x16x32_bf16 v[120:123], v[140:143], v[194:197], v[120:123]
	v_mfma_f32_16x16x32_bf16 v[108:111], v[132:135], v[202:205], v[108:111]
	v_mfma_f32_16x16x32_bf16 v[104:107], v[140:143], v[202:205], v[104:107]
	v_mfma_f32_16x16x32_bf16 v[92:95], v[132:135], v[210:213], v[92:95]
	v_mfma_f32_16x16x32_bf16 v[88:91], v[140:143], v[210:213], v[88:91]
	v_mfma_f32_16x16x32_bf16 v[76:79], v[132:135], v[218:221], v[76:79]
	v_mfma_f32_16x16x32_bf16 v[72:75], v[140:143], v[218:221], v[72:75]
	s_setprio 0
	s_setprio 1
	v_mfma_f32_16x16x32_bf16 v[116:119], v[144:147], v[180:183], 0
	v_mfma_f32_16x16x32_bf16 v[112:115], v[172:175], v[180:183], 0
	v_mfma_f32_16x16x32_bf16 v[100:103], v[144:147], v[198:201], 0
	v_mfma_f32_16x16x32_bf16 v[96:99], v[172:175], v[198:201], 0
	v_mfma_f32_16x16x32_bf16 v[84:87], v[144:147], v[206:209], 0
	v_mfma_f32_16x16x32_bf16 v[80:83], v[172:175], v[206:209], 0
	v_mfma_f32_16x16x32_bf16 v[68:71], v[144:147], v[214:217], 0
	v_mfma_f32_16x16x32_bf16 v[64:67], v[172:175], v[214:217], 0
	v_mfma_f32_16x16x32_bf16 v[116:119], v[148:151], v[194:197], v[116:119]
	v_mfma_f32_16x16x32_bf16 v[112:115], v[176:179], v[194:197], v[112:115]
	v_mfma_f32_16x16x32_bf16 v[100:103], v[148:151], v[202:205], v[100:103]
	v_mfma_f32_16x16x32_bf16 v[96:99], v[176:179], v[202:205], v[96:99]
	v_mfma_f32_16x16x32_bf16 v[84:87], v[148:151], v[210:213], v[84:87]
	v_mfma_f32_16x16x32_bf16 v[80:83], v[176:179], v[210:213], v[80:83]
	v_mfma_f32_16x16x32_bf16 v[68:71], v[148:151], v[218:221], v[68:71]
	v_mfma_f32_16x16x32_bf16 v[64:67], v[176:179], v[218:221], v[64:67]
	s_setprio 0
	s_barrier
	s_add_i32 s54, s77, s65
	v_lshl_add_u64 v[222:223], s[58:59], 0, v[154:155]
	s_mov_b32 m0, s54
	ds_read_b128 v[180:183], v191 offset:16384
	ds_read_b128 v[194:197], v191 offset:17408
	ds_read_b128 v[198:201], v191 offset:18432
	ds_read_b128 v[202:205], v191 offset:19456
	ds_read_b128 v[206:209], v191 offset:20480
	ds_read_b128 v[210:213], v191 offset:21504
	ds_read_b128 v[214:217], v191 offset:22528
	ds_read_b128 v[218:221], v191 offset:23552
	global_load_lds_dwordx4 v[222:223], off
	s_add_i32 m0, s54, 0x2000
	s_add_u32 s54, s58, 0xb0000
	v_lshl_add_u64 v[224:225], s[58:59], 0, v[162:163]
	s_addc_u32 s55, s59, 0
	s_add_i32 s84, s78, s65
	global_load_lds_dwordx4 v[224:225], off
	v_lshl_add_u64 v[226:227], s[54:55], 0, v[154:155]
	s_mov_b32 m0, s84
	v_lshl_add_u64 v[228:229], s[60:61], 0, v[160:161]
	global_load_lds_dwordx4 v[226:227], off
	v_lshl_add_u64 v[226:227], s[54:55], 0, v[162:163]
	s_add_i32 m0, s84, 0x2000
	s_nop 0
	global_load_lds_dwordx4 v[226:227], off
	v_lshl_add_u64 v[226:227], s[60:61], 0, v[152:153]
	s_mov_b32 m0, s66
	s_nop 0
	global_load_lds_dwordx4 v[226:227], off
	s_mov_b32 m0, s67
	s_nop 0
	global_load_lds_dwordx4 v[228:229], off
	s_waitcnt vmcnt(24)
	s_waitcnt lgkmcnt(0)
	s_barrier
	s_setprio 1
	s_waitcnt lgkmcnt(0)
	v_mfma_f32_16x16x32_bf16 v[60:63], v[128:131], v[180:183], 0
	v_mfma_f32_16x16x32_bf16 v[56:59], v[136:139], v[180:183], 0
	v_mfma_f32_16x16x32_bf16 v[44:47], v[128:131], v[198:201], 0
	v_mfma_f32_16x16x32_bf16 v[40:43], v[136:139], v[198:201], 0
	v_mfma_f32_16x16x32_bf16 v[28:31], v[128:131], v[206:209], 0
	v_mfma_f32_16x16x32_bf16 v[24:27], v[136:139], v[206:209], 0
	v_mfma_f32_16x16x32_bf16 v[12:15], v[128:131], v[214:217], 0
	v_mfma_f32_16x16x32_bf16 v[8:11], v[136:139], v[214:217], 0
	v_mfma_f32_16x16x32_bf16 v[60:63], v[132:135], v[194:197], v[60:63]
	v_mfma_f32_16x16x32_bf16 v[56:59], v[140:143], v[194:197], v[56:59]
	v_mfma_f32_16x16x32_bf16 v[44:47], v[132:135], v[202:205], v[44:47]
	v_mfma_f32_16x16x32_bf16 v[40:43], v[140:143], v[202:205], v[40:43]
	v_mfma_f32_16x16x32_bf16 v[28:31], v[132:135], v[210:213], v[28:31]
	v_mfma_f32_16x16x32_bf16 v[24:27], v[140:143], v[210:213], v[24:27]
	v_mfma_f32_16x16x32_bf16 v[12:15], v[132:135], v[218:221], v[12:15]
	v_mfma_f32_16x16x32_bf16 v[8:11], v[140:143], v[218:221], v[8:11]
	s_setprio 0
	s_setprio 1
	v_mfma_f32_16x16x32_bf16 v[52:55], v[144:147], v[180:183], 0
	v_mfma_f32_16x16x32_bf16 v[48:51], v[172:175], v[180:183], 0
	v_mfma_f32_16x16x32_bf16 v[36:39], v[144:147], v[198:201], 0
	v_mfma_f32_16x16x32_bf16 v[32:35], v[172:175], v[198:201], 0
	v_mfma_f32_16x16x32_bf16 v[20:23], v[144:147], v[206:209], 0
	v_mfma_f32_16x16x32_bf16 v[16:19], v[172:175], v[206:209], 0
	v_mfma_f32_16x16x32_bf16 v[4:7], v[144:147], v[214:217], 0
	v_mfma_f32_16x16x32_bf16 v[0:3], v[172:175], v[214:217], 0
	v_mfma_f32_16x16x32_bf16 v[52:55], v[148:151], v[194:197], v[52:55]
	v_mfma_f32_16x16x32_bf16 v[48:51], v[176:179], v[194:197], v[48:51]
	v_mfma_f32_16x16x32_bf16 v[36:39], v[148:151], v[202:205], v[36:39]
	v_mfma_f32_16x16x32_bf16 v[32:35], v[176:179], v[202:205], v[32:35]
	v_mfma_f32_16x16x32_bf16 v[20:23], v[148:151], v[210:213], v[20:23]
	v_mfma_f32_16x16x32_bf16 v[16:19], v[176:179], v[210:213], v[16:19]
	v_mfma_f32_16x16x32_bf16 v[4:7], v[148:151], v[218:221], v[4:7]
	v_mfma_f32_16x16x32_bf16 v[0:3], v[176:179], v[218:221], v[0:3]
	s_setprio 0
	s_barrier
	s_add_i32 s84, 0, 0x18000
	s_add_i32 s85, 0, 0x1c000
	v_add_u32_e32 v140, s84, v186
	v_add_u32_e32 v176, s85, v186
	ds_read_b128 v[128:131], v140
	ds_read_b128 v[132:135], v140 offset:1024
	ds_read_b128 v[136:139], v140 offset:2048
	ds_read_b128 v[140:143], v140 offset:3072
	ds_read_b128 v[144:147], v176
	ds_read_b128 v[148:151], v176 offset:1024
	ds_read_b128 v[172:175], v176 offset:2048
	ds_read_b128 v[176:179], v176 offset:3072
	s_add_u32 s54, s60, 0xb0000
	s_addc_u32 s55, s61, 0
	s_mov_b32 m0, s68
	v_lshl_add_u64 v[230:231], s[54:55], 0, v[152:153]
	ds_read_b128 v[180:183], v191 offset:32768
	ds_read_b128 v[194:197], v191 offset:33792
	ds_read_b128 v[198:201], v191 offset:34816
	ds_read_b128 v[202:205], v191 offset:35840
	ds_read_b128 v[206:209], v191 offset:36864
	ds_read_b128 v[210:213], v191 offset:37888
	ds_read_b128 v[214:217], v191 offset:38912
	ds_read_b128 v[218:221], v191 offset:39936
	global_load_lds_dwordx4 v[230:231], off
	v_lshl_add_u64 v[230:231], s[54:55], 0, v[160:161]
	s_mov_b32 m0, s69
	s_nop 0
	global_load_lds_dwordx4 v[230:231], off
	s_waitcnt vmcnt(8)
	s_waitcnt lgkmcnt(0)
	s_barrier
	s_setprio 1
	s_waitcnt lgkmcnt(0)
	v_mfma_f32_16x16x32_bf16 v[124:127], v[128:131], v[180:183], v[124:127]
	v_mfma_f32_16x16x32_bf16 v[120:123], v[136:139], v[180:183], v[120:123]
	v_mfma_f32_16x16x32_bf16 v[108:111], v[128:131], v[198:201], v[108:111]
	v_mfma_f32_16x16x32_bf16 v[104:107], v[136:139], v[198:201], v[104:107]
	v_mfma_f32_16x16x32_bf16 v[92:95], v[128:131], v[206:209], v[92:95]
	v_mfma_f32_16x16x32_bf16 v[88:91], v[136:139], v[206:209], v[88:91]
	v_mfma_f32_16x16x32_bf16 v[76:79], v[128:131], v[214:217], v[76:79]
	v_mfma_f32_16x16x32_bf16 v[72:75], v[136:139], v[214:217], v[72:75]
	v_mfma_f32_16x16x32_bf16 v[124:127], v[132:135], v[194:197], v[124:127]
	v_mfma_f32_16x16x32_bf16 v[120:123], v[140:143], v[194:197], v[120:123]
	v_mfma_f32_16x16x32_bf16 v[108:111], v[132:135], v[202:205], v[108:111]
	v_mfma_f32_16x16x32_bf16 v[104:107], v[140:143], v[202:205], v[104:107]
	v_mfma_f32_16x16x32_bf16 v[92:95], v[132:135], v[210:213], v[92:95]
	v_mfma_f32_16x16x32_bf16 v[88:91], v[140:143], v[210:213], v[88:91]
	v_mfma_f32_16x16x32_bf16 v[76:79], v[132:135], v[218:221], v[76:79]
	v_mfma_f32_16x16x32_bf16 v[72:75], v[140:143], v[218:221], v[72:75]
	s_setprio 0
	s_setprio 1
	v_mfma_f32_16x16x32_bf16 v[116:119], v[144:147], v[180:183], v[116:119]
	v_mfma_f32_16x16x32_bf16 v[112:115], v[172:175], v[180:183], v[112:115]
	v_mfma_f32_16x16x32_bf16 v[100:103], v[144:147], v[198:201], v[100:103]
	v_mfma_f32_16x16x32_bf16 v[96:99], v[172:175], v[198:201], v[96:99]
	v_mfma_f32_16x16x32_bf16 v[84:87], v[144:147], v[206:209], v[84:87]
	v_mfma_f32_16x16x32_bf16 v[80:83], v[172:175], v[206:209], v[80:83]
	v_mfma_f32_16x16x32_bf16 v[68:71], v[144:147], v[214:217], v[68:71]
	v_mfma_f32_16x16x32_bf16 v[64:67], v[172:175], v[214:217], v[64:67]
	v_mfma_f32_16x16x32_bf16 v[116:119], v[148:151], v[194:197], v[116:119]
	v_mfma_f32_16x16x32_bf16 v[112:115], v[176:179], v[194:197], v[112:115]
	v_mfma_f32_16x16x32_bf16 v[100:103], v[148:151], v[202:205], v[100:103]
	v_mfma_f32_16x16x32_bf16 v[96:99], v[176:179], v[202:205], v[96:99]
	v_mfma_f32_16x16x32_bf16 v[84:87], v[148:151], v[210:213], v[84:87]
	v_mfma_f32_16x16x32_bf16 v[80:83], v[176:179], v[210:213], v[80:83]
	v_mfma_f32_16x16x32_bf16 v[68:71], v[148:151], v[218:221], v[68:71]
	v_mfma_f32_16x16x32_bf16 v[64:67], v[176:179], v[218:221], v[64:67]
	s_setprio 0
	s_barrier
	s_add_i32 s54, s84, s65
	v_lshl_add_u64 v[222:223], v[222:223], 0, s[28:29]
	s_mov_b32 m0, s54
	ds_read_b128 v[180:183], v191 offset:49152
	ds_read_b128 v[194:197], v191 offset:50176
	ds_read_b128 v[198:201], v191 offset:51200
	ds_read_b128 v[202:205], v191 offset:52224
	ds_read_b128 v[206:209], v191 offset:53248
	ds_read_b128 v[210:213], v191 offset:54272
	ds_read_b128 v[214:217], v191 offset:55296
	ds_read_b128 v[218:221], v191 offset:56320
	global_load_lds_dwordx4 v[222:223], off
	s_add_i32 m0, s54, 0x2000
	s_add_u32 s54, s58, 0xb0080
	v_lshl_add_u64 v[222:223], v[224:225], 0, s[28:29]
	s_addc_u32 s55, s59, 0
	s_add_i32 s58, s85, s65
	global_load_lds_dwordx4 v[222:223], off
	v_lshl_add_u64 v[222:223], s[54:55], 0, v[154:155]
	s_mov_b32 m0, s58
	s_nop 0
	global_load_lds_dwordx4 v[222:223], off
	v_lshl_add_u64 v[222:223], s[54:55], 0, v[162:163]
	s_add_i32 m0, s58, 0x2000
	s_nop 0
	global_load_lds_dwordx4 v[222:223], off
	v_lshl_add_u64 v[222:223], v[226:227], 0, s[28:29]
	s_mov_b32 m0, s3
	s_nop 0
	global_load_lds_dwordx4 v[222:223], off
	v_lshl_add_u64 v[222:223], v[228:229], 0, s[28:29]
	s_mov_b32 m0, s71
	s_nop 0
	global_load_lds_dwordx4 v[222:223], off
	s_waitcnt vmcnt(8)
	s_waitcnt lgkmcnt(0)
	s_barrier
	s_setprio 1
	s_waitcnt lgkmcnt(0)
	v_mfma_f32_16x16x32_bf16 v[60:63], v[128:131], v[180:183], v[60:63]
	v_mfma_f32_16x16x32_bf16 v[56:59], v[136:139], v[180:183], v[56:59]
	v_mfma_f32_16x16x32_bf16 v[44:47], v[128:131], v[198:201], v[44:47]
	v_mfma_f32_16x16x32_bf16 v[40:43], v[136:139], v[198:201], v[40:43]
	v_mfma_f32_16x16x32_bf16 v[28:31], v[128:131], v[206:209], v[28:31]
	v_mfma_f32_16x16x32_bf16 v[24:27], v[136:139], v[206:209], v[24:27]
	v_mfma_f32_16x16x32_bf16 v[12:15], v[128:131], v[214:217], v[12:15]
	v_mfma_f32_16x16x32_bf16 v[8:11], v[136:139], v[214:217], v[8:11]
	v_mfma_f32_16x16x32_bf16 v[60:63], v[132:135], v[194:197], v[60:63]
	v_mfma_f32_16x16x32_bf16 v[56:59], v[140:143], v[194:197], v[56:59]
	v_mfma_f32_16x16x32_bf16 v[44:47], v[132:135], v[202:205], v[44:47]
	v_mfma_f32_16x16x32_bf16 v[40:43], v[140:143], v[202:205], v[40:43]
	v_mfma_f32_16x16x32_bf16 v[28:31], v[132:135], v[210:213], v[28:31]
	v_mfma_f32_16x16x32_bf16 v[24:27], v[140:143], v[210:213], v[24:27]
	v_mfma_f32_16x16x32_bf16 v[12:15], v[132:135], v[218:221], v[12:15]
	v_mfma_f32_16x16x32_bf16 v[8:11], v[140:143], v[218:221], v[8:11]
	s_setprio 0
	s_setprio 1
	v_mfma_f32_16x16x32_bf16 v[52:55], v[144:147], v[180:183], v[52:55]
	v_mfma_f32_16x16x32_bf16 v[48:51], v[172:175], v[180:183], v[48:51]
	v_mfma_f32_16x16x32_bf16 v[36:39], v[144:147], v[198:201], v[36:39]
	v_mfma_f32_16x16x32_bf16 v[32:35], v[172:175], v[198:201], v[32:35]
	v_mfma_f32_16x16x32_bf16 v[20:23], v[144:147], v[206:209], v[20:23]
	v_mfma_f32_16x16x32_bf16 v[16:19], v[172:175], v[206:209], v[16:19]
	v_mfma_f32_16x16x32_bf16 v[4:7], v[144:147], v[214:217], v[4:7]
	v_mfma_f32_16x16x32_bf16 v[0:3], v[172:175], v[214:217], v[0:3]
	v_mfma_f32_16x16x32_bf16 v[52:55], v[148:151], v[194:197], v[52:55]
	v_mfma_f32_16x16x32_bf16 v[48:51], v[176:179], v[194:197], v[48:51]
	v_mfma_f32_16x16x32_bf16 v[36:39], v[148:151], v[202:205], v[36:39]
	v_mfma_f32_16x16x32_bf16 v[32:35], v[176:179], v[202:205], v[32:35]
	v_mfma_f32_16x16x32_bf16 v[20:23], v[148:151], v[210:213], v[20:23]
	v_mfma_f32_16x16x32_bf16 v[16:19], v[176:179], v[210:213], v[16:19]
	v_mfma_f32_16x16x32_bf16 v[4:7], v[148:151], v[218:221], v[4:7]
	v_mfma_f32_16x16x32_bf16 v[0:3], v[176:179], v[218:221], v[0:3]
	s_setprio 0
	s_barrier
	s_add_i32 s83, s83, 2
	s_add_u32 s81, s81, 0x100
	s_addc_u32 s82, s82, 0
	s_cmp_gt_u32 s83, 41
	s_mov_b64 s[54:55], s[56:57]
	s_branch .LBB0_159
.Lfa_1:
	ds_read_b128 v[128:131], v189
	ds_read_b128 v[132:135], v189 offset:1024
	ds_read_b128 v[136:139], v189 offset:2048
	ds_read_b128 v[140:143], v189 offset:3072
	ds_read_b128 v[144:147], v190
	ds_read_b128 v[148:151], v190 offset:1024
	ds_read_b128 v[172:175], v190 offset:2048
	ds_read_b128 v[176:179], v190 offset:3072
	s_add_u32 s56, s54, 0x100
	s_addc_u32 s57, s55, 0
	s_cmp_eq_u32 s83, 40
	s_cselect_b32 s61, s15, s57
	s_cselect_b32 s60, s14, s56
	s_cselect_b32 s59, s53, s82
	s_cselect_b32 s58, s52, s81
	v_lshl_add_u64 v[222:223], s[54:55], 0, v[166:167]
	s_add_i32 m0, s66, 0xc000
	ds_read_b128 v[180:183], v191
	ds_read_b128 v[194:197], v191 offset:1024
	ds_read_b128 v[198:201], v191 offset:2048
	ds_read_b128 v[202:205], v191 offset:3072
	ds_read_b128 v[206:209], v191 offset:4096
	ds_read_b128 v[210:213], v191 offset:5120
	ds_read_b128 v[214:217], v191 offset:6144
	ds_read_b128 v[218:221], v191 offset:7168
	global_load_lds_dwordx4 v[222:223], off
	v_lshl_add_u64 v[222:223], s[54:55], 0, v[164:165]
	s_add_i32 m0, s66, 0xe000
	s_nop 0
	global_load_lds_dwordx4 v[222:223], off
	s_waitcnt vmcnt(8)
	s_waitcnt lgkmcnt(0)
	s_barrier
	s_setprio 1
	s_waitcnt lgkmcnt(0)
	v_mfma_f32_16x16x32_bf16 v[124:127], v[128:131], v[180:183], 0
	v_mfma_f32_16x16x32_bf16 v[120:123], v[136:139], v[180:183], 0
	v_mfma_f32_16x16x32_bf16 v[108:111], v[128:131], v[198:201], 0
	v_mfma_f32_16x16x32_bf16 v[104:107], v[136:139], v[198:201], 0
	v_mfma_f32_16x16x32_bf16 v[92:95], v[128:131], v[206:209], 0
	v_mfma_f32_16x16x32_bf16 v[88:91], v[136:139], v[206:209], 0
	v_mfma_f32_16x16x32_bf16 v[76:79], v[128:131], v[214:217], 0
	v_mfma_f32_16x16x32_bf16 v[72:75], v[136:139], v[214:217], 0
	v_mfma_f32_16x16x32_bf16 v[124:127], v[132:135], v[194:197], v[124:127]
	v_mfma_f32_16x16x32_bf16 v[120:123], v[140:143], v[194:197], v[120:123]
	v_mfma_f32_16x16x32_bf16 v[108:111], v[132:135], v[202:205], v[108:111]
	v_mfma_f32_16x16x32_bf16 v[104:107], v[140:143], v[202:205], v[104:107]
	v_mfma_f32_16x16x32_bf16 v[92:95], v[132:135], v[210:213], v[92:95]
	v_mfma_f32_16x16x32_bf16 v[88:91], v[140:143], v[210:213], v[88:91]
	v_mfma_f32_16x16x32_bf16 v[76:79], v[132:135], v[218:221], v[76:79]
	v_mfma_f32_16x16x32_bf16 v[72:75], v[140:143], v[218:221], v[72:75]
	s_setprio 0
	s_setprio 1
	v_mfma_f32_16x16x32_bf16 v[116:119], v[144:147], v[180:183], 0
	v_mfma_f32_16x16x32_bf16 v[112:115], v[172:175], v[180:183], 0
	v_mfma_f32_16x16x32_bf16 v[100:103], v[144:147], v[198:201], 0
	v_mfma_f32_16x16x32_bf16 v[96:99], v[172:175], v[198:201], 0
	v_mfma_f32_16x16x32_bf16 v[84:87], v[144:147], v[206:209], 0
	v_mfma_f32_16x16x32_bf16 v[80:83], v[172:175], v[206:209], 0
	v_mfma_f32_16x16x32_bf16 v[68:71], v[144:147], v[214:217], 0
	v_mfma_f32_16x16x32_bf16 v[64:67], v[172:175], v[214:217], 0
	v_mfma_f32_16x16x32_bf16 v[116:119], v[148:151], v[194:197], v[116:119]
	v_mfma_f32_16x16x32_bf16 v[112:115], v[176:179], v[194:197], v[112:115]
	v_mfma_f32_16x16x32_bf16 v[100:103], v[148:151], v[202:205], v[100:103]
	v_mfma_f32_16x16x32_bf16 v[96:99], v[176:179], v[202:205], v[96:99]
	v_mfma_f32_16x16x32_bf16 v[84:87], v[148:151], v[210:213], v[84:87]
	v_mfma_f32_16x16x32_bf16 v[80:83], v[176:179], v[210:213], v[80:83]
	v_mfma_f32_16x16x32_bf16 v[68:71], v[148:151], v[218:221], v[68:71]
	v_mfma_f32_16x16x32_bf16 v[64:67], v[176:179], v[218:221], v[64:67]
	s_setprio 0
	s_barrier
	s_add_i32 s54, s77, s65
	v_lshl_add_u64 v[222:223], s[58:59], 0, v[154:155]
	s_mov_b32 m0, s54
	ds_read_b128 v[180:183], v191 offset:16384
	ds_read_b128 v[194:197], v191 offset:17408
	ds_read_b128 v[198:201], v191 offset:18432
	ds_read_b128 v[202:205], v191 offset:19456
	ds_read_b128 v[206:209], v191 offset:20480
	ds_read_b128 v[210:213], v191 offset:21504
	ds_read_b128 v[214:217], v191 offset:22528
	ds_read_b128 v[218:221], v191 offset:23552
	global_load_lds_dwordx4 v[222:223], off
	s_add_i32 m0, s54, 0x2000
	s_add_u32 s54, s58, 0xb0000
	v_lshl_add_u64 v[224:225], s[58:59], 0, v[162:163]
	s_addc_u32 s55, s59, 0
	s_add_i32 s84, s78, s65
	global_load_lds_dwordx4 v[224:225], off
	v_lshl_add_u64 v[226:227], s[54:55], 0, v[154:155]
	s_mov_b32 m0, s84
	v_lshl_add_u64 v[228:229], s[60:61], 0, v[160:161]
	global_load_lds_dwordx4 v[226:227], off
	v_lshl_add_u64 v[226:227], s[54:55], 0, v[162:163]
	s_add_i32 m0, s84, 0x2000
	s_nop 0
	global_load_lds_dwordx4 v[226:227], off
	v_lshl_add_u64 v[226:227], s[60:61], 0, v[152:153]
	s_mov_b32 m0, s66
	s_nop 0
	global_load_lds_dwordx4 v[226:227], off
	s_mov_b32 m0, s67
	s_nop 0
	global_load_lds_dwordx4 v[228:229], off
	s_waitcnt vmcnt(8)
	s_waitcnt lgkmcnt(0)
	s_barrier
	s_setprio 1
	s_waitcnt lgkmcnt(0)
	v_mfma_f32_16x16x32_bf16 v[60:63], v[128:131], v[180:183], 0
	v_mfma_f32_16x16x32_bf16 v[56:59], v[136:139], v[180:183], 0
	v_mfma_f32_16x16x32_bf16 v[44:47], v[128:131], v[198:201], 0
	v_mfma_f32_16x16x32_bf16 v[40:43], v[136:139], v[198:201], 0
	v_mfma_f32_16x16x32_bf16 v[28:31], v[128:131], v[206:209], 0
	v_mfma_f32_16x16x32_bf16 v[24:27], v[136:139], v[206:209], 0
	v_mfma_f32_16x16x32_bf16 v[12:15], v[128:131], v[214:217], 0
	v_mfma_f32_16x16x32_bf16 v[8:11], v[136:139], v[214:217], 0
	v_mfma_f32_16x16x32_bf16 v[60:63], v[132:135], v[194:197], v[60:63]
	v_mfma_f32_16x16x32_bf16 v[56:59], v[140:143], v[194:197], v[56:59]
	v_mfma_f32_16x16x32_bf16 v[44:47], v[132:135], v[202:205], v[44:47]
	v_mfma_f32_16x16x32_bf16 v[40:43], v[140:143], v[202:205], v[40:43]
	v_mfma_f32_16x16x32_bf16 v[28:31], v[132:135], v[210:213], v[28:31]
	v_mfma_f32_16x16x32_bf16 v[24:27], v[140:143], v[210:213], v[24:27]
	v_mfma_f32_16x16x32_bf16 v[12:15], v[132:135], v[218:221], v[12:15]
	v_mfma_f32_16x16x32_bf16 v[8:11], v[140:143], v[218:221], v[8:11]
	s_setprio 0
	s_setprio 1
	v_mfma_f32_16x16x32_bf16 v[52:55], v[144:147], v[180:183], 0
	v_mfma_f32_16x16x32_bf16 v[48:51], v[172:175], v[180:183], 0
	v_mfma_f32_16x16x32_bf16 v[36:39], v[144:147], v[198:201], 0
	v_mfma_f32_16x16x32_bf16 v[32:35], v[172:175], v[198:201], 0
	v_mfma_f32_16x16x32_bf16 v[20:23], v[144:147], v[206:209], 0
	v_mfma_f32_16x16x32_bf16 v[16:19], v[172:175], v[206:209], 0
	v_mfma_f32_16x16x32_bf16 v[4:7], v[144:147], v[214:217], 0
	v_mfma_f32_16x16x32_bf16 v[0:3], v[172:175], v[214:217], 0
	v_mfma_f32_16x16x32_bf16 v[52:55], v[148:151], v[194:197], v[52:55]
	v_mfma_f32_16x16x32_bf16 v[48:51], v[176:179], v[194:197], v[48:51]
	v_mfma_f32_16x16x32_bf16 v[36:39], v[148:151], v[202:205], v[36:39]
	v_mfma_f32_16x16x32_bf16 v[32:35], v[176:179], v[202:205], v[32:35]
	v_mfma_f32_16x16x32_bf16 v[20:23], v[148:151], v[210:213], v[20:23]
	v_mfma_f32_16x16x32_bf16 v[16:19], v[176:179], v[210:213], v[16:19]
	v_mfma_f32_16x16x32_bf16 v[4:7], v[148:151], v[218:221], v[4:7]
	v_mfma_f32_16x16x32_bf16 v[0:3], v[176:179], v[218:221], v[0:3]
	s_setprio 0
	s_barrier
	s_add_i32 s84, 0, 0x18000
	s_add_i32 s85, 0, 0x1c000
	v_add_u32_e32 v140, s84, v186
	v_add_u32_e32 v176, s85, v186
	ds_read_b128 v[128:131], v140
	ds_read_b128 v[132:135], v140 offset:1024
	ds_read_b128 v[136:139], v140 offset:2048
	ds_read_b128 v[140:143], v140 offset:3072
	ds_read_b128 v[144:147], v176
	ds_read_b128 v[148:151], v176 offset:1024
	ds_read_b128 v[172:175], v176 offset:2048
	ds_read_b128 v[176:179], v176 offset:3072
	s_add_u32 s54, s60, 0xb0000
	s_addc_u32 s55, s61, 0
	s_mov_b32 m0, s68
	v_lshl_add_u64 v[230:231], s[54:55], 0, v[152:153]
	ds_read_b128 v[180:183], v191 offset:32768
	ds_read_b128 v[194:197], v191 offset:33792
	ds_read_b128 v[198:201], v191 offset:34816
	ds_read_b128 v[202:205], v191 offset:35840
	ds_read_b128 v[206:209], v191 offset:36864
	ds_read_b128 v[210:213], v191 offset:37888
	ds_read_b128 v[214:217], v191 offset:38912
	ds_read_b128 v[218:221], v191 offset:39936
	global_load_lds_dwordx4 v[230:231], off
	v_lshl_add_u64 v[230:231], s[54:55], 0, v[160:161]
	s_mov_b32 m0, s69
	s_nop 0
	global_load_lds_dwordx4 v[230:231], off
	s_waitcnt vmcnt(8)
	s_waitcnt lgkmcnt(0)
	s_barrier
	s_setprio 1
	s_waitcnt lgkmcnt(0)
	v_mfma_f32_16x16x32_bf16 v[124:127], v[128:131], v[180:183], v[124:127]
	v_mfma_f32_16x16x32_bf16 v[120:123], v[136:139], v[180:183], v[120:123]
	v_mfma_f32_16x16x32_bf16 v[108:111], v[128:131], v[198:201], v[108:111]
	v_mfma_f32_16x16x32_bf16 v[104:107], v[136:139], v[198:201], v[104:107]
	v_mfma_f32_16x16x32_bf16 v[92:95], v[128:131], v[206:209], v[92:95]
	v_mfma_f32_16x16x32_bf16 v[88:91], v[136:139], v[206:209], v[88:91]
	v_mfma_f32_16x16x32_bf16 v[76:79], v[128:131], v[214:217], v[76:79]
	v_mfma_f32_16x16x32_bf16 v[72:75], v[136:139], v[214:217], v[72:75]
	v_mfma_f32_16x16x32_bf16 v[124:127], v[132:135], v[194:197], v[124:127]
	v_mfma_f32_16x16x32_bf16 v[120:123], v[140:143], v[194:197], v[120:123]
	v_mfma_f32_16x16x32_bf16 v[108:111], v[132:135], v[202:205], v[108:111]
	v_mfma_f32_16x16x32_bf16 v[104:107], v[140:143], v[202:205], v[104:107]
	v_mfma_f32_16x16x32_bf16 v[92:95], v[132:135], v[210:213], v[92:95]
	v_mfma_f32_16x16x32_bf16 v[88:91], v[140:143], v[210:213], v[88:91]
	v_mfma_f32_16x16x32_bf16 v[76:79], v[132:135], v[218:221], v[76:79]
	v_mfma_f32_16x16x32_bf16 v[72:75], v[140:143], v[218:221], v[72:75]
	s_setprio 0
	s_setprio 1
	v_mfma_f32_16x16x32_bf16 v[116:119], v[144:147], v[180:183], v[116:119]
	v_mfma_f32_16x16x32_bf16 v[112:115], v[172:175], v[180:183], v[112:115]
	v_mfma_f32_16x16x32_bf16 v[100:103], v[144:147], v[198:201], v[100:103]
	v_mfma_f32_16x16x32_bf16 v[96:99], v[172:175], v[198:201], v[96:99]
	v_mfma_f32_16x16x32_bf16 v[84:87], v[144:147], v[206:209], v[84:87]
	v_mfma_f32_16x16x32_bf16 v[80:83], v[172:175], v[206:209], v[80:83]
	v_mfma_f32_16x16x32_bf16 v[68:71], v[144:147], v[214:217], v[68:71]
	v_mfma_f32_16x16x32_bf16 v[64:67], v[172:175], v[214:217], v[64:67]
	v_mfma_f32_16x16x32_bf16 v[116:119], v[148:151], v[194:197], v[116:119]
	v_mfma_f32_16x16x32_bf16 v[112:115], v[176:179], v[194:197], v[112:115]
	v_mfma_f32_16x16x32_bf16 v[100:103], v[148:151], v[202:205], v[100:103]
	v_mfma_f32_16x16x32_bf16 v[96:99], v[176:179], v[202:205], v[96:99]
	v_mfma_f32_16x16x32_bf16 v[84:87], v[148:151], v[210:213], v[84:87]
	v_mfma_f32_16x16x32_bf16 v[80:83], v[176:179], v[210:213], v[80:83]
	v_mfma_f32_16x16x32_bf16 v[68:71], v[148:151], v[218:221], v[68:71]
	v_mfma_f32_16x16x32_bf16 v[64:67], v[176:179], v[218:221], v[64:67]
	s_setprio 0
	s_barrier
	s_add_i32 s54, s84, s65
	v_lshl_add_u64 v[222:223], v[222:223], 0, s[28:29]
	s_mov_b32 m0, s54
	ds_read_b128 v[180:183], v191 offset:49152
	ds_read_b128 v[194:197], v191 offset:50176
	ds_read_b128 v[198:201], v191 offset:51200
	ds_read_b128 v[202:205], v191 offset:52224
	ds_read_b128 v[206:209], v191 offset:53248
	ds_read_b128 v[210:213], v191 offset:54272
	ds_read_b128 v[214:217], v191 offset:55296
	ds_read_b128 v[218:221], v191 offset:56320
	global_load_lds_dwordx4 v[222:223], off
	s_add_i32 m0, s54, 0x2000
	s_add_u32 s54, s58, 0xb0080
	v_lshl_add_u64 v[222:223], v[224:225], 0, s[28:29]
	s_addc_u32 s55, s59, 0
	s_add_i32 s58, s85, s65
	global_load_lds_dwordx4 v[222:223], off
	v_lshl_add_u64 v[222:223], s[54:55], 0, v[154:155]
	s_mov_b32 m0, s58
	s_nop 0
	global_load_lds_dwordx4 v[222:223], off
	v_lshl_add_u64 v[222:223], s[54:55], 0, v[162:163]
	s_add_i32 m0, s58, 0x2000
	s_nop 0
	global_load_lds_dwordx4 v[222:223], off
	v_lshl_add_u64 v[222:223], v[226:227], 0, s[28:29]
	s_mov_b32 m0, s3
	s_nop 0
	global_load_lds_dwordx4 v[222:223], off
	v_lshl_add_u64 v[222:223], v[228:229], 0, s[28:29]
	s_mov_b32 m0, s71
	s_nop 0
	global_load_lds_dwordx4 v[222:223], off
	s_waitcnt vmcnt(8)
	s_waitcnt lgkmcnt(0)
	s_barrier
	s_setprio 1
	s_waitcnt lgkmcnt(0)
	v_mfma_f32_16x16x32_bf16 v[60:63], v[128:131], v[180:183], v[60:63]
	v_mfma_f32_16x16x32_bf16 v[56:59], v[136:139], v[180:183], v[56:59]
	v_mfma_f32_16x16x32_bf16 v[44:47], v[128:131], v[198:201], v[44:47]
	v_mfma_f32_16x16x32_bf16 v[40:43], v[136:139], v[198:201], v[40:43]
	v_mfma_f32_16x16x32_bf16 v[28:31], v[128:131], v[206:209], v[28:31]
	v_mfma_f32_16x16x32_bf16 v[24:27], v[136:139], v[206:209], v[24:27]
	v_mfma_f32_16x16x32_bf16 v[12:15], v[128:131], v[214:217], v[12:15]
	v_mfma_f32_16x16x32_bf16 v[8:11], v[136:139], v[214:217], v[8:11]
	v_mfma_f32_16x16x32_bf16 v[60:63], v[132:135], v[194:197], v[60:63]
	v_mfma_f32_16x16x32_bf16 v[56:59], v[140:143], v[194:197], v[56:59]
	v_mfma_f32_16x16x32_bf16 v[44:47], v[132:135], v[202:205], v[44:47]
	v_mfma_f32_16x16x32_bf16 v[40:43], v[140:143], v[202:205], v[40:43]
	v_mfma_f32_16x16x32_bf16 v[28:31], v[132:135], v[210:213], v[28:31]
	v_mfma_f32_16x16x32_bf16 v[24:27], v[140:143], v[210:213], v[24:27]
	v_mfma_f32_16x16x32_bf16 v[12:15], v[132:135], v[218:221], v[12:15]
	v_mfma_f32_16x16x32_bf16 v[8:11], v[140:143], v[218:221], v[8:11]
	s_setprio 0
	s_setprio 1
	v_mfma_f32_16x16x32_bf16 v[52:55], v[144:147], v[180:183], v[52:55]
	v_mfma_f32_16x16x32_bf16 v[48:51], v[172:175], v[180:183], v[48:51]
	v_mfma_f32_16x16x32_bf16 v[36:39], v[144:147], v[198:201], v[36:39]
	v_mfma_f32_16x16x32_bf16 v[32:35], v[172:175], v[198:201], v[32:35]
	v_mfma_f32_16x16x32_bf16 v[20:23], v[144:147], v[206:209], v[20:23]
	v_mfma_f32_16x16x32_bf16 v[16:19], v[172:175], v[206:209], v[16:19]
	v_mfma_f32_16x16x32_bf16 v[4:7], v[144:147], v[214:217], v[4:7]
	v_mfma_f32_16x16x32_bf16 v[0:3], v[172:175], v[214:217], v[0:3]
	v_mfma_f32_16x16x32_bf16 v[52:55], v[148:151], v[194:197], v[52:55]
	v_mfma_f32_16x16x32_bf16 v[48:51], v[176:179], v[194:197], v[48:51]
	v_mfma_f32_16x16x32_bf16 v[36:39], v[148:151], v[202:205], v[36:39]
	v_mfma_f32_16x16x32_bf16 v[32:35], v[176:179], v[202:205], v[32:35]
	v_mfma_f32_16x16x32_bf16 v[20:23], v[148:151], v[210:213], v[20:23]
	v_mfma_f32_16x16x32_bf16 v[16:19], v[176:179], v[210:213], v[16:19]
	v_mfma_f32_16x16x32_bf16 v[4:7], v[148:151], v[218:221], v[4:7]
	v_mfma_f32_16x16x32_bf16 v[0:3], v[176:179], v[218:221], v[0:3]
	s_setprio 0
	s_barrier
	s_add_i32 s83, s83, 2
	s_add_u32 s81, s81, 0x100
	s_addc_u32 s82, s82, 0
	s_cmp_gt_u32 s83, 41
	s_mov_b64 s[54:55], s[56:57]

.LBB0_254:
	s_ashr_i32 s61, s60, 31
	s_lshl_b64 s[62:63], s[60:61], 19
	s_add_u32 s62, s35, s62
	s_addc_u32 s63, s47, s63
	s_and_b64 s[64:65], s[12:13], exec
	s_cselect_b32 s3, s63, s69
	s_cselect_b32 s61, s62, s68
	s_ashr_i32 s59, s58, 31
	s_lshl_b64 s[64:65], s[58:59], 19
	s_add_u32 s64, s49, s64
	s_addc_u32 s65, s70, s65
	s_and_b64 s[92:93], s[12:13], exec
	s_cselect_b32 s91, s65, s67
	s_cselect_b32 s92, s64, s66
	s_lshl_b32 s59, s14, 8
	v_add_u32_e32 v0, s59, v182
	s_add_u32 s93, s66, 0x100
	s_waitcnt lgkmcnt(0)
	v_ashrrev_i32_e32 v1, 31, v0
	s_addc_u32 s94, s67, 0
	v_lshl_add_u64 v[72:73], v[0:1], 4, s[26:27]
	s_add_u32 s14, s68, 0x40080
	s_addc_u32 s15, s69, 0
	s_mov_b32 s95, -2
	s_mov_b64 s[66:67], 0
	s_cmp_eq_u32 s90, 1
	s_cbranch_scc1 .Lfa_2
	v_add_u32_e32 v74, s83, v181
	ds_read_b128 v[88:91], v74
	ds_read_b128 v[108:111], v74 offset:1024
	ds_read_b128 v[128:131], v74 offset:2048
	ds_read_b128 v[144:147], v74 offset:3072
	v_add_u32_e32 v74, s84, v181
	ds_read_b128 v[148:151], v74
	ds_read_b128 v[152:155], v74 offset:1024
	ds_read_b128 v[176:179], v74 offset:2048
	ds_read_b128 v[190:193], v74 offset:3072
	s_add_u32 s68, s14, 0xfffc0080
	s_addc_u32 s69, s15, -1
	s_and_b64 s[66:67], s[66:67], exec
	s_cselect_b32 s69, s3, s69
	s_cselect_b32 s68, s61, s68
	s_cselect_b32 s67, s91, s94
	s_cselect_b32 s66, s92, s93
	v_lshl_add_u64 v[74:75], s[14:15], 0, v[170:171]
	s_add_i32 m0, s74, 0xc000
	ds_read_b128 v[194:197], v187
	ds_read_b128 v[198:201], v187 offset:1024
	ds_read_b128 v[202:205], v187 offset:2048
	ds_read_b128 v[206:209], v187 offset:3072
	ds_read_b128 v[210:213], v187 offset:4096
	ds_read_b128 v[214:217], v187 offset:5120
	ds_read_b128 v[218:221], v187 offset:6144
	ds_read_b128 v[222:225], v187 offset:7168
	global_load_lds_dwordx4 v[74:75], off
	v_lshl_add_u64 v[74:75], s[14:15], 0, v[168:169]
	s_add_i32 m0, s74, 0xe000
	s_nop 0
	global_load_lds_dwordx4 v[74:75], off
	s_waitcnt vmcnt(24)
	s_waitcnt lgkmcnt(0)
	s_barrier
	s_setprio 1
	s_waitcnt lgkmcnt(0)
	v_mfma_f32_16x16x32_bf16 v[140:143], v[88:91], v[194:197], 0
	v_mfma_f32_16x16x32_bf16 v[136:139], v[128:131], v[194:197], 0
	v_mfma_f32_16x16x32_bf16 v[120:123], v[88:91], v[202:205], 0
	v_mfma_f32_16x16x32_bf16 v[116:119], v[128:131], v[202:205], 0
	v_mfma_f32_16x16x32_bf16 v[100:103], v[88:91], v[210:213], 0
	v_mfma_f32_16x16x32_bf16 v[96:99], v[128:131], v[210:213], 0
	v_mfma_f32_16x16x32_bf16 v[80:83], v[88:91], v[218:221], 0
	v_mfma_f32_16x16x32_bf16 v[74:77], v[128:131], v[218:221], 0
	v_mfma_f32_16x16x32_bf16 v[140:143], v[108:111], v[198:201], v[140:143]
	v_mfma_f32_16x16x32_bf16 v[136:139], v[144:147], v[198:201], v[136:139]
	v_mfma_f32_16x16x32_bf16 v[120:123], v[108:111], v[206:209], v[120:123]
	v_mfma_f32_16x16x32_bf16 v[116:119], v[144:147], v[206:209], v[116:119]
	v_mfma_f32_16x16x32_bf16 v[100:103], v[108:111], v[214:217], v[100:103]
	v_mfma_f32_16x16x32_bf16 v[96:99], v[144:147], v[214:217], v[96:99]
	v_mfma_f32_16x16x32_bf16 v[80:83], v[108:111], v[222:225], v[80:83]
	v_mfma_f32_16x16x32_bf16 v[74:77], v[144:147], v[222:225], v[74:77]
	s_setprio 0
	s_setprio 1
	v_mfma_f32_16x16x32_bf16 v[132:135], v[148:151], v[194:197], 0
	v_mfma_f32_16x16x32_bf16 v[124:127], v[176:179], v[194:197], 0
	v_mfma_f32_16x16x32_bf16 v[112:115], v[148:151], v[202:205], 0
	v_mfma_f32_16x16x32_bf16 v[104:107], v[176:179], v[202:205], 0
	v_mfma_f32_16x16x32_bf16 v[92:95], v[148:151], v[210:213], 0
	v_mfma_f32_16x16x32_bf16 v[84:87], v[176:179], v[210:213], 0
	v_mfma_f32_16x16x32_bf16 v[68:71], v[148:151], v[218:221], 0
	v_mfma_f32_16x16x32_bf16 v[64:67], v[176:179], v[218:221], 0
	v_mfma_f32_16x16x32_bf16 v[132:135], v[152:155], v[198:201], v[132:135]
	v_mfma_f32_16x16x32_bf16 v[124:127], v[190:193], v[198:201], v[124:127]
	v_mfma_f32_16x16x32_bf16 v[112:115], v[152:155], v[206:209], v[112:115]
	v_mfma_f32_16x16x32_bf16 v[104:107], v[190:193], v[206:209], v[104:107]
	v_mfma_f32_16x16x32_bf16 v[92:95], v[152:155], v[214:217], v[92:95]
	v_mfma_f32_16x16x32_bf16 v[84:87], v[190:193], v[214:217], v[84:87]
	v_mfma_f32_16x16x32_bf16 v[68:71], v[152:155], v[222:225], v[68:71]
	v_mfma_f32_16x16x32_bf16 v[64:67], v[190:193], v[222:225], v[64:67]
	s_setprio 0
	s_barrier
	s_add_i32 s96, s83, s71
	v_lshl_add_u64 v[226:227], s[66:67], 0, v[162:163]
	s_mov_b32 m0, s96
	ds_read_b128 v[194:197], v187 offset:16384
	ds_read_b128 v[198:201], v187 offset:17408
	ds_read_b128 v[202:205], v187 offset:18432
	ds_read_b128 v[206:209], v187 offset:19456
	ds_read_b128 v[210:213], v187 offset:20480
	ds_read_b128 v[214:217], v187 offset:21504
	ds_read_b128 v[218:221], v187 offset:22528
	ds_read_b128 v[222:225], v187 offset:23552
	global_load_lds_dwordx4 v[226:227], off
	s_add_i32 m0, s96, 0x2000
	s_add_u32 s96, s66, 0x40000
	v_lshl_add_u64 v[228:229], s[66:67], 0, v[166:167]
	s_addc_u32 s97, s67, 0
	s_add_i32 vcc_lo, s84, s71
	global_load_lds_dwordx4 v[228:229], off
	v_lshl_add_u64 v[78:79], s[96:97], 0, v[162:163]
	s_mov_b32 m0, vcc_lo
	v_lshl_add_u64 v[230:231], s[68:69], 0, v[160:161]
	global_load_lds_dwordx4 v[78:79], off
	v_lshl_add_u64 v[78:79], s[96:97], 0, v[166:167]
	s_add_i32 m0, vcc_lo, 0x2000
	v_lshl_add_u64 v[232:233], s[68:69], 0, v[164:165]
	global_load_lds_dwordx4 v[78:79], off
	s_mov_b32 m0, s74
	s_nop 0
	global_load_lds_dwordx4 v[230:231], off
	s_mov_b32 m0, s75
	s_nop 0
	global_load_lds_dwordx4 v[232:233], off
	s_waitcnt vmcnt(24)
	s_waitcnt lgkmcnt(0)
	s_barrier
	s_setprio 1
	s_waitcnt lgkmcnt(0)
	v_mfma_f32_16x16x32_bf16 v[60:63], v[88:91], v[194:197], 0
	v_mfma_f32_16x16x32_bf16 v[56:59], v[128:131], v[194:197], 0
	v_mfma_f32_16x16x32_bf16 v[44:47], v[88:91], v[202:205], 0
	v_mfma_f32_16x16x32_bf16 v[40:43], v[128:131], v[202:205], 0
	v_mfma_f32_16x16x32_bf16 v[28:31], v[88:91], v[210:213], 0
	v_mfma_f32_16x16x32_bf16 v[24:27], v[128:131], v[210:213], 0
	v_mfma_f32_16x16x32_bf16 v[12:15], v[88:91], v[218:221], 0
	v_mfma_f32_16x16x32_bf16 v[8:11], v[128:131], v[218:221], 0
	v_mfma_f32_16x16x32_bf16 v[60:63], v[108:111], v[198:201], v[60:63]
	v_mfma_f32_16x16x32_bf16 v[56:59], v[144:147], v[198:201], v[56:59]
	v_mfma_f32_16x16x32_bf16 v[44:47], v[108:111], v[206:209], v[44:47]
	v_mfma_f32_16x16x32_bf16 v[40:43], v[144:147], v[206:209], v[40:43]
	v_mfma_f32_16x16x32_bf16 v[28:31], v[108:111], v[214:217], v[28:31]
	v_mfma_f32_16x16x32_bf16 v[24:27], v[144:147], v[214:217], v[24:27]
	v_mfma_f32_16x16x32_bf16 v[12:15], v[108:111], v[222:225], v[12:15]
	v_mfma_f32_16x16x32_bf16 v[8:11], v[144:147], v[222:225], v[8:11]
	s_setprio 0
	s_setprio 1
	v_mfma_f32_16x16x32_bf16 v[52:55], v[148:151], v[194:197], 0
	v_mfma_f32_16x16x32_bf16 v[48:51], v[176:179], v[194:197], 0
	v_mfma_f32_16x16x32_bf16 v[36:39], v[148:151], v[202:205], 0
	v_mfma_f32_16x16x32_bf16 v[32:35], v[176:179], v[202:205], 0
	v_mfma_f32_16x16x32_bf16 v[20:23], v[148:151], v[210:213], 0
	v_mfma_f32_16x16x32_bf16 v[16:19], v[176:179], v[210:213], 0
	v_mfma_f32_16x16x32_bf16 v[4:7], v[148:151], v[218:221], 0
	v_mfma_f32_16x16x32_bf16 v[0:3], v[176:179], v[218:221], 0
	v_mfma_f32_16x16x32_bf16 v[52:55], v[152:155], v[198:201], v[52:55]
	v_mfma_f32_16x16x32_bf16 v[48:51], v[190:193], v[198:201], v[48:51]
	v_mfma_f32_16x16x32_bf16 v[36:39], v[152:155], v[206:209], v[36:39]
	v_mfma_f32_16x16x32_bf16 v[32:35], v[190:193], v[206:209], v[32:35]
	v_mfma_f32_16x16x32_bf16 v[20:23], v[152:155], v[214:217], v[20:23]
	v_mfma_f32_16x16x32_bf16 v[16:19], v[190:193], v[214:217], v[16:19]
	v_mfma_f32_16x16x32_bf16 v[4:7], v[152:155], v[222:225], v[4:7]
	v_mfma_f32_16x16x32_bf16 v[0:3], v[190:193], v[222:225], v[0:3]
	s_setprio 0
	s_barrier
	s_add_i32 s96, 0, 0x18000
	v_add_u32_e32 v78, s96, v181
	s_add_i32 s97, 0, 0x1c000
	ds_read_b128 v[88:91], v78
	ds_read_b128 v[108:111], v78 offset:1024
	ds_read_b128 v[128:131], v78 offset:2048
	ds_read_b128 v[144:147], v78 offset:3072
	v_add_u32_e32 v78, s97, v181
	ds_read_b128 v[148:151], v78
	ds_read_b128 v[152:155], v78 offset:1024
	ds_read_b128 v[176:179], v78 offset:2048
	ds_read_b128 v[190:193], v78 offset:3072
	s_add_u32 s68, s68, 0x40000
	s_addc_u32 s69, s69, 0
	s_mov_b32 m0, s76
	v_lshl_add_u64 v[78:79], s[68:69], 0, v[160:161]
	ds_read_b128 v[194:197], v187 offset:32768
	ds_read_b128 v[198:201], v187 offset:33792
	ds_read_b128 v[202:205], v187 offset:34816
	ds_read_b128 v[206:209], v187 offset:35840
	ds_read_b128 v[210:213], v187 offset:36864
	ds_read_b128 v[214:217], v187 offset:37888
	ds_read_b128 v[218:221], v187 offset:38912
	ds_read_b128 v[222:225], v187 offset:39936
	global_load_lds_dwordx4 v[78:79], off
	v_lshl_add_u64 v[78:79], s[68:69], 0, v[164:165]
	s_mov_b32 m0, s77
	s_nop 0
	global_load_lds_dwordx4 v[78:79], off
	s_waitcnt vmcnt(8)
	s_waitcnt lgkmcnt(0)
	s_barrier
	s_setprio 1
	s_waitcnt lgkmcnt(0)
	v_mfma_f32_16x16x32_bf16 v[140:143], v[88:91], v[194:197], v[140:143]
	v_mfma_f32_16x16x32_bf16 v[136:139], v[128:131], v[194:197], v[136:139]
	v_mfma_f32_16x16x32_bf16 v[120:123], v[88:91], v[202:205], v[120:123]
	v_mfma_f32_16x16x32_bf16 v[116:119], v[128:131], v[202:205], v[116:119]
	v_mfma_f32_16x16x32_bf16 v[100:103], v[88:91], v[210:213], v[100:103]
	v_mfma_f32_16x16x32_bf16 v[96:99], v[128:131], v[210:213], v[96:99]
	v_mfma_f32_16x16x32_bf16 v[78:81], v[88:91], v[218:221], v[80:83]
	v_mfma_f32_16x16x32_bf16 v[74:77], v[128:131], v[218:221], v[74:77]
	v_mfma_f32_16x16x32_bf16 v[140:143], v[108:111], v[198:201], v[140:143]
	v_mfma_f32_16x16x32_bf16 v[136:139], v[144:147], v[198:201], v[136:139]
	v_mfma_f32_16x16x32_bf16 v[120:123], v[108:111], v[206:209], v[120:123]
	v_mfma_f32_16x16x32_bf16 v[116:119], v[144:147], v[206:209], v[116:119]
	v_mfma_f32_16x16x32_bf16 v[100:103], v[108:111], v[214:217], v[100:103]
	v_mfma_f32_16x16x32_bf16 v[96:99], v[144:147], v[214:217], v[96:99]
	v_mfma_f32_16x16x32_bf16 v[80:83], v[108:111], v[222:225], v[78:81]
	v_mfma_f32_16x16x32_bf16 v[76:79], v[144:147], v[222:225], v[74:77]
	s_setprio 0
	s_setprio 1
	v_mfma_f32_16x16x32_bf16 v[132:135], v[148:151], v[194:197], v[132:135]
	v_mfma_f32_16x16x32_bf16 v[124:127], v[176:179], v[194:197], v[124:127]
	v_mfma_f32_16x16x32_bf16 v[112:115], v[148:151], v[202:205], v[112:115]
	v_mfma_f32_16x16x32_bf16 v[104:107], v[176:179], v[202:205], v[104:107]
	v_mfma_f32_16x16x32_bf16 v[92:95], v[148:151], v[210:213], v[92:95]
	v_mfma_f32_16x16x32_bf16 v[84:87], v[176:179], v[210:213], v[84:87]
	v_mfma_f32_16x16x32_bf16 v[68:71], v[148:151], v[218:221], v[68:71]
	v_mfma_f32_16x16x32_bf16 v[64:67], v[176:179], v[218:221], v[64:67]
	v_mfma_f32_16x16x32_bf16 v[132:135], v[152:155], v[198:201], v[132:135]
	v_mfma_f32_16x16x32_bf16 v[124:127], v[190:193], v[198:201], v[124:127]
	v_mfma_f32_16x16x32_bf16 v[112:115], v[152:155], v[206:209], v[112:115]
	v_mfma_f32_16x16x32_bf16 v[104:107], v[190:193], v[206:209], v[104:107]
	v_mfma_f32_16x16x32_bf16 v[92:95], v[152:155], v[214:217], v[92:95]
	v_mfma_f32_16x16x32_bf16 v[84:87], v[190:193], v[214:217], v[84:87]
	v_mfma_f32_16x16x32_bf16 v[68:71], v[152:155], v[222:225], v[68:71]
	v_mfma_f32_16x16x32_bf16 v[64:67], v[190:193], v[222:225], v[64:67]
	s_setprio 0
	s_barrier
	s_add_i32 s68, s96, s71
	v_lshl_add_u64 v[74:75], v[226:227], 0, s[28:29]
	s_mov_b32 m0, s68
	ds_read_b128 v[194:197], v187 offset:49152
	ds_read_b128 v[198:201], v187 offset:50176
	ds_read_b128 v[202:205], v187 offset:51200
	ds_read_b128 v[206:209], v187 offset:52224
	ds_read_b128 v[210:213], v187 offset:53248
	ds_read_b128 v[214:217], v187 offset:54272
	ds_read_b128 v[218:221], v187 offset:55296
	ds_read_b128 v[222:225], v187 offset:56320
	global_load_lds_dwordx4 v[74:75], off
	s_add_i32 m0, s68, 0x2000
	s_add_u32 s66, s66, 0x40080
	v_lshl_add_u64 v[74:75], v[228:229], 0, s[28:29]
	s_addc_u32 s67, s67, 0
	s_add_i32 s68, s97, s71
	global_load_lds_dwordx4 v[74:75], off
	v_lshl_add_u64 v[74:75], s[66:67], 0, v[162:163]
	s_mov_b32 m0, s68
	s_nop 0
	global_load_lds_dwordx4 v[74:75], off
	v_lshl_add_u64 v[74:75], s[66:67], 0, v[166:167]
	s_add_i32 m0, s68, 0x2000
	s_nop 0
	global_load_lds_dwordx4 v[74:75], off
	v_lshl_add_u64 v[74:75], v[230:231], 0, s[28:29]
	s_mov_b32 m0, s78
	s_nop 0
	global_load_lds_dwordx4 v[74:75], off
	v_lshl_add_u64 v[74:75], v[232:233], 0, s[28:29]
	s_mov_b32 m0, s79
	s_nop 0
	global_load_lds_dwordx4 v[74:75], off
	s_waitcnt vmcnt(8)
	s_waitcnt lgkmcnt(0)
	s_barrier
	s_setprio 1
	s_waitcnt lgkmcnt(0)
	v_mfma_f32_16x16x32_bf16 v[60:63], v[88:91], v[194:197], v[60:63]
	v_mfma_f32_16x16x32_bf16 v[56:59], v[128:131], v[194:197], v[56:59]
	v_mfma_f32_16x16x32_bf16 v[44:47], v[88:91], v[202:205], v[44:47]
	v_mfma_f32_16x16x32_bf16 v[40:43], v[128:131], v[202:205], v[40:43]
	v_mfma_f32_16x16x32_bf16 v[28:31], v[88:91], v[210:213], v[28:31]
	v_mfma_f32_16x16x32_bf16 v[24:27], v[128:131], v[210:213], v[24:27]
	v_mfma_f32_16x16x32_bf16 v[12:15], v[88:91], v[218:221], v[12:15]
	v_mfma_f32_16x16x32_bf16 v[8:11], v[128:131], v[218:221], v[8:11]
	v_mfma_f32_16x16x32_bf16 v[60:63], v[108:111], v[198:201], v[60:63]
	v_mfma_f32_16x16x32_bf16 v[56:59], v[144:147], v[198:201], v[56:59]
	v_mfma_f32_16x16x32_bf16 v[44:47], v[108:111], v[206:209], v[44:47]
	v_mfma_f32_16x16x32_bf16 v[40:43], v[144:147], v[206:209], v[40:43]
	v_mfma_f32_16x16x32_bf16 v[28:31], v[108:111], v[214:217], v[28:31]
	v_mfma_f32_16x16x32_bf16 v[24:27], v[144:147], v[214:217], v[24:27]
	v_mfma_f32_16x16x32_bf16 v[12:15], v[108:111], v[222:225], v[12:15]
	v_mfma_f32_16x16x32_bf16 v[8:11], v[144:147], v[222:225], v[8:11]
	s_setprio 0
	s_setprio 1
	v_mfma_f32_16x16x32_bf16 v[52:55], v[148:151], v[194:197], v[52:55]
	v_mfma_f32_16x16x32_bf16 v[48:51], v[176:179], v[194:197], v[48:51]
	v_mfma_f32_16x16x32_bf16 v[36:39], v[148:151], v[202:205], v[36:39]
	v_mfma_f32_16x16x32_bf16 v[32:35], v[176:179], v[202:205], v[32:35]
	v_mfma_f32_16x16x32_bf16 v[20:23], v[148:151], v[210:213], v[20:23]
	v_mfma_f32_16x16x32_bf16 v[16:19], v[176:179], v[210:213], v[16:19]
	v_mfma_f32_16x16x32_bf16 v[4:7], v[148:151], v[218:221], v[4:7]
	v_mfma_f32_16x16x32_bf16 v[0:3], v[176:179], v[218:221], v[0:3]
	v_mfma_f32_16x16x32_bf16 v[52:55], v[152:155], v[198:201], v[52:55]
	v_mfma_f32_16x16x32_bf16 v[48:51], v[190:193], v[198:201], v[48:51]
	v_mfma_f32_16x16x32_bf16 v[36:39], v[152:155], v[206:209], v[36:39]
	v_mfma_f32_16x16x32_bf16 v[32:35], v[190:193], v[206:209], v[32:35]
	v_mfma_f32_16x16x32_bf16 v[20:23], v[152:155], v[214:217], v[20:23]
	v_mfma_f32_16x16x32_bf16 v[16:19], v[190:193], v[214:217], v[16:19]
	v_mfma_f32_16x16x32_bf16 v[4:7], v[152:155], v[222:225], v[4:7]
	v_mfma_f32_16x16x32_bf16 v[0:3], v[190:193], v[222:225], v[0:3]
	s_setprio 0
	s_barrier
	s_add_i32 s95, s95, 2
	s_add_u32 s93, s93, 0x100
	s_addc_u32 s94, s94, 0
	s_add_u32 s14, s14, 0x100
	s_addc_u32 s15, s15, 0
	s_branch .LBB0_256
.Lfa_2:
	v_add_u32_e32 v74, s83, v181
	ds_read_b128 v[88:91], v74
	ds_read_b128 v[108:111], v74 offset:1024
	ds_read_b128 v[128:131], v74 offset:2048
	ds_read_b128 v[144:147], v74 offset:3072
	v_add_u32_e32 v74, s84, v181
	ds_read_b128 v[148:151], v74
	ds_read_b128 v[152:155], v74 offset:1024
	ds_read_b128 v[176:179], v74 offset:2048
	ds_read_b128 v[190:193], v74 offset:3072
	s_add_u32 s68, s14, 0xfffc0080
	s_addc_u32 s69, s15, -1
	s_and_b64 s[66:67], s[66:67], exec
	s_cselect_b32 s69, s3, s69
	s_cselect_b32 s68, s61, s68
	s_cselect_b32 s67, s91, s94
	s_cselect_b32 s66, s92, s93
	v_lshl_add_u64 v[74:75], s[14:15], 0, v[170:171]
	s_add_i32 m0, s74, 0xc000
	ds_read_b128 v[194:197], v187
	ds_read_b128 v[198:201], v187 offset:1024
	ds_read_b128 v[202:205], v187 offset:2048
	ds_read_b128 v[206:209], v187 offset:3072
	ds_read_b128 v[210:213], v187 offset:4096
	ds_read_b128 v[214:217], v187 offset:5120
	ds_read_b128 v[218:221], v187 offset:6144
	ds_read_b128 v[222:225], v187 offset:7168
	global_load_lds_dwordx4 v[74:75], off
	v_lshl_add_u64 v[74:75], s[14:15], 0, v[168:169]
	s_add_i32 m0, s74, 0xe000
	s_nop 0
	global_load_lds_dwordx4 v[74:75], off
	s_waitcnt vmcnt(8)
	s_waitcnt lgkmcnt(0)
	s_barrier
	s_setprio 1
	s_waitcnt lgkmcnt(0)
	v_mfma_f32_16x16x32_bf16 v[140:143], v[88:91], v[194:197], 0
	v_mfma_f32_16x16x32_bf16 v[136:139], v[128:131], v[194:197], 0
	v_mfma_f32_16x16x32_bf16 v[120:123], v[88:91], v[202:205], 0
	v_mfma_f32_16x16x32_bf16 v[116:119], v[128:131], v[202:205], 0
	v_mfma_f32_16x16x32_bf16 v[100:103], v[88:91], v[210:213], 0
	v_mfma_f32_16x16x32_bf16 v[96:99], v[128:131], v[210:213], 0
	v_mfma_f32_16x16x32_bf16 v[80:83], v[88:91], v[218:221], 0
	v_mfma_f32_16x16x32_bf16 v[74:77], v[128:131], v[218:221], 0
	v_mfma_f32_16x16x32_bf16 v[140:143], v[108:111], v[198:201], v[140:143]
	v_mfma_f32_16x16x32_bf16 v[136:139], v[144:147], v[198:201], v[136:139]
	v_mfma_f32_16x16x32_bf16 v[120:123], v[108:111], v[206:209], v[120:123]
	v_mfma_f32_16x16x32_bf16 v[116:119], v[144:147], v[206:209], v[116:119]
	v_mfma_f32_16x16x32_bf16 v[100:103], v[108:111], v[214:217], v[100:103]
	v_mfma_f32_16x16x32_bf16 v[96:99], v[144:147], v[214:217], v[96:99]
	v_mfma_f32_16x16x32_bf16 v[80:83], v[108:111], v[222:225], v[80:83]
	v_mfma_f32_16x16x32_bf16 v[74:77], v[144:147], v[222:225], v[74:77]
	s_setprio 0
	s_setprio 1
	v_mfma_f32_16x16x32_bf16 v[132:135], v[148:151], v[194:197], 0
	v_mfma_f32_16x16x32_bf16 v[124:127], v[176:179], v[194:197], 0
	v_mfma_f32_16x16x32_bf16 v[112:115], v[148:151], v[202:205], 0
	v_mfma_f32_16x16x32_bf16 v[104:107], v[176:179], v[202:205], 0
	v_mfma_f32_16x16x32_bf16 v[92:95], v[148:151], v[210:213], 0
	v_mfma_f32_16x16x32_bf16 v[84:87], v[176:179], v[210:213], 0
	v_mfma_f32_16x16x32_bf16 v[68:71], v[148:151], v[218:221], 0
	v_mfma_f32_16x16x32_bf16 v[64:67], v[176:179], v[218:221], 0
	v_mfma_f32_16x16x32_bf16 v[132:135], v[152:155], v[198:201], v[132:135]
	v_mfma_f32_16x16x32_bf16 v[124:127], v[190:193], v[198:201], v[124:127]
	v_mfma_f32_16x16x32_bf16 v[112:115], v[152:155], v[206:209], v[112:115]
	v_mfma_f32_16x16x32_bf16 v[104:107], v[190:193], v[206:209], v[104:107]
	v_mfma_f32_16x16x32_bf16 v[92:95], v[152:155], v[214:217], v[92:95]
	v_mfma_f32_16x16x32_bf16 v[84:87], v[190:193], v[214:217], v[84:87]
	v_mfma_f32_16x16x32_bf16 v[68:71], v[152:155], v[222:225], v[68:71]
	v_mfma_f32_16x16x32_bf16 v[64:67], v[190:193], v[222:225], v[64:67]
	s_setprio 0
	s_barrier
	s_add_i32 s96, s83, s71
	v_lshl_add_u64 v[226:227], s[66:67], 0, v[162:163]
	s_mov_b32 m0, s96
	ds_read_b128 v[194:197], v187 offset:16384
	ds_read_b128 v[198:201], v187 offset:17408
	ds_read_b128 v[202:205], v187 offset:18432
	ds_read_b128 v[206:209], v187 offset:19456
	ds_read_b128 v[210:213], v187 offset:20480
	ds_read_b128 v[214:217], v187 offset:21504
	ds_read_b128 v[218:221], v187 offset:22528
	ds_read_b128 v[222:225], v187 offset:23552
	global_load_lds_dwordx4 v[226:227], off
	s_add_i32 m0, s96, 0x2000
	s_add_u32 s96, s66, 0x40000
	v_lshl_add_u64 v[228:229], s[66:67], 0, v[166:167]
	s_addc_u32 s97, s67, 0
	s_add_i32 vcc_lo, s84, s71
	global_load_lds_dwordx4 v[228:229], off
	v_lshl_add_u64 v[78:79], s[96:97], 0, v[162:163]
	s_mov_b32 m0, vcc_lo
	v_lshl_add_u64 v[230:231], s[68:69], 0, v[160:161]
	global_load_lds_dwordx4 v[78:79], off
	v_lshl_add_u64 v[78:79], s[96:97], 0, v[166:167]
	s_add_i32 m0, vcc_lo, 0x2000
	v_lshl_add_u64 v[232:233], s[68:69], 0, v[164:165]
	global_load_lds_dwordx4 v[78:79], off
	s_mov_b32 m0, s74
	s_nop 0
	global_load_lds_dwordx4 v[230:231], off
	s_mov_b32 m0, s75
	s_nop 0
	global_load_lds_dwordx4 v[232:233], off
	s_waitcnt vmcnt(8)
	s_waitcnt lgkmcnt(0)
	s_barrier
	s_setprio 1
	s_waitcnt lgkmcnt(0)
	v_mfma_f32_16x16x32_bf16 v[60:63], v[88:91], v[194:197], 0
	v_mfma_f32_16x16x32_bf16 v[56:59], v[128:131], v[194:197], 0
	v_mfma_f32_16x16x32_bf16 v[44:47], v[88:91], v[202:205], 0
	v_mfma_f32_16x16x32_bf16 v[40:43], v[128:131], v[202:205], 0
	v_mfma_f32_16x16x32_bf16 v[28:31], v[88:91], v[210:213], 0
	v_mfma_f32_16x16x32_bf16 v[24:27], v[128:131], v[210:213], 0
	v_mfma_f32_16x16x32_bf16 v[12:15], v[88:91], v[218:221], 0
	v_mfma_f32_16x16x32_bf16 v[8:11], v[128:131], v[218:221], 0
	v_mfma_f32_16x16x32_bf16 v[60:63], v[108:111], v[198:201], v[60:63]
	v_mfma_f32_16x16x32_bf16 v[56:59], v[144:147], v[198:201], v[56:59]
	v_mfma_f32_16x16x32_bf16 v[44:47], v[108:111], v[206:209], v[44:47]
	v_mfma_f32_16x16x32_bf16 v[40:43], v[144:147], v[206:209], v[40:43]
	v_mfma_f32_16x16x32_bf16 v[28:31], v[108:111], v[214:217], v[28:31]
	v_mfma_f32_16x16x32_bf16 v[24:27], v[144:147], v[214:217], v[24:27]
	v_mfma_f32_16x16x32_bf16 v[12:15], v[108:111], v[222:225], v[12:15]
	v_mfma_f32_16x16x32_bf16 v[8:11], v[144:147], v[222:225], v[8:11]
	s_setprio 0
	s_setprio 1
	v_mfma_f32_16x16x32_bf16 v[52:55], v[148:151], v[194:197], 0
	v_mfma_f32_16x16x32_bf16 v[48:51], v[176:179], v[194:197], 0
	v_mfma_f32_16x16x32_bf16 v[36:39], v[148:151], v[202:205], 0
	v_mfma_f32_16x16x32_bf16 v[32:35], v[176:179], v[202:205], 0
	v_mfma_f32_16x16x32_bf16 v[20:23], v[148:151], v[210:213], 0
	v_mfma_f32_16x16x32_bf16 v[16:19], v[176:179], v[210:213], 0
	v_mfma_f32_16x16x32_bf16 v[4:7], v[148:151], v[218:221], 0
	v_mfma_f32_16x16x32_bf16 v[0:3], v[176:179], v[218:221], 0
	v_mfma_f32_16x16x32_bf16 v[52:55], v[152:155], v[198:201], v[52:55]
	v_mfma_f32_16x16x32_bf16 v[48:51], v[190:193], v[198:201], v[48:51]
	v_mfma_f32_16x16x32_bf16 v[36:39], v[152:155], v[206:209], v[36:39]
	v_mfma_f32_16x16x32_bf16 v[32:35], v[190:193], v[206:209], v[32:35]
	v_mfma_f32_16x16x32_bf16 v[20:23], v[152:155], v[214:217], v[20:23]
	v_mfma_f32_16x16x32_bf16 v[16:19], v[190:193], v[214:217], v[16:19]
	v_mfma_f32_16x16x32_bf16 v[4:7], v[152:155], v[222:225], v[4:7]
	v_mfma_f32_16x16x32_bf16 v[0:3], v[190:193], v[222:225], v[0:3]
	s_setprio 0
	s_barrier
	s_add_i32 s96, 0, 0x18000
	v_add_u32_e32 v78, s96, v181
	s_add_i32 s97, 0, 0x1c000
	ds_read_b128 v[88:91], v78
	ds_read_b128 v[108:111], v78 offset:1024
	ds_read_b128 v[128:131], v78 offset:2048
	ds_read_b128 v[144:147], v78 offset:3072
	v_add_u32_e32 v78, s97, v181
	ds_read_b128 v[148:151], v78
	ds_read_b128 v[152:155], v78 offset:1024
	ds_read_b128 v[176:179], v78 offset:2048
	ds_read_b128 v[190:193], v78 offset:3072
	s_add_u32 s68, s68, 0x40000
	s_addc_u32 s69, s69, 0
	s_mov_b32 m0, s76
	v_lshl_add_u64 v[78:79], s[68:69], 0, v[160:161]
	ds_read_b128 v[194:197], v187 offset:32768
	ds_read_b128 v[198:201], v187 offset:33792
	ds_read_b128 v[202:205], v187 offset:34816
	ds_read_b128 v[206:209], v187 offset:35840
	ds_read_b128 v[210:213], v187 offset:36864
	ds_read_b128 v[214:217], v187 offset:37888
	ds_read_b128 v[218:221], v187 offset:38912
	ds_read_b128 v[222:225], v187 offset:39936
	global_load_lds_dwordx4 v[78:79], off
	v_lshl_add_u64 v[78:79], s[68:69], 0, v[164:165]
	s_mov_b32 m0, s77
	s_nop 0
	global_load_lds_dwordx4 v[78:79], off
	s_waitcnt vmcnt(8)
	s_waitcnt lgkmcnt(0)
	s_barrier
	s_setprio 1
	s_waitcnt lgkmcnt(0)
	v_mfma_f32_16x16x32_bf16 v[140:143], v[88:91], v[194:197], v[140:143]
	v_mfma_f32_16x16x32_bf16 v[136:139], v[128:131], v[194:197], v[136:139]
	v_mfma_f32_16x16x32_bf16 v[120:123], v[88:91], v[202:205], v[120:123]
	v_mfma_f32_16x16x32_bf16 v[116:119], v[128:131], v[202:205], v[116:119]
	v_mfma_f32_16x16x32_bf16 v[100:103], v[88:91], v[210:213], v[100:103]
	v_mfma_f32_16x16x32_bf16 v[96:99], v[128:131], v[210:213], v[96:99]
	v_mfma_f32_16x16x32_bf16 v[78:81], v[88:91], v[218:221], v[80:83]
	v_mfma_f32_16x16x32_bf16 v[74:77], v[128:131], v[218:221], v[74:77]
	v_mfma_f32_16x16x32_bf16 v[140:143], v[108:111], v[198:201], v[140:143]
	v_mfma_f32_16x16x32_bf16 v[136:139], v[144:147], v[198:201], v[136:139]
	v_mfma_f32_16x16x32_bf16 v[120:123], v[108:111], v[206:209], v[120:123]
	v_mfma_f32_16x16x32_bf16 v[116:119], v[144:147], v[206:209], v[116:119]
	v_mfma_f32_16x16x32_bf16 v[100:103], v[108:111], v[214:217], v[100:103]
	v_mfma_f32_16x16x32_bf16 v[96:99], v[144:147], v[214:217], v[96:99]
	v_mfma_f32_16x16x32_bf16 v[80:83], v[108:111], v[222:225], v[78:81]
	v_mfma_f32_16x16x32_bf16 v[76:79], v[144:147], v[222:225], v[74:77]
	s_setprio 0
	s_setprio 1
	v_mfma_f32_16x16x32_bf16 v[132:135], v[148:151], v[194:197], v[132:135]
	v_mfma_f32_16x16x32_bf16 v[124:127], v[176:179], v[194:197], v[124:127]
	v_mfma_f32_16x16x32_bf16 v[112:115], v[148:151], v[202:205], v[112:115]
	v_mfma_f32_16x16x32_bf16 v[104:107], v[176:179], v[202:205], v[104:107]
	v_mfma_f32_16x16x32_bf16 v[92:95], v[148:151], v[210:213], v[92:95]
	v_mfma_f32_16x16x32_bf16 v[84:87], v[176:179], v[210:213], v[84:87]
	v_mfma_f32_16x16x32_bf16 v[68:71], v[148:151], v[218:221], v[68:71]
	v_mfma_f32_16x16x32_bf16 v[64:67], v[176:179], v[218:221], v[64:67]
	v_mfma_f32_16x16x32_bf16 v[132:135], v[152:155], v[198:201], v[132:135]
	v_mfma_f32_16x16x32_bf16 v[124:127], v[190:193], v[198:201], v[124:127]
	v_mfma_f32_16x16x32_bf16 v[112:115], v[152:155], v[206:209], v[112:115]
	v_mfma_f32_16x16x32_bf16 v[104:107], v[190:193], v[206:209], v[104:107]
	v_mfma_f32_16x16x32_bf16 v[92:95], v[152:155], v[214:217], v[92:95]
	v_mfma_f32_16x16x32_bf16 v[84:87], v[190:193], v[214:217], v[84:87]
	v_mfma_f32_16x16x32_bf16 v[68:71], v[152:155], v[222:225], v[68:71]
	v_mfma_f32_16x16x32_bf16 v[64:67], v[190:193], v[222:225], v[64:67]
	s_setprio 0
	s_barrier
	s_add_i32 s68, s96, s71
	v_lshl_add_u64 v[74:75], v[226:227], 0, s[28:29]
	s_mov_b32 m0, s68
	ds_read_b128 v[194:197], v187 offset:49152
	ds_read_b128 v[198:201], v187 offset:50176
	ds_read_b128 v[202:205], v187 offset:51200
	ds_read_b128 v[206:209], v187 offset:52224
	ds_read_b128 v[210:213], v187 offset:53248
	ds_read_b128 v[214:217], v187 offset:54272
	ds_read_b128 v[218:221], v187 offset:55296
	ds_read_b128 v[222:225], v187 offset:56320
	global_load_lds_dwordx4 v[74:75], off
	s_add_i32 m0, s68, 0x2000
	s_add_u32 s66, s66, 0x40080
	v_lshl_add_u64 v[74:75], v[228:229], 0, s[28:29]
	s_addc_u32 s67, s67, 0
	s_add_i32 s68, s97, s71
	global_load_lds_dwordx4 v[74:75], off
	v_lshl_add_u64 v[74:75], s[66:67], 0, v[162:163]
	s_mov_b32 m0, s68
	s_nop 0
	global_load_lds_dwordx4 v[74:75], off
	v_lshl_add_u64 v[74:75], s[66:67], 0, v[166:167]
	s_add_i32 m0, s68, 0x2000
	s_nop 0
	global_load_lds_dwordx4 v[74:75], off
	v_lshl_add_u64 v[74:75], v[230:231], 0, s[28:29]
	s_mov_b32 m0, s78
	s_nop 0
	global_load_lds_dwordx4 v[74:75], off
	v_lshl_add_u64 v[74:75], v[232:233], 0, s[28:29]
	s_mov_b32 m0, s79
	s_nop 0
	global_load_lds_dwordx4 v[74:75], off
	s_waitcnt vmcnt(8)
	s_waitcnt lgkmcnt(0)
	s_barrier
	s_setprio 1
	s_waitcnt lgkmcnt(0)
	v_mfma_f32_16x16x32_bf16 v[60:63], v[88:91], v[194:197], v[60:63]
	v_mfma_f32_16x16x32_bf16 v[56:59], v[128:131], v[194:197], v[56:59]
	v_mfma_f32_16x16x32_bf16 v[44:47], v[88:91], v[202:205], v[44:47]
	v_mfma_f32_16x16x32_bf16 v[40:43], v[128:131], v[202:205], v[40:43]
	v_mfma_f32_16x16x32_bf16 v[28:31], v[88:91], v[210:213], v[28:31]
	v_mfma_f32_16x16x32_bf16 v[24:27], v[128:131], v[210:213], v[24:27]
	v_mfma_f32_16x16x32_bf16 v[12:15], v[88:91], v[218:221], v[12:15]
	v_mfma_f32_16x16x32_bf16 v[8:11], v[128:131], v[218:221], v[8:11]
	v_mfma_f32_16x16x32_bf16 v[60:63], v[108:111], v[198:201], v[60:63]
	v_mfma_f32_16x16x32_bf16 v[56:59], v[144:147], v[198:201], v[56:59]
	v_mfma_f32_16x16x32_bf16 v[44:47], v[108:111], v[206:209], v[44:47]
	v_mfma_f32_16x16x32_bf16 v[40:43], v[144:147], v[206:209], v[40:43]
	v_mfma_f32_16x16x32_bf16 v[28:31], v[108:111], v[214:217], v[28:31]
	v_mfma_f32_16x16x32_bf16 v[24:27], v[144:147], v[214:217], v[24:27]
	v_mfma_f32_16x16x32_bf16 v[12:15], v[108:111], v[222:225], v[12:15]
	v_mfma_f32_16x16x32_bf16 v[8:11], v[144:147], v[222:225], v[8:11]
	s_setprio 0
	s_setprio 1
	v_mfma_f32_16x16x32_bf16 v[52:55], v[148:151], v[194:197], v[52:55]
	v_mfma_f32_16x16x32_bf16 v[48:51], v[176:179], v[194:197], v[48:51]
	v_mfma_f32_16x16x32_bf16 v[36:39], v[148:151], v[202:205], v[36:39]
	v_mfma_f32_16x16x32_bf16 v[32:35], v[176:179], v[202:205], v[32:35]
	v_mfma_f32_16x16x32_bf16 v[20:23], v[148:151], v[210:213], v[20:23]
	v_mfma_f32_16x16x32_bf16 v[16:19], v[176:179], v[210:213], v[16:19]
	v_mfma_f32_16x16x32_bf16 v[4:7], v[148:151], v[218:221], v[4:7]
	v_mfma_f32_16x16x32_bf16 v[0:3], v[176:179], v[218:221], v[0:3]
	v_mfma_f32_16x16x32_bf16 v[52:55], v[152:155], v[198:201], v[52:55]
	v_mfma_f32_16x16x32_bf16 v[48:51], v[190:193], v[198:201], v[48:51]
	v_mfma_f32_16x16x32_bf16 v[36:39], v[152:155], v[206:209], v[36:39]
	v_mfma_f32_16x16x32_bf16 v[32:35], v[190:193], v[206:209], v[32:35]
	v_mfma_f32_16x16x32_bf16 v[20:23], v[152:155], v[214:217], v[20:23]
	v_mfma_f32_16x16x32_bf16 v[16:19], v[190:193], v[214:217], v[16:19]
	v_mfma_f32_16x16x32_bf16 v[4:7], v[152:155], v[222:225], v[4:7]
	v_mfma_f32_16x16x32_bf16 v[0:3], v[190:193], v[222:225], v[0:3]
	s_setprio 0
	s_barrier
	s_add_i32 s95, s95, 2
	s_add_u32 s93, s93, 0x100
	s_addc_u32 s94, s94, 0
	s_add_u32 s14, s14, 0x100
	s_addc_u32 s15, s15, 0
	s_branch .LBB0_256

.LBB0_439:
	s_ashr_i32 s53, s52, 31
	s_lshl_b64 s[54:55], s[52:53], 20
	s_add_u32 s54, s35, s54
	s_addc_u32 s55, s66, s55
	s_and_b64 s[56:57], s[12:13], exec
	s_cselect_b32 s15, s55, s63
	s_cselect_b32 s53, s54, s62
	s_ashr_i32 s51, s50, 31
	s_lshl_b64 s[56:57], s[50:51], 20
	s_add_u32 s56, s67, s56
	s_addc_u32 s57, s68, s57
	s_and_b64 s[64:65], s[12:13], exec
	s_cselect_b32 s51, s57, s61
	s_cselect_b32 s59, s56, s60
	s_add_u32 s81, s60, 0x100
	s_addc_u32 s82, s61, 0
	s_add_u32 s60, s62, 0x80080
	s_addc_u32 s61, s63, 0
	s_mov_b32 s83, -2
	s_waitcnt lgkmcnt(0)
	s_cmp_eq_u32 s74, 1
	s_cbranch_scc1 .Lfa_3
	ds_read_b128 v[128:131], v189
	ds_read_b128 v[132:135], v189 offset:1024
	ds_read_b128 v[136:139], v189 offset:2048
	ds_read_b128 v[140:143], v189 offset:3072
	ds_read_b128 v[144:147], v190
	ds_read_b128 v[148:151], v190 offset:1024
	ds_read_b128 v[172:175], v190 offset:2048
	ds_read_b128 v[176:179], v190 offset:3072
	s_add_u32 s62, s60, 0xfff80080
	s_addc_u32 s63, s61, -1
	s_cmp_eq_u32 s83, 28
	s_cselect_b32 s65, s15, s63
	s_cselect_b32 s64, s53, s62
	s_cselect_b32 s63, s51, s82
	s_cselect_b32 s62, s59, s81
	v_lshl_add_u64 v[222:223], s[60:61], 0, v[166:167]
	s_add_i32 m0, s70, 0xc000
	ds_read_b128 v[180:183], v191
	ds_read_b128 v[194:197], v191 offset:1024
	ds_read_b128 v[198:201], v191 offset:2048
	ds_read_b128 v[202:205], v191 offset:3072
	ds_read_b128 v[206:209], v191 offset:4096
	ds_read_b128 v[210:213], v191 offset:5120
	ds_read_b128 v[214:217], v191 offset:6144
	ds_read_b128 v[218:221], v191 offset:7168
	global_load_lds_dwordx4 v[222:223], off
	v_lshl_add_u64 v[222:223], s[60:61], 0, v[164:165]
	s_add_i32 m0, s70, 0xe000
	s_nop 0
	global_load_lds_dwordx4 v[222:223], off
	s_waitcnt vmcnt(24)
	s_waitcnt lgkmcnt(0)
	s_barrier
	s_setprio 1
	s_waitcnt lgkmcnt(0)
	v_mfma_f32_16x16x32_bf16 v[124:127], v[128:131], v[180:183], 0
	v_mfma_f32_16x16x32_bf16 v[120:123], v[136:139], v[180:183], 0
	v_mfma_f32_16x16x32_bf16 v[108:111], v[128:131], v[198:201], 0
	v_mfma_f32_16x16x32_bf16 v[104:107], v[136:139], v[198:201], 0
	v_mfma_f32_16x16x32_bf16 v[92:95], v[128:131], v[206:209], 0
	v_mfma_f32_16x16x32_bf16 v[88:91], v[136:139], v[206:209], 0
	v_mfma_f32_16x16x32_bf16 v[76:79], v[128:131], v[214:217], 0
	v_mfma_f32_16x16x32_bf16 v[72:75], v[136:139], v[214:217], 0
	v_mfma_f32_16x16x32_bf16 v[124:127], v[132:135], v[194:197], v[124:127]
	v_mfma_f32_16x16x32_bf16 v[120:123], v[140:143], v[194:197], v[120:123]
	v_mfma_f32_16x16x32_bf16 v[108:111], v[132:135], v[202:205], v[108:111]
	v_mfma_f32_16x16x32_bf16 v[104:107], v[140:143], v[202:205], v[104:107]
	v_mfma_f32_16x16x32_bf16 v[92:95], v[132:135], v[210:213], v[92:95]
	v_mfma_f32_16x16x32_bf16 v[88:91], v[140:143], v[210:213], v[88:91]
	v_mfma_f32_16x16x32_bf16 v[76:79], v[132:135], v[218:221], v[76:79]
	v_mfma_f32_16x16x32_bf16 v[72:75], v[140:143], v[218:221], v[72:75]
	s_setprio 0
	s_setprio 1
	v_mfma_f32_16x16x32_bf16 v[116:119], v[144:147], v[180:183], 0
	v_mfma_f32_16x16x32_bf16 v[112:115], v[172:175], v[180:183], 0
	v_mfma_f32_16x16x32_bf16 v[100:103], v[144:147], v[198:201], 0
	v_mfma_f32_16x16x32_bf16 v[96:99], v[172:175], v[198:201], 0
	v_mfma_f32_16x16x32_bf16 v[84:87], v[144:147], v[206:209], 0
	v_mfma_f32_16x16x32_bf16 v[80:83], v[172:175], v[206:209], 0
	v_mfma_f32_16x16x32_bf16 v[68:71], v[144:147], v[214:217], 0
	v_mfma_f32_16x16x32_bf16 v[64:67], v[172:175], v[214:217], 0
	v_mfma_f32_16x16x32_bf16 v[116:119], v[148:151], v[194:197], v[116:119]
	v_mfma_f32_16x16x32_bf16 v[112:115], v[176:179], v[194:197], v[112:115]
	v_mfma_f32_16x16x32_bf16 v[100:103], v[148:151], v[202:205], v[100:103]
	v_mfma_f32_16x16x32_bf16 v[96:99], v[176:179], v[202:205], v[96:99]
	v_mfma_f32_16x16x32_bf16 v[84:87], v[148:151], v[210:213], v[84:87]
	v_mfma_f32_16x16x32_bf16 v[80:83], v[176:179], v[210:213], v[80:83]
	v_mfma_f32_16x16x32_bf16 v[68:71], v[148:151], v[218:221], v[68:71]
	v_mfma_f32_16x16x32_bf16 v[64:67], v[176:179], v[218:221], v[64:67]
	s_setprio 0
	s_barrier
	s_add_i32 s84, s79, s69
	v_lshl_add_u64 v[222:223], s[62:63], 0, v[154:155]
	s_mov_b32 m0, s84
	ds_read_b128 v[180:183], v191 offset:16384
	ds_read_b128 v[194:197], v191 offset:17408
	ds_read_b128 v[198:201], v191 offset:18432
	ds_read_b128 v[202:205], v191 offset:19456
	ds_read_b128 v[206:209], v191 offset:20480
	ds_read_b128 v[210:213], v191 offset:21504
	ds_read_b128 v[214:217], v191 offset:22528
	ds_read_b128 v[218:221], v191 offset:23552
	global_load_lds_dwordx4 v[222:223], off
	s_add_i32 m0, s84, 0x2000
	s_add_u32 s84, s62, 0x80000
	v_lshl_add_u64 v[224:225], s[62:63], 0, v[162:163]
	s_addc_u32 s85, s63, 0
	s_add_i32 s86, s80, s69
	global_load_lds_dwordx4 v[224:225], off
	v_lshl_add_u64 v[226:227], s[84:85], 0, v[154:155]
	s_mov_b32 m0, s86
	v_lshl_add_u64 v[228:229], s[64:65], 0, v[160:161]
	global_load_lds_dwordx4 v[226:227], off
	v_lshl_add_u64 v[226:227], s[84:85], 0, v[162:163]
	s_add_i32 m0, s86, 0x2000
	s_nop 0
	global_load_lds_dwordx4 v[226:227], off
	v_lshl_add_u64 v[226:227], s[64:65], 0, v[152:153]
	s_mov_b32 m0, s70
	s_nop 0
	global_load_lds_dwordx4 v[226:227], off
	s_mov_b32 m0, s71
	s_nop 0
	global_load_lds_dwordx4 v[228:229], off
	s_waitcnt vmcnt(24)
	s_waitcnt lgkmcnt(0)
	s_barrier
	s_setprio 1
	s_waitcnt lgkmcnt(0)
	v_mfma_f32_16x16x32_bf16 v[60:63], v[128:131], v[180:183], 0
	v_mfma_f32_16x16x32_bf16 v[56:59], v[136:139], v[180:183], 0
	v_mfma_f32_16x16x32_bf16 v[44:47], v[128:131], v[198:201], 0
	v_mfma_f32_16x16x32_bf16 v[40:43], v[136:139], v[198:201], 0
	v_mfma_f32_16x16x32_bf16 v[28:31], v[128:131], v[206:209], 0
	v_mfma_f32_16x16x32_bf16 v[24:27], v[136:139], v[206:209], 0
	v_mfma_f32_16x16x32_bf16 v[12:15], v[128:131], v[214:217], 0
	v_mfma_f32_16x16x32_bf16 v[8:11], v[136:139], v[214:217], 0
	v_mfma_f32_16x16x32_bf16 v[60:63], v[132:135], v[194:197], v[60:63]
	v_mfma_f32_16x16x32_bf16 v[56:59], v[140:143], v[194:197], v[56:59]
	v_mfma_f32_16x16x32_bf16 v[44:47], v[132:135], v[202:205], v[44:47]
	v_mfma_f32_16x16x32_bf16 v[40:43], v[140:143], v[202:205], v[40:43]
	v_mfma_f32_16x16x32_bf16 v[28:31], v[132:135], v[210:213], v[28:31]
	v_mfma_f32_16x16x32_bf16 v[24:27], v[140:143], v[210:213], v[24:27]
	v_mfma_f32_16x16x32_bf16 v[12:15], v[132:135], v[218:221], v[12:15]
	v_mfma_f32_16x16x32_bf16 v[8:11], v[140:143], v[218:221], v[8:11]
	s_setprio 0
	s_setprio 1
	v_mfma_f32_16x16x32_bf16 v[52:55], v[144:147], v[180:183], 0
	v_mfma_f32_16x16x32_bf16 v[48:51], v[172:175], v[180:183], 0
	v_mfma_f32_16x16x32_bf16 v[36:39], v[144:147], v[198:201], 0
	v_mfma_f32_16x16x32_bf16 v[32:35], v[172:175], v[198:201], 0
	v_mfma_f32_16x16x32_bf16 v[20:23], v[144:147], v[206:209], 0
	v_mfma_f32_16x16x32_bf16 v[16:19], v[172:175], v[206:209], 0
	v_mfma_f32_16x16x32_bf16 v[4:7], v[144:147], v[214:217], 0
	v_mfma_f32_16x16x32_bf16 v[0:3], v[172:175], v[214:217], 0
	v_mfma_f32_16x16x32_bf16 v[52:55], v[148:151], v[194:197], v[52:55]
	v_mfma_f32_16x16x32_bf16 v[48:51], v[176:179], v[194:197], v[48:51]
	v_mfma_f32_16x16x32_bf16 v[36:39], v[148:151], v[202:205], v[36:39]
	v_mfma_f32_16x16x32_bf16 v[32:35], v[176:179], v[202:205], v[32:35]
	v_mfma_f32_16x16x32_bf16 v[20:23], v[148:151], v[210:213], v[20:23]
	v_mfma_f32_16x16x32_bf16 v[16:19], v[176:179], v[210:213], v[16:19]
	v_mfma_f32_16x16x32_bf16 v[4:7], v[148:151], v[218:221], v[4:7]
	v_mfma_f32_16x16x32_bf16 v[0:3], v[176:179], v[218:221], v[0:3]
	s_setprio 0
	s_barrier
	s_add_i32 s84, 0, 0x18000
	s_add_i32 s85, 0, 0x1c000
	v_add_u32_e32 v140, s84, v186
	v_add_u32_e32 v176, s85, v186
	ds_read_b128 v[128:131], v140
	ds_read_b128 v[132:135], v140 offset:1024
	ds_read_b128 v[136:139], v140 offset:2048
	ds_read_b128 v[140:143], v140 offset:3072
	ds_read_b128 v[144:147], v176
	ds_read_b128 v[148:151], v176 offset:1024
	ds_read_b128 v[172:175], v176 offset:2048
	ds_read_b128 v[176:179], v176 offset:3072
	s_add_u32 s64, s64, 0x80000
	s_addc_u32 s65, s65, 0
	s_mov_b32 m0, s72
	v_lshl_add_u64 v[230:231], s[64:65], 0, v[152:153]
	ds_read_b128 v[180:183], v191 offset:32768
	ds_read_b128 v[194:197], v191 offset:33792
	ds_read_b128 v[198:201], v191 offset:34816
	ds_read_b128 v[202:205], v191 offset:35840
	ds_read_b128 v[206:209], v191 offset:36864
	ds_read_b128 v[210:213], v191 offset:37888
	ds_read_b128 v[214:217], v191 offset:38912
	ds_read_b128 v[218:221], v191 offset:39936
	global_load_lds_dwordx4 v[230:231], off
	v_lshl_add_u64 v[230:231], s[64:65], 0, v[160:161]
	s_mov_b32 m0, s73
	s_nop 0
	global_load_lds_dwordx4 v[230:231], off
	s_waitcnt vmcnt(8)
	s_waitcnt lgkmcnt(0)
	s_barrier
	s_setprio 1
	s_waitcnt lgkmcnt(0)
	v_mfma_f32_16x16x32_bf16 v[124:127], v[128:131], v[180:183], v[124:127]
	v_mfma_f32_16x16x32_bf16 v[120:123], v[136:139], v[180:183], v[120:123]
	v_mfma_f32_16x16x32_bf16 v[108:111], v[128:131], v[198:201], v[108:111]
	v_mfma_f32_16x16x32_bf16 v[104:107], v[136:139], v[198:201], v[104:107]
	v_mfma_f32_16x16x32_bf16 v[92:95], v[128:131], v[206:209], v[92:95]
	v_mfma_f32_16x16x32_bf16 v[88:91], v[136:139], v[206:209], v[88:91]
	v_mfma_f32_16x16x32_bf16 v[76:79], v[128:131], v[214:217], v[76:79]
	v_mfma_f32_16x16x32_bf16 v[72:75], v[136:139], v[214:217], v[72:75]
	v_mfma_f32_16x16x32_bf16 v[124:127], v[132:135], v[194:197], v[124:127]
	v_mfma_f32_16x16x32_bf16 v[120:123], v[140:143], v[194:197], v[120:123]
	v_mfma_f32_16x16x32_bf16 v[108:111], v[132:135], v[202:205], v[108:111]
	v_mfma_f32_16x16x32_bf16 v[104:107], v[140:143], v[202:205], v[104:107]
	v_mfma_f32_16x16x32_bf16 v[92:95], v[132:135], v[210:213], v[92:95]
	v_mfma_f32_16x16x32_bf16 v[88:91], v[140:143], v[210:213], v[88:91]
	v_mfma_f32_16x16x32_bf16 v[76:79], v[132:135], v[218:221], v[76:79]
	v_mfma_f32_16x16x32_bf16 v[72:75], v[140:143], v[218:221], v[72:75]
	s_setprio 0
	s_setprio 1
	v_mfma_f32_16x16x32_bf16 v[116:119], v[144:147], v[180:183], v[116:119]
	v_mfma_f32_16x16x32_bf16 v[112:115], v[172:175], v[180:183], v[112:115]
	v_mfma_f32_16x16x32_bf16 v[100:103], v[144:147], v[198:201], v[100:103]
	v_mfma_f32_16x16x32_bf16 v[96:99], v[172:175], v[198:201], v[96:99]
	v_mfma_f32_16x16x32_bf16 v[84:87], v[144:147], v[206:209], v[84:87]
	v_mfma_f32_16x16x32_bf16 v[80:83], v[172:175], v[206:209], v[80:83]
	v_mfma_f32_16x16x32_bf16 v[68:71], v[144:147], v[214:217], v[68:71]
	v_mfma_f32_16x16x32_bf16 v[64:67], v[172:175], v[214:217], v[64:67]
	v_mfma_f32_16x16x32_bf16 v[116:119], v[148:151], v[194:197], v[116:119]
	v_mfma_f32_16x16x32_bf16 v[112:115], v[176:179], v[194:197], v[112:115]
	v_mfma_f32_16x16x32_bf16 v[100:103], v[148:151], v[202:205], v[100:103]
	v_mfma_f32_16x16x32_bf16 v[96:99], v[176:179], v[202:205], v[96:99]
	v_mfma_f32_16x16x32_bf16 v[84:87], v[148:151], v[210:213], v[84:87]
	v_mfma_f32_16x16x32_bf16 v[80:83], v[176:179], v[210:213], v[80:83]
	v_mfma_f32_16x16x32_bf16 v[68:71], v[148:151], v[218:221], v[68:71]
	v_mfma_f32_16x16x32_bf16 v[64:67], v[176:179], v[218:221], v[64:67]
	s_setprio 0
	s_barrier
	s_add_i32 s64, s84, s69
	v_lshl_add_u64 v[222:223], v[222:223], 0, s[26:27]
	s_mov_b32 m0, s64
	ds_read_b128 v[180:183], v191 offset:49152
	ds_read_b128 v[194:197], v191 offset:50176
	ds_read_b128 v[198:201], v191 offset:51200
	ds_read_b128 v[202:205], v191 offset:52224
	ds_read_b128 v[206:209], v191 offset:53248
	ds_read_b128 v[210:213], v191 offset:54272
	ds_read_b128 v[214:217], v191 offset:55296
	ds_read_b128 v[218:221], v191 offset:56320
	global_load_lds_dwordx4 v[222:223], off
	s_add_i32 m0, s64, 0x2000
	s_add_u32 s62, s62, 0x80080
	v_lshl_add_u64 v[222:223], v[224:225], 0, s[26:27]
	s_addc_u32 s63, s63, 0
	s_add_i32 s64, s85, s69
	global_load_lds_dwordx4 v[222:223], off
	v_lshl_add_u64 v[222:223], s[62:63], 0, v[154:155]
	s_mov_b32 m0, s64
	s_nop 0
	global_load_lds_dwordx4 v[222:223], off
	v_lshl_add_u64 v[222:223], s[62:63], 0, v[162:163]
	s_add_i32 m0, s64, 0x2000
	s_nop 0
	global_load_lds_dwordx4 v[222:223], off
	v_lshl_add_u64 v[222:223], v[226:227], 0, s[26:27]
	s_mov_b32 m0, s3
	s_nop 0
	global_load_lds_dwordx4 v[222:223], off
	v_lshl_add_u64 v[222:223], v[228:229], 0, s[26:27]
	s_mov_b32 m0, s75
	s_nop 0
	global_load_lds_dwordx4 v[222:223], off
	s_waitcnt vmcnt(8)
	s_waitcnt lgkmcnt(0)
	s_barrier
	s_setprio 1
	s_waitcnt lgkmcnt(0)
	v_mfma_f32_16x16x32_bf16 v[60:63], v[128:131], v[180:183], v[60:63]
	v_mfma_f32_16x16x32_bf16 v[56:59], v[136:139], v[180:183], v[56:59]
	v_mfma_f32_16x16x32_bf16 v[44:47], v[128:131], v[198:201], v[44:47]
	v_mfma_f32_16x16x32_bf16 v[40:43], v[136:139], v[198:201], v[40:43]
	v_mfma_f32_16x16x32_bf16 v[28:31], v[128:131], v[206:209], v[28:31]
	v_mfma_f32_16x16x32_bf16 v[24:27], v[136:139], v[206:209], v[24:27]
	v_mfma_f32_16x16x32_bf16 v[12:15], v[128:131], v[214:217], v[12:15]
	v_mfma_f32_16x16x32_bf16 v[8:11], v[136:139], v[214:217], v[8:11]
	v_mfma_f32_16x16x32_bf16 v[60:63], v[132:135], v[194:197], v[60:63]
	v_mfma_f32_16x16x32_bf16 v[56:59], v[140:143], v[194:197], v[56:59]
	v_mfma_f32_16x16x32_bf16 v[44:47], v[132:135], v[202:205], v[44:47]
	v_mfma_f32_16x16x32_bf16 v[40:43], v[140:143], v[202:205], v[40:43]
	v_mfma_f32_16x16x32_bf16 v[28:31], v[132:135], v[210:213], v[28:31]
	v_mfma_f32_16x16x32_bf16 v[24:27], v[140:143], v[210:213], v[24:27]
	v_mfma_f32_16x16x32_bf16 v[12:15], v[132:135], v[218:221], v[12:15]
	v_mfma_f32_16x16x32_bf16 v[8:11], v[140:143], v[218:221], v[8:11]
	s_setprio 0
	s_setprio 1
	v_mfma_f32_16x16x32_bf16 v[52:55], v[144:147], v[180:183], v[52:55]
	v_mfma_f32_16x16x32_bf16 v[48:51], v[172:175], v[180:183], v[48:51]
	v_mfma_f32_16x16x32_bf16 v[36:39], v[144:147], v[198:201], v[36:39]
	v_mfma_f32_16x16x32_bf16 v[32:35], v[172:175], v[198:201], v[32:35]
	v_mfma_f32_16x16x32_bf16 v[20:23], v[144:147], v[206:209], v[20:23]
	v_mfma_f32_16x16x32_bf16 v[16:19], v[172:175], v[206:209], v[16:19]
	v_mfma_f32_16x16x32_bf16 v[4:7], v[144:147], v[214:217], v[4:7]
	v_mfma_f32_16x16x32_bf16 v[0:3], v[172:175], v[214:217], v[0:3]
	v_mfma_f32_16x16x32_bf16 v[52:55], v[148:151], v[194:197], v[52:55]
	v_mfma_f32_16x16x32_bf16 v[48:51], v[176:179], v[194:197], v[48:51]
	v_mfma_f32_16x16x32_bf16 v[36:39], v[148:151], v[202:205], v[36:39]
	v_mfma_f32_16x16x32_bf16 v[32:35], v[176:179], v[202:205], v[32:35]
	v_mfma_f32_16x16x32_bf16 v[20:23], v[148:151], v[210:213], v[20:23]
	v_mfma_f32_16x16x32_bf16 v[16:19], v[176:179], v[210:213], v[16:19]
	v_mfma_f32_16x16x32_bf16 v[4:7], v[148:151], v[218:221], v[4:7]
	v_mfma_f32_16x16x32_bf16 v[0:3], v[176:179], v[218:221], v[0:3]
	s_setprio 0
	s_barrier
	s_add_i32 s83, s83, 2
	s_add_u32 s81, s81, 0x100
	s_addc_u32 s82, s82, 0
	s_add_u32 s60, s60, 0x100
	s_addc_u32 s61, s61, 0
	s_cmp_gt_u32 s83, 29
	s_branch .LBB0_440
.Lfa_3:
	ds_read_b128 v[128:131], v189
	ds_read_b128 v[132:135], v189 offset:1024
	ds_read_b128 v[136:139], v189 offset:2048
	ds_read_b128 v[140:143], v189 offset:3072
	ds_read_b128 v[144:147], v190
	ds_read_b128 v[148:151], v190 offset:1024
	ds_read_b128 v[172:175], v190 offset:2048
	ds_read_b128 v[176:179], v190 offset:3072
	s_add_u32 s62, s60, 0xfff80080
	s_addc_u32 s63, s61, -1
	s_cmp_eq_u32 s83, 28
	s_cselect_b32 s65, s15, s63
	s_cselect_b32 s64, s53, s62
	s_cselect_b32 s63, s51, s82
	s_cselect_b32 s62, s59, s81
	v_lshl_add_u64 v[222:223], s[60:61], 0, v[166:167]
	s_add_i32 m0, s70, 0xc000
	ds_read_b128 v[180:183], v191
	ds_read_b128 v[194:197], v191 offset:1024
	ds_read_b128 v[198:201], v191 offset:2048
	ds_read_b128 v[202:205], v191 offset:3072
	ds_read_b128 v[206:209], v191 offset:4096
	ds_read_b128 v[210:213], v191 offset:5120
	ds_read_b128 v[214:217], v191 offset:6144
	ds_read_b128 v[218:221], v191 offset:7168
	global_load_lds_dwordx4 v[222:223], off
	v_lshl_add_u64 v[222:223], s[60:61], 0, v[164:165]
	s_add_i32 m0, s70, 0xe000
	s_nop 0
	global_load_lds_dwordx4 v[222:223], off
	s_waitcnt vmcnt(8)
	s_waitcnt lgkmcnt(0)
	s_barrier
	s_setprio 1
	s_waitcnt lgkmcnt(0)
	v_mfma_f32_16x16x32_bf16 v[124:127], v[128:131], v[180:183], 0
	v_mfma_f32_16x16x32_bf16 v[120:123], v[136:139], v[180:183], 0
	v_mfma_f32_16x16x32_bf16 v[108:111], v[128:131], v[198:201], 0
	v_mfma_f32_16x16x32_bf16 v[104:107], v[136:139], v[198:201], 0
	v_mfma_f32_16x16x32_bf16 v[92:95], v[128:131], v[206:209], 0
	v_mfma_f32_16x16x32_bf16 v[88:91], v[136:139], v[206:209], 0
	v_mfma_f32_16x16x32_bf16 v[76:79], v[128:131], v[214:217], 0
	v_mfma_f32_16x16x32_bf16 v[72:75], v[136:139], v[214:217], 0
	v_mfma_f32_16x16x32_bf16 v[124:127], v[132:135], v[194:197], v[124:127]
	v_mfma_f32_16x16x32_bf16 v[120:123], v[140:143], v[194:197], v[120:123]
	v_mfma_f32_16x16x32_bf16 v[108:111], v[132:135], v[202:205], v[108:111]
	v_mfma_f32_16x16x32_bf16 v[104:107], v[140:143], v[202:205], v[104:107]
	v_mfma_f32_16x16x32_bf16 v[92:95], v[132:135], v[210:213], v[92:95]
	v_mfma_f32_16x16x32_bf16 v[88:91], v[140:143], v[210:213], v[88:91]
	v_mfma_f32_16x16x32_bf16 v[76:79], v[132:135], v[218:221], v[76:79]
	v_mfma_f32_16x16x32_bf16 v[72:75], v[140:143], v[218:221], v[72:75]
	s_setprio 0
	s_setprio 1
	v_mfma_f32_16x16x32_bf16 v[116:119], v[144:147], v[180:183], 0
	v_mfma_f32_16x16x32_bf16 v[112:115], v[172:175], v[180:183], 0
	v_mfma_f32_16x16x32_bf16 v[100:103], v[144:147], v[198:201], 0
	v_mfma_f32_16x16x32_bf16 v[96:99], v[172:175], v[198:201], 0
	v_mfma_f32_16x16x32_bf16 v[84:87], v[144:147], v[206:209], 0
	v_mfma_f32_16x16x32_bf16 v[80:83], v[172:175], v[206:209], 0
	v_mfma_f32_16x16x32_bf16 v[68:71], v[144:147], v[214:217], 0
	v_mfma_f32_16x16x32_bf16 v[64:67], v[172:175], v[214:217], 0
	v_mfma_f32_16x16x32_bf16 v[116:119], v[148:151], v[194:197], v[116:119]
	v_mfma_f32_16x16x32_bf16 v[112:115], v[176:179], v[194:197], v[112:115]
	v_mfma_f32_16x16x32_bf16 v[100:103], v[148:151], v[202:205], v[100:103]
	v_mfma_f32_16x16x32_bf16 v[96:99], v[176:179], v[202:205], v[96:99]
	v_mfma_f32_16x16x32_bf16 v[84:87], v[148:151], v[210:213], v[84:87]
	v_mfma_f32_16x16x32_bf16 v[80:83], v[176:179], v[210:213], v[80:83]
	v_mfma_f32_16x16x32_bf16 v[68:71], v[148:151], v[218:221], v[68:71]
	v_mfma_f32_16x16x32_bf16 v[64:67], v[176:179], v[218:221], v[64:67]
	s_setprio 0
	s_barrier
	s_add_i32 s84, s79, s69
	v_lshl_add_u64 v[222:223], s[62:63], 0, v[154:155]
	s_mov_b32 m0, s84
	ds_read_b128 v[180:183], v191 offset:16384
	ds_read_b128 v[194:197], v191 offset:17408
	ds_read_b128 v[198:201], v191 offset:18432
	ds_read_b128 v[202:205], v191 offset:19456
	ds_read_b128 v[206:209], v191 offset:20480
	ds_read_b128 v[210:213], v191 offset:21504
	ds_read_b128 v[214:217], v191 offset:22528
	ds_read_b128 v[218:221], v191 offset:23552
	global_load_lds_dwordx4 v[222:223], off
	s_add_i32 m0, s84, 0x2000
	s_add_u32 s84, s62, 0x80000
	v_lshl_add_u64 v[224:225], s[62:63], 0, v[162:163]
	s_addc_u32 s85, s63, 0
	s_add_i32 s86, s80, s69
	global_load_lds_dwordx4 v[224:225], off
	v_lshl_add_u64 v[226:227], s[84:85], 0, v[154:155]
	s_mov_b32 m0, s86
	v_lshl_add_u64 v[228:229], s[64:65], 0, v[160:161]
	global_load_lds_dwordx4 v[226:227], off
	v_lshl_add_u64 v[226:227], s[84:85], 0, v[162:163]
	s_add_i32 m0, s86, 0x2000
	s_nop 0
	global_load_lds_dwordx4 v[226:227], off
	v_lshl_add_u64 v[226:227], s[64:65], 0, v[152:153]
	s_mov_b32 m0, s70
	s_nop 0
	global_load_lds_dwordx4 v[226:227], off
	s_mov_b32 m0, s71
	s_nop 0
	global_load_lds_dwordx4 v[228:229], off
	s_waitcnt vmcnt(8)
	s_waitcnt lgkmcnt(0)
	s_barrier
	s_setprio 1
	s_waitcnt lgkmcnt(0)
	v_mfma_f32_16x16x32_bf16 v[60:63], v[128:131], v[180:183], 0
	v_mfma_f32_16x16x32_bf16 v[56:59], v[136:139], v[180:183], 0
	v_mfma_f32_16x16x32_bf16 v[44:47], v[128:131], v[198:201], 0
	v_mfma_f32_16x16x32_bf16 v[40:43], v[136:139], v[198:201], 0
	v_mfma_f32_16x16x32_bf16 v[28:31], v[128:131], v[206:209], 0
	v_mfma_f32_16x16x32_bf16 v[24:27], v[136:139], v[206:209], 0
	v_mfma_f32_16x16x32_bf16 v[12:15], v[128:131], v[214:217], 0
	v_mfma_f32_16x16x32_bf16 v[8:11], v[136:139], v[214:217], 0
	v_mfma_f32_16x16x32_bf16 v[60:63], v[132:135], v[194:197], v[60:63]
	v_mfma_f32_16x16x32_bf16 v[56:59], v[140:143], v[194:197], v[56:59]
	v_mfma_f32_16x16x32_bf16 v[44:47], v[132:135], v[202:205], v[44:47]
	v_mfma_f32_16x16x32_bf16 v[40:43], v[140:143], v[202:205], v[40:43]
	v_mfma_f32_16x16x32_bf16 v[28:31], v[132:135], v[210:213], v[28:31]
	v_mfma_f32_16x16x32_bf16 v[24:27], v[140:143], v[210:213], v[24:27]
	v_mfma_f32_16x16x32_bf16 v[12:15], v[132:135], v[218:221], v[12:15]
	v_mfma_f32_16x16x32_bf16 v[8:11], v[140:143], v[218:221], v[8:11]
	s_setprio 0
	s_setprio 1
	v_mfma_f32_16x16x32_bf16 v[52:55], v[144:147], v[180:183], 0
	v_mfma_f32_16x16x32_bf16 v[48:51], v[172:175], v[180:183], 0
	v_mfma_f32_16x16x32_bf16 v[36:39], v[144:147], v[198:201], 0
	v_mfma_f32_16x16x32_bf16 v[32:35], v[172:175], v[198:201], 0
	v_mfma_f32_16x16x32_bf16 v[20:23], v[144:147], v[206:209], 0
	v_mfma_f32_16x16x32_bf16 v[16:19], v[172:175], v[206:209], 0
	v_mfma_f32_16x16x32_bf16 v[4:7], v[144:147], v[214:217], 0
	v_mfma_f32_16x16x32_bf16 v[0:3], v[172:175], v[214:217], 0
	v_mfma_f32_16x16x32_bf16 v[52:55], v[148:151], v[194:197], v[52:55]
	v_mfma_f32_16x16x32_bf16 v[48:51], v[176:179], v[194:197], v[48:51]
	v_mfma_f32_16x16x32_bf16 v[36:39], v[148:151], v[202:205], v[36:39]
	v_mfma_f32_16x16x32_bf16 v[32:35], v[176:179], v[202:205], v[32:35]
	v_mfma_f32_16x16x32_bf16 v[20:23], v[148:151], v[210:213], v[20:23]
	v_mfma_f32_16x16x32_bf16 v[16:19], v[176:179], v[210:213], v[16:19]
	v_mfma_f32_16x16x32_bf16 v[4:7], v[148:151], v[218:221], v[4:7]
	v_mfma_f32_16x16x32_bf16 v[0:3], v[176:179], v[218:221], v[0:3]
	s_setprio 0
	s_barrier
	s_add_i32 s84, 0, 0x18000
	s_add_i32 s85, 0, 0x1c000
	v_add_u32_e32 v140, s84, v186
	v_add_u32_e32 v176, s85, v186
	ds_read_b128 v[128:131], v140
	ds_read_b128 v[132:135], v140 offset:1024
	ds_read_b128 v[136:139], v140 offset:2048
	ds_read_b128 v[140:143], v140 offset:3072
	ds_read_b128 v[144:147], v176
	ds_read_b128 v[148:151], v176 offset:1024
	ds_read_b128 v[172:175], v176 offset:2048
	ds_read_b128 v[176:179], v176 offset:3072
	s_add_u32 s64, s64, 0x80000
	s_addc_u32 s65, s65, 0
	s_mov_b32 m0, s72
	v_lshl_add_u64 v[230:231], s[64:65], 0, v[152:153]
	ds_read_b128 v[180:183], v191 offset:32768
	ds_read_b128 v[194:197], v191 offset:33792
	ds_read_b128 v[198:201], v191 offset:34816
	ds_read_b128 v[202:205], v191 offset:35840
	ds_read_b128 v[206:209], v191 offset:36864
	ds_read_b128 v[210:213], v191 offset:37888
	ds_read_b128 v[214:217], v191 offset:38912
	ds_read_b128 v[218:221], v191 offset:39936
	global_load_lds_dwordx4 v[230:231], off
	v_lshl_add_u64 v[230:231], s[64:65], 0, v[160:161]
	s_mov_b32 m0, s73
	s_nop 0
	global_load_lds_dwordx4 v[230:231], off
	s_waitcnt vmcnt(8)
	s_waitcnt lgkmcnt(0)
	s_barrier
	s_setprio 1
	s_waitcnt lgkmcnt(0)
	v_mfma_f32_16x16x32_bf16 v[124:127], v[128:131], v[180:183], v[124:127]
	v_mfma_f32_16x16x32_bf16 v[120:123], v[136:139], v[180:183], v[120:123]
	v_mfma_f32_16x16x32_bf16 v[108:111], v[128:131], v[198:201], v[108:111]
	v_mfma_f32_16x16x32_bf16 v[104:107], v[136:139], v[198:201], v[104:107]
	v_mfma_f32_16x16x32_bf16 v[92:95], v[128:131], v[206:209], v[92:95]
	v_mfma_f32_16x16x32_bf16 v[88:91], v[136:139], v[206:209], v[88:91]
	v_mfma_f32_16x16x32_bf16 v[76:79], v[128:131], v[214:217], v[76:79]
	v_mfma_f32_16x16x32_bf16 v[72:75], v[136:139], v[214:217], v[72:75]
	v_mfma_f32_16x16x32_bf16 v[124:127], v[132:135], v[194:197], v[124:127]
	v_mfma_f32_16x16x32_bf16 v[120:123], v[140:143], v[194:197], v[120:123]
	v_mfma_f32_16x16x32_bf16 v[108:111], v[132:135], v[202:205], v[108:111]
	v_mfma_f32_16x16x32_bf16 v[104:107], v[140:143], v[202:205], v[104:107]
	v_mfma_f32_16x16x32_bf16 v[92:95], v[132:135], v[210:213], v[92:95]
	v_mfma_f32_16x16x32_bf16 v[88:91], v[140:143], v[210:213], v[88:91]
	v_mfma_f32_16x16x32_bf16 v[76:79], v[132:135], v[218:221], v[76:79]
	v_mfma_f32_16x16x32_bf16 v[72:75], v[140:143], v[218:221], v[72:75]
	s_setprio 0
	s_setprio 1
	v_mfma_f32_16x16x32_bf16 v[116:119], v[144:147], v[180:183], v[116:119]
	v_mfma_f32_16x16x32_bf16 v[112:115], v[172:175], v[180:183], v[112:115]
	v_mfma_f32_16x16x32_bf16 v[100:103], v[144:147], v[198:201], v[100:103]
	v_mfma_f32_16x16x32_bf16 v[96:99], v[172:175], v[198:201], v[96:99]
	v_mfma_f32_16x16x32_bf16 v[84:87], v[144:147], v[206:209], v[84:87]
	v_mfma_f32_16x16x32_bf16 v[80:83], v[172:175], v[206:209], v[80:83]
	v_mfma_f32_16x16x32_bf16 v[68:71], v[144:147], v[214:217], v[68:71]
	v_mfma_f32_16x16x32_bf16 v[64:67], v[172:175], v[214:217], v[64:67]
	v_mfma_f32_16x16x32_bf16 v[116:119], v[148:151], v[194:197], v[116:119]
	v_mfma_f32_16x16x32_bf16 v[112:115], v[176:179], v[194:197], v[112:115]
	v_mfma_f32_16x16x32_bf16 v[100:103], v[148:151], v[202:205], v[100:103]
	v_mfma_f32_16x16x32_bf16 v[96:99], v[176:179], v[202:205], v[96:99]
	v_mfma_f32_16x16x32_bf16 v[84:87], v[148:151], v[210:213], v[84:87]
	v_mfma_f32_16x16x32_bf16 v[80:83], v[176:179], v[210:213], v[80:83]
	v_mfma_f32_16x16x32_bf16 v[68:71], v[148:151], v[218:221], v[68:71]
	v_mfma_f32_16x16x32_bf16 v[64:67], v[176:179], v[218:221], v[64:67]
	s_setprio 0
	s_barrier
	s_add_i32 s64, s84, s69
	v_lshl_add_u64 v[222:223], v[222:223], 0, s[26:27]
	s_mov_b32 m0, s64
	ds_read_b128 v[180:183], v191 offset:49152
	ds_read_b128 v[194:197], v191 offset:50176
	ds_read_b128 v[198:201], v191 offset:51200
	ds_read_b128 v[202:205], v191 offset:52224
	ds_read_b128 v[206:209], v191 offset:53248
	ds_read_b128 v[210:213], v191 offset:54272
	ds_read_b128 v[214:217], v191 offset:55296
	ds_read_b128 v[218:221], v191 offset:56320
	global_load_lds_dwordx4 v[222:223], off
	s_add_i32 m0, s64, 0x2000
	s_add_u32 s62, s62, 0x80080
	v_lshl_add_u64 v[222:223], v[224:225], 0, s[26:27]
	s_addc_u32 s63, s63, 0
	s_add_i32 s64, s85, s69
	global_load_lds_dwordx4 v[222:223], off
	v_lshl_add_u64 v[222:223], s[62:63], 0, v[154:155]
	s_mov_b32 m0, s64
	s_nop 0
	global_load_lds_dwordx4 v[222:223], off
	v_lshl_add_u64 v[222:223], s[62:63], 0, v[162:163]
	s_add_i32 m0, s64, 0x2000
	s_nop 0
	global_load_lds_dwordx4 v[222:223], off
	v_lshl_add_u64 v[222:223], v[226:227], 0, s[26:27]
	s_mov_b32 m0, s3
	s_nop 0
	global_load_lds_dwordx4 v[222:223], off
	v_lshl_add_u64 v[222:223], v[228:229], 0, s[26:27]
	s_mov_b32 m0, s75
	s_nop 0
	global_load_lds_dwordx4 v[222:223], off
	s_waitcnt vmcnt(8)
	s_waitcnt lgkmcnt(0)
	s_barrier
	s_setprio 1
	s_waitcnt lgkmcnt(0)
	v_mfma_f32_16x16x32_bf16 v[60:63], v[128:131], v[180:183], v[60:63]
	v_mfma_f32_16x16x32_bf16 v[56:59], v[136:139], v[180:183], v[56:59]
	v_mfma_f32_16x16x32_bf16 v[44:47], v[128:131], v[198:201], v[44:47]
	v_mfma_f32_16x16x32_bf16 v[40:43], v[136:139], v[198:201], v[40:43]
	v_mfma_f32_16x16x32_bf16 v[28:31], v[128:131], v[206:209], v[28:31]
	v_mfma_f32_16x16x32_bf16 v[24:27], v[136:139], v[206:209], v[24:27]
	v_mfma_f32_16x16x32_bf16 v[12:15], v[128:131], v[214:217], v[12:15]
	v_mfma_f32_16x16x32_bf16 v[8:11], v[136:139], v[214:217], v[8:11]
	v_mfma_f32_16x16x32_bf16 v[60:63], v[132:135], v[194:197], v[60:63]
	v_mfma_f32_16x16x32_bf16 v[56:59], v[140:143], v[194:197], v[56:59]
	v_mfma_f32_16x16x32_bf16 v[44:47], v[132:135], v[202:205], v[44:47]
	v_mfma_f32_16x16x32_bf16 v[40:43], v[140:143], v[202:205], v[40:43]
	v_mfma_f32_16x16x32_bf16 v[28:31], v[132:135], v[210:213], v[28:31]
	v_mfma_f32_16x16x32_bf16 v[24:27], v[140:143], v[210:213], v[24:27]
	v_mfma_f32_16x16x32_bf16 v[12:15], v[132:135], v[218:221], v[12:15]
	v_mfma_f32_16x16x32_bf16 v[8:11], v[140:143], v[218:221], v[8:11]
	s_setprio 0
	s_setprio 1
	v_mfma_f32_16x16x32_bf16 v[52:55], v[144:147], v[180:183], v[52:55]
	v_mfma_f32_16x16x32_bf16 v[48:51], v[172:175], v[180:183], v[48:51]
	v_mfma_f32_16x16x32_bf16 v[36:39], v[144:147], v[198:201], v[36:39]
	v_mfma_f32_16x16x32_bf16 v[32:35], v[172:175], v[198:201], v[32:35]
	v_mfma_f32_16x16x32_bf16 v[20:23], v[144:147], v[206:209], v[20:23]
	v_mfma_f32_16x16x32_bf16 v[16:19], v[172:175], v[206:209], v[16:19]
	v_mfma_f32_16x16x32_bf16 v[4:7], v[144:147], v[214:217], v[4:7]
	v_mfma_f32_16x16x32_bf16 v[0:3], v[172:175], v[214:217], v[0:3]
	v_mfma_f32_16x16x32_bf16 v[52:55], v[148:151], v[194:197], v[52:55]
	v_mfma_f32_16x16x32_bf16 v[48:51], v[176:179], v[194:197], v[48:51]
	v_mfma_f32_16x16x32_bf16 v[36:39], v[148:151], v[202:205], v[36:39]
	v_mfma_f32_16x16x32_bf16 v[32:35], v[176:179], v[202:205], v[32:35]
	v_mfma_f32_16x16x32_bf16 v[20:23], v[148:151], v[210:213], v[20:23]
	v_mfma_f32_16x16x32_bf16 v[16:19], v[176:179], v[210:213], v[16:19]
	v_mfma_f32_16x16x32_bf16 v[4:7], v[148:151], v[218:221], v[4:7]
	v_mfma_f32_16x16x32_bf16 v[0:3], v[176:179], v[218:221], v[0:3]
	s_setprio 0
	s_barrier
	s_add_i32 s83, s83, 2
	s_add_u32 s81, s81, 0x100
	s_addc_u32 s82, s82, 0
	s_add_u32 s60, s60, 0x100
	s_addc_u32 s61, s61, 0
	s_cmp_gt_u32 s83, 29

.LBB0_525:
	s_ashr_i32 s29, s28, 31
	s_lshl_b64 s[30:31], s[28:29], 19
	s_add_u32 s30, s3, s30
	s_addc_u32 s31, s35, s31
	s_and_b64 s[44:45], s[10:11], exec
	s_cselect_b32 s29, s31, s51
	s_cselect_b32 s70, s30, s50
	s_ashr_i32 s27, s26, 31
	s_lshl_b64 s[44:45], s[26:27], 19
	s_add_u32 s44, s52, s44
	s_addc_u32 s45, s53, s45
	s_and_b64 s[72:73], s[10:11], exec
	s_cselect_b32 s71, s45, s49
	s_cselect_b32 s72, s44, s48
	s_lshl_b32 s27, s46, 8
	v_add_u32_e32 v0, s27, v148
	s_add_u32 s73, s48, 0x100
	v_ashrrev_i32_e32 v1, 31, v0
	s_addc_u32 s74, s49, 0
	v_lshl_add_u64 v[144:145], v[0:1], 4, s[16:17]
	s_add_u32 s46, s50, 0x40080
	s_addc_u32 s47, s51, 0
	s_mov_b32 s75, -2
	s_mov_b64 s[48:49], 0
	s_cmp_eq_u32 s61, 1
	s_cbranch_scc1 .Lfa_4
	v_add_u32_e32 v153, s66, v147
	ds_read_b128 v[160:163], v153
	ds_read_b128 v[164:167], v153 offset:1024
	ds_read_b128 v[168:171], v153 offset:2048
	ds_read_b128 v[172:175], v153 offset:3072
	v_add_u32_e32 v153, s67, v147
	ds_read_b128 v[176:179], v153
	ds_read_b128 v[180:183], v153 offset:1024
	ds_read_b128 v[186:189], v153 offset:2048
	ds_read_b128 v[190:193], v153 offset:3072
	s_add_u32 s50, s46, 0xfffc0080
	s_addc_u32 s51, s47, -1
	s_and_b64 s[48:49], s[48:49], exec
	s_cselect_b32 s51, s29, s51
	s_cselect_b32 s50, s70, s50
	s_cselect_b32 s49, s71, s74
	s_cselect_b32 s48, s72, s73
	v_lshl_add_u64 v[154:155], s[46:47], 0, v[138:139]
	s_add_i32 m0, s57, 0xc000
	ds_read_b128 v[194:197], v150
	ds_read_b128 v[198:201], v150 offset:1024
	ds_read_b128 v[202:205], v150 offset:2048
	ds_read_b128 v[206:209], v150 offset:3072
	ds_read_b128 v[210:213], v150 offset:4096
	ds_read_b128 v[214:217], v150 offset:5120
	ds_read_b128 v[218:221], v150 offset:6144
	ds_read_b128 v[222:225], v150 offset:7168
	global_load_lds_dwordx4 v[154:155], off
	v_lshl_add_u64 v[154:155], s[46:47], 0, v[136:137]
	s_add_i32 m0, s57, 0xe000
	s_nop 0
	global_load_lds_dwordx4 v[154:155], off
	s_waitcnt vmcnt(16)
	s_waitcnt lgkmcnt(0)
	s_barrier
	s_setprio 1
	s_waitcnt lgkmcnt(0)
	v_mfma_f32_16x16x32_bf16 v[124:127], v[160:163], v[194:197], 0
	v_mfma_f32_16x16x32_bf16 v[116:119], v[168:171], v[194:197], 0
	v_mfma_f32_16x16x32_bf16 v[108:111], v[160:163], v[202:205], 0
	v_mfma_f32_16x16x32_bf16 v[100:103], v[168:171], v[202:205], 0
	v_mfma_f32_16x16x32_bf16 v[92:95], v[160:163], v[210:213], 0
	v_mfma_f32_16x16x32_bf16 v[84:87], v[168:171], v[210:213], 0
	v_mfma_f32_16x16x32_bf16 v[76:79], v[160:163], v[218:221], 0
	v_mfma_f32_16x16x32_bf16 v[68:71], v[168:171], v[218:221], 0
	v_mfma_f32_16x16x32_bf16 v[124:127], v[164:167], v[198:201], v[124:127]
	v_mfma_f32_16x16x32_bf16 v[116:119], v[172:175], v[198:201], v[116:119]
	v_mfma_f32_16x16x32_bf16 v[108:111], v[164:167], v[206:209], v[108:111]
	v_mfma_f32_16x16x32_bf16 v[100:103], v[172:175], v[206:209], v[100:103]
	v_mfma_f32_16x16x32_bf16 v[92:95], v[164:167], v[214:217], v[92:95]
	v_mfma_f32_16x16x32_bf16 v[84:87], v[172:175], v[214:217], v[84:87]
	v_mfma_f32_16x16x32_bf16 v[76:79], v[164:167], v[222:225], v[76:79]
	v_mfma_f32_16x16x32_bf16 v[68:71], v[172:175], v[222:225], v[68:71]
	s_setprio 0
	s_setprio 1
	v_mfma_f32_16x16x32_bf16 v[120:123], v[176:179], v[194:197], 0
	v_mfma_f32_16x16x32_bf16 v[112:115], v[186:189], v[194:197], 0
	v_mfma_f32_16x16x32_bf16 v[104:107], v[176:179], v[202:205], 0
	v_mfma_f32_16x16x32_bf16 v[96:99], v[186:189], v[202:205], 0
	v_mfma_f32_16x16x32_bf16 v[88:91], v[176:179], v[210:213], 0
	v_mfma_f32_16x16x32_bf16 v[80:83], v[186:189], v[210:213], 0
	v_mfma_f32_16x16x32_bf16 v[72:75], v[176:179], v[218:221], 0
	v_mfma_f32_16x16x32_bf16 v[64:67], v[186:189], v[218:221], 0
	v_mfma_f32_16x16x32_bf16 v[120:123], v[180:183], v[198:201], v[120:123]
	v_mfma_f32_16x16x32_bf16 v[112:115], v[190:193], v[198:201], v[112:115]
	v_mfma_f32_16x16x32_bf16 v[104:107], v[180:183], v[206:209], v[104:107]
	v_mfma_f32_16x16x32_bf16 v[96:99], v[190:193], v[206:209], v[96:99]
	v_mfma_f32_16x16x32_bf16 v[88:91], v[180:183], v[214:217], v[88:91]
	v_mfma_f32_16x16x32_bf16 v[80:83], v[190:193], v[214:217], v[80:83]
	v_mfma_f32_16x16x32_bf16 v[72:75], v[180:183], v[222:225], v[72:75]
	v_mfma_f32_16x16x32_bf16 v[64:67], v[190:193], v[222:225], v[64:67]
	s_setprio 0
	s_barrier
	s_add_i32 s76, s66, s54
	v_lshl_add_u64 v[154:155], s[48:49], 0, v[132:133]
	s_mov_b32 m0, s76
	ds_read_b128 v[194:197], v150 offset:16384
	ds_read_b128 v[198:201], v150 offset:17408
	ds_read_b128 v[202:205], v150 offset:18432
	ds_read_b128 v[206:209], v150 offset:19456
	ds_read_b128 v[210:213], v150 offset:20480
	ds_read_b128 v[214:217], v150 offset:21504
	ds_read_b128 v[218:221], v150 offset:22528
	ds_read_b128 v[222:225], v150 offset:23552
	global_load_lds_dwordx4 v[154:155], off
	s_add_i32 m0, s76, 0x2000
	s_add_u32 s76, s48, 0x40000
	v_lshl_add_u64 v[226:227], s[48:49], 0, v[128:129]
	s_addc_u32 s77, s49, 0
	s_add_i32 s78, s67, s54
	global_load_lds_dwordx4 v[226:227], off
	v_lshl_add_u64 v[228:229], s[76:77], 0, v[132:133]
	s_mov_b32 m0, s78
	v_lshl_add_u64 v[230:231], s[50:51], 0, v[130:131]
	global_load_lds_dwordx4 v[228:229], off
	v_lshl_add_u64 v[228:229], s[76:77], 0, v[128:129]
	s_add_i32 m0, s78, 0x2000
	s_nop 0
	global_load_lds_dwordx4 v[228:229], off
	v_lshl_add_u64 v[228:229], s[50:51], 0, v[134:135]
	s_mov_b32 m0, s57
	s_nop 0
	global_load_lds_dwordx4 v[228:229], off
	s_mov_b32 m0, s58
	s_nop 0
	global_load_lds_dwordx4 v[230:231], off
	s_waitcnt vmcnt(16)
	s_waitcnt lgkmcnt(0)
	s_barrier
	s_setprio 1
	s_waitcnt lgkmcnt(0)
	v_mfma_f32_16x16x32_bf16 v[60:63], v[160:163], v[194:197], 0
	v_mfma_f32_16x16x32_bf16 v[52:55], v[168:171], v[194:197], 0
	v_mfma_f32_16x16x32_bf16 v[44:47], v[160:163], v[202:205], 0
	v_mfma_f32_16x16x32_bf16 v[36:39], v[168:171], v[202:205], 0
	v_mfma_f32_16x16x32_bf16 v[28:31], v[160:163], v[210:213], 0
	v_mfma_f32_16x16x32_bf16 v[20:23], v[168:171], v[210:213], 0
	v_mfma_f32_16x16x32_bf16 v[12:15], v[160:163], v[218:221], 0
	v_mfma_f32_16x16x32_bf16 v[4:7], v[168:171], v[218:221], 0
	v_mfma_f32_16x16x32_bf16 v[60:63], v[164:167], v[198:201], v[60:63]
	v_mfma_f32_16x16x32_bf16 v[52:55], v[172:175], v[198:201], v[52:55]
	v_mfma_f32_16x16x32_bf16 v[44:47], v[164:167], v[206:209], v[44:47]
	v_mfma_f32_16x16x32_bf16 v[36:39], v[172:175], v[206:209], v[36:39]
	v_mfma_f32_16x16x32_bf16 v[28:31], v[164:167], v[214:217], v[28:31]
	v_mfma_f32_16x16x32_bf16 v[20:23], v[172:175], v[214:217], v[20:23]
	v_mfma_f32_16x16x32_bf16 v[12:15], v[164:167], v[222:225], v[12:15]
	v_mfma_f32_16x16x32_bf16 v[4:7], v[172:175], v[222:225], v[4:7]
	s_setprio 0
	s_setprio 1
	v_mfma_f32_16x16x32_bf16 v[56:59], v[176:179], v[194:197], 0
	v_mfma_f32_16x16x32_bf16 v[48:51], v[186:189], v[194:197], 0
	v_mfma_f32_16x16x32_bf16 v[40:43], v[176:179], v[202:205], 0
	v_mfma_f32_16x16x32_bf16 v[32:35], v[186:189], v[202:205], 0
	v_mfma_f32_16x16x32_bf16 v[24:27], v[176:179], v[210:213], 0
	v_mfma_f32_16x16x32_bf16 v[16:19], v[186:189], v[210:213], 0
	v_mfma_f32_16x16x32_bf16 v[8:11], v[176:179], v[218:221], 0
	v_mfma_f32_16x16x32_bf16 v[0:3], v[186:189], v[218:221], 0
	v_mfma_f32_16x16x32_bf16 v[56:59], v[180:183], v[198:201], v[56:59]
	v_mfma_f32_16x16x32_bf16 v[48:51], v[190:193], v[198:201], v[48:51]
	v_mfma_f32_16x16x32_bf16 v[40:43], v[180:183], v[206:209], v[40:43]
	v_mfma_f32_16x16x32_bf16 v[32:35], v[190:193], v[206:209], v[32:35]
	v_mfma_f32_16x16x32_bf16 v[24:27], v[180:183], v[214:217], v[24:27]
	v_mfma_f32_16x16x32_bf16 v[16:19], v[190:193], v[214:217], v[16:19]
	v_mfma_f32_16x16x32_bf16 v[8:11], v[180:183], v[222:225], v[8:11]
	v_mfma_f32_16x16x32_bf16 v[0:3], v[190:193], v[222:225], v[0:3]
	s_setprio 0
	s_barrier
	s_add_i32 s76, 0, 0x18000
	v_add_u32_e32 v153, s76, v147
	s_add_i32 s77, 0, 0x1c000
	ds_read_b128 v[160:163], v153
	ds_read_b128 v[164:167], v153 offset:1024
	ds_read_b128 v[168:171], v153 offset:2048
	ds_read_b128 v[172:175], v153 offset:3072
	v_add_u32_e32 v153, s77, v147
	ds_read_b128 v[176:179], v153
	ds_read_b128 v[180:183], v153 offset:1024
	ds_read_b128 v[186:189], v153 offset:2048
	ds_read_b128 v[190:193], v153 offset:3072
	s_add_u32 s50, s50, 0x40000
	s_addc_u32 s51, s51, 0
	s_mov_b32 m0, s59
	v_lshl_add_u64 v[232:233], s[50:51], 0, v[134:135]
	ds_read_b128 v[194:197], v150 offset:32768
	ds_read_b128 v[198:201], v150 offset:33792
	ds_read_b128 v[202:205], v150 offset:34816
	ds_read_b128 v[206:209], v150 offset:35840
	ds_read_b128 v[210:213], v150 offset:36864
	ds_read_b128 v[214:217], v150 offset:37888
	ds_read_b128 v[218:221], v150 offset:38912
	ds_read_b128 v[222:225], v150 offset:39936
	global_load_lds_dwordx4 v[232:233], off
	v_lshl_add_u64 v[232:233], s[50:51], 0, v[130:131]
	s_mov_b32 m0, s60
	s_nop 0
	global_load_lds_dwordx4 v[232:233], off
	s_waitcnt vmcnt(8)
	s_waitcnt lgkmcnt(0)
	s_barrier
	s_setprio 1
	s_waitcnt lgkmcnt(0)
	v_mfma_f32_16x16x32_bf16 v[124:127], v[160:163], v[194:197], v[124:127]
	v_mfma_f32_16x16x32_bf16 v[116:119], v[168:171], v[194:197], v[116:119]
	v_mfma_f32_16x16x32_bf16 v[108:111], v[160:163], v[202:205], v[108:111]
	v_mfma_f32_16x16x32_bf16 v[100:103], v[168:171], v[202:205], v[100:103]
	v_mfma_f32_16x16x32_bf16 v[92:95], v[160:163], v[210:213], v[92:95]
	v_mfma_f32_16x16x32_bf16 v[84:87], v[168:171], v[210:213], v[84:87]
	v_mfma_f32_16x16x32_bf16 v[76:79], v[160:163], v[218:221], v[76:79]
	v_mfma_f32_16x16x32_bf16 v[68:71], v[168:171], v[218:221], v[68:71]
	v_mfma_f32_16x16x32_bf16 v[124:127], v[164:167], v[198:201], v[124:127]
	v_mfma_f32_16x16x32_bf16 v[116:119], v[172:175], v[198:201], v[116:119]
	v_mfma_f32_16x16x32_bf16 v[108:111], v[164:167], v[206:209], v[108:111]
	v_mfma_f32_16x16x32_bf16 v[100:103], v[172:175], v[206:209], v[100:103]
	v_mfma_f32_16x16x32_bf16 v[92:95], v[164:167], v[214:217], v[92:95]
	v_mfma_f32_16x16x32_bf16 v[84:87], v[172:175], v[214:217], v[84:87]
	v_mfma_f32_16x16x32_bf16 v[76:79], v[164:167], v[222:225], v[76:79]
	v_mfma_f32_16x16x32_bf16 v[68:71], v[172:175], v[222:225], v[68:71]
	s_setprio 0
	s_setprio 1
	v_mfma_f32_16x16x32_bf16 v[120:123], v[176:179], v[194:197], v[120:123]
	v_mfma_f32_16x16x32_bf16 v[112:115], v[186:189], v[194:197], v[112:115]
	v_mfma_f32_16x16x32_bf16 v[104:107], v[176:179], v[202:205], v[104:107]
	v_mfma_f32_16x16x32_bf16 v[96:99], v[186:189], v[202:205], v[96:99]
	v_mfma_f32_16x16x32_bf16 v[88:91], v[176:179], v[210:213], v[88:91]
	v_mfma_f32_16x16x32_bf16 v[80:83], v[186:189], v[210:213], v[80:83]
	v_mfma_f32_16x16x32_bf16 v[72:75], v[176:179], v[218:221], v[72:75]
	v_mfma_f32_16x16x32_bf16 v[64:67], v[186:189], v[218:221], v[64:67]
	v_mfma_f32_16x16x32_bf16 v[120:123], v[180:183], v[198:201], v[120:123]
	v_mfma_f32_16x16x32_bf16 v[112:115], v[190:193], v[198:201], v[112:115]
	v_mfma_f32_16x16x32_bf16 v[104:107], v[180:183], v[206:209], v[104:107]
	v_mfma_f32_16x16x32_bf16 v[96:99], v[190:193], v[206:209], v[96:99]
	v_mfma_f32_16x16x32_bf16 v[88:91], v[180:183], v[214:217], v[88:91]
	v_mfma_f32_16x16x32_bf16 v[80:83], v[190:193], v[214:217], v[80:83]
	v_mfma_f32_16x16x32_bf16 v[72:75], v[180:183], v[222:225], v[72:75]
	v_mfma_f32_16x16x32_bf16 v[64:67], v[190:193], v[222:225], v[64:67]
	s_setprio 0
	s_barrier
	s_add_i32 s50, s76, s54
	v_lshl_add_u64 v[154:155], v[154:155], 0, s[20:21]
	s_mov_b32 m0, s50
	ds_read_b128 v[194:197], v150 offset:49152
	ds_read_b128 v[198:201], v150 offset:50176
	ds_read_b128 v[202:205], v150 offset:51200
	ds_read_b128 v[206:209], v150 offset:52224
	ds_read_b128 v[210:213], v150 offset:53248
	ds_read_b128 v[214:217], v150 offset:54272
	ds_read_b128 v[218:221], v150 offset:55296
	ds_read_b128 v[222:225], v150 offset:56320
	global_load_lds_dwordx4 v[154:155], off
	s_add_i32 m0, s50, 0x2000
	s_add_u32 s48, s48, 0x40080
	v_lshl_add_u64 v[154:155], v[226:227], 0, s[20:21]
	s_addc_u32 s49, s49, 0
	s_add_i32 s50, s77, s54
	global_load_lds_dwordx4 v[154:155], off
	v_lshl_add_u64 v[154:155], s[48:49], 0, v[132:133]
	s_mov_b32 m0, s50
	s_nop 0
	global_load_lds_dwordx4 v[154:155], off
	v_lshl_add_u64 v[154:155], s[48:49], 0, v[128:129]
	s_add_i32 m0, s50, 0x2000
	s_nop 0
	global_load_lds_dwordx4 v[154:155], off
	v_lshl_add_u64 v[154:155], v[228:229], 0, s[20:21]
	s_mov_b32 m0, s62
	s_nop 0
	global_load_lds_dwordx4 v[154:155], off
	v_lshl_add_u64 v[154:155], v[230:231], 0, s[20:21]
	s_mov_b32 m0, s63
	s_nop 0
	global_load_lds_dwordx4 v[154:155], off
	s_waitcnt vmcnt(8)
	s_waitcnt lgkmcnt(0)
	s_barrier
	s_setprio 1
	s_waitcnt lgkmcnt(0)
	v_mfma_f32_16x16x32_bf16 v[60:63], v[160:163], v[194:197], v[60:63]
	v_mfma_f32_16x16x32_bf16 v[52:55], v[168:171], v[194:197], v[52:55]
	v_mfma_f32_16x16x32_bf16 v[44:47], v[160:163], v[202:205], v[44:47]
	v_mfma_f32_16x16x32_bf16 v[36:39], v[168:171], v[202:205], v[36:39]
	v_mfma_f32_16x16x32_bf16 v[28:31], v[160:163], v[210:213], v[28:31]
	v_mfma_f32_16x16x32_bf16 v[20:23], v[168:171], v[210:213], v[20:23]
	v_mfma_f32_16x16x32_bf16 v[12:15], v[160:163], v[218:221], v[12:15]
	v_mfma_f32_16x16x32_bf16 v[4:7], v[168:171], v[218:221], v[4:7]
	v_mfma_f32_16x16x32_bf16 v[60:63], v[164:167], v[198:201], v[60:63]
	v_mfma_f32_16x16x32_bf16 v[52:55], v[172:175], v[198:201], v[52:55]
	v_mfma_f32_16x16x32_bf16 v[44:47], v[164:167], v[206:209], v[44:47]
	v_mfma_f32_16x16x32_bf16 v[36:39], v[172:175], v[206:209], v[36:39]
	v_mfma_f32_16x16x32_bf16 v[28:31], v[164:167], v[214:217], v[28:31]
	v_mfma_f32_16x16x32_bf16 v[20:23], v[172:175], v[214:217], v[20:23]
	v_mfma_f32_16x16x32_bf16 v[12:15], v[164:167], v[222:225], v[12:15]
	v_mfma_f32_16x16x32_bf16 v[4:7], v[172:175], v[222:225], v[4:7]
	s_setprio 0
	s_setprio 1
	v_mfma_f32_16x16x32_bf16 v[56:59], v[176:179], v[194:197], v[56:59]
	v_mfma_f32_16x16x32_bf16 v[48:51], v[186:189], v[194:197], v[48:51]
	v_mfma_f32_16x16x32_bf16 v[40:43], v[176:179], v[202:205], v[40:43]
	v_mfma_f32_16x16x32_bf16 v[32:35], v[186:189], v[202:205], v[32:35]
	v_mfma_f32_16x16x32_bf16 v[24:27], v[176:179], v[210:213], v[24:27]
	v_mfma_f32_16x16x32_bf16 v[16:19], v[186:189], v[210:213], v[16:19]
	v_mfma_f32_16x16x32_bf16 v[8:11], v[176:179], v[218:221], v[8:11]
	v_mfma_f32_16x16x32_bf16 v[0:3], v[186:189], v[218:221], v[0:3]
	v_mfma_f32_16x16x32_bf16 v[56:59], v[180:183], v[198:201], v[56:59]
	v_mfma_f32_16x16x32_bf16 v[48:51], v[190:193], v[198:201], v[48:51]
	v_mfma_f32_16x16x32_bf16 v[40:43], v[180:183], v[206:209], v[40:43]
	v_mfma_f32_16x16x32_bf16 v[32:35], v[190:193], v[206:209], v[32:35]
	v_mfma_f32_16x16x32_bf16 v[24:27], v[180:183], v[214:217], v[24:27]
	v_mfma_f32_16x16x32_bf16 v[16:19], v[190:193], v[214:217], v[16:19]
	v_mfma_f32_16x16x32_bf16 v[8:11], v[180:183], v[222:225], v[8:11]
	v_mfma_f32_16x16x32_bf16 v[0:3], v[190:193], v[222:225], v[0:3]
	s_setprio 0
	s_barrier
	s_add_i32 s75, s75, 2
	s_add_u32 s73, s73, 0x100
	s_addc_u32 s74, s74, 0
	s_add_u32 s46, s46, 0x100
	s_addc_u32 s47, s47, 0
	s_branch .LBB0_527
.Lfa_4:
	v_add_u32_e32 v153, s66, v147
	ds_read_b128 v[160:163], v153
	ds_read_b128 v[164:167], v153 offset:1024
	ds_read_b128 v[168:171], v153 offset:2048
	ds_read_b128 v[172:175], v153 offset:3072
	v_add_u32_e32 v153, s67, v147
	ds_read_b128 v[176:179], v153
	ds_read_b128 v[180:183], v153 offset:1024
	ds_read_b128 v[186:189], v153 offset:2048
	ds_read_b128 v[190:193], v153 offset:3072
	s_add_u32 s50, s46, 0xfffc0080
	s_addc_u32 s51, s47, -1
	s_and_b64 s[48:49], s[48:49], exec
	s_cselect_b32 s51, s29, s51
	s_cselect_b32 s50, s70, s50
	s_cselect_b32 s49, s71, s74
	s_cselect_b32 s48, s72, s73
	v_lshl_add_u64 v[154:155], s[46:47], 0, v[138:139]
	s_add_i32 m0, s57, 0xc000
	ds_read_b128 v[194:197], v150
	ds_read_b128 v[198:201], v150 offset:1024
	ds_read_b128 v[202:205], v150 offset:2048
	ds_read_b128 v[206:209], v150 offset:3072
	ds_read_b128 v[210:213], v150 offset:4096
	ds_read_b128 v[214:217], v150 offset:5120
	ds_read_b128 v[218:221], v150 offset:6144
	ds_read_b128 v[222:225], v150 offset:7168
	global_load_lds_dwordx4 v[154:155], off
	v_lshl_add_u64 v[154:155], s[46:47], 0, v[136:137]
	s_add_i32 m0, s57, 0xe000
	s_nop 0
	global_load_lds_dwordx4 v[154:155], off
	s_waitcnt vmcnt(8)
	s_waitcnt lgkmcnt(0)
	s_barrier
	s_setprio 1
	s_waitcnt lgkmcnt(0)
	v_mfma_f32_16x16x32_bf16 v[124:127], v[160:163], v[194:197], 0
	v_mfma_f32_16x16x32_bf16 v[116:119], v[168:171], v[194:197], 0
	v_mfma_f32_16x16x32_bf16 v[108:111], v[160:163], v[202:205], 0
	v_mfma_f32_16x16x32_bf16 v[100:103], v[168:171], v[202:205], 0
	v_mfma_f32_16x16x32_bf16 v[92:95], v[160:163], v[210:213], 0
	v_mfma_f32_16x16x32_bf16 v[84:87], v[168:171], v[210:213], 0
	v_mfma_f32_16x16x32_bf16 v[76:79], v[160:163], v[218:221], 0
	v_mfma_f32_16x16x32_bf16 v[68:71], v[168:171], v[218:221], 0
	v_mfma_f32_16x16x32_bf16 v[124:127], v[164:167], v[198:201], v[124:127]
	v_mfma_f32_16x16x32_bf16 v[116:119], v[172:175], v[198:201], v[116:119]
	v_mfma_f32_16x16x32_bf16 v[108:111], v[164:167], v[206:209], v[108:111]
	v_mfma_f32_16x16x32_bf16 v[100:103], v[172:175], v[206:209], v[100:103]
	v_mfma_f32_16x16x32_bf16 v[92:95], v[164:167], v[214:217], v[92:95]
	v_mfma_f32_16x16x32_bf16 v[84:87], v[172:175], v[214:217], v[84:87]
	v_mfma_f32_16x16x32_bf16 v[76:79], v[164:167], v[222:225], v[76:79]
	v_mfma_f32_16x16x32_bf16 v[68:71], v[172:175], v[222:225], v[68:71]
	s_setprio 0
	s_setprio 1
	v_mfma_f32_16x16x32_bf16 v[120:123], v[176:179], v[194:197], 0
	v_mfma_f32_16x16x32_bf16 v[112:115], v[186:189], v[194:197], 0
	v_mfma_f32_16x16x32_bf16 v[104:107], v[176:179], v[202:205], 0
	v_mfma_f32_16x16x32_bf16 v[96:99], v[186:189], v[202:205], 0
	v_mfma_f32_16x16x32_bf16 v[88:91], v[176:179], v[210:213], 0
	v_mfma_f32_16x16x32_bf16 v[80:83], v[186:189], v[210:213], 0
	v_mfma_f32_16x16x32_bf16 v[72:75], v[176:179], v[218:221], 0
	v_mfma_f32_16x16x32_bf16 v[64:67], v[186:189], v[218:221], 0
	v_mfma_f32_16x16x32_bf16 v[120:123], v[180:183], v[198:201], v[120:123]
	v_mfma_f32_16x16x32_bf16 v[112:115], v[190:193], v[198:201], v[112:115]
	v_mfma_f32_16x16x32_bf16 v[104:107], v[180:183], v[206:209], v[104:107]
	v_mfma_f32_16x16x32_bf16 v[96:99], v[190:193], v[206:209], v[96:99]
	v_mfma_f32_16x16x32_bf16 v[88:91], v[180:183], v[214:217], v[88:91]
	v_mfma_f32_16x16x32_bf16 v[80:83], v[190:193], v[214:217], v[80:83]
	v_mfma_f32_16x16x32_bf16 v[72:75], v[180:183], v[222:225], v[72:75]
	v_mfma_f32_16x16x32_bf16 v[64:67], v[190:193], v[222:225], v[64:67]
	s_setprio 0
	s_barrier
	s_add_i32 s76, s66, s54
	v_lshl_add_u64 v[154:155], s[48:49], 0, v[132:133]
	s_mov_b32 m0, s76
	ds_read_b128 v[194:197], v150 offset:16384
	ds_read_b128 v[198:201], v150 offset:17408
	ds_read_b128 v[202:205], v150 offset:18432
	ds_read_b128 v[206:209], v150 offset:19456
	ds_read_b128 v[210:213], v150 offset:20480
	ds_read_b128 v[214:217], v150 offset:21504
	ds_read_b128 v[218:221], v150 offset:22528
	ds_read_b128 v[222:225], v150 offset:23552
	global_load_lds_dwordx4 v[154:155], off
	s_add_i32 m0, s76, 0x2000
	s_add_u32 s76, s48, 0x40000
	v_lshl_add_u64 v[226:227], s[48:49], 0, v[128:129]
	s_addc_u32 s77, s49, 0
	s_add_i32 s78, s67, s54
	global_load_lds_dwordx4 v[226:227], off
	v_lshl_add_u64 v[228:229], s[76:77], 0, v[132:133]
	s_mov_b32 m0, s78
	v_lshl_add_u64 v[230:231], s[50:51], 0, v[130:131]
	global_load_lds_dwordx4 v[228:229], off
	v_lshl_add_u64 v[228:229], s[76:77], 0, v[128:129]
	s_add_i32 m0, s78, 0x2000
	s_nop 0
	global_load_lds_dwordx4 v[228:229], off
	v_lshl_add_u64 v[228:229], s[50:51], 0, v[134:135]
	s_mov_b32 m0, s57
	s_nop 0
	global_load_lds_dwordx4 v[228:229], off
	s_mov_b32 m0, s58
	s_nop 0
	global_load_lds_dwordx4 v[230:231], off
	s_waitcnt vmcnt(8)
	s_waitcnt lgkmcnt(0)
	s_barrier
	s_setprio 1
	s_waitcnt lgkmcnt(0)
	v_mfma_f32_16x16x32_bf16 v[60:63], v[160:163], v[194:197], 0
	v_mfma_f32_16x16x32_bf16 v[52:55], v[168:171], v[194:197], 0
	v_mfma_f32_16x16x32_bf16 v[44:47], v[160:163], v[202:205], 0
	v_mfma_f32_16x16x32_bf16 v[36:39], v[168:171], v[202:205], 0
	v_mfma_f32_16x16x32_bf16 v[28:31], v[160:163], v[210:213], 0
	v_mfma_f32_16x16x32_bf16 v[20:23], v[168:171], v[210:213], 0
	v_mfma_f32_16x16x32_bf16 v[12:15], v[160:163], v[218:221], 0
	v_mfma_f32_16x16x32_bf16 v[4:7], v[168:171], v[218:221], 0
	v_mfma_f32_16x16x32_bf16 v[60:63], v[164:167], v[198:201], v[60:63]
	v_mfma_f32_16x16x32_bf16 v[52:55], v[172:175], v[198:201], v[52:55]
	v_mfma_f32_16x16x32_bf16 v[44:47], v[164:167], v[206:209], v[44:47]
	v_mfma_f32_16x16x32_bf16 v[36:39], v[172:175], v[206:209], v[36:39]
	v_mfma_f32_16x16x32_bf16 v[28:31], v[164:167], v[214:217], v[28:31]
	v_mfma_f32_16x16x32_bf16 v[20:23], v[172:175], v[214:217], v[20:23]
	v_mfma_f32_16x16x32_bf16 v[12:15], v[164:167], v[222:225], v[12:15]
	v_mfma_f32_16x16x32_bf16 v[4:7], v[172:175], v[222:225], v[4:7]
	s_setprio 0
	s_setprio 1
	v_mfma_f32_16x16x32_bf16 v[56:59], v[176:179], v[194:197], 0
	v_mfma_f32_16x16x32_bf16 v[48:51], v[186:189], v[194:197], 0
	v_mfma_f32_16x16x32_bf16 v[40:43], v[176:179], v[202:205], 0
	v_mfma_f32_16x16x32_bf16 v[32:35], v[186:189], v[202:205], 0
	v_mfma_f32_16x16x32_bf16 v[24:27], v[176:179], v[210:213], 0
	v_mfma_f32_16x16x32_bf16 v[16:19], v[186:189], v[210:213], 0
	v_mfma_f32_16x16x32_bf16 v[8:11], v[176:179], v[218:221], 0
	v_mfma_f32_16x16x32_bf16 v[0:3], v[186:189], v[218:221], 0
	v_mfma_f32_16x16x32_bf16 v[56:59], v[180:183], v[198:201], v[56:59]
	v_mfma_f32_16x16x32_bf16 v[48:51], v[190:193], v[198:201], v[48:51]
	v_mfma_f32_16x16x32_bf16 v[40:43], v[180:183], v[206:209], v[40:43]
	v_mfma_f32_16x16x32_bf16 v[32:35], v[190:193], v[206:209], v[32:35]
	v_mfma_f32_16x16x32_bf16 v[24:27], v[180:183], v[214:217], v[24:27]
	v_mfma_f32_16x16x32_bf16 v[16:19], v[190:193], v[214:217], v[16:19]
	v_mfma_f32_16x16x32_bf16 v[8:11], v[180:183], v[222:225], v[8:11]
	v_mfma_f32_16x16x32_bf16 v[0:3], v[190:193], v[222:225], v[0:3]
	s_setprio 0
	s_barrier
	s_add_i32 s76, 0, 0x18000
	v_add_u32_e32 v153, s76, v147
	s_add_i32 s77, 0, 0x1c000
	ds_read_b128 v[160:163], v153
	ds_read_b128 v[164:167], v153 offset:1024
	ds_read_b128 v[168:171], v153 offset:2048
	ds_read_b128 v[172:175], v153 offset:3072
	v_add_u32_e32 v153, s77, v147
	ds_read_b128 v[176:179], v153
	ds_read_b128 v[180:183], v153 offset:1024
	ds_read_b128 v[186:189], v153 offset:2048
	ds_read_b128 v[190:193], v153 offset:3072
	s_add_u32 s50, s50, 0x40000
	s_addc_u32 s51, s51, 0
	s_mov_b32 m0, s59
	v_lshl_add_u64 v[232:233], s[50:51], 0, v[134:135]
	ds_read_b128 v[194:197], v150 offset:32768
	ds_read_b128 v[198:201], v150 offset:33792
	ds_read_b128 v[202:205], v150 offset:34816
	ds_read_b128 v[206:209], v150 offset:35840
	ds_read_b128 v[210:213], v150 offset:36864
	ds_read_b128 v[214:217], v150 offset:37888
	ds_read_b128 v[218:221], v150 offset:38912
	ds_read_b128 v[222:225], v150 offset:39936
	global_load_lds_dwordx4 v[232:233], off
	v_lshl_add_u64 v[232:233], s[50:51], 0, v[130:131]
	s_mov_b32 m0, s60
	s_nop 0
	global_load_lds_dwordx4 v[232:233], off
	s_waitcnt vmcnt(8)
	s_waitcnt lgkmcnt(0)
	s_barrier
	s_setprio 1
	s_waitcnt lgkmcnt(0)
	v_mfma_f32_16x16x32_bf16 v[124:127], v[160:163], v[194:197], v[124:127]
	v_mfma_f32_16x16x32_bf16 v[116:119], v[168:171], v[194:197], v[116:119]
	v_mfma_f32_16x16x32_bf16 v[108:111], v[160:163], v[202:205], v[108:111]
	v_mfma_f32_16x16x32_bf16 v[100:103], v[168:171], v[202:205], v[100:103]
	v_mfma_f32_16x16x32_bf16 v[92:95], v[160:163], v[210:213], v[92:95]
	v_mfma_f32_16x16x32_bf16 v[84:87], v[168:171], v[210:213], v[84:87]
	v_mfma_f32_16x16x32_bf16 v[76:79], v[160:163], v[218:221], v[76:79]
	v_mfma_f32_16x16x32_bf16 v[68:71], v[168:171], v[218:221], v[68:71]
	v_mfma_f32_16x16x32_bf16 v[124:127], v[164:167], v[198:201], v[124:127]
	v_mfma_f32_16x16x32_bf16 v[116:119], v[172:175], v[198:201], v[116:119]
	v_mfma_f32_16x16x32_bf16 v[108:111], v[164:167], v[206:209], v[108:111]
	v_mfma_f32_16x16x32_bf16 v[100:103], v[172:175], v[206:209], v[100:103]
	v_mfma_f32_16x16x32_bf16 v[92:95], v[164:167], v[214:217], v[92:95]
	v_mfma_f32_16x16x32_bf16 v[84:87], v[172:175], v[214:217], v[84:87]
	v_mfma_f32_16x16x32_bf16 v[76:79], v[164:167], v[222:225], v[76:79]
	v_mfma_f32_16x16x32_bf16 v[68:71], v[172:175], v[222:225], v[68:71]
	s_setprio 0
	s_setprio 1
	v_mfma_f32_16x16x32_bf16 v[120:123], v[176:179], v[194:197], v[120:123]
	v_mfma_f32_16x16x32_bf16 v[112:115], v[186:189], v[194:197], v[112:115]
	v_mfma_f32_16x16x32_bf16 v[104:107], v[176:179], v[202:205], v[104:107]
	v_mfma_f32_16x16x32_bf16 v[96:99], v[186:189], v[202:205], v[96:99]
	v_mfma_f32_16x16x32_bf16 v[88:91], v[176:179], v[210:213], v[88:91]
	v_mfma_f32_16x16x32_bf16 v[80:83], v[186:189], v[210:213], v[80:83]
	v_mfma_f32_16x16x32_bf16 v[72:75], v[176:179], v[218:221], v[72:75]
	v_mfma_f32_16x16x32_bf16 v[64:67], v[186:189], v[218:221], v[64:67]
	v_mfma_f32_16x16x32_bf16 v[120:123], v[180:183], v[198:201], v[120:123]
	v_mfma_f32_16x16x32_bf16 v[112:115], v[190:193], v[198:201], v[112:115]
	v_mfma_f32_16x16x32_bf16 v[104:107], v[180:183], v[206:209], v[104:107]
	v_mfma_f32_16x16x32_bf16 v[96:99], v[190:193], v[206:209], v[96:99]
	v_mfma_f32_16x16x32_bf16 v[88:91], v[180:183], v[214:217], v[88:91]
	v_mfma_f32_16x16x32_bf16 v[80:83], v[190:193], v[214:217], v[80:83]
	v_mfma_f32_16x16x32_bf16 v[72:75], v[180:183], v[222:225], v[72:75]
	v_mfma_f32_16x16x32_bf16 v[64:67], v[190:193], v[222:225], v[64:67]
	s_setprio 0
	s_barrier
	s_add_i32 s50, s76, s54
	v_lshl_add_u64 v[154:155], v[154:155], 0, s[20:21]
	s_mov_b32 m0, s50
	ds_read_b128 v[194:197], v150 offset:49152
	ds_read_b128 v[198:201], v150 offset:50176
	ds_read_b128 v[202:205], v150 offset:51200
	ds_read_b128 v[206:209], v150 offset:52224
	ds_read_b128 v[210:213], v150 offset:53248
	ds_read_b128 v[214:217], v150 offset:54272
	ds_read_b128 v[218:221], v150 offset:55296
	ds_read_b128 v[222:225], v150 offset:56320
	global_load_lds_dwordx4 v[154:155], off
	s_add_i32 m0, s50, 0x2000
	s_add_u32 s48, s48, 0x40080
	v_lshl_add_u64 v[154:155], v[226:227], 0, s[20:21]
	s_addc_u32 s49, s49, 0
	s_add_i32 s50, s77, s54
	global_load_lds_dwordx4 v[154:155], off
	v_lshl_add_u64 v[154:155], s[48:49], 0, v[132:133]
	s_mov_b32 m0, s50
	s_nop 0
	global_load_lds_dwordx4 v[154:155], off
	v_lshl_add_u64 v[154:155], s[48:49], 0, v[128:129]
	s_add_i32 m0, s50, 0x2000
	s_nop 0
	global_load_lds_dwordx4 v[154:155], off
	v_lshl_add_u64 v[154:155], v[228:229], 0, s[20:21]
	s_mov_b32 m0, s62
	s_nop 0
	global_load_lds_dwordx4 v[154:155], off
	v_lshl_add_u64 v[154:155], v[230:231], 0, s[20:21]
	s_mov_b32 m0, s63
	s_nop 0
	global_load_lds_dwordx4 v[154:155], off
	s_waitcnt vmcnt(8)
	s_waitcnt lgkmcnt(0)
	s_barrier
	s_setprio 1
	s_waitcnt lgkmcnt(0)
	v_mfma_f32_16x16x32_bf16 v[60:63], v[160:163], v[194:197], v[60:63]
	v_mfma_f32_16x16x32_bf16 v[52:55], v[168:171], v[194:197], v[52:55]
	v_mfma_f32_16x16x32_bf16 v[44:47], v[160:163], v[202:205], v[44:47]
	v_mfma_f32_16x16x32_bf16 v[36:39], v[168:171], v[202:205], v[36:39]
	v_mfma_f32_16x16x32_bf16 v[28:31], v[160:163], v[210:213], v[28:31]
	v_mfma_f32_16x16x32_bf16 v[20:23], v[168:171], v[210:213], v[20:23]
	v_mfma_f32_16x16x32_bf16 v[12:15], v[160:163], v[218:221], v[12:15]
	v_mfma_f32_16x16x32_bf16 v[4:7], v[168:171], v[218:221], v[4:7]
	v_mfma_f32_16x16x32_bf16 v[60:63], v[164:167], v[198:201], v[60:63]
	v_mfma_f32_16x16x32_bf16 v[52:55], v[172:175], v[198:201], v[52:55]
	v_mfma_f32_16x16x32_bf16 v[44:47], v[164:167], v[206:209], v[44:47]
	v_mfma_f32_16x16x32_bf16 v[36:39], v[172:175], v[206:209], v[36:39]
	v_mfma_f32_16x16x32_bf16 v[28:31], v[164:167], v[214:217], v[28:31]
	v_mfma_f32_16x16x32_bf16 v[20:23], v[172:175], v[214:217], v[20:23]
	v_mfma_f32_16x16x32_bf16 v[12:15], v[164:167], v[222:225], v[12:15]
	v_mfma_f32_16x16x32_bf16 v[4:7], v[172:175], v[222:225], v[4:7]
	s_setprio 0
	s_setprio 1
	v_mfma_f32_16x16x32_bf16 v[56:59], v[176:179], v[194:197], v[56:59]
	v_mfma_f32_16x16x32_bf16 v[48:51], v[186:189], v[194:197], v[48:51]
	v_mfma_f32_16x16x32_bf16 v[40:43], v[176:179], v[202:205], v[40:43]
	v_mfma_f32_16x16x32_bf16 v[32:35], v[186:189], v[202:205], v[32:35]
	v_mfma_f32_16x16x32_bf16 v[24:27], v[176:179], v[210:213], v[24:27]
	v_mfma_f32_16x16x32_bf16 v[16:19], v[186:189], v[210:213], v[16:19]
	v_mfma_f32_16x16x32_bf16 v[8:11], v[176:179], v[218:221], v[8:11]
	v_mfma_f32_16x16x32_bf16 v[0:3], v[186:189], v[218:221], v[0:3]
	v_mfma_f32_16x16x32_bf16 v[56:59], v[180:183], v[198:201], v[56:59]
	v_mfma_f32_16x16x32_bf16 v[48:51], v[190:193], v[198:201], v[48:51]
	v_mfma_f32_16x16x32_bf16 v[40:43], v[180:183], v[206:209], v[40:43]
	v_mfma_f32_16x16x32_bf16 v[32:35], v[190:193], v[206:209], v[32:35]
	v_mfma_f32_16x16x32_bf16 v[24:27], v[180:183], v[214:217], v[24:27]
	v_mfma_f32_16x16x32_bf16 v[16:19], v[190:193], v[214:217], v[16:19]
	v_mfma_f32_16x16x32_bf16 v[8:11], v[180:183], v[222:225], v[8:11]
	v_mfma_f32_16x16x32_bf16 v[0:3], v[190:193], v[222:225], v[0:3]
	s_setprio 0
	s_barrier
	s_add_i32 s75, s75, 2
	s_add_u32 s73, s73, 0x100
	s_addc_u32 s74, s74, 0
	s_add_u32 s46, s46, 0x100
	s_addc_u32 s47, s47, 0
	s_branch .LBB0_527

.LBB0_609:
	s_add_u32 s79, s56, 0x100
	s_addc_u32 s80, s57, 0
	s_mov_b32 s81, -2
	s_waitcnt lgkmcnt(0)
	s_cmp_eq_u32 s70, 1
	s_cbranch_scc1 .Lfa_5
	ds_read_b128 v[128:131], v189
	ds_read_b128 v[132:135], v189 offset:1024
	ds_read_b128 v[136:139], v189 offset:2048
	ds_read_b128 v[140:143], v189 offset:3072
	ds_read_b128 v[144:147], v190
	ds_read_b128 v[148:151], v190 offset:1024
	ds_read_b128 v[172:175], v190 offset:2048
	ds_read_b128 v[176:179], v190 offset:3072
	s_add_u32 s56, s54, 0x100
	s_addc_u32 s57, s55, 0
	s_cmp_eq_u32 s81, 40
	s_cselect_b32 s61, s17, s57
	s_cselect_b32 s60, s16, s56
	s_cselect_b32 s59, s53, s80
	s_cselect_b32 s58, s52, s79
	v_lshl_add_u64 v[222:223], s[54:55], 0, v[166:167]
	s_add_i32 m0, s66, 0xc000
	ds_read_b128 v[180:183], v191
	ds_read_b128 v[194:197], v191 offset:1024
	ds_read_b128 v[198:201], v191 offset:2048
	ds_read_b128 v[202:205], v191 offset:3072
	ds_read_b128 v[206:209], v191 offset:4096
	ds_read_b128 v[210:213], v191 offset:5120
	ds_read_b128 v[214:217], v191 offset:6144
	ds_read_b128 v[218:221], v191 offset:7168
	global_load_lds_dwordx4 v[222:223], off
	v_lshl_add_u64 v[222:223], s[54:55], 0, v[164:165]
	s_add_i32 m0, s66, 0xe000
	s_nop 0
	global_load_lds_dwordx4 v[222:223], off
	s_waitcnt vmcnt(24)
	s_waitcnt lgkmcnt(0)
	s_barrier
	s_setprio 1
	s_waitcnt lgkmcnt(0)
	v_mfma_f32_16x16x32_bf16 v[124:127], v[128:131], v[180:183], 0
	v_mfma_f32_16x16x32_bf16 v[120:123], v[136:139], v[180:183], 0
	v_mfma_f32_16x16x32_bf16 v[108:111], v[128:131], v[198:201], 0
	v_mfma_f32_16x16x32_bf16 v[104:107], v[136:139], v[198:201], 0
	v_mfma_f32_16x16x32_bf16 v[92:95], v[128:131], v[206:209], 0
	v_mfma_f32_16x16x32_bf16 v[88:91], v[136:139], v[206:209], 0
	v_mfma_f32_16x16x32_bf16 v[76:79], v[128:131], v[214:217], 0
	v_mfma_f32_16x16x32_bf16 v[72:75], v[136:139], v[214:217], 0
	v_mfma_f32_16x16x32_bf16 v[124:127], v[132:135], v[194:197], v[124:127]
	v_mfma_f32_16x16x32_bf16 v[120:123], v[140:143], v[194:197], v[120:123]
	v_mfma_f32_16x16x32_bf16 v[108:111], v[132:135], v[202:205], v[108:111]
	v_mfma_f32_16x16x32_bf16 v[104:107], v[140:143], v[202:205], v[104:107]
	v_mfma_f32_16x16x32_bf16 v[92:95], v[132:135], v[210:213], v[92:95]
	v_mfma_f32_16x16x32_bf16 v[88:91], v[140:143], v[210:213], v[88:91]
	v_mfma_f32_16x16x32_bf16 v[76:79], v[132:135], v[218:221], v[76:79]
	v_mfma_f32_16x16x32_bf16 v[72:75], v[140:143], v[218:221], v[72:75]
	s_setprio 0
	s_setprio 1
	v_mfma_f32_16x16x32_bf16 v[116:119], v[144:147], v[180:183], 0
	v_mfma_f32_16x16x32_bf16 v[112:115], v[172:175], v[180:183], 0
	v_mfma_f32_16x16x32_bf16 v[100:103], v[144:147], v[198:201], 0
	v_mfma_f32_16x16x32_bf16 v[96:99], v[172:175], v[198:201], 0
	v_mfma_f32_16x16x32_bf16 v[84:87], v[144:147], v[206:209], 0
	v_mfma_f32_16x16x32_bf16 v[80:83], v[172:175], v[206:209], 0
	v_mfma_f32_16x16x32_bf16 v[68:71], v[144:147], v[214:217], 0
	v_mfma_f32_16x16x32_bf16 v[64:67], v[172:175], v[214:217], 0
	v_mfma_f32_16x16x32_bf16 v[116:119], v[148:151], v[194:197], v[116:119]
	v_mfma_f32_16x16x32_bf16 v[112:115], v[176:179], v[194:197], v[112:115]
	v_mfma_f32_16x16x32_bf16 v[100:103], v[148:151], v[202:205], v[100:103]
	v_mfma_f32_16x16x32_bf16 v[96:99], v[176:179], v[202:205], v[96:99]
	v_mfma_f32_16x16x32_bf16 v[84:87], v[148:151], v[210:213], v[84:87]
	v_mfma_f32_16x16x32_bf16 v[80:83], v[176:179], v[210:213], v[80:83]
	v_mfma_f32_16x16x32_bf16 v[68:71], v[148:151], v[218:221], v[68:71]
	v_mfma_f32_16x16x32_bf16 v[64:67], v[176:179], v[218:221], v[64:67]
	s_setprio 0
	s_barrier
	s_add_i32 s54, s75, s65
	v_lshl_add_u64 v[222:223], s[58:59], 0, v[154:155]
	s_mov_b32 m0, s54
	ds_read_b128 v[180:183], v191 offset:16384
	ds_read_b128 v[194:197], v191 offset:17408
	ds_read_b128 v[198:201], v191 offset:18432
	ds_read_b128 v[202:205], v191 offset:19456
	ds_read_b128 v[206:209], v191 offset:20480
	ds_read_b128 v[210:213], v191 offset:21504
	ds_read_b128 v[214:217], v191 offset:22528
	ds_read_b128 v[218:221], v191 offset:23552
	global_load_lds_dwordx4 v[222:223], off
	s_add_i32 m0, s54, 0x2000
	s_add_u32 s54, s58, 0xb0000
	v_lshl_add_u64 v[224:225], s[58:59], 0, v[162:163]
	s_addc_u32 s55, s59, 0
	s_add_i32 s82, s76, s65
	global_load_lds_dwordx4 v[224:225], off
	v_lshl_add_u64 v[226:227], s[54:55], 0, v[154:155]
	s_mov_b32 m0, s82
	v_lshl_add_u64 v[228:229], s[60:61], 0, v[160:161]
	global_load_lds_dwordx4 v[226:227], off
	v_lshl_add_u64 v[226:227], s[54:55], 0, v[162:163]
	s_add_i32 m0, s82, 0x2000
	s_nop 0
	global_load_lds_dwordx4 v[226:227], off
	v_lshl_add_u64 v[226:227], s[60:61], 0, v[152:153]
	s_mov_b32 m0, s66
	s_nop 0
	global_load_lds_dwordx4 v[226:227], off
	s_mov_b32 m0, s67
	s_nop 0
	global_load_lds_dwordx4 v[228:229], off
	s_waitcnt vmcnt(24)
	s_waitcnt lgkmcnt(0)
	s_barrier
	s_setprio 1
	s_waitcnt lgkmcnt(0)
	v_mfma_f32_16x16x32_bf16 v[60:63], v[128:131], v[180:183], 0
	v_mfma_f32_16x16x32_bf16 v[56:59], v[136:139], v[180:183], 0
	v_mfma_f32_16x16x32_bf16 v[44:47], v[128:131], v[198:201], 0
	v_mfma_f32_16x16x32_bf16 v[40:43], v[136:139], v[198:201], 0
	v_mfma_f32_16x16x32_bf16 v[28:31], v[128:131], v[206:209], 0
	v_mfma_f32_16x16x32_bf16 v[24:27], v[136:139], v[206:209], 0
	v_mfma_f32_16x16x32_bf16 v[12:15], v[128:131], v[214:217], 0
	v_mfma_f32_16x16x32_bf16 v[8:11], v[136:139], v[214:217], 0
	v_mfma_f32_16x16x32_bf16 v[60:63], v[132:135], v[194:197], v[60:63]
	v_mfma_f32_16x16x32_bf16 v[56:59], v[140:143], v[194:197], v[56:59]
	v_mfma_f32_16x16x32_bf16 v[44:47], v[132:135], v[202:205], v[44:47]
	v_mfma_f32_16x16x32_bf16 v[40:43], v[140:143], v[202:205], v[40:43]
	v_mfma_f32_16x16x32_bf16 v[28:31], v[132:135], v[210:213], v[28:31]
	v_mfma_f32_16x16x32_bf16 v[24:27], v[140:143], v[210:213], v[24:27]
	v_mfma_f32_16x16x32_bf16 v[12:15], v[132:135], v[218:221], v[12:15]
	v_mfma_f32_16x16x32_bf16 v[8:11], v[140:143], v[218:221], v[8:11]
	s_setprio 0
	s_setprio 1
	v_mfma_f32_16x16x32_bf16 v[52:55], v[144:147], v[180:183], 0
	v_mfma_f32_16x16x32_bf16 v[48:51], v[172:175], v[180:183], 0
	v_mfma_f32_16x16x32_bf16 v[36:39], v[144:147], v[198:201], 0
	v_mfma_f32_16x16x32_bf16 v[32:35], v[172:175], v[198:201], 0
	v_mfma_f32_16x16x32_bf16 v[20:23], v[144:147], v[206:209], 0
	v_mfma_f32_16x16x32_bf16 v[16:19], v[172:175], v[206:209], 0
	v_mfma_f32_16x16x32_bf16 v[4:7], v[144:147], v[214:217], 0
	v_mfma_f32_16x16x32_bf16 v[0:3], v[172:175], v[214:217], 0
	v_mfma_f32_16x16x32_bf16 v[52:55], v[148:151], v[194:197], v[52:55]
	v_mfma_f32_16x16x32_bf16 v[48:51], v[176:179], v[194:197], v[48:51]
	v_mfma_f32_16x16x32_bf16 v[36:39], v[148:151], v[202:205], v[36:39]
	v_mfma_f32_16x16x32_bf16 v[32:35], v[176:179], v[202:205], v[32:35]
	v_mfma_f32_16x16x32_bf16 v[20:23], v[148:151], v[210:213], v[20:23]
	v_mfma_f32_16x16x32_bf16 v[16:19], v[176:179], v[210:213], v[16:19]
	v_mfma_f32_16x16x32_bf16 v[4:7], v[148:151], v[218:221], v[4:7]
	v_mfma_f32_16x16x32_bf16 v[0:3], v[176:179], v[218:221], v[0:3]
	s_setprio 0
	s_barrier
	s_add_i32 s82, 0, 0x18000
	s_add_i32 s83, 0, 0x1c000
	v_add_u32_e32 v140, s82, v186
	v_add_u32_e32 v176, s83, v186
	ds_read_b128 v[128:131], v140
	ds_read_b128 v[132:135], v140 offset:1024
	ds_read_b128 v[136:139], v140 offset:2048
	ds_read_b128 v[140:143], v140 offset:3072
	ds_read_b128 v[144:147], v176
	ds_read_b128 v[148:151], v176 offset:1024
	ds_read_b128 v[172:175], v176 offset:2048
	ds_read_b128 v[176:179], v176 offset:3072
	s_add_u32 s54, s60, 0xb0000
	s_addc_u32 s55, s61, 0
	s_mov_b32 m0, s68
	v_lshl_add_u64 v[230:231], s[54:55], 0, v[152:153]
	ds_read_b128 v[180:183], v191 offset:32768
	ds_read_b128 v[194:197], v191 offset:33792
	ds_read_b128 v[198:201], v191 offset:34816
	ds_read_b128 v[202:205], v191 offset:35840
	ds_read_b128 v[206:209], v191 offset:36864
	ds_read_b128 v[210:213], v191 offset:37888
	ds_read_b128 v[214:217], v191 offset:38912
	ds_read_b128 v[218:221], v191 offset:39936
	global_load_lds_dwordx4 v[230:231], off
	v_lshl_add_u64 v[230:231], s[54:55], 0, v[160:161]
	s_mov_b32 m0, s69
	s_nop 0
	global_load_lds_dwordx4 v[230:231], off
	s_waitcnt vmcnt(8)
	s_waitcnt lgkmcnt(0)
	s_barrier
	s_setprio 1
	s_waitcnt lgkmcnt(0)
	v_mfma_f32_16x16x32_bf16 v[124:127], v[128:131], v[180:183], v[124:127]
	v_mfma_f32_16x16x32_bf16 v[120:123], v[136:139], v[180:183], v[120:123]
	v_mfma_f32_16x16x32_bf16 v[108:111], v[128:131], v[198:201], v[108:111]
	v_mfma_f32_16x16x32_bf16 v[104:107], v[136:139], v[198:201], v[104:107]
	v_mfma_f32_16x16x32_bf16 v[92:95], v[128:131], v[206:209], v[92:95]
	v_mfma_f32_16x16x32_bf16 v[88:91], v[136:139], v[206:209], v[88:91]
	v_mfma_f32_16x16x32_bf16 v[76:79], v[128:131], v[214:217], v[76:79]
	v_mfma_f32_16x16x32_bf16 v[72:75], v[136:139], v[214:217], v[72:75]
	v_mfma_f32_16x16x32_bf16 v[124:127], v[132:135], v[194:197], v[124:127]
	v_mfma_f32_16x16x32_bf16 v[120:123], v[140:143], v[194:197], v[120:123]
	v_mfma_f32_16x16x32_bf16 v[108:111], v[132:135], v[202:205], v[108:111]
	v_mfma_f32_16x16x32_bf16 v[104:107], v[140:143], v[202:205], v[104:107]
	v_mfma_f32_16x16x32_bf16 v[92:95], v[132:135], v[210:213], v[92:95]
	v_mfma_f32_16x16x32_bf16 v[88:91], v[140:143], v[210:213], v[88:91]
	v_mfma_f32_16x16x32_bf16 v[76:79], v[132:135], v[218:221], v[76:79]
	v_mfma_f32_16x16x32_bf16 v[72:75], v[140:143], v[218:221], v[72:75]
	s_setprio 0
	s_setprio 1
	v_mfma_f32_16x16x32_bf16 v[116:119], v[144:147], v[180:183], v[116:119]
	v_mfma_f32_16x16x32_bf16 v[112:115], v[172:175], v[180:183], v[112:115]
	v_mfma_f32_16x16x32_bf16 v[100:103], v[144:147], v[198:201], v[100:103]
	v_mfma_f32_16x16x32_bf16 v[96:99], v[172:175], v[198:201], v[96:99]
	v_mfma_f32_16x16x32_bf16 v[84:87], v[144:147], v[206:209], v[84:87]
	v_mfma_f32_16x16x32_bf16 v[80:83], v[172:175], v[206:209], v[80:83]
	v_mfma_f32_16x16x32_bf16 v[68:71], v[144:147], v[214:217], v[68:71]
	v_mfma_f32_16x16x32_bf16 v[64:67], v[172:175], v[214:217], v[64:67]
	v_mfma_f32_16x16x32_bf16 v[116:119], v[148:151], v[194:197], v[116:119]
	v_mfma_f32_16x16x32_bf16 v[112:115], v[176:179], v[194:197], v[112:115]
	v_mfma_f32_16x16x32_bf16 v[100:103], v[148:151], v[202:205], v[100:103]
	v_mfma_f32_16x16x32_bf16 v[96:99], v[176:179], v[202:205], v[96:99]
	v_mfma_f32_16x16x32_bf16 v[84:87], v[148:151], v[210:213], v[84:87]
	v_mfma_f32_16x16x32_bf16 v[80:83], v[176:179], v[210:213], v[80:83]
	v_mfma_f32_16x16x32_bf16 v[68:71], v[148:151], v[218:221], v[68:71]
	v_mfma_f32_16x16x32_bf16 v[64:67], v[176:179], v[218:221], v[64:67]
	s_setprio 0
	s_barrier
	s_add_i32 s54, s82, s65
	v_lshl_add_u64 v[222:223], v[222:223], 0, s[28:29]
	s_mov_b32 m0, s54
	ds_read_b128 v[180:183], v191 offset:49152
	ds_read_b128 v[194:197], v191 offset:50176
	ds_read_b128 v[198:201], v191 offset:51200
	ds_read_b128 v[202:205], v191 offset:52224
	ds_read_b128 v[206:209], v191 offset:53248
	ds_read_b128 v[210:213], v191 offset:54272
	ds_read_b128 v[214:217], v191 offset:55296
	ds_read_b128 v[218:221], v191 offset:56320
	global_load_lds_dwordx4 v[222:223], off
	s_add_i32 m0, s54, 0x2000
	s_add_u32 s54, s58, 0xb0080
	v_lshl_add_u64 v[222:223], v[224:225], 0, s[28:29]
	s_addc_u32 s55, s59, 0
	s_add_i32 s58, s83, s65
	global_load_lds_dwordx4 v[222:223], off
	v_lshl_add_u64 v[222:223], s[54:55], 0, v[154:155]
	s_mov_b32 m0, s58
	s_nop 0
	global_load_lds_dwordx4 v[222:223], off
	v_lshl_add_u64 v[222:223], s[54:55], 0, v[162:163]
	s_add_i32 m0, s58, 0x2000
	s_nop 0
	global_load_lds_dwordx4 v[222:223], off
	v_lshl_add_u64 v[222:223], v[226:227], 0, s[28:29]
	s_mov_b32 m0, s3
	s_nop 0
	global_load_lds_dwordx4 v[222:223], off
	v_lshl_add_u64 v[222:223], v[228:229], 0, s[28:29]
	s_mov_b32 m0, s71
	s_nop 0
	global_load_lds_dwordx4 v[222:223], off
	s_waitcnt vmcnt(8)
	s_waitcnt lgkmcnt(0)
	s_barrier
	s_setprio 1
	s_waitcnt lgkmcnt(0)
	v_mfma_f32_16x16x32_bf16 v[60:63], v[128:131], v[180:183], v[60:63]
	v_mfma_f32_16x16x32_bf16 v[56:59], v[136:139], v[180:183], v[56:59]
	v_mfma_f32_16x16x32_bf16 v[44:47], v[128:131], v[198:201], v[44:47]
	v_mfma_f32_16x16x32_bf16 v[40:43], v[136:139], v[198:201], v[40:43]
	v_mfma_f32_16x16x32_bf16 v[28:31], v[128:131], v[206:209], v[28:31]
	v_mfma_f32_16x16x32_bf16 v[24:27], v[136:139], v[206:209], v[24:27]
	v_mfma_f32_16x16x32_bf16 v[12:15], v[128:131], v[214:217], v[12:15]
	v_mfma_f32_16x16x32_bf16 v[8:11], v[136:139], v[214:217], v[8:11]
	v_mfma_f32_16x16x32_bf16 v[60:63], v[132:135], v[194:197], v[60:63]
	v_mfma_f32_16x16x32_bf16 v[56:59], v[140:143], v[194:197], v[56:59]
	v_mfma_f32_16x16x32_bf16 v[44:47], v[132:135], v[202:205], v[44:47]
	v_mfma_f32_16x16x32_bf16 v[40:43], v[140:143], v[202:205], v[40:43]
	v_mfma_f32_16x16x32_bf16 v[28:31], v[132:135], v[210:213], v[28:31]
	v_mfma_f32_16x16x32_bf16 v[24:27], v[140:143], v[210:213], v[24:27]
	v_mfma_f32_16x16x32_bf16 v[12:15], v[132:135], v[218:221], v[12:15]
	v_mfma_f32_16x16x32_bf16 v[8:11], v[140:143], v[218:221], v[8:11]
	s_setprio 0
	s_setprio 1
	v_mfma_f32_16x16x32_bf16 v[52:55], v[144:147], v[180:183], v[52:55]
	v_mfma_f32_16x16x32_bf16 v[48:51], v[172:175], v[180:183], v[48:51]
	v_mfma_f32_16x16x32_bf16 v[36:39], v[144:147], v[198:201], v[36:39]
	v_mfma_f32_16x16x32_bf16 v[32:35], v[172:175], v[198:201], v[32:35]
	v_mfma_f32_16x16x32_bf16 v[20:23], v[144:147], v[206:209], v[20:23]
	v_mfma_f32_16x16x32_bf16 v[16:19], v[172:175], v[206:209], v[16:19]
	v_mfma_f32_16x16x32_bf16 v[4:7], v[144:147], v[214:217], v[4:7]
	v_mfma_f32_16x16x32_bf16 v[0:3], v[172:175], v[214:217], v[0:3]
	v_mfma_f32_16x16x32_bf16 v[52:55], v[148:151], v[194:197], v[52:55]
	v_mfma_f32_16x16x32_bf16 v[48:51], v[176:179], v[194:197], v[48:51]
	v_mfma_f32_16x16x32_bf16 v[36:39], v[148:151], v[202:205], v[36:39]
	v_mfma_f32_16x16x32_bf16 v[32:35], v[176:179], v[202:205], v[32:35]
	v_mfma_f32_16x16x32_bf16 v[20:23], v[148:151], v[210:213], v[20:23]
	v_mfma_f32_16x16x32_bf16 v[16:19], v[176:179], v[210:213], v[16:19]
	v_mfma_f32_16x16x32_bf16 v[4:7], v[148:151], v[218:221], v[4:7]
	v_mfma_f32_16x16x32_bf16 v[0:3], v[176:179], v[218:221], v[0:3]
	s_setprio 0
	s_barrier
	s_add_i32 s81, s81, 2
	s_add_u32 s79, s79, 0x100
	s_addc_u32 s80, s80, 0
	s_cmp_gt_u32 s81, 41
	s_mov_b64 s[54:55], s[56:57]
	s_branch .LBB0_610
.Lfa_5:
	ds_read_b128 v[128:131], v189
	ds_read_b128 v[132:135], v189 offset:1024
	ds_read_b128 v[136:139], v189 offset:2048
	ds_read_b128 v[140:143], v189 offset:3072
	ds_read_b128 v[144:147], v190
	ds_read_b128 v[148:151], v190 offset:1024
	ds_read_b128 v[172:175], v190 offset:2048
	ds_read_b128 v[176:179], v190 offset:3072
	s_add_u32 s56, s54, 0x100
	s_addc_u32 s57, s55, 0
	s_cmp_eq_u32 s81, 40
	s_cselect_b32 s61, s17, s57
	s_cselect_b32 s60, s16, s56
	s_cselect_b32 s59, s53, s80
	s_cselect_b32 s58, s52, s79
	v_lshl_add_u64 v[222:223], s[54:55], 0, v[166:167]
	s_add_i32 m0, s66, 0xc000
	ds_read_b128 v[180:183], v191
	ds_read_b128 v[194:197], v191 offset:1024
	ds_read_b128 v[198:201], v191 offset:2048
	ds_read_b128 v[202:205], v191 offset:3072
	ds_read_b128 v[206:209], v191 offset:4096
	ds_read_b128 v[210:213], v191 offset:5120
	ds_read_b128 v[214:217], v191 offset:6144
	ds_read_b128 v[218:221], v191 offset:7168
	global_load_lds_dwordx4 v[222:223], off
	v_lshl_add_u64 v[222:223], s[54:55], 0, v[164:165]
	s_add_i32 m0, s66, 0xe000
	s_nop 0
	global_load_lds_dwordx4 v[222:223], off
	s_waitcnt vmcnt(8)
	s_waitcnt lgkmcnt(0)
	s_barrier
	s_setprio 1
	s_waitcnt lgkmcnt(0)
	v_mfma_f32_16x16x32_bf16 v[124:127], v[128:131], v[180:183], 0
	v_mfma_f32_16x16x32_bf16 v[120:123], v[136:139], v[180:183], 0
	v_mfma_f32_16x16x32_bf16 v[108:111], v[128:131], v[198:201], 0
	v_mfma_f32_16x16x32_bf16 v[104:107], v[136:139], v[198:201], 0
	v_mfma_f32_16x16x32_bf16 v[92:95], v[128:131], v[206:209], 0
	v_mfma_f32_16x16x32_bf16 v[88:91], v[136:139], v[206:209], 0
	v_mfma_f32_16x16x32_bf16 v[76:79], v[128:131], v[214:217], 0
	v_mfma_f32_16x16x32_bf16 v[72:75], v[136:139], v[214:217], 0
	v_mfma_f32_16x16x32_bf16 v[124:127], v[132:135], v[194:197], v[124:127]
	v_mfma_f32_16x16x32_bf16 v[120:123], v[140:143], v[194:197], v[120:123]
	v_mfma_f32_16x16x32_bf16 v[108:111], v[132:135], v[202:205], v[108:111]
	v_mfma_f32_16x16x32_bf16 v[104:107], v[140:143], v[202:205], v[104:107]
	v_mfma_f32_16x16x32_bf16 v[92:95], v[132:135], v[210:213], v[92:95]
	v_mfma_f32_16x16x32_bf16 v[88:91], v[140:143], v[210:213], v[88:91]
	v_mfma_f32_16x16x32_bf16 v[76:79], v[132:135], v[218:221], v[76:79]
	v_mfma_f32_16x16x32_bf16 v[72:75], v[140:143], v[218:221], v[72:75]
	s_setprio 0
	s_setprio 1
	v_mfma_f32_16x16x32_bf16 v[116:119], v[144:147], v[180:183], 0
	v_mfma_f32_16x16x32_bf16 v[112:115], v[172:175], v[180:183], 0
	v_mfma_f32_16x16x32_bf16 v[100:103], v[144:147], v[198:201], 0
	v_mfma_f32_16x16x32_bf16 v[96:99], v[172:175], v[198:201], 0
	v_mfma_f32_16x16x32_bf16 v[84:87], v[144:147], v[206:209], 0
	v_mfma_f32_16x16x32_bf16 v[80:83], v[172:175], v[206:209], 0
	v_mfma_f32_16x16x32_bf16 v[68:71], v[144:147], v[214:217], 0
	v_mfma_f32_16x16x32_bf16 v[64:67], v[172:175], v[214:217], 0
	v_mfma_f32_16x16x32_bf16 v[116:119], v[148:151], v[194:197], v[116:119]
	v_mfma_f32_16x16x32_bf16 v[112:115], v[176:179], v[194:197], v[112:115]
	v_mfma_f32_16x16x32_bf16 v[100:103], v[148:151], v[202:205], v[100:103]
	v_mfma_f32_16x16x32_bf16 v[96:99], v[176:179], v[202:205], v[96:99]
	v_mfma_f32_16x16x32_bf16 v[84:87], v[148:151], v[210:213], v[84:87]
	v_mfma_f32_16x16x32_bf16 v[80:83], v[176:179], v[210:213], v[80:83]
	v_mfma_f32_16x16x32_bf16 v[68:71], v[148:151], v[218:221], v[68:71]
	v_mfma_f32_16x16x32_bf16 v[64:67], v[176:179], v[218:221], v[64:67]
	s_setprio 0
	s_barrier
	s_add_i32 s54, s75, s65
	v_lshl_add_u64 v[222:223], s[58:59], 0, v[154:155]
	s_mov_b32 m0, s54
	ds_read_b128 v[180:183], v191 offset:16384
	ds_read_b128 v[194:197], v191 offset:17408
	ds_read_b128 v[198:201], v191 offset:18432
	ds_read_b128 v[202:205], v191 offset:19456
	ds_read_b128 v[206:209], v191 offset:20480
	ds_read_b128 v[210:213], v191 offset:21504
	ds_read_b128 v[214:217], v191 offset:22528
	ds_read_b128 v[218:221], v191 offset:23552
	global_load_lds_dwordx4 v[222:223], off
	s_add_i32 m0, s54, 0x2000
	s_add_u32 s54, s58, 0xb0000
	v_lshl_add_u64 v[224:225], s[58:59], 0, v[162:163]
	s_addc_u32 s55, s59, 0
	s_add_i32 s82, s76, s65
	global_load_lds_dwordx4 v[224:225], off
	v_lshl_add_u64 v[226:227], s[54:55], 0, v[154:155]
	s_mov_b32 m0, s82
	v_lshl_add_u64 v[228:229], s[60:61], 0, v[160:161]
	global_load_lds_dwordx4 v[226:227], off
	v_lshl_add_u64 v[226:227], s[54:55], 0, v[162:163]
	s_add_i32 m0, s82, 0x2000
	s_nop 0
	global_load_lds_dwordx4 v[226:227], off
	v_lshl_add_u64 v[226:227], s[60:61], 0, v[152:153]
	s_mov_b32 m0, s66
	s_nop 0
	global_load_lds_dwordx4 v[226:227], off
	s_mov_b32 m0, s67
	s_nop 0
	global_load_lds_dwordx4 v[228:229], off
	s_waitcnt vmcnt(8)
	s_waitcnt lgkmcnt(0)
	s_barrier
	s_setprio 1
	s_waitcnt lgkmcnt(0)
	v_mfma_f32_16x16x32_bf16 v[60:63], v[128:131], v[180:183], 0
	v_mfma_f32_16x16x32_bf16 v[56:59], v[136:139], v[180:183], 0
	v_mfma_f32_16x16x32_bf16 v[44:47], v[128:131], v[198:201], 0
	v_mfma_f32_16x16x32_bf16 v[40:43], v[136:139], v[198:201], 0
	v_mfma_f32_16x16x32_bf16 v[28:31], v[128:131], v[206:209], 0
	v_mfma_f32_16x16x32_bf16 v[24:27], v[136:139], v[206:209], 0
	v_mfma_f32_16x16x32_bf16 v[12:15], v[128:131], v[214:217], 0
	v_mfma_f32_16x16x32_bf16 v[8:11], v[136:139], v[214:217], 0
	v_mfma_f32_16x16x32_bf16 v[60:63], v[132:135], v[194:197], v[60:63]
	v_mfma_f32_16x16x32_bf16 v[56:59], v[140:143], v[194:197], v[56:59]
	v_mfma_f32_16x16x32_bf16 v[44:47], v[132:135], v[202:205], v[44:47]
	v_mfma_f32_16x16x32_bf16 v[40:43], v[140:143], v[202:205], v[40:43]
	v_mfma_f32_16x16x32_bf16 v[28:31], v[132:135], v[210:213], v[28:31]
	v_mfma_f32_16x16x32_bf16 v[24:27], v[140:143], v[210:213], v[24:27]
	v_mfma_f32_16x16x32_bf16 v[12:15], v[132:135], v[218:221], v[12:15]
	v_mfma_f32_16x16x32_bf16 v[8:11], v[140:143], v[218:221], v[8:11]
	s_setprio 0
	s_setprio 1
	v_mfma_f32_16x16x32_bf16 v[52:55], v[144:147], v[180:183], 0
	v_mfma_f32_16x16x32_bf16 v[48:51], v[172:175], v[180:183], 0
	v_mfma_f32_16x16x32_bf16 v[36:39], v[144:147], v[198:201], 0
	v_mfma_f32_16x16x32_bf16 v[32:35], v[172:175], v[198:201], 0
	v_mfma_f32_16x16x32_bf16 v[20:23], v[144:147], v[206:209], 0
	v_mfma_f32_16x16x32_bf16 v[16:19], v[172:175], v[206:209], 0
	v_mfma_f32_16x16x32_bf16 v[4:7], v[144:147], v[214:217], 0
	v_mfma_f32_16x16x32_bf16 v[0:3], v[172:175], v[214:217], 0
	v_mfma_f32_16x16x32_bf16 v[52:55], v[148:151], v[194:197], v[52:55]
	v_mfma_f32_16x16x32_bf16 v[48:51], v[176:179], v[194:197], v[48:51]
	v_mfma_f32_16x16x32_bf16 v[36:39], v[148:151], v[202:205], v[36:39]
	v_mfma_f32_16x16x32_bf16 v[32:35], v[176:179], v[202:205], v[32:35]
	v_mfma_f32_16x16x32_bf16 v[20:23], v[148:151], v[210:213], v[20:23]
	v_mfma_f32_16x16x32_bf16 v[16:19], v[176:179], v[210:213], v[16:19]
	v_mfma_f32_16x16x32_bf16 v[4:7], v[148:151], v[218:221], v[4:7]
	v_mfma_f32_16x16x32_bf16 v[0:3], v[176:179], v[218:221], v[0:3]
	s_setprio 0
	s_barrier
	s_add_i32 s82, 0, 0x18000
	s_add_i32 s83, 0, 0x1c000
	v_add_u32_e32 v140, s82, v186
	v_add_u32_e32 v176, s83, v186
	ds_read_b128 v[128:131], v140
	ds_read_b128 v[132:135], v140 offset:1024
	ds_read_b128 v[136:139], v140 offset:2048
	ds_read_b128 v[140:143], v140 offset:3072
	ds_read_b128 v[144:147], v176
	ds_read_b128 v[148:151], v176 offset:1024
	ds_read_b128 v[172:175], v176 offset:2048
	ds_read_b128 v[176:179], v176 offset:3072
	s_add_u32 s54, s60, 0xb0000
	s_addc_u32 s55, s61, 0
	s_mov_b32 m0, s68
	v_lshl_add_u64 v[230:231], s[54:55], 0, v[152:153]
	ds_read_b128 v[180:183], v191 offset:32768
	ds_read_b128 v[194:197], v191 offset:33792
	ds_read_b128 v[198:201], v191 offset:34816
	ds_read_b128 v[202:205], v191 offset:35840
	ds_read_b128 v[206:209], v191 offset:36864
	ds_read_b128 v[210:213], v191 offset:37888
	ds_read_b128 v[214:217], v191 offset:38912
	ds_read_b128 v[218:221], v191 offset:39936
	global_load_lds_dwordx4 v[230:231], off
	v_lshl_add_u64 v[230:231], s[54:55], 0, v[160:161]
	s_mov_b32 m0, s69
	s_nop 0
	global_load_lds_dwordx4 v[230:231], off
	s_waitcnt vmcnt(8)
	s_waitcnt lgkmcnt(0)
	s_barrier
	s_setprio 1
	s_waitcnt lgkmcnt(0)
	v_mfma_f32_16x16x32_bf16 v[124:127], v[128:131], v[180:183], v[124:127]
	v_mfma_f32_16x16x32_bf16 v[120:123], v[136:139], v[180:183], v[120:123]
	v_mfma_f32_16x16x32_bf16 v[108:111], v[128:131], v[198:201], v[108:111]
	v_mfma_f32_16x16x32_bf16 v[104:107], v[136:139], v[198:201], v[104:107]
	v_mfma_f32_16x16x32_bf16 v[92:95], v[128:131], v[206:209], v[92:95]
	v_mfma_f32_16x16x32_bf16 v[88:91], v[136:139], v[206:209], v[88:91]
	v_mfma_f32_16x16x32_bf16 v[76:79], v[128:131], v[214:217], v[76:79]
	v_mfma_f32_16x16x32_bf16 v[72:75], v[136:139], v[214:217], v[72:75]
	v_mfma_f32_16x16x32_bf16 v[124:127], v[132:135], v[194:197], v[124:127]
	v_mfma_f32_16x16x32_bf16 v[120:123], v[140:143], v[194:197], v[120:123]
	v_mfma_f32_16x16x32_bf16 v[108:111], v[132:135], v[202:205], v[108:111]
	v_mfma_f32_16x16x32_bf16 v[104:107], v[140:143], v[202:205], v[104:107]
	v_mfma_f32_16x16x32_bf16 v[92:95], v[132:135], v[210:213], v[92:95]
	v_mfma_f32_16x16x32_bf16 v[88:91], v[140:143], v[210:213], v[88:91]
	v_mfma_f32_16x16x32_bf16 v[76:79], v[132:135], v[218:221], v[76:79]
	v_mfma_f32_16x16x32_bf16 v[72:75], v[140:143], v[218:221], v[72:75]
	s_setprio 0
	s_setprio 1
	v_mfma_f32_16x16x32_bf16 v[116:119], v[144:147], v[180:183], v[116:119]
	v_mfma_f32_16x16x32_bf16 v[112:115], v[172:175], v[180:183], v[112:115]
	v_mfma_f32_16x16x32_bf16 v[100:103], v[144:147], v[198:201], v[100:103]
	v_mfma_f32_16x16x32_bf16 v[96:99], v[172:175], v[198:201], v[96:99]
	v_mfma_f32_16x16x32_bf16 v[84:87], v[144:147], v[206:209], v[84:87]
	v_mfma_f32_16x16x32_bf16 v[80:83], v[172:175], v[206:209], v[80:83]
	v_mfma_f32_16x16x32_bf16 v[68:71], v[144:147], v[214:217], v[68:71]
	v_mfma_f32_16x16x32_bf16 v[64:67], v[172:175], v[214:217], v[64:67]
	v_mfma_f32_16x16x32_bf16 v[116:119], v[148:151], v[194:197], v[116:119]
	v_mfma_f32_16x16x32_bf16 v[112:115], v[176:179], v[194:197], v[112:115]
	v_mfma_f32_16x16x32_bf16 v[100:103], v[148:151], v[202:205], v[100:103]
	v_mfma_f32_16x16x32_bf16 v[96:99], v[176:179], v[202:205], v[96:99]
	v_mfma_f32_16x16x32_bf16 v[84:87], v[148:151], v[210:213], v[84:87]
	v_mfma_f32_16x16x32_bf16 v[80:83], v[176:179], v[210:213], v[80:83]
	v_mfma_f32_16x16x32_bf16 v[68:71], v[148:151], v[218:221], v[68:71]
	v_mfma_f32_16x16x32_bf16 v[64:67], v[176:179], v[218:221], v[64:67]
	s_setprio 0
	s_barrier
	s_add_i32 s54, s82, s65
	v_lshl_add_u64 v[222:223], v[222:223], 0, s[28:29]
	s_mov_b32 m0, s54
	ds_read_b128 v[180:183], v191 offset:49152
	ds_read_b128 v[194:197], v191 offset:50176
	ds_read_b128 v[198:201], v191 offset:51200
	ds_read_b128 v[202:205], v191 offset:52224
	ds_read_b128 v[206:209], v191 offset:53248
	ds_read_b128 v[210:213], v191 offset:54272
	ds_read_b128 v[214:217], v191 offset:55296
	ds_read_b128 v[218:221], v191 offset:56320
	global_load_lds_dwordx4 v[222:223], off
	s_add_i32 m0, s54, 0x2000
	s_add_u32 s54, s58, 0xb0080
	v_lshl_add_u64 v[222:223], v[224:225], 0, s[28:29]
	s_addc_u32 s55, s59, 0
	s_add_i32 s58, s83, s65
	global_load_lds_dwordx4 v[222:223], off
	v_lshl_add_u64 v[222:223], s[54:55], 0, v[154:155]
	s_mov_b32 m0, s58
	s_nop 0
	global_load_lds_dwordx4 v[222:223], off
	v_lshl_add_u64 v[222:223], s[54:55], 0, v[162:163]
	s_add_i32 m0, s58, 0x2000
	s_nop 0
	global_load_lds_dwordx4 v[222:223], off
	v_lshl_add_u64 v[222:223], v[226:227], 0, s[28:29]
	s_mov_b32 m0, s3
	s_nop 0
	global_load_lds_dwordx4 v[222:223], off
	v_lshl_add_u64 v[222:223], v[228:229], 0, s[28:29]
	s_mov_b32 m0, s71
	s_nop 0
	global_load_lds_dwordx4 v[222:223], off
	s_waitcnt vmcnt(8)
	s_waitcnt lgkmcnt(0)
	s_barrier
	s_setprio 1
	s_waitcnt lgkmcnt(0)
	v_mfma_f32_16x16x32_bf16 v[60:63], v[128:131], v[180:183], v[60:63]
	v_mfma_f32_16x16x32_bf16 v[56:59], v[136:139], v[180:183], v[56:59]
	v_mfma_f32_16x16x32_bf16 v[44:47], v[128:131], v[198:201], v[44:47]
	v_mfma_f32_16x16x32_bf16 v[40:43], v[136:139], v[198:201], v[40:43]
	v_mfma_f32_16x16x32_bf16 v[28:31], v[128:131], v[206:209], v[28:31]
	v_mfma_f32_16x16x32_bf16 v[24:27], v[136:139], v[206:209], v[24:27]
	v_mfma_f32_16x16x32_bf16 v[12:15], v[128:131], v[214:217], v[12:15]
	v_mfma_f32_16x16x32_bf16 v[8:11], v[136:139], v[214:217], v[8:11]
	v_mfma_f32_16x16x32_bf16 v[60:63], v[132:135], v[194:197], v[60:63]
	v_mfma_f32_16x16x32_bf16 v[56:59], v[140:143], v[194:197], v[56:59]
	v_mfma_f32_16x16x32_bf16 v[44:47], v[132:135], v[202:205], v[44:47]
	v_mfma_f32_16x16x32_bf16 v[40:43], v[140:143], v[202:205], v[40:43]
	v_mfma_f32_16x16x32_bf16 v[28:31], v[132:135], v[210:213], v[28:31]
	v_mfma_f32_16x16x32_bf16 v[24:27], v[140:143], v[210:213], v[24:27]
	v_mfma_f32_16x16x32_bf16 v[12:15], v[132:135], v[218:221], v[12:15]
	v_mfma_f32_16x16x32_bf16 v[8:11], v[140:143], v[218:221], v[8:11]
	s_setprio 0
	s_setprio 1
	v_mfma_f32_16x16x32_bf16 v[52:55], v[144:147], v[180:183], v[52:55]
	v_mfma_f32_16x16x32_bf16 v[48:51], v[172:175], v[180:183], v[48:51]
	v_mfma_f32_16x16x32_bf16 v[36:39], v[144:147], v[198:201], v[36:39]
	v_mfma_f32_16x16x32_bf16 v[32:35], v[172:175], v[198:201], v[32:35]
	v_mfma_f32_16x16x32_bf16 v[20:23], v[144:147], v[206:209], v[20:23]
	v_mfma_f32_16x16x32_bf16 v[16:19], v[172:175], v[206:209], v[16:19]
	v_mfma_f32_16x16x32_bf16 v[4:7], v[144:147], v[214:217], v[4:7]
	v_mfma_f32_16x16x32_bf16 v[0:3], v[172:175], v[214:217], v[0:3]
	v_mfma_f32_16x16x32_bf16 v[52:55], v[148:151], v[194:197], v[52:55]
	v_mfma_f32_16x16x32_bf16 v[48:51], v[176:179], v[194:197], v[48:51]
	v_mfma_f32_16x16x32_bf16 v[36:39], v[148:151], v[202:205], v[36:39]
	v_mfma_f32_16x16x32_bf16 v[32:35], v[176:179], v[202:205], v[32:35]
	v_mfma_f32_16x16x32_bf16 v[20:23], v[148:151], v[210:213], v[20:23]
	v_mfma_f32_16x16x32_bf16 v[16:19], v[176:179], v[210:213], v[16:19]
	v_mfma_f32_16x16x32_bf16 v[4:7], v[148:151], v[218:221], v[4:7]
	v_mfma_f32_16x16x32_bf16 v[0:3], v[176:179], v[218:221], v[0:3]
	s_setprio 0
	s_barrier
	s_add_i32 s81, s81, 2
	s_add_u32 s79, s79, 0x100
	s_addc_u32 s80, s80, 0
	s_cmp_gt_u32 s81, 41
	s_mov_b64 s[54:55], s[56:57]

.LBB0_873:
	s_ashr_i32 s49, s48, 31
	s_lshl_b64 s[50:51], s[48:49], 19
	s_add_u32 s50, s35, s50
	s_addc_u32 s51, s60, s51
	s_and_b64 s[52:53], s[10:11], exec
	s_cselect_b32 s49, s51, s59
	s_cselect_b32 s80, s50, s58
	s_ashr_i32 s47, s46, 31
	s_lshl_b64 s[52:53], s[46:47], 19
	s_add_u32 s52, s61, s52
	s_addc_u32 s53, s62, s53
	s_and_b64 s[82:83], s[10:11], exec
	s_cselect_b32 s81, s53, s57
	s_cselect_b32 s82, s52, s56
	s_lshl_b32 s47, s54, 8
	v_add_u32_e32 v0, s47, v151
	s_add_u32 s83, s56, 0x100
	v_ashrrev_i32_e32 v1, 31, v0
	s_addc_u32 s84, s57, 0
	v_lshl_add_u64 v[144:145], v[0:1], 4, s[20:21]
	s_add_u32 s54, s58, 0x40080
	s_addc_u32 s55, s59, 0
	s_mov_b32 s85, -2
	s_mov_b64 s[56:57], 0
	s_cmp_eq_u32 s68, 1
	s_cbranch_scc1 .Lfa_8
	v_add_u32_e32 v146, s73, v149
	ds_read_b128 v[162:165], v146
	ds_read_b128 v[166:169], v146 offset:1024
	ds_read_b128 v[170:173], v146 offset:2048
	ds_read_b128 v[174:177], v146 offset:3072
	v_add_u32_e32 v146, s74, v149
	ds_read_b128 v[178:181], v146
	ds_read_b128 v[186:189], v146 offset:1024
	ds_read_b128 v[190:193], v146 offset:2048
	ds_read_b128 v[194:197], v146 offset:3072
	s_add_u32 s58, s54, 0xfffc0080
	s_addc_u32 s59, s55, -1
	s_and_b64 s[56:57], s[56:57], exec
	s_cselect_b32 s59, s49, s59
	s_cselect_b32 s58, s80, s58
	s_cselect_b32 s57, s81, s84
	s_cselect_b32 s56, s82, s83
	v_lshl_add_u64 v[182:183], s[54:55], 0, v[138:139]
	s_add_i32 m0, s64, 0xc000
	ds_read_b128 v[198:201], v154
	ds_read_b128 v[202:205], v154 offset:1024
	ds_read_b128 v[206:209], v154 offset:2048
	ds_read_b128 v[210:213], v154 offset:3072
	ds_read_b128 v[214:217], v154 offset:4096
	ds_read_b128 v[218:221], v154 offset:5120
	ds_read_b128 v[222:225], v154 offset:6144
	ds_read_b128 v[226:229], v154 offset:7168
	global_load_lds_dwordx4 v[182:183], off
	v_lshl_add_u64 v[182:183], s[54:55], 0, v[136:137]
	s_add_i32 m0, s64, 0xe000
	s_nop 0
	global_load_lds_dwordx4 v[182:183], off
	s_waitcnt vmcnt(24)
	s_waitcnt lgkmcnt(0)
	s_barrier
	s_setprio 1
	s_waitcnt lgkmcnt(0)
	v_mfma_f32_16x16x32_bf16 v[124:127], v[162:165], v[198:201], 0
	v_mfma_f32_16x16x32_bf16 v[120:123], v[170:173], v[198:201], 0
	v_mfma_f32_16x16x32_bf16 v[112:115], v[162:165], v[206:209], 0
	v_mfma_f32_16x16x32_bf16 v[104:107], v[170:173], v[206:209], 0
	v_mfma_f32_16x16x32_bf16 v[96:99], v[162:165], v[214:217], 0
	v_mfma_f32_16x16x32_bf16 v[88:91], v[170:173], v[214:217], 0
	v_mfma_f32_16x16x32_bf16 v[80:83], v[162:165], v[222:225], 0
	v_mfma_f32_16x16x32_bf16 v[72:75], v[170:173], v[222:225], 0
	v_mfma_f32_16x16x32_bf16 v[124:127], v[166:169], v[202:205], v[124:127]
	v_mfma_f32_16x16x32_bf16 v[120:123], v[174:177], v[202:205], v[120:123]
	v_mfma_f32_16x16x32_bf16 v[112:115], v[166:169], v[210:213], v[112:115]
	v_mfma_f32_16x16x32_bf16 v[104:107], v[174:177], v[210:213], v[104:107]
	v_mfma_f32_16x16x32_bf16 v[96:99], v[166:169], v[218:221], v[96:99]
	v_mfma_f32_16x16x32_bf16 v[88:91], v[174:177], v[218:221], v[88:91]
	v_mfma_f32_16x16x32_bf16 v[80:83], v[166:169], v[226:229], v[80:83]
	v_mfma_f32_16x16x32_bf16 v[72:75], v[174:177], v[226:229], v[72:75]
	s_setprio 0
	s_setprio 1
	v_mfma_f32_16x16x32_bf16 v[116:119], v[178:181], v[198:201], 0
	v_mfma_f32_16x16x32_bf16 v[108:111], v[190:193], v[198:201], 0
	v_mfma_f32_16x16x32_bf16 v[100:103], v[178:181], v[206:209], 0
	v_mfma_f32_16x16x32_bf16 v[92:95], v[190:193], v[206:209], 0
	v_mfma_f32_16x16x32_bf16 v[84:87], v[178:181], v[214:217], 0
	v_mfma_f32_16x16x32_bf16 v[76:79], v[190:193], v[214:217], 0
	v_mfma_f32_16x16x32_bf16 v[68:71], v[178:181], v[222:225], 0
	v_mfma_f32_16x16x32_bf16 v[64:67], v[190:193], v[222:225], 0
	v_mfma_f32_16x16x32_bf16 v[116:119], v[186:189], v[202:205], v[116:119]
	v_mfma_f32_16x16x32_bf16 v[108:111], v[194:197], v[202:205], v[108:111]
	v_mfma_f32_16x16x32_bf16 v[100:103], v[186:189], v[210:213], v[100:103]
	v_mfma_f32_16x16x32_bf16 v[92:95], v[194:197], v[210:213], v[92:95]
	v_mfma_f32_16x16x32_bf16 v[84:87], v[186:189], v[218:221], v[84:87]
	v_mfma_f32_16x16x32_bf16 v[76:79], v[194:197], v[218:221], v[76:79]
	v_mfma_f32_16x16x32_bf16 v[68:71], v[186:189], v[226:229], v[68:71]
	v_mfma_f32_16x16x32_bf16 v[64:67], v[194:197], v[226:229], v[64:67]
	s_setprio 0
	s_barrier
	s_add_i32 s86, s73, s63
	v_lshl_add_u64 v[182:183], s[56:57], 0, v[130:131]
	s_mov_b32 m0, s86
	ds_read_b128 v[198:201], v154 offset:16384
	ds_read_b128 v[202:205], v154 offset:17408
	ds_read_b128 v[206:209], v154 offset:18432
	ds_read_b128 v[210:213], v154 offset:19456
	ds_read_b128 v[214:217], v154 offset:20480
	ds_read_b128 v[218:221], v154 offset:21504
	ds_read_b128 v[222:225], v154 offset:22528
	ds_read_b128 v[226:229], v154 offset:23552
	global_load_lds_dwordx4 v[182:183], off
	s_add_i32 m0, s86, 0x2000
	s_add_u32 s86, s56, 0x40000
	v_lshl_add_u64 v[230:231], s[56:57], 0, v[134:135]
	s_addc_u32 s87, s57, 0
	s_add_i32 s88, s74, s63
	global_load_lds_dwordx4 v[230:231], off
	v_lshl_add_u64 v[232:233], s[86:87], 0, v[130:131]
	s_mov_b32 m0, s88
	v_lshl_add_u64 v[234:235], s[58:59], 0, v[132:133]
	global_load_lds_dwordx4 v[232:233], off
	v_lshl_add_u64 v[232:233], s[86:87], 0, v[134:135]
	s_add_i32 m0, s88, 0x2000
	s_nop 0
	global_load_lds_dwordx4 v[232:233], off
	v_lshl_add_u64 v[232:233], s[58:59], 0, v[128:129]
	s_mov_b32 m0, s64
	s_nop 0
	global_load_lds_dwordx4 v[232:233], off
	s_mov_b32 m0, s65
	s_nop 0
	global_load_lds_dwordx4 v[234:235], off
	s_waitcnt vmcnt(24)
	s_waitcnt lgkmcnt(0)
	s_barrier
	s_setprio 1
	s_waitcnt lgkmcnt(0)
	v_mfma_f32_16x16x32_bf16 v[60:63], v[162:165], v[198:201], 0
	v_mfma_f32_16x16x32_bf16 v[56:59], v[170:173], v[198:201], 0
	v_mfma_f32_16x16x32_bf16 v[48:51], v[162:165], v[206:209], 0
	v_mfma_f32_16x16x32_bf16 v[40:43], v[170:173], v[206:209], 0
	v_mfma_f32_16x16x32_bf16 v[32:35], v[162:165], v[214:217], 0
	v_mfma_f32_16x16x32_bf16 v[24:27], v[170:173], v[214:217], 0
	v_mfma_f32_16x16x32_bf16 v[16:19], v[162:165], v[222:225], 0
	v_mfma_f32_16x16x32_bf16 v[8:11], v[170:173], v[222:225], 0
	v_mfma_f32_16x16x32_bf16 v[60:63], v[166:169], v[202:205], v[60:63]
	v_mfma_f32_16x16x32_bf16 v[56:59], v[174:177], v[202:205], v[56:59]
	v_mfma_f32_16x16x32_bf16 v[48:51], v[166:169], v[210:213], v[48:51]
	v_mfma_f32_16x16x32_bf16 v[40:43], v[174:177], v[210:213], v[40:43]
	v_mfma_f32_16x16x32_bf16 v[32:35], v[166:169], v[218:221], v[32:35]
	v_mfma_f32_16x16x32_bf16 v[24:27], v[174:177], v[218:221], v[24:27]
	v_mfma_f32_16x16x32_bf16 v[16:19], v[166:169], v[226:229], v[16:19]
	v_mfma_f32_16x16x32_bf16 v[8:11], v[174:177], v[226:229], v[8:11]
	s_setprio 0
	s_setprio 1
	v_mfma_f32_16x16x32_bf16 v[52:55], v[178:181], v[198:201], 0
	v_mfma_f32_16x16x32_bf16 v[44:47], v[190:193], v[198:201], 0
	v_mfma_f32_16x16x32_bf16 v[36:39], v[178:181], v[206:209], 0
	v_mfma_f32_16x16x32_bf16 v[28:31], v[190:193], v[206:209], 0
	v_mfma_f32_16x16x32_bf16 v[20:23], v[178:181], v[214:217], 0
	v_mfma_f32_16x16x32_bf16 v[12:15], v[190:193], v[214:217], 0
	v_mfma_f32_16x16x32_bf16 v[4:7], v[178:181], v[222:225], 0
	v_mfma_f32_16x16x32_bf16 v[0:3], v[190:193], v[222:225], 0
	v_mfma_f32_16x16x32_bf16 v[52:55], v[186:189], v[202:205], v[52:55]
	v_mfma_f32_16x16x32_bf16 v[44:47], v[194:197], v[202:205], v[44:47]
	v_mfma_f32_16x16x32_bf16 v[36:39], v[186:189], v[210:213], v[36:39]
	v_mfma_f32_16x16x32_bf16 v[28:31], v[194:197], v[210:213], v[28:31]
	v_mfma_f32_16x16x32_bf16 v[20:23], v[186:189], v[218:221], v[20:23]
	v_mfma_f32_16x16x32_bf16 v[12:15], v[194:197], v[218:221], v[12:15]
	v_mfma_f32_16x16x32_bf16 v[4:7], v[186:189], v[226:229], v[4:7]
	v_mfma_f32_16x16x32_bf16 v[0:3], v[194:197], v[226:229], v[0:3]
	s_setprio 0
	s_barrier
	s_add_i32 s86, 0, 0x18000
	v_add_u32_e32 v146, s86, v149
	s_add_i32 s87, 0, 0x1c000
	ds_read_b128 v[162:165], v146
	ds_read_b128 v[166:169], v146 offset:1024
	ds_read_b128 v[170:173], v146 offset:2048
	ds_read_b128 v[174:177], v146 offset:3072
	v_add_u32_e32 v146, s87, v149
	ds_read_b128 v[178:181], v146
	ds_read_b128 v[186:189], v146 offset:1024
	ds_read_b128 v[190:193], v146 offset:2048
	ds_read_b128 v[194:197], v146 offset:3072
	s_add_u32 s58, s58, 0x40000
	s_addc_u32 s59, s59, 0
	s_mov_b32 m0, s66
	v_lshl_add_u64 v[236:237], s[58:59], 0, v[128:129]
	ds_read_b128 v[198:201], v154 offset:32768
	ds_read_b128 v[202:205], v154 offset:33792
	ds_read_b128 v[206:209], v154 offset:34816
	ds_read_b128 v[210:213], v154 offset:35840
	ds_read_b128 v[214:217], v154 offset:36864
	ds_read_b128 v[218:221], v154 offset:37888
	ds_read_b128 v[222:225], v154 offset:38912
	ds_read_b128 v[226:229], v154 offset:39936
	global_load_lds_dwordx4 v[236:237], off
	v_lshl_add_u64 v[236:237], s[58:59], 0, v[132:133]
	s_mov_b32 m0, s67
	s_nop 0
	global_load_lds_dwordx4 v[236:237], off
	s_waitcnt vmcnt(8)
	s_waitcnt lgkmcnt(0)
	s_barrier
	s_setprio 1
	s_waitcnt lgkmcnt(0)
	v_mfma_f32_16x16x32_bf16 v[124:127], v[162:165], v[198:201], v[124:127]
	v_mfma_f32_16x16x32_bf16 v[120:123], v[170:173], v[198:201], v[120:123]
	v_mfma_f32_16x16x32_bf16 v[112:115], v[162:165], v[206:209], v[112:115]
	v_mfma_f32_16x16x32_bf16 v[104:107], v[170:173], v[206:209], v[104:107]
	v_mfma_f32_16x16x32_bf16 v[96:99], v[162:165], v[214:217], v[96:99]
	v_mfma_f32_16x16x32_bf16 v[88:91], v[170:173], v[214:217], v[88:91]
	v_mfma_f32_16x16x32_bf16 v[80:83], v[162:165], v[222:225], v[80:83]
	v_mfma_f32_16x16x32_bf16 v[72:75], v[170:173], v[222:225], v[72:75]
	v_mfma_f32_16x16x32_bf16 v[124:127], v[166:169], v[202:205], v[124:127]
	v_mfma_f32_16x16x32_bf16 v[120:123], v[174:177], v[202:205], v[120:123]
	v_mfma_f32_16x16x32_bf16 v[112:115], v[166:169], v[210:213], v[112:115]
	v_mfma_f32_16x16x32_bf16 v[104:107], v[174:177], v[210:213], v[104:107]
	v_mfma_f32_16x16x32_bf16 v[96:99], v[166:169], v[218:221], v[96:99]
	v_mfma_f32_16x16x32_bf16 v[88:91], v[174:177], v[218:221], v[88:91]
	v_mfma_f32_16x16x32_bf16 v[80:83], v[166:169], v[226:229], v[80:83]
	v_mfma_f32_16x16x32_bf16 v[72:75], v[174:177], v[226:229], v[72:75]
	s_setprio 0
	s_setprio 1
	v_mfma_f32_16x16x32_bf16 v[116:119], v[178:181], v[198:201], v[116:119]
	v_mfma_f32_16x16x32_bf16 v[108:111], v[190:193], v[198:201], v[108:111]
	v_mfma_f32_16x16x32_bf16 v[100:103], v[178:181], v[206:209], v[100:103]
	v_mfma_f32_16x16x32_bf16 v[92:95], v[190:193], v[206:209], v[92:95]
	v_mfma_f32_16x16x32_bf16 v[84:87], v[178:181], v[214:217], v[84:87]
	v_mfma_f32_16x16x32_bf16 v[76:79], v[190:193], v[214:217], v[76:79]
	v_mfma_f32_16x16x32_bf16 v[68:71], v[178:181], v[222:225], v[68:71]
	v_mfma_f32_16x16x32_bf16 v[64:67], v[190:193], v[222:225], v[64:67]
	v_mfma_f32_16x16x32_bf16 v[116:119], v[186:189], v[202:205], v[116:119]
	v_mfma_f32_16x16x32_bf16 v[108:111], v[194:197], v[202:205], v[108:111]
	v_mfma_f32_16x16x32_bf16 v[100:103], v[186:189], v[210:213], v[100:103]
	v_mfma_f32_16x16x32_bf16 v[92:95], v[194:197], v[210:213], v[92:95]
	v_mfma_f32_16x16x32_bf16 v[84:87], v[186:189], v[218:221], v[84:87]
	v_mfma_f32_16x16x32_bf16 v[76:79], v[194:197], v[218:221], v[76:79]
	v_mfma_f32_16x16x32_bf16 v[68:71], v[186:189], v[226:229], v[68:71]
	v_mfma_f32_16x16x32_bf16 v[64:67], v[194:197], v[226:229], v[64:67]
	s_setprio 0
	s_barrier
	s_add_i32 s58, s86, s63
	v_lshl_add_u64 v[182:183], v[182:183], 0, s[22:23]
	s_mov_b32 m0, s58
	ds_read_b128 v[198:201], v154 offset:49152
	ds_read_b128 v[202:205], v154 offset:50176
	ds_read_b128 v[206:209], v154 offset:51200
	ds_read_b128 v[210:213], v154 offset:52224
	ds_read_b128 v[214:217], v154 offset:53248
	ds_read_b128 v[218:221], v154 offset:54272
	ds_read_b128 v[222:225], v154 offset:55296
	ds_read_b128 v[226:229], v154 offset:56320
	global_load_lds_dwordx4 v[182:183], off
	s_add_i32 m0, s58, 0x2000
	s_add_u32 s56, s56, 0x40080
	v_lshl_add_u64 v[182:183], v[230:231], 0, s[22:23]
	s_addc_u32 s57, s57, 0
	s_add_i32 s58, s87, s63
	global_load_lds_dwordx4 v[182:183], off
	v_lshl_add_u64 v[182:183], s[56:57], 0, v[130:131]
	s_mov_b32 m0, s58
	s_nop 0
	global_load_lds_dwordx4 v[182:183], off
	v_lshl_add_u64 v[182:183], s[56:57], 0, v[134:135]
	s_add_i32 m0, s58, 0x2000
	s_nop 0
	global_load_lds_dwordx4 v[182:183], off
	v_lshl_add_u64 v[182:183], v[232:233], 0, s[22:23]
	s_mov_b32 m0, s69
	s_nop 0
	global_load_lds_dwordx4 v[182:183], off
	v_lshl_add_u64 v[182:183], v[234:235], 0, s[22:23]
	s_mov_b32 m0, s70
	s_nop 0
	global_load_lds_dwordx4 v[182:183], off
	s_waitcnt vmcnt(8)
	s_waitcnt lgkmcnt(0)
	s_barrier
	s_setprio 1
	s_waitcnt lgkmcnt(0)
	v_mfma_f32_16x16x32_bf16 v[60:63], v[162:165], v[198:201], v[60:63]
	v_mfma_f32_16x16x32_bf16 v[56:59], v[170:173], v[198:201], v[56:59]
	v_mfma_f32_16x16x32_bf16 v[48:51], v[162:165], v[206:209], v[48:51]
	v_mfma_f32_16x16x32_bf16 v[40:43], v[170:173], v[206:209], v[40:43]
	v_mfma_f32_16x16x32_bf16 v[32:35], v[162:165], v[214:217], v[32:35]
	v_mfma_f32_16x16x32_bf16 v[24:27], v[170:173], v[214:217], v[24:27]
	v_mfma_f32_16x16x32_bf16 v[16:19], v[162:165], v[222:225], v[16:19]
	v_mfma_f32_16x16x32_bf16 v[8:11], v[170:173], v[222:225], v[8:11]
	v_mfma_f32_16x16x32_bf16 v[60:63], v[166:169], v[202:205], v[60:63]
	v_mfma_f32_16x16x32_bf16 v[56:59], v[174:177], v[202:205], v[56:59]
	v_mfma_f32_16x16x32_bf16 v[48:51], v[166:169], v[210:213], v[48:51]
	v_mfma_f32_16x16x32_bf16 v[40:43], v[174:177], v[210:213], v[40:43]
	v_mfma_f32_16x16x32_bf16 v[32:35], v[166:169], v[218:221], v[32:35]
	v_mfma_f32_16x16x32_bf16 v[24:27], v[174:177], v[218:221], v[24:27]
	v_mfma_f32_16x16x32_bf16 v[16:19], v[166:169], v[226:229], v[16:19]
	v_mfma_f32_16x16x32_bf16 v[8:11], v[174:177], v[226:229], v[8:11]
	s_setprio 0
	s_setprio 1
	v_mfma_f32_16x16x32_bf16 v[52:55], v[178:181], v[198:201], v[52:55]
	v_mfma_f32_16x16x32_bf16 v[44:47], v[190:193], v[198:201], v[44:47]
	v_mfma_f32_16x16x32_bf16 v[36:39], v[178:181], v[206:209], v[36:39]
	v_mfma_f32_16x16x32_bf16 v[28:31], v[190:193], v[206:209], v[28:31]
	v_mfma_f32_16x16x32_bf16 v[20:23], v[178:181], v[214:217], v[20:23]
	v_mfma_f32_16x16x32_bf16 v[12:15], v[190:193], v[214:217], v[12:15]
	v_mfma_f32_16x16x32_bf16 v[4:7], v[178:181], v[222:225], v[4:7]
	v_mfma_f32_16x16x32_bf16 v[0:3], v[190:193], v[222:225], v[0:3]
	v_mfma_f32_16x16x32_bf16 v[52:55], v[186:189], v[202:205], v[52:55]
	v_mfma_f32_16x16x32_bf16 v[44:47], v[194:197], v[202:205], v[44:47]
	v_mfma_f32_16x16x32_bf16 v[36:39], v[186:189], v[210:213], v[36:39]
	v_mfma_f32_16x16x32_bf16 v[28:31], v[194:197], v[210:213], v[28:31]
	v_mfma_f32_16x16x32_bf16 v[20:23], v[186:189], v[218:221], v[20:23]
	v_mfma_f32_16x16x32_bf16 v[12:15], v[194:197], v[218:221], v[12:15]
	v_mfma_f32_16x16x32_bf16 v[4:7], v[186:189], v[226:229], v[4:7]
	v_mfma_f32_16x16x32_bf16 v[0:3], v[194:197], v[226:229], v[0:3]
	s_setprio 0
	s_barrier
	s_add_i32 s85, s85, 2
	s_add_u32 s83, s83, 0x100
	s_addc_u32 s84, s84, 0
	s_add_u32 s54, s54, 0x100
	s_addc_u32 s55, s55, 0
	s_branch .LBB0_875
.Lfa_8:
	v_add_u32_e32 v146, s73, v149
	ds_read_b128 v[162:165], v146
	ds_read_b128 v[166:169], v146 offset:1024
	ds_read_b128 v[170:173], v146 offset:2048
	ds_read_b128 v[174:177], v146 offset:3072
	v_add_u32_e32 v146, s74, v149
	ds_read_b128 v[178:181], v146
	ds_read_b128 v[186:189], v146 offset:1024
	ds_read_b128 v[190:193], v146 offset:2048
	ds_read_b128 v[194:197], v146 offset:3072
	s_add_u32 s58, s54, 0xfffc0080
	s_addc_u32 s59, s55, -1
	s_and_b64 s[56:57], s[56:57], exec
	s_cselect_b32 s59, s49, s59
	s_cselect_b32 s58, s80, s58
	s_cselect_b32 s57, s81, s84
	s_cselect_b32 s56, s82, s83
	v_lshl_add_u64 v[182:183], s[54:55], 0, v[138:139]
	s_add_i32 m0, s64, 0xc000
	ds_read_b128 v[198:201], v154
	ds_read_b128 v[202:205], v154 offset:1024
	ds_read_b128 v[206:209], v154 offset:2048
	ds_read_b128 v[210:213], v154 offset:3072
	ds_read_b128 v[214:217], v154 offset:4096
	ds_read_b128 v[218:221], v154 offset:5120
	ds_read_b128 v[222:225], v154 offset:6144
	ds_read_b128 v[226:229], v154 offset:7168
	global_load_lds_dwordx4 v[182:183], off
	v_lshl_add_u64 v[182:183], s[54:55], 0, v[136:137]
	s_add_i32 m0, s64, 0xe000
	s_nop 0
	global_load_lds_dwordx4 v[182:183], off
	s_waitcnt vmcnt(8)
	s_waitcnt lgkmcnt(0)
	s_barrier
	s_setprio 1
	s_waitcnt lgkmcnt(0)
	v_mfma_f32_16x16x32_bf16 v[124:127], v[162:165], v[198:201], 0
	v_mfma_f32_16x16x32_bf16 v[120:123], v[170:173], v[198:201], 0
	v_mfma_f32_16x16x32_bf16 v[112:115], v[162:165], v[206:209], 0
	v_mfma_f32_16x16x32_bf16 v[104:107], v[170:173], v[206:209], 0
	v_mfma_f32_16x16x32_bf16 v[96:99], v[162:165], v[214:217], 0
	v_mfma_f32_16x16x32_bf16 v[88:91], v[170:173], v[214:217], 0
	v_mfma_f32_16x16x32_bf16 v[80:83], v[162:165], v[222:225], 0
	v_mfma_f32_16x16x32_bf16 v[72:75], v[170:173], v[222:225], 0
	v_mfma_f32_16x16x32_bf16 v[124:127], v[166:169], v[202:205], v[124:127]
	v_mfma_f32_16x16x32_bf16 v[120:123], v[174:177], v[202:205], v[120:123]
	v_mfma_f32_16x16x32_bf16 v[112:115], v[166:169], v[210:213], v[112:115]
	v_mfma_f32_16x16x32_bf16 v[104:107], v[174:177], v[210:213], v[104:107]
	v_mfma_f32_16x16x32_bf16 v[96:99], v[166:169], v[218:221], v[96:99]
	v_mfma_f32_16x16x32_bf16 v[88:91], v[174:177], v[218:221], v[88:91]
	v_mfma_f32_16x16x32_bf16 v[80:83], v[166:169], v[226:229], v[80:83]
	v_mfma_f32_16x16x32_bf16 v[72:75], v[174:177], v[226:229], v[72:75]
	s_setprio 0
	s_setprio 1
	v_mfma_f32_16x16x32_bf16 v[116:119], v[178:181], v[198:201], 0
	v_mfma_f32_16x16x32_bf16 v[108:111], v[190:193], v[198:201], 0
	v_mfma_f32_16x16x32_bf16 v[100:103], v[178:181], v[206:209], 0
	v_mfma_f32_16x16x32_bf16 v[92:95], v[190:193], v[206:209], 0
	v_mfma_f32_16x16x32_bf16 v[84:87], v[178:181], v[214:217], 0
	v_mfma_f32_16x16x32_bf16 v[76:79], v[190:193], v[214:217], 0
	v_mfma_f32_16x16x32_bf16 v[68:71], v[178:181], v[222:225], 0
	v_mfma_f32_16x16x32_bf16 v[64:67], v[190:193], v[222:225], 0
	v_mfma_f32_16x16x32_bf16 v[116:119], v[186:189], v[202:205], v[116:119]
	v_mfma_f32_16x16x32_bf16 v[108:111], v[194:197], v[202:205], v[108:111]
	v_mfma_f32_16x16x32_bf16 v[100:103], v[186:189], v[210:213], v[100:103]
	v_mfma_f32_16x16x32_bf16 v[92:95], v[194:197], v[210:213], v[92:95]
	v_mfma_f32_16x16x32_bf16 v[84:87], v[186:189], v[218:221], v[84:87]
	v_mfma_f32_16x16x32_bf16 v[76:79], v[194:197], v[218:221], v[76:79]
	v_mfma_f32_16x16x32_bf16 v[68:71], v[186:189], v[226:229], v[68:71]
	v_mfma_f32_16x16x32_bf16 v[64:67], v[194:197], v[226:229], v[64:67]
	s_setprio 0
	s_barrier
	s_add_i32 s86, s73, s63
	v_lshl_add_u64 v[182:183], s[56:57], 0, v[130:131]
	s_mov_b32 m0, s86
	ds_read_b128 v[198:201], v154 offset:16384
	ds_read_b128 v[202:205], v154 offset:17408
	ds_read_b128 v[206:209], v154 offset:18432
	ds_read_b128 v[210:213], v154 offset:19456
	ds_read_b128 v[214:217], v154 offset:20480
	ds_read_b128 v[218:221], v154 offset:21504
	ds_read_b128 v[222:225], v154 offset:22528
	ds_read_b128 v[226:229], v154 offset:23552
	global_load_lds_dwordx4 v[182:183], off
	s_add_i32 m0, s86, 0x2000
	s_add_u32 s86, s56, 0x40000
	v_lshl_add_u64 v[230:231], s[56:57], 0, v[134:135]
	s_addc_u32 s87, s57, 0
	s_add_i32 s88, s74, s63
	global_load_lds_dwordx4 v[230:231], off
	v_lshl_add_u64 v[232:233], s[86:87], 0, v[130:131]
	s_mov_b32 m0, s88
	v_lshl_add_u64 v[234:235], s[58:59], 0, v[132:133]
	global_load_lds_dwordx4 v[232:233], off
	v_lshl_add_u64 v[232:233], s[86:87], 0, v[134:135]
	s_add_i32 m0, s88, 0x2000
	s_nop 0
	global_load_lds_dwordx4 v[232:233], off
	v_lshl_add_u64 v[232:233], s[58:59], 0, v[128:129]
	s_mov_b32 m0, s64
	s_nop 0
	global_load_lds_dwordx4 v[232:233], off
	s_mov_b32 m0, s65
	s_nop 0
	global_load_lds_dwordx4 v[234:235], off
	s_waitcnt vmcnt(8)
	s_waitcnt lgkmcnt(0)
	s_barrier
	s_setprio 1
	s_waitcnt lgkmcnt(0)
	v_mfma_f32_16x16x32_bf16 v[60:63], v[162:165], v[198:201], 0
	v_mfma_f32_16x16x32_bf16 v[56:59], v[170:173], v[198:201], 0
	v_mfma_f32_16x16x32_bf16 v[48:51], v[162:165], v[206:209], 0
	v_mfma_f32_16x16x32_bf16 v[40:43], v[170:173], v[206:209], 0
	v_mfma_f32_16x16x32_bf16 v[32:35], v[162:165], v[214:217], 0
	v_mfma_f32_16x16x32_bf16 v[24:27], v[170:173], v[214:217], 0
	v_mfma_f32_16x16x32_bf16 v[16:19], v[162:165], v[222:225], 0
	v_mfma_f32_16x16x32_bf16 v[8:11], v[170:173], v[222:225], 0
	v_mfma_f32_16x16x32_bf16 v[60:63], v[166:169], v[202:205], v[60:63]
	v_mfma_f32_16x16x32_bf16 v[56:59], v[174:177], v[202:205], v[56:59]
	v_mfma_f32_16x16x32_bf16 v[48:51], v[166:169], v[210:213], v[48:51]
	v_mfma_f32_16x16x32_bf16 v[40:43], v[174:177], v[210:213], v[40:43]
	v_mfma_f32_16x16x32_bf16 v[32:35], v[166:169], v[218:221], v[32:35]
	v_mfma_f32_16x16x32_bf16 v[24:27], v[174:177], v[218:221], v[24:27]
	v_mfma_f32_16x16x32_bf16 v[16:19], v[166:169], v[226:229], v[16:19]
	v_mfma_f32_16x16x32_bf16 v[8:11], v[174:177], v[226:229], v[8:11]
	s_setprio 0
	s_setprio 1
	v_mfma_f32_16x16x32_bf16 v[52:55], v[178:181], v[198:201], 0
	v_mfma_f32_16x16x32_bf16 v[44:47], v[190:193], v[198:201], 0
	v_mfma_f32_16x16x32_bf16 v[36:39], v[178:181], v[206:209], 0
	v_mfma_f32_16x16x32_bf16 v[28:31], v[190:193], v[206:209], 0
	v_mfma_f32_16x16x32_bf16 v[20:23], v[178:181], v[214:217], 0
	v_mfma_f32_16x16x32_bf16 v[12:15], v[190:193], v[214:217], 0
	v_mfma_f32_16x16x32_bf16 v[4:7], v[178:181], v[222:225], 0
	v_mfma_f32_16x16x32_bf16 v[0:3], v[190:193], v[222:225], 0
	v_mfma_f32_16x16x32_bf16 v[52:55], v[186:189], v[202:205], v[52:55]
	v_mfma_f32_16x16x32_bf16 v[44:47], v[194:197], v[202:205], v[44:47]
	v_mfma_f32_16x16x32_bf16 v[36:39], v[186:189], v[210:213], v[36:39]
	v_mfma_f32_16x16x32_bf16 v[28:31], v[194:197], v[210:213], v[28:31]
	v_mfma_f32_16x16x32_bf16 v[20:23], v[186:189], v[218:221], v[20:23]
	v_mfma_f32_16x16x32_bf16 v[12:15], v[194:197], v[218:221], v[12:15]
	v_mfma_f32_16x16x32_bf16 v[4:7], v[186:189], v[226:229], v[4:7]
	v_mfma_f32_16x16x32_bf16 v[0:3], v[194:197], v[226:229], v[0:3]
	s_setprio 0
	s_barrier
	s_add_i32 s86, 0, 0x18000
	v_add_u32_e32 v146, s86, v149
	s_add_i32 s87, 0, 0x1c000
	ds_read_b128 v[162:165], v146
	ds_read_b128 v[166:169], v146 offset:1024
	ds_read_b128 v[170:173], v146 offset:2048
	ds_read_b128 v[174:177], v146 offset:3072
	v_add_u32_e32 v146, s87, v149
	ds_read_b128 v[178:181], v146
	ds_read_b128 v[186:189], v146 offset:1024
	ds_read_b128 v[190:193], v146 offset:2048
	ds_read_b128 v[194:197], v146 offset:3072
	s_add_u32 s58, s58, 0x40000
	s_addc_u32 s59, s59, 0
	s_mov_b32 m0, s66
	v_lshl_add_u64 v[236:237], s[58:59], 0, v[128:129]
	ds_read_b128 v[198:201], v154 offset:32768
	ds_read_b128 v[202:205], v154 offset:33792
	ds_read_b128 v[206:209], v154 offset:34816
	ds_read_b128 v[210:213], v154 offset:35840
	ds_read_b128 v[214:217], v154 offset:36864
	ds_read_b128 v[218:221], v154 offset:37888
	ds_read_b128 v[222:225], v154 offset:38912
	ds_read_b128 v[226:229], v154 offset:39936
	global_load_lds_dwordx4 v[236:237], off
	v_lshl_add_u64 v[236:237], s[58:59], 0, v[132:133]
	s_mov_b32 m0, s67
	s_nop 0
	global_load_lds_dwordx4 v[236:237], off
	s_waitcnt vmcnt(8)
	s_waitcnt lgkmcnt(0)
	s_barrier
	s_setprio 1
	s_waitcnt lgkmcnt(0)
	v_mfma_f32_16x16x32_bf16 v[124:127], v[162:165], v[198:201], v[124:127]
	v_mfma_f32_16x16x32_bf16 v[120:123], v[170:173], v[198:201], v[120:123]
	v_mfma_f32_16x16x32_bf16 v[112:115], v[162:165], v[206:209], v[112:115]
	v_mfma_f32_16x16x32_bf16 v[104:107], v[170:173], v[206:209], v[104:107]
	v_mfma_f32_16x16x32_bf16 v[96:99], v[162:165], v[214:217], v[96:99]
	v_mfma_f32_16x16x32_bf16 v[88:91], v[170:173], v[214:217], v[88:91]
	v_mfma_f32_16x16x32_bf16 v[80:83], v[162:165], v[222:225], v[80:83]
	v_mfma_f32_16x16x32_bf16 v[72:75], v[170:173], v[222:225], v[72:75]
	v_mfma_f32_16x16x32_bf16 v[124:127], v[166:169], v[202:205], v[124:127]
	v_mfma_f32_16x16x32_bf16 v[120:123], v[174:177], v[202:205], v[120:123]
	v_mfma_f32_16x16x32_bf16 v[112:115], v[166:169], v[210:213], v[112:115]
	v_mfma_f32_16x16x32_bf16 v[104:107], v[174:177], v[210:213], v[104:107]
	v_mfma_f32_16x16x32_bf16 v[96:99], v[166:169], v[218:221], v[96:99]
	v_mfma_f32_16x16x32_bf16 v[88:91], v[174:177], v[218:221], v[88:91]
	v_mfma_f32_16x16x32_bf16 v[80:83], v[166:169], v[226:229], v[80:83]
	v_mfma_f32_16x16x32_bf16 v[72:75], v[174:177], v[226:229], v[72:75]
	s_setprio 0
	s_setprio 1
	v_mfma_f32_16x16x32_bf16 v[116:119], v[178:181], v[198:201], v[116:119]
	v_mfma_f32_16x16x32_bf16 v[108:111], v[190:193], v[198:201], v[108:111]
	v_mfma_f32_16x16x32_bf16 v[100:103], v[178:181], v[206:209], v[100:103]
	v_mfma_f32_16x16x32_bf16 v[92:95], v[190:193], v[206:209], v[92:95]
	v_mfma_f32_16x16x32_bf16 v[84:87], v[178:181], v[214:217], v[84:87]
	v_mfma_f32_16x16x32_bf16 v[76:79], v[190:193], v[214:217], v[76:79]
	v_mfma_f32_16x16x32_bf16 v[68:71], v[178:181], v[222:225], v[68:71]
	v_mfma_f32_16x16x32_bf16 v[64:67], v[190:193], v[222:225], v[64:67]
	v_mfma_f32_16x16x32_bf16 v[116:119], v[186:189], v[202:205], v[116:119]
	v_mfma_f32_16x16x32_bf16 v[108:111], v[194:197], v[202:205], v[108:111]
	v_mfma_f32_16x16x32_bf16 v[100:103], v[186:189], v[210:213], v[100:103]
	v_mfma_f32_16x16x32_bf16 v[92:95], v[194:197], v[210:213], v[92:95]
	v_mfma_f32_16x16x32_bf16 v[84:87], v[186:189], v[218:221], v[84:87]
	v_mfma_f32_16x16x32_bf16 v[76:79], v[194:197], v[218:221], v[76:79]
	v_mfma_f32_16x16x32_bf16 v[68:71], v[186:189], v[226:229], v[68:71]
	v_mfma_f32_16x16x32_bf16 v[64:67], v[194:197], v[226:229], v[64:67]
	s_setprio 0
	s_barrier
	s_add_i32 s58, s86, s63
	v_lshl_add_u64 v[182:183], v[182:183], 0, s[22:23]
	s_mov_b32 m0, s58
	ds_read_b128 v[198:201], v154 offset:49152
	ds_read_b128 v[202:205], v154 offset:50176
	ds_read_b128 v[206:209], v154 offset:51200
	ds_read_b128 v[210:213], v154 offset:52224
	ds_read_b128 v[214:217], v154 offset:53248
	ds_read_b128 v[218:221], v154 offset:54272
	ds_read_b128 v[222:225], v154 offset:55296
	ds_read_b128 v[226:229], v154 offset:56320
	global_load_lds_dwordx4 v[182:183], off
	s_add_i32 m0, s58, 0x2000
	s_add_u32 s56, s56, 0x40080
	v_lshl_add_u64 v[182:183], v[230:231], 0, s[22:23]
	s_addc_u32 s57, s57, 0
	s_add_i32 s58, s87, s63
	global_load_lds_dwordx4 v[182:183], off
	v_lshl_add_u64 v[182:183], s[56:57], 0, v[130:131]
	s_mov_b32 m0, s58
	s_nop 0
	global_load_lds_dwordx4 v[182:183], off
	v_lshl_add_u64 v[182:183], s[56:57], 0, v[134:135]
	s_add_i32 m0, s58, 0x2000
	s_nop 0
	global_load_lds_dwordx4 v[182:183], off
	v_lshl_add_u64 v[182:183], v[232:233], 0, s[22:23]
	s_mov_b32 m0, s69
	s_nop 0
	global_load_lds_dwordx4 v[182:183], off
	v_lshl_add_u64 v[182:183], v[234:235], 0, s[22:23]
	s_mov_b32 m0, s70
	s_nop 0
	global_load_lds_dwordx4 v[182:183], off
	s_waitcnt vmcnt(8)
	s_waitcnt lgkmcnt(0)
	s_barrier
	s_setprio 1
	s_waitcnt lgkmcnt(0)
	v_mfma_f32_16x16x32_bf16 v[60:63], v[162:165], v[198:201], v[60:63]
	v_mfma_f32_16x16x32_bf16 v[56:59], v[170:173], v[198:201], v[56:59]
	v_mfma_f32_16x16x32_bf16 v[48:51], v[162:165], v[206:209], v[48:51]
	v_mfma_f32_16x16x32_bf16 v[40:43], v[170:173], v[206:209], v[40:43]
	v_mfma_f32_16x16x32_bf16 v[32:35], v[162:165], v[214:217], v[32:35]
	v_mfma_f32_16x16x32_bf16 v[24:27], v[170:173], v[214:217], v[24:27]
	v_mfma_f32_16x16x32_bf16 v[16:19], v[162:165], v[222:225], v[16:19]
	v_mfma_f32_16x16x32_bf16 v[8:11], v[170:173], v[222:225], v[8:11]
	v_mfma_f32_16x16x32_bf16 v[60:63], v[166:169], v[202:205], v[60:63]
	v_mfma_f32_16x16x32_bf16 v[56:59], v[174:177], v[202:205], v[56:59]
	v_mfma_f32_16x16x32_bf16 v[48:51], v[166:169], v[210:213], v[48:51]
	v_mfma_f32_16x16x32_bf16 v[40:43], v[174:177], v[210:213], v[40:43]
	v_mfma_f32_16x16x32_bf16 v[32:35], v[166:169], v[218:221], v[32:35]
	v_mfma_f32_16x16x32_bf16 v[24:27], v[174:177], v[218:221], v[24:27]
	v_mfma_f32_16x16x32_bf16 v[16:19], v[166:169], v[226:229], v[16:19]
	v_mfma_f32_16x16x32_bf16 v[8:11], v[174:177], v[226:229], v[8:11]
	s_setprio 0
	s_setprio 1
	v_mfma_f32_16x16x32_bf16 v[52:55], v[178:181], v[198:201], v[52:55]
	v_mfma_f32_16x16x32_bf16 v[44:47], v[190:193], v[198:201], v[44:47]
	v_mfma_f32_16x16x32_bf16 v[36:39], v[178:181], v[206:209], v[36:39]
	v_mfma_f32_16x16x32_bf16 v[28:31], v[190:193], v[206:209], v[28:31]
	v_mfma_f32_16x16x32_bf16 v[20:23], v[178:181], v[214:217], v[20:23]
	v_mfma_f32_16x16x32_bf16 v[12:15], v[190:193], v[214:217], v[12:15]
	v_mfma_f32_16x16x32_bf16 v[4:7], v[178:181], v[222:225], v[4:7]
	v_mfma_f32_16x16x32_bf16 v[0:3], v[190:193], v[222:225], v[0:3]
	v_mfma_f32_16x16x32_bf16 v[52:55], v[186:189], v[202:205], v[52:55]
	v_mfma_f32_16x16x32_bf16 v[44:47], v[194:197], v[202:205], v[44:47]
	v_mfma_f32_16x16x32_bf16 v[36:39], v[186:189], v[210:213], v[36:39]
	v_mfma_f32_16x16x32_bf16 v[28:31], v[194:197], v[210:213], v[28:31]
	v_mfma_f32_16x16x32_bf16 v[20:23], v[186:189], v[218:221], v[20:23]
	v_mfma_f32_16x16x32_bf16 v[12:15], v[194:197], v[218:221], v[12:15]
	v_mfma_f32_16x16x32_bf16 v[4:7], v[186:189], v[226:229], v[4:7]
	v_mfma_f32_16x16x32_bf16 v[0:3], v[194:197], v[226:229], v[0:3]
	s_setprio 0
	s_barrier
	s_add_i32 s85, s85, 2
	s_add_u32 s83, s83, 0x100
	s_addc_u32 s84, s84, 0
	s_add_u32 s54, s54, 0x100
	s_addc_u32 s55, s55, 0
	s_branch .LBB0_875

.LBB0_1010:
	s_ashr_i32 s51, s50, 31
	s_lshl_b64 s[52:53], s[50:51], 19
	s_add_u32 s52, s33, s52
	s_addc_u32 s53, s35, s53
	s_and_b64 s[54:55], s[12:13], exec
	s_cselect_b32 s15, s53, s61
	s_cselect_b32 s51, s52, s60
	s_ashr_i32 s49, s48, 31
	s_lshl_b64 s[54:55], s[48:49], 19
	s_add_u32 s54, s64, s54
	s_addc_u32 s55, s65, s55
	s_and_b64 s[62:63], s[12:13], exec
	s_cselect_b32 s49, s55, s59
	s_cselect_b32 s57, s54, s58
	s_add_u32 s78, s58, 0x100
	s_addc_u32 s79, s59, 0
	s_add_u32 s58, s60, 0x40080
	s_addc_u32 s59, s61, 0
	s_mov_b32 s80, -2
	s_waitcnt lgkmcnt(0)
	s_cmp_eq_u32 s71, 1
	s_cbranch_scc1 .Lfa_9
	ds_read_b128 v[128:131], v188
	ds_read_b128 v[132:135], v188 offset:1024
	ds_read_b128 v[136:139], v188 offset:2048
	ds_read_b128 v[140:143], v188 offset:3072
	ds_read_b128 v[144:147], v189
	ds_read_b128 v[148:151], v189 offset:1024
	ds_read_b128 v[172:175], v189 offset:2048
	ds_read_b128 v[176:179], v189 offset:3072
	s_add_u32 s60, s58, 0xfffc0080
	s_addc_u32 s61, s59, -1
	s_cmp_eq_u32 s80, 12
	s_cselect_b32 s63, s15, s61
	s_cselect_b32 s62, s51, s60
	s_cselect_b32 s61, s49, s79
	s_cselect_b32 s60, s57, s78
	v_lshl_add_u64 v[220:221], s[58:59], 0, v[166:167]
	s_add_i32 m0, s67, 0xc000
	ds_read_b128 v[180:183], v190
	ds_read_b128 v[192:195], v190 offset:1024
	ds_read_b128 v[196:199], v190 offset:2048
	ds_read_b128 v[200:203], v190 offset:3072
	ds_read_b128 v[204:207], v190 offset:4096
	ds_read_b128 v[208:211], v190 offset:5120
	ds_read_b128 v[212:215], v190 offset:6144
	ds_read_b128 v[216:219], v190 offset:7168
	global_load_lds_dwordx4 v[220:221], off
	v_lshl_add_u64 v[220:221], s[58:59], 0, v[164:165]
	s_add_i32 m0, s67, 0xe000
	s_nop 0
	global_load_lds_dwordx4 v[220:221], off
	s_waitcnt vmcnt(24)
	s_waitcnt lgkmcnt(0)
	s_barrier
	s_setprio 1
	s_waitcnt lgkmcnt(0)
	v_mfma_f32_16x16x32_bf16 v[124:127], v[128:131], v[180:183], 0
	v_mfma_f32_16x16x32_bf16 v[120:123], v[136:139], v[180:183], 0
	v_mfma_f32_16x16x32_bf16 v[108:111], v[128:131], v[196:199], 0
	v_mfma_f32_16x16x32_bf16 v[104:107], v[136:139], v[196:199], 0
	v_mfma_f32_16x16x32_bf16 v[92:95], v[128:131], v[204:207], 0
	v_mfma_f32_16x16x32_bf16 v[88:91], v[136:139], v[204:207], 0
	v_mfma_f32_16x16x32_bf16 v[76:79], v[128:131], v[212:215], 0
	v_mfma_f32_16x16x32_bf16 v[72:75], v[136:139], v[212:215], 0
	v_mfma_f32_16x16x32_bf16 v[124:127], v[132:135], v[192:195], v[124:127]
	v_mfma_f32_16x16x32_bf16 v[120:123], v[140:143], v[192:195], v[120:123]
	v_mfma_f32_16x16x32_bf16 v[108:111], v[132:135], v[200:203], v[108:111]
	v_mfma_f32_16x16x32_bf16 v[104:107], v[140:143], v[200:203], v[104:107]
	v_mfma_f32_16x16x32_bf16 v[92:95], v[132:135], v[208:211], v[92:95]
	v_mfma_f32_16x16x32_bf16 v[88:91], v[140:143], v[208:211], v[88:91]
	v_mfma_f32_16x16x32_bf16 v[76:79], v[132:135], v[216:219], v[76:79]
	v_mfma_f32_16x16x32_bf16 v[72:75], v[140:143], v[216:219], v[72:75]
	s_setprio 0
	s_setprio 1
	v_mfma_f32_16x16x32_bf16 v[116:119], v[144:147], v[180:183], 0
	v_mfma_f32_16x16x32_bf16 v[112:115], v[172:175], v[180:183], 0
	v_mfma_f32_16x16x32_bf16 v[100:103], v[144:147], v[196:199], 0
	v_mfma_f32_16x16x32_bf16 v[96:99], v[172:175], v[196:199], 0
	v_mfma_f32_16x16x32_bf16 v[84:87], v[144:147], v[204:207], 0
	v_mfma_f32_16x16x32_bf16 v[80:83], v[172:175], v[204:207], 0
	v_mfma_f32_16x16x32_bf16 v[68:71], v[144:147], v[212:215], 0
	v_mfma_f32_16x16x32_bf16 v[64:67], v[172:175], v[212:215], 0
	v_mfma_f32_16x16x32_bf16 v[116:119], v[148:151], v[192:195], v[116:119]
	v_mfma_f32_16x16x32_bf16 v[112:115], v[176:179], v[192:195], v[112:115]
	v_mfma_f32_16x16x32_bf16 v[100:103], v[148:151], v[200:203], v[100:103]
	v_mfma_f32_16x16x32_bf16 v[96:99], v[176:179], v[200:203], v[96:99]
	v_mfma_f32_16x16x32_bf16 v[84:87], v[148:151], v[208:211], v[84:87]
	v_mfma_f32_16x16x32_bf16 v[80:83], v[176:179], v[208:211], v[80:83]
	v_mfma_f32_16x16x32_bf16 v[68:71], v[148:151], v[216:219], v[68:71]
	v_mfma_f32_16x16x32_bf16 v[64:67], v[176:179], v[216:219], v[64:67]
	s_setprio 0
	s_barrier
	s_add_i32 s81, s76, s66
	v_lshl_add_u64 v[220:221], s[60:61], 0, v[154:155]
	s_mov_b32 m0, s81
	ds_read_b128 v[180:183], v190 offset:16384
	ds_read_b128 v[192:195], v190 offset:17408
	ds_read_b128 v[196:199], v190 offset:18432
	ds_read_b128 v[200:203], v190 offset:19456
	ds_read_b128 v[204:207], v190 offset:20480
	ds_read_b128 v[208:211], v190 offset:21504
	ds_read_b128 v[212:215], v190 offset:22528
	ds_read_b128 v[216:219], v190 offset:23552
	global_load_lds_dwordx4 v[220:221], off
	s_add_i32 m0, s81, 0x2000
	s_add_u32 s82, s60, 0x40000
	v_lshl_add_u64 v[222:223], s[60:61], 0, v[162:163]
	s_addc_u32 s83, s61, 0
	s_add_i32 s81, s77, s66
	global_load_lds_dwordx4 v[222:223], off
	v_lshl_add_u64 v[224:225], s[82:83], 0, v[154:155]
	s_mov_b32 m0, s81
	v_lshl_add_u64 v[226:227], s[62:63], 0, v[160:161]
	global_load_lds_dwordx4 v[224:225], off
	v_lshl_add_u64 v[224:225], s[82:83], 0, v[162:163]
	s_add_i32 m0, s81, 0x2000
	s_nop 0
	global_load_lds_dwordx4 v[224:225], off
	v_lshl_add_u64 v[224:225], s[62:63], 0, v[152:153]
	s_mov_b32 m0, s67
	s_nop 0
	global_load_lds_dwordx4 v[224:225], off
	s_mov_b32 m0, s68
	s_nop 0
	global_load_lds_dwordx4 v[226:227], off
	s_waitcnt vmcnt(24)
	s_waitcnt lgkmcnt(0)
	s_barrier
	s_setprio 1
	s_waitcnt lgkmcnt(0)
	v_mfma_f32_16x16x32_bf16 v[60:63], v[128:131], v[180:183], 0
	v_mfma_f32_16x16x32_bf16 v[56:59], v[136:139], v[180:183], 0
	v_mfma_f32_16x16x32_bf16 v[44:47], v[128:131], v[196:199], 0
	v_mfma_f32_16x16x32_bf16 v[40:43], v[136:139], v[196:199], 0
	v_mfma_f32_16x16x32_bf16 v[28:31], v[128:131], v[204:207], 0
	v_mfma_f32_16x16x32_bf16 v[24:27], v[136:139], v[204:207], 0
	v_mfma_f32_16x16x32_bf16 v[12:15], v[128:131], v[212:215], 0
	v_mfma_f32_16x16x32_bf16 v[8:11], v[136:139], v[212:215], 0
	v_mfma_f32_16x16x32_bf16 v[60:63], v[132:135], v[192:195], v[60:63]
	v_mfma_f32_16x16x32_bf16 v[56:59], v[140:143], v[192:195], v[56:59]
	v_mfma_f32_16x16x32_bf16 v[44:47], v[132:135], v[200:203], v[44:47]
	v_mfma_f32_16x16x32_bf16 v[40:43], v[140:143], v[200:203], v[40:43]
	v_mfma_f32_16x16x32_bf16 v[28:31], v[132:135], v[208:211], v[28:31]
	v_mfma_f32_16x16x32_bf16 v[24:27], v[140:143], v[208:211], v[24:27]
	v_mfma_f32_16x16x32_bf16 v[12:15], v[132:135], v[216:219], v[12:15]
	v_mfma_f32_16x16x32_bf16 v[8:11], v[140:143], v[216:219], v[8:11]
	s_setprio 0
	s_setprio 1
	v_mfma_f32_16x16x32_bf16 v[52:55], v[144:147], v[180:183], 0
	v_mfma_f32_16x16x32_bf16 v[48:51], v[172:175], v[180:183], 0
	v_mfma_f32_16x16x32_bf16 v[36:39], v[144:147], v[196:199], 0
	v_mfma_f32_16x16x32_bf16 v[32:35], v[172:175], v[196:199], 0
	v_mfma_f32_16x16x32_bf16 v[20:23], v[144:147], v[204:207], 0
	v_mfma_f32_16x16x32_bf16 v[16:19], v[172:175], v[204:207], 0
	v_mfma_f32_16x16x32_bf16 v[4:7], v[144:147], v[212:215], 0
	v_mfma_f32_16x16x32_bf16 v[0:3], v[172:175], v[212:215], 0
	v_mfma_f32_16x16x32_bf16 v[52:55], v[148:151], v[192:195], v[52:55]
	v_mfma_f32_16x16x32_bf16 v[48:51], v[176:179], v[192:195], v[48:51]
	v_mfma_f32_16x16x32_bf16 v[36:39], v[148:151], v[200:203], v[36:39]
	v_mfma_f32_16x16x32_bf16 v[32:35], v[176:179], v[200:203], v[32:35]
	v_mfma_f32_16x16x32_bf16 v[20:23], v[148:151], v[208:211], v[20:23]
	v_mfma_f32_16x16x32_bf16 v[16:19], v[176:179], v[208:211], v[16:19]
	v_mfma_f32_16x16x32_bf16 v[4:7], v[148:151], v[216:219], v[4:7]
	v_mfma_f32_16x16x32_bf16 v[0:3], v[176:179], v[216:219], v[0:3]
	s_setprio 0
	s_barrier
	s_add_i32 s81, 0, 0x18000
	s_add_i32 s82, 0, 0x1c000
	v_add_u32_e32 v140, s81, v185
	v_add_u32_e32 v176, s82, v185
	ds_read_b128 v[128:131], v140
	ds_read_b128 v[132:135], v140 offset:1024
	ds_read_b128 v[136:139], v140 offset:2048
	ds_read_b128 v[140:143], v140 offset:3072
	ds_read_b128 v[144:147], v176
	ds_read_b128 v[148:151], v176 offset:1024
	ds_read_b128 v[172:175], v176 offset:2048
	ds_read_b128 v[176:179], v176 offset:3072
	s_add_u32 s62, s62, 0x40000
	s_addc_u32 s63, s63, 0
	s_mov_b32 m0, s69
	v_lshl_add_u64 v[228:229], s[62:63], 0, v[152:153]
	ds_read_b128 v[180:183], v190 offset:32768
	ds_read_b128 v[192:195], v190 offset:33792
	ds_read_b128 v[196:199], v190 offset:34816
	ds_read_b128 v[200:203], v190 offset:35840
	ds_read_b128 v[204:207], v190 offset:36864
	ds_read_b128 v[208:211], v190 offset:37888
	ds_read_b128 v[212:215], v190 offset:38912
	ds_read_b128 v[216:219], v190 offset:39936
	global_load_lds_dwordx4 v[228:229], off
	v_lshl_add_u64 v[228:229], s[62:63], 0, v[160:161]
	s_mov_b32 m0, s70
	s_nop 0
	global_load_lds_dwordx4 v[228:229], off
	s_waitcnt vmcnt(8)
	s_waitcnt lgkmcnt(0)
	s_barrier
	s_setprio 1
	s_waitcnt lgkmcnt(0)
	v_mfma_f32_16x16x32_bf16 v[124:127], v[128:131], v[180:183], v[124:127]
	v_mfma_f32_16x16x32_bf16 v[120:123], v[136:139], v[180:183], v[120:123]
	v_mfma_f32_16x16x32_bf16 v[108:111], v[128:131], v[196:199], v[108:111]
	v_mfma_f32_16x16x32_bf16 v[104:107], v[136:139], v[196:199], v[104:107]
	v_mfma_f32_16x16x32_bf16 v[92:95], v[128:131], v[204:207], v[92:95]
	v_mfma_f32_16x16x32_bf16 v[88:91], v[136:139], v[204:207], v[88:91]
	v_mfma_f32_16x16x32_bf16 v[76:79], v[128:131], v[212:215], v[76:79]
	v_mfma_f32_16x16x32_bf16 v[72:75], v[136:139], v[212:215], v[72:75]
	v_mfma_f32_16x16x32_bf16 v[124:127], v[132:135], v[192:195], v[124:127]
	v_mfma_f32_16x16x32_bf16 v[120:123], v[140:143], v[192:195], v[120:123]
	v_mfma_f32_16x16x32_bf16 v[108:111], v[132:135], v[200:203], v[108:111]
	v_mfma_f32_16x16x32_bf16 v[104:107], v[140:143], v[200:203], v[104:107]
	v_mfma_f32_16x16x32_bf16 v[92:95], v[132:135], v[208:211], v[92:95]
	v_mfma_f32_16x16x32_bf16 v[88:91], v[140:143], v[208:211], v[88:91]
	v_mfma_f32_16x16x32_bf16 v[76:79], v[132:135], v[216:219], v[76:79]
	v_mfma_f32_16x16x32_bf16 v[72:75], v[140:143], v[216:219], v[72:75]
	s_setprio 0
	s_setprio 1
	v_mfma_f32_16x16x32_bf16 v[116:119], v[144:147], v[180:183], v[116:119]
	v_mfma_f32_16x16x32_bf16 v[112:115], v[172:175], v[180:183], v[112:115]
	v_mfma_f32_16x16x32_bf16 v[100:103], v[144:147], v[196:199], v[100:103]
	v_mfma_f32_16x16x32_bf16 v[96:99], v[172:175], v[196:199], v[96:99]
	v_mfma_f32_16x16x32_bf16 v[84:87], v[144:147], v[204:207], v[84:87]
	v_mfma_f32_16x16x32_bf16 v[80:83], v[172:175], v[204:207], v[80:83]
	v_mfma_f32_16x16x32_bf16 v[68:71], v[144:147], v[212:215], v[68:71]
	v_mfma_f32_16x16x32_bf16 v[64:67], v[172:175], v[212:215], v[64:67]
	v_mfma_f32_16x16x32_bf16 v[116:119], v[148:151], v[192:195], v[116:119]
	v_mfma_f32_16x16x32_bf16 v[112:115], v[176:179], v[192:195], v[112:115]
	v_mfma_f32_16x16x32_bf16 v[100:103], v[148:151], v[200:203], v[100:103]
	v_mfma_f32_16x16x32_bf16 v[96:99], v[176:179], v[200:203], v[96:99]
	v_mfma_f32_16x16x32_bf16 v[84:87], v[148:151], v[208:211], v[84:87]
	v_mfma_f32_16x16x32_bf16 v[80:83], v[176:179], v[208:211], v[80:83]
	v_mfma_f32_16x16x32_bf16 v[68:71], v[148:151], v[216:219], v[68:71]
	v_mfma_f32_16x16x32_bf16 v[64:67], v[176:179], v[216:219], v[64:67]
	s_setprio 0
	s_barrier
	s_add_i32 s62, s81, s66
	v_lshl_add_u64 v[220:221], v[220:221], 0, s[26:27]
	s_mov_b32 m0, s62
	ds_read_b128 v[180:183], v190 offset:49152
	ds_read_b128 v[192:195], v190 offset:50176
	ds_read_b128 v[196:199], v190 offset:51200
	ds_read_b128 v[200:203], v190 offset:52224
	ds_read_b128 v[204:207], v190 offset:53248
	ds_read_b128 v[208:211], v190 offset:54272
	ds_read_b128 v[212:215], v190 offset:55296
	ds_read_b128 v[216:219], v190 offset:56320
	global_load_lds_dwordx4 v[220:221], off
	s_add_i32 m0, s62, 0x2000
	s_add_u32 s60, s60, 0x40080
	v_lshl_add_u64 v[220:221], v[222:223], 0, s[26:27]
	s_addc_u32 s61, s61, 0
	s_add_i32 s62, s82, s66
	global_load_lds_dwordx4 v[220:221], off
	v_lshl_add_u64 v[220:221], s[60:61], 0, v[154:155]
	s_mov_b32 m0, s62
	s_nop 0
	global_load_lds_dwordx4 v[220:221], off
	v_lshl_add_u64 v[220:221], s[60:61], 0, v[162:163]
	s_add_i32 m0, s62, 0x2000
	s_nop 0
	global_load_lds_dwordx4 v[220:221], off
	v_lshl_add_u64 v[220:221], v[224:225], 0, s[26:27]
	s_mov_b32 m0, s3
	s_nop 0
	global_load_lds_dwordx4 v[220:221], off
	v_lshl_add_u64 v[220:221], v[226:227], 0, s[26:27]
	s_mov_b32 m0, s72
	s_nop 0
	global_load_lds_dwordx4 v[220:221], off
	s_waitcnt vmcnt(8)
	s_waitcnt lgkmcnt(0)
	s_barrier
	s_setprio 1
	s_waitcnt lgkmcnt(0)
	v_mfma_f32_16x16x32_bf16 v[60:63], v[128:131], v[180:183], v[60:63]
	v_mfma_f32_16x16x32_bf16 v[56:59], v[136:139], v[180:183], v[56:59]
	v_mfma_f32_16x16x32_bf16 v[44:47], v[128:131], v[196:199], v[44:47]
	v_mfma_f32_16x16x32_bf16 v[40:43], v[136:139], v[196:199], v[40:43]
	v_mfma_f32_16x16x32_bf16 v[28:31], v[128:131], v[204:207], v[28:31]
	v_mfma_f32_16x16x32_bf16 v[24:27], v[136:139], v[204:207], v[24:27]
	v_mfma_f32_16x16x32_bf16 v[12:15], v[128:131], v[212:215], v[12:15]
	v_mfma_f32_16x16x32_bf16 v[8:11], v[136:139], v[212:215], v[8:11]
	v_mfma_f32_16x16x32_bf16 v[60:63], v[132:135], v[192:195], v[60:63]
	v_mfma_f32_16x16x32_bf16 v[56:59], v[140:143], v[192:195], v[56:59]
	v_mfma_f32_16x16x32_bf16 v[44:47], v[132:135], v[200:203], v[44:47]
	v_mfma_f32_16x16x32_bf16 v[40:43], v[140:143], v[200:203], v[40:43]
	v_mfma_f32_16x16x32_bf16 v[28:31], v[132:135], v[208:211], v[28:31]
	v_mfma_f32_16x16x32_bf16 v[24:27], v[140:143], v[208:211], v[24:27]
	v_mfma_f32_16x16x32_bf16 v[12:15], v[132:135], v[216:219], v[12:15]
	v_mfma_f32_16x16x32_bf16 v[8:11], v[140:143], v[216:219], v[8:11]
	s_setprio 0
	s_setprio 1
	v_mfma_f32_16x16x32_bf16 v[52:55], v[144:147], v[180:183], v[52:55]
	v_mfma_f32_16x16x32_bf16 v[48:51], v[172:175], v[180:183], v[48:51]
	v_mfma_f32_16x16x32_bf16 v[36:39], v[144:147], v[196:199], v[36:39]
	v_mfma_f32_16x16x32_bf16 v[32:35], v[172:175], v[196:199], v[32:35]
	v_mfma_f32_16x16x32_bf16 v[20:23], v[144:147], v[204:207], v[20:23]
	v_mfma_f32_16x16x32_bf16 v[16:19], v[172:175], v[204:207], v[16:19]
	v_mfma_f32_16x16x32_bf16 v[4:7], v[144:147], v[212:215], v[4:7]
	v_mfma_f32_16x16x32_bf16 v[0:3], v[172:175], v[212:215], v[0:3]
	v_mfma_f32_16x16x32_bf16 v[52:55], v[148:151], v[192:195], v[52:55]
	v_mfma_f32_16x16x32_bf16 v[48:51], v[176:179], v[192:195], v[48:51]
	v_mfma_f32_16x16x32_bf16 v[36:39], v[148:151], v[200:203], v[36:39]
	v_mfma_f32_16x16x32_bf16 v[32:35], v[176:179], v[200:203], v[32:35]
	v_mfma_f32_16x16x32_bf16 v[20:23], v[148:151], v[208:211], v[20:23]
	v_mfma_f32_16x16x32_bf16 v[16:19], v[176:179], v[208:211], v[16:19]
	v_mfma_f32_16x16x32_bf16 v[4:7], v[148:151], v[216:219], v[4:7]
	v_mfma_f32_16x16x32_bf16 v[0:3], v[176:179], v[216:219], v[0:3]
	s_setprio 0
	s_barrier
	s_add_i32 s80, s80, 2
	s_add_u32 s78, s78, 0x100
	s_addc_u32 s79, s79, 0
	s_add_u32 s58, s58, 0x100
	s_addc_u32 s59, s59, 0
	s_cmp_gt_u32 s80, 13
	s_branch .LBB0_1011
.Lfa_9:
	ds_read_b128 v[128:131], v188
	ds_read_b128 v[132:135], v188 offset:1024
	ds_read_b128 v[136:139], v188 offset:2048
	ds_read_b128 v[140:143], v188 offset:3072
	ds_read_b128 v[144:147], v189
	ds_read_b128 v[148:151], v189 offset:1024
	ds_read_b128 v[172:175], v189 offset:2048
	ds_read_b128 v[176:179], v189 offset:3072
	s_add_u32 s60, s58, 0xfffc0080
	s_addc_u32 s61, s59, -1
	s_cmp_eq_u32 s80, 12
	s_cselect_b32 s63, s15, s61
	s_cselect_b32 s62, s51, s60
	s_cselect_b32 s61, s49, s79
	s_cselect_b32 s60, s57, s78
	v_lshl_add_u64 v[220:221], s[58:59], 0, v[166:167]
	s_add_i32 m0, s67, 0xc000
	ds_read_b128 v[180:183], v190
	ds_read_b128 v[192:195], v190 offset:1024
	ds_read_b128 v[196:199], v190 offset:2048
	ds_read_b128 v[200:203], v190 offset:3072
	ds_read_b128 v[204:207], v190 offset:4096
	ds_read_b128 v[208:211], v190 offset:5120
	ds_read_b128 v[212:215], v190 offset:6144
	ds_read_b128 v[216:219], v190 offset:7168
	global_load_lds_dwordx4 v[220:221], off
	v_lshl_add_u64 v[220:221], s[58:59], 0, v[164:165]
	s_add_i32 m0, s67, 0xe000
	s_nop 0
	global_load_lds_dwordx4 v[220:221], off
	s_waitcnt vmcnt(8)
	s_waitcnt lgkmcnt(0)
	s_barrier
	s_setprio 1
	s_waitcnt lgkmcnt(0)
	v_mfma_f32_16x16x32_bf16 v[124:127], v[128:131], v[180:183], 0
	v_mfma_f32_16x16x32_bf16 v[120:123], v[136:139], v[180:183], 0
	v_mfma_f32_16x16x32_bf16 v[108:111], v[128:131], v[196:199], 0
	v_mfma_f32_16x16x32_bf16 v[104:107], v[136:139], v[196:199], 0
	v_mfma_f32_16x16x32_bf16 v[92:95], v[128:131], v[204:207], 0
	v_mfma_f32_16x16x32_bf16 v[88:91], v[136:139], v[204:207], 0
	v_mfma_f32_16x16x32_bf16 v[76:79], v[128:131], v[212:215], 0
	v_mfma_f32_16x16x32_bf16 v[72:75], v[136:139], v[212:215], 0
	v_mfma_f32_16x16x32_bf16 v[124:127], v[132:135], v[192:195], v[124:127]
	v_mfma_f32_16x16x32_bf16 v[120:123], v[140:143], v[192:195], v[120:123]
	v_mfma_f32_16x16x32_bf16 v[108:111], v[132:135], v[200:203], v[108:111]
	v_mfma_f32_16x16x32_bf16 v[104:107], v[140:143], v[200:203], v[104:107]
	v_mfma_f32_16x16x32_bf16 v[92:95], v[132:135], v[208:211], v[92:95]
	v_mfma_f32_16x16x32_bf16 v[88:91], v[140:143], v[208:211], v[88:91]
	v_mfma_f32_16x16x32_bf16 v[76:79], v[132:135], v[216:219], v[76:79]
	v_mfma_f32_16x16x32_bf16 v[72:75], v[140:143], v[216:219], v[72:75]
	s_setprio 0
	s_setprio 1
	v_mfma_f32_16x16x32_bf16 v[116:119], v[144:147], v[180:183], 0
	v_mfma_f32_16x16x32_bf16 v[112:115], v[172:175], v[180:183], 0
	v_mfma_f32_16x16x32_bf16 v[100:103], v[144:147], v[196:199], 0
	v_mfma_f32_16x16x32_bf16 v[96:99], v[172:175], v[196:199], 0
	v_mfma_f32_16x16x32_bf16 v[84:87], v[144:147], v[204:207], 0
	v_mfma_f32_16x16x32_bf16 v[80:83], v[172:175], v[204:207], 0
	v_mfma_f32_16x16x32_bf16 v[68:71], v[144:147], v[212:215], 0
	v_mfma_f32_16x16x32_bf16 v[64:67], v[172:175], v[212:215], 0
	v_mfma_f32_16x16x32_bf16 v[116:119], v[148:151], v[192:195], v[116:119]
	v_mfma_f32_16x16x32_bf16 v[112:115], v[176:179], v[192:195], v[112:115]
	v_mfma_f32_16x16x32_bf16 v[100:103], v[148:151], v[200:203], v[100:103]
	v_mfma_f32_16x16x32_bf16 v[96:99], v[176:179], v[200:203], v[96:99]
	v_mfma_f32_16x16x32_bf16 v[84:87], v[148:151], v[208:211], v[84:87]
	v_mfma_f32_16x16x32_bf16 v[80:83], v[176:179], v[208:211], v[80:83]
	v_mfma_f32_16x16x32_bf16 v[68:71], v[148:151], v[216:219], v[68:71]
	v_mfma_f32_16x16x32_bf16 v[64:67], v[176:179], v[216:219], v[64:67]
	s_setprio 0
	s_barrier
	s_add_i32 s81, s76, s66
	v_lshl_add_u64 v[220:221], s[60:61], 0, v[154:155]
	s_mov_b32 m0, s81
	ds_read_b128 v[180:183], v190 offset:16384
	ds_read_b128 v[192:195], v190 offset:17408
	ds_read_b128 v[196:199], v190 offset:18432
	ds_read_b128 v[200:203], v190 offset:19456
	ds_read_b128 v[204:207], v190 offset:20480
	ds_read_b128 v[208:211], v190 offset:21504
	ds_read_b128 v[212:215], v190 offset:22528
	ds_read_b128 v[216:219], v190 offset:23552
	global_load_lds_dwordx4 v[220:221], off
	s_add_i32 m0, s81, 0x2000
	s_add_u32 s82, s60, 0x40000
	v_lshl_add_u64 v[222:223], s[60:61], 0, v[162:163]
	s_addc_u32 s83, s61, 0
	s_add_i32 s81, s77, s66
	global_load_lds_dwordx4 v[222:223], off
	v_lshl_add_u64 v[224:225], s[82:83], 0, v[154:155]
	s_mov_b32 m0, s81
	v_lshl_add_u64 v[226:227], s[62:63], 0, v[160:161]
	global_load_lds_dwordx4 v[224:225], off
	v_lshl_add_u64 v[224:225], s[82:83], 0, v[162:163]
	s_add_i32 m0, s81, 0x2000
	s_nop 0
	global_load_lds_dwordx4 v[224:225], off
	v_lshl_add_u64 v[224:225], s[62:63], 0, v[152:153]
	s_mov_b32 m0, s67
	s_nop 0
	global_load_lds_dwordx4 v[224:225], off
	s_mov_b32 m0, s68
	s_nop 0
	global_load_lds_dwordx4 v[226:227], off
	s_waitcnt vmcnt(8)
	s_waitcnt lgkmcnt(0)
	s_barrier
	s_setprio 1
	s_waitcnt lgkmcnt(0)
	v_mfma_f32_16x16x32_bf16 v[60:63], v[128:131], v[180:183], 0
	v_mfma_f32_16x16x32_bf16 v[56:59], v[136:139], v[180:183], 0
	v_mfma_f32_16x16x32_bf16 v[44:47], v[128:131], v[196:199], 0
	v_mfma_f32_16x16x32_bf16 v[40:43], v[136:139], v[196:199], 0
	v_mfma_f32_16x16x32_bf16 v[28:31], v[128:131], v[204:207], 0
	v_mfma_f32_16x16x32_bf16 v[24:27], v[136:139], v[204:207], 0
	v_mfma_f32_16x16x32_bf16 v[12:15], v[128:131], v[212:215], 0
	v_mfma_f32_16x16x32_bf16 v[8:11], v[136:139], v[212:215], 0
	v_mfma_f32_16x16x32_bf16 v[60:63], v[132:135], v[192:195], v[60:63]
	v_mfma_f32_16x16x32_bf16 v[56:59], v[140:143], v[192:195], v[56:59]
	v_mfma_f32_16x16x32_bf16 v[44:47], v[132:135], v[200:203], v[44:47]
	v_mfma_f32_16x16x32_bf16 v[40:43], v[140:143], v[200:203], v[40:43]
	v_mfma_f32_16x16x32_bf16 v[28:31], v[132:135], v[208:211], v[28:31]
	v_mfma_f32_16x16x32_bf16 v[24:27], v[140:143], v[208:211], v[24:27]
	v_mfma_f32_16x16x32_bf16 v[12:15], v[132:135], v[216:219], v[12:15]
	v_mfma_f32_16x16x32_bf16 v[8:11], v[140:143], v[216:219], v[8:11]
	s_setprio 0
	s_setprio 1
	v_mfma_f32_16x16x32_bf16 v[52:55], v[144:147], v[180:183], 0
	v_mfma_f32_16x16x32_bf16 v[48:51], v[172:175], v[180:183], 0
	v_mfma_f32_16x16x32_bf16 v[36:39], v[144:147], v[196:199], 0
	v_mfma_f32_16x16x32_bf16 v[32:35], v[172:175], v[196:199], 0
	v_mfma_f32_16x16x32_bf16 v[20:23], v[144:147], v[204:207], 0
	v_mfma_f32_16x16x32_bf16 v[16:19], v[172:175], v[204:207], 0
	v_mfma_f32_16x16x32_bf16 v[4:7], v[144:147], v[212:215], 0
	v_mfma_f32_16x16x32_bf16 v[0:3], v[172:175], v[212:215], 0
	v_mfma_f32_16x16x32_bf16 v[52:55], v[148:151], v[192:195], v[52:55]
	v_mfma_f32_16x16x32_bf16 v[48:51], v[176:179], v[192:195], v[48:51]
	v_mfma_f32_16x16x32_bf16 v[36:39], v[148:151], v[200:203], v[36:39]
	v_mfma_f32_16x16x32_bf16 v[32:35], v[176:179], v[200:203], v[32:35]
	v_mfma_f32_16x16x32_bf16 v[20:23], v[148:151], v[208:211], v[20:23]
	v_mfma_f32_16x16x32_bf16 v[16:19], v[176:179], v[208:211], v[16:19]
	v_mfma_f32_16x16x32_bf16 v[4:7], v[148:151], v[216:219], v[4:7]
	v_mfma_f32_16x16x32_bf16 v[0:3], v[176:179], v[216:219], v[0:3]
	s_setprio 0
	s_barrier
	s_add_i32 s81, 0, 0x18000
	s_add_i32 s82, 0, 0x1c000
	v_add_u32_e32 v140, s81, v185
	v_add_u32_e32 v176, s82, v185
	ds_read_b128 v[128:131], v140
	ds_read_b128 v[132:135], v140 offset:1024
	ds_read_b128 v[136:139], v140 offset:2048
	ds_read_b128 v[140:143], v140 offset:3072
	ds_read_b128 v[144:147], v176
	ds_read_b128 v[148:151], v176 offset:1024
	ds_read_b128 v[172:175], v176 offset:2048
	ds_read_b128 v[176:179], v176 offset:3072
	s_add_u32 s62, s62, 0x40000
	s_addc_u32 s63, s63, 0
	s_mov_b32 m0, s69
	v_lshl_add_u64 v[228:229], s[62:63], 0, v[152:153]
	ds_read_b128 v[180:183], v190 offset:32768
	ds_read_b128 v[192:195], v190 offset:33792
	ds_read_b128 v[196:199], v190 offset:34816
	ds_read_b128 v[200:203], v190 offset:35840
	ds_read_b128 v[204:207], v190 offset:36864
	ds_read_b128 v[208:211], v190 offset:37888
	ds_read_b128 v[212:215], v190 offset:38912
	ds_read_b128 v[216:219], v190 offset:39936
	global_load_lds_dwordx4 v[228:229], off
	v_lshl_add_u64 v[228:229], s[62:63], 0, v[160:161]
	s_mov_b32 m0, s70
	s_nop 0
	global_load_lds_dwordx4 v[228:229], off
	s_waitcnt vmcnt(8)
	s_waitcnt lgkmcnt(0)
	s_barrier
	s_setprio 1
	s_waitcnt lgkmcnt(0)
	v_mfma_f32_16x16x32_bf16 v[124:127], v[128:131], v[180:183], v[124:127]
	v_mfma_f32_16x16x32_bf16 v[120:123], v[136:139], v[180:183], v[120:123]
	v_mfma_f32_16x16x32_bf16 v[108:111], v[128:131], v[196:199], v[108:111]
	v_mfma_f32_16x16x32_bf16 v[104:107], v[136:139], v[196:199], v[104:107]
	v_mfma_f32_16x16x32_bf16 v[92:95], v[128:131], v[204:207], v[92:95]
	v_mfma_f32_16x16x32_bf16 v[88:91], v[136:139], v[204:207], v[88:91]
	v_mfma_f32_16x16x32_bf16 v[76:79], v[128:131], v[212:215], v[76:79]
	v_mfma_f32_16x16x32_bf16 v[72:75], v[136:139], v[212:215], v[72:75]
	v_mfma_f32_16x16x32_bf16 v[124:127], v[132:135], v[192:195], v[124:127]
	v_mfma_f32_16x16x32_bf16 v[120:123], v[140:143], v[192:195], v[120:123]
	v_mfma_f32_16x16x32_bf16 v[108:111], v[132:135], v[200:203], v[108:111]
	v_mfma_f32_16x16x32_bf16 v[104:107], v[140:143], v[200:203], v[104:107]
	v_mfma_f32_16x16x32_bf16 v[92:95], v[132:135], v[208:211], v[92:95]
	v_mfma_f32_16x16x32_bf16 v[88:91], v[140:143], v[208:211], v[88:91]
	v_mfma_f32_16x16x32_bf16 v[76:79], v[132:135], v[216:219], v[76:79]
	v_mfma_f32_16x16x32_bf16 v[72:75], v[140:143], v[216:219], v[72:75]
	s_setprio 0
	s_setprio 1
	v_mfma_f32_16x16x32_bf16 v[116:119], v[144:147], v[180:183], v[116:119]
	v_mfma_f32_16x16x32_bf16 v[112:115], v[172:175], v[180:183], v[112:115]
	v_mfma_f32_16x16x32_bf16 v[100:103], v[144:147], v[196:199], v[100:103]
	v_mfma_f32_16x16x32_bf16 v[96:99], v[172:175], v[196:199], v[96:99]
	v_mfma_f32_16x16x32_bf16 v[84:87], v[144:147], v[204:207], v[84:87]
	v_mfma_f32_16x16x32_bf16 v[80:83], v[172:175], v[204:207], v[80:83]
	v_mfma_f32_16x16x32_bf16 v[68:71], v[144:147], v[212:215], v[68:71]
	v_mfma_f32_16x16x32_bf16 v[64:67], v[172:175], v[212:215], v[64:67]
	v_mfma_f32_16x16x32_bf16 v[116:119], v[148:151], v[192:195], v[116:119]
	v_mfma_f32_16x16x32_bf16 v[112:115], v[176:179], v[192:195], v[112:115]
	v_mfma_f32_16x16x32_bf16 v[100:103], v[148:151], v[200:203], v[100:103]
	v_mfma_f32_16x16x32_bf16 v[96:99], v[176:179], v[200:203], v[96:99]
	v_mfma_f32_16x16x32_bf16 v[84:87], v[148:151], v[208:211], v[84:87]
	v_mfma_f32_16x16x32_bf16 v[80:83], v[176:179], v[208:211], v[80:83]
	v_mfma_f32_16x16x32_bf16 v[68:71], v[148:151], v[216:219], v[68:71]
	v_mfma_f32_16x16x32_bf16 v[64:67], v[176:179], v[216:219], v[64:67]
	s_setprio 0
	s_barrier
	s_add_i32 s62, s81, s66
	v_lshl_add_u64 v[220:221], v[220:221], 0, s[26:27]
	s_mov_b32 m0, s62
	ds_read_b128 v[180:183], v190 offset:49152
	ds_read_b128 v[192:195], v190 offset:50176
	ds_read_b128 v[196:199], v190 offset:51200
	ds_read_b128 v[200:203], v190 offset:52224
	ds_read_b128 v[204:207], v190 offset:53248
	ds_read_b128 v[208:211], v190 offset:54272
	ds_read_b128 v[212:215], v190 offset:55296
	ds_read_b128 v[216:219], v190 offset:56320
	global_load_lds_dwordx4 v[220:221], off
	s_add_i32 m0, s62, 0x2000
	s_add_u32 s60, s60, 0x40080
	v_lshl_add_u64 v[220:221], v[222:223], 0, s[26:27]
	s_addc_u32 s61, s61, 0
	s_add_i32 s62, s82, s66
	global_load_lds_dwordx4 v[220:221], off
	v_lshl_add_u64 v[220:221], s[60:61], 0, v[154:155]
	s_mov_b32 m0, s62
	s_nop 0
	global_load_lds_dwordx4 v[220:221], off
	v_lshl_add_u64 v[220:221], s[60:61], 0, v[162:163]
	s_add_i32 m0, s62, 0x2000
	s_nop 0
	global_load_lds_dwordx4 v[220:221], off
	v_lshl_add_u64 v[220:221], v[224:225], 0, s[26:27]
	s_mov_b32 m0, s3
	s_nop 0
	global_load_lds_dwordx4 v[220:221], off
	v_lshl_add_u64 v[220:221], v[226:227], 0, s[26:27]
	s_mov_b32 m0, s72
	s_nop 0
	global_load_lds_dwordx4 v[220:221], off
	s_waitcnt vmcnt(8)
	s_waitcnt lgkmcnt(0)
	s_barrier
	s_setprio 1
	s_waitcnt lgkmcnt(0)
	v_mfma_f32_16x16x32_bf16 v[60:63], v[128:131], v[180:183], v[60:63]
	v_mfma_f32_16x16x32_bf16 v[56:59], v[136:139], v[180:183], v[56:59]
	v_mfma_f32_16x16x32_bf16 v[44:47], v[128:131], v[196:199], v[44:47]
	v_mfma_f32_16x16x32_bf16 v[40:43], v[136:139], v[196:199], v[40:43]
	v_mfma_f32_16x16x32_bf16 v[28:31], v[128:131], v[204:207], v[28:31]
	v_mfma_f32_16x16x32_bf16 v[24:27], v[136:139], v[204:207], v[24:27]
	v_mfma_f32_16x16x32_bf16 v[12:15], v[128:131], v[212:215], v[12:15]
	v_mfma_f32_16x16x32_bf16 v[8:11], v[136:139], v[212:215], v[8:11]
	v_mfma_f32_16x16x32_bf16 v[60:63], v[132:135], v[192:195], v[60:63]
	v_mfma_f32_16x16x32_bf16 v[56:59], v[140:143], v[192:195], v[56:59]
	v_mfma_f32_16x16x32_bf16 v[44:47], v[132:135], v[200:203], v[44:47]
	v_mfma_f32_16x16x32_bf16 v[40:43], v[140:143], v[200:203], v[40:43]
	v_mfma_f32_16x16x32_bf16 v[28:31], v[132:135], v[208:211], v[28:31]
	v_mfma_f32_16x16x32_bf16 v[24:27], v[140:143], v[208:211], v[24:27]
	v_mfma_f32_16x16x32_bf16 v[12:15], v[132:135], v[216:219], v[12:15]
	v_mfma_f32_16x16x32_bf16 v[8:11], v[140:143], v[216:219], v[8:11]
	s_setprio 0
	s_setprio 1
	v_mfma_f32_16x16x32_bf16 v[52:55], v[144:147], v[180:183], v[52:55]
	v_mfma_f32_16x16x32_bf16 v[48:51], v[172:175], v[180:183], v[48:51]
	v_mfma_f32_16x16x32_bf16 v[36:39], v[144:147], v[196:199], v[36:39]
	v_mfma_f32_16x16x32_bf16 v[32:35], v[172:175], v[196:199], v[32:35]
	v_mfma_f32_16x16x32_bf16 v[20:23], v[144:147], v[204:207], v[20:23]
	v_mfma_f32_16x16x32_bf16 v[16:19], v[172:175], v[204:207], v[16:19]
	v_mfma_f32_16x16x32_bf16 v[4:7], v[144:147], v[212:215], v[4:7]
	v_mfma_f32_16x16x32_bf16 v[0:3], v[172:175], v[212:215], v[0:3]
	v_mfma_f32_16x16x32_bf16 v[52:55], v[148:151], v[192:195], v[52:55]
	v_mfma_f32_16x16x32_bf16 v[48:51], v[176:179], v[192:195], v[48:51]
	v_mfma_f32_16x16x32_bf16 v[36:39], v[148:151], v[200:203], v[36:39]
	v_mfma_f32_16x16x32_bf16 v[32:35], v[176:179], v[200:203], v[32:35]
	v_mfma_f32_16x16x32_bf16 v[20:23], v[148:151], v[208:211], v[20:23]
	v_mfma_f32_16x16x32_bf16 v[16:19], v[176:179], v[208:211], v[16:19]
	v_mfma_f32_16x16x32_bf16 v[4:7], v[148:151], v[216:219], v[4:7]
	v_mfma_f32_16x16x32_bf16 v[0:3], v[176:179], v[216:219], v[0:3]
	s_setprio 0
	s_barrier
	s_add_i32 s80, s80, 2
	s_add_u32 s78, s78, 0x100
	s_addc_u32 s79, s79, 0
	s_add_u32 s58, s58, 0x100
	s_addc_u32 s59, s59, 0
	s_cmp_gt_u32 s80, 13

.LBB0_1096:
	s_ashr_i32 s25, s24, 31
	s_lshl_b64 s[26:27], s[24:25], 19
	s_add_u32 s26, s3, s26
	s_addc_u32 s27, s33, s27
	s_and_b64 s[28:29], s[6:7], exec
	s_cselect_b32 s25, s27, s47
	s_cselect_b32 s65, s26, s46
	s_ashr_i32 s23, s22, 31
	s_lshl_b64 s[28:29], s[22:23], 19
	s_add_u32 s28, s35, s28
	s_addc_u32 s29, s48, s29
	s_and_b64 s[66:67], s[6:7], exec
	s_cselect_b32 s66, s29, s45
	s_cselect_b32 s67, s28, s44
	s_lshl_b32 s23, s30, 8
	v_add_u32_e32 v0, s23, v148
	s_add_u32 s68, s44, 0x100
	v_ashrrev_i32_e32 v1, 31, v0
	s_addc_u32 s69, s45, 0
	v_lshl_add_u64 v[144:145], v[0:1], 4, s[12:13]
	s_add_u32 s30, s46, 0x40080
	s_addc_u32 s31, s47, 0
	s_mov_b32 s70, -2
	s_mov_b64 s[44:45], 0
	s_cmp_eq_u32 s56, 1
	s_cbranch_scc1 .Lfa_10
	v_add_u32_e32 v153, s61, v147
	ds_read_b128 v[160:163], v153
	ds_read_b128 v[164:167], v153 offset:1024
	ds_read_b128 v[168:171], v153 offset:2048
	ds_read_b128 v[172:175], v153 offset:3072
	v_add_u32_e32 v153, s62, v147
	ds_read_b128 v[176:179], v153
	ds_read_b128 v[180:183], v153 offset:1024
	ds_read_b128 v[184:187], v153 offset:2048
	ds_read_b128 v[188:191], v153 offset:3072
	s_add_u32 s46, s30, 0xfffc0080
	s_addc_u32 s47, s31, -1
	s_and_b64 s[44:45], s[44:45], exec
	s_cselect_b32 s47, s25, s47
	s_cselect_b32 s46, s65, s46
	s_cselect_b32 s45, s66, s69
	s_cselect_b32 s44, s67, s68
	v_lshl_add_u64 v[154:155], s[30:31], 0, v[138:139]
	s_add_i32 m0, s52, 0xc000
	ds_read_b128 v[192:195], v150
	ds_read_b128 v[196:199], v150 offset:1024
	ds_read_b128 v[200:203], v150 offset:2048
	ds_read_b128 v[204:207], v150 offset:3072
	ds_read_b128 v[208:211], v150 offset:4096
	ds_read_b128 v[212:215], v150 offset:5120
	ds_read_b128 v[216:219], v150 offset:6144
	ds_read_b128 v[220:223], v150 offset:7168
	global_load_lds_dwordx4 v[154:155], off
	v_lshl_add_u64 v[154:155], s[30:31], 0, v[136:137]
	s_add_i32 m0, s52, 0xe000
	s_nop 0
	global_load_lds_dwordx4 v[154:155], off
	s_waitcnt vmcnt(16)
	s_waitcnt lgkmcnt(0)
	s_barrier
	s_setprio 1
	s_waitcnt lgkmcnt(0)
	v_mfma_f32_16x16x32_bf16 v[124:127], v[160:163], v[192:195], 0
	v_mfma_f32_16x16x32_bf16 v[116:119], v[168:171], v[192:195], 0
	v_mfma_f32_16x16x32_bf16 v[108:111], v[160:163], v[200:203], 0
	v_mfma_f32_16x16x32_bf16 v[100:103], v[168:171], v[200:203], 0
	v_mfma_f32_16x16x32_bf16 v[92:95], v[160:163], v[208:211], 0
	v_mfma_f32_16x16x32_bf16 v[84:87], v[168:171], v[208:211], 0
	v_mfma_f32_16x16x32_bf16 v[76:79], v[160:163], v[216:219], 0
	v_mfma_f32_16x16x32_bf16 v[68:71], v[168:171], v[216:219], 0
	v_mfma_f32_16x16x32_bf16 v[124:127], v[164:167], v[196:199], v[124:127]
	v_mfma_f32_16x16x32_bf16 v[116:119], v[172:175], v[196:199], v[116:119]
	v_mfma_f32_16x16x32_bf16 v[108:111], v[164:167], v[204:207], v[108:111]
	v_mfma_f32_16x16x32_bf16 v[100:103], v[172:175], v[204:207], v[100:103]
	v_mfma_f32_16x16x32_bf16 v[92:95], v[164:167], v[212:215], v[92:95]
	v_mfma_f32_16x16x32_bf16 v[84:87], v[172:175], v[212:215], v[84:87]
	v_mfma_f32_16x16x32_bf16 v[76:79], v[164:167], v[220:223], v[76:79]
	v_mfma_f32_16x16x32_bf16 v[68:71], v[172:175], v[220:223], v[68:71]
	s_setprio 0
	s_setprio 1
	v_mfma_f32_16x16x32_bf16 v[120:123], v[176:179], v[192:195], 0
	v_mfma_f32_16x16x32_bf16 v[112:115], v[184:187], v[192:195], 0
	v_mfma_f32_16x16x32_bf16 v[104:107], v[176:179], v[200:203], 0
	v_mfma_f32_16x16x32_bf16 v[96:99], v[184:187], v[200:203], 0
	v_mfma_f32_16x16x32_bf16 v[88:91], v[176:179], v[208:211], 0
	v_mfma_f32_16x16x32_bf16 v[80:83], v[184:187], v[208:211], 0
	v_mfma_f32_16x16x32_bf16 v[72:75], v[176:179], v[216:219], 0
	v_mfma_f32_16x16x32_bf16 v[64:67], v[184:187], v[216:219], 0
	v_mfma_f32_16x16x32_bf16 v[120:123], v[180:183], v[196:199], v[120:123]
	v_mfma_f32_16x16x32_bf16 v[112:115], v[188:191], v[196:199], v[112:115]
	v_mfma_f32_16x16x32_bf16 v[104:107], v[180:183], v[204:207], v[104:107]
	v_mfma_f32_16x16x32_bf16 v[96:99], v[188:191], v[204:207], v[96:99]
	v_mfma_f32_16x16x32_bf16 v[88:91], v[180:183], v[212:215], v[88:91]
	v_mfma_f32_16x16x32_bf16 v[80:83], v[188:191], v[212:215], v[80:83]
	v_mfma_f32_16x16x32_bf16 v[72:75], v[180:183], v[220:223], v[72:75]
	v_mfma_f32_16x16x32_bf16 v[64:67], v[188:191], v[220:223], v[64:67]
	s_setprio 0
	s_barrier
	s_add_i32 s71, s61, s49
	v_lshl_add_u64 v[154:155], s[44:45], 0, v[132:133]
	s_mov_b32 m0, s71
	ds_read_b128 v[192:195], v150 offset:16384
	ds_read_b128 v[196:199], v150 offset:17408
	ds_read_b128 v[200:203], v150 offset:18432
	ds_read_b128 v[204:207], v150 offset:19456
	ds_read_b128 v[208:211], v150 offset:20480
	ds_read_b128 v[212:215], v150 offset:21504
	ds_read_b128 v[216:219], v150 offset:22528
	ds_read_b128 v[220:223], v150 offset:23552
	global_load_lds_dwordx4 v[154:155], off
	s_add_i32 m0, s71, 0x2000
	s_add_u32 s72, s44, 0x40000
	v_lshl_add_u64 v[224:225], s[44:45], 0, v[128:129]
	s_addc_u32 s73, s45, 0
	s_add_i32 s71, s62, s49
	global_load_lds_dwordx4 v[224:225], off
	v_lshl_add_u64 v[226:227], s[72:73], 0, v[132:133]
	s_mov_b32 m0, s71
	v_lshl_add_u64 v[228:229], s[46:47], 0, v[130:131]
	global_load_lds_dwordx4 v[226:227], off
	v_lshl_add_u64 v[226:227], s[72:73], 0, v[128:129]
	s_add_i32 m0, s71, 0x2000
	s_nop 0
	global_load_lds_dwordx4 v[226:227], off
	v_lshl_add_u64 v[226:227], s[46:47], 0, v[134:135]
	s_mov_b32 m0, s52
	s_nop 0
	global_load_lds_dwordx4 v[226:227], off
	s_mov_b32 m0, s53
	s_nop 0
	global_load_lds_dwordx4 v[228:229], off
	s_waitcnt vmcnt(16)
	s_waitcnt lgkmcnt(0)
	s_barrier
	s_setprio 1
	s_waitcnt lgkmcnt(0)
	v_mfma_f32_16x16x32_bf16 v[60:63], v[160:163], v[192:195], 0
	v_mfma_f32_16x16x32_bf16 v[52:55], v[168:171], v[192:195], 0
	v_mfma_f32_16x16x32_bf16 v[44:47], v[160:163], v[200:203], 0
	v_mfma_f32_16x16x32_bf16 v[36:39], v[168:171], v[200:203], 0
	v_mfma_f32_16x16x32_bf16 v[28:31], v[160:163], v[208:211], 0
	v_mfma_f32_16x16x32_bf16 v[20:23], v[168:171], v[208:211], 0
	v_mfma_f32_16x16x32_bf16 v[12:15], v[160:163], v[216:219], 0
	v_mfma_f32_16x16x32_bf16 v[4:7], v[168:171], v[216:219], 0
	v_mfma_f32_16x16x32_bf16 v[60:63], v[164:167], v[196:199], v[60:63]
	v_mfma_f32_16x16x32_bf16 v[52:55], v[172:175], v[196:199], v[52:55]
	v_mfma_f32_16x16x32_bf16 v[44:47], v[164:167], v[204:207], v[44:47]
	v_mfma_f32_16x16x32_bf16 v[36:39], v[172:175], v[204:207], v[36:39]
	v_mfma_f32_16x16x32_bf16 v[28:31], v[164:167], v[212:215], v[28:31]
	v_mfma_f32_16x16x32_bf16 v[20:23], v[172:175], v[212:215], v[20:23]
	v_mfma_f32_16x16x32_bf16 v[12:15], v[164:167], v[220:223], v[12:15]
	v_mfma_f32_16x16x32_bf16 v[4:7], v[172:175], v[220:223], v[4:7]
	s_setprio 0
	s_setprio 1
	v_mfma_f32_16x16x32_bf16 v[56:59], v[176:179], v[192:195], 0
	v_mfma_f32_16x16x32_bf16 v[48:51], v[184:187], v[192:195], 0
	v_mfma_f32_16x16x32_bf16 v[40:43], v[176:179], v[200:203], 0
	v_mfma_f32_16x16x32_bf16 v[32:35], v[184:187], v[200:203], 0
	v_mfma_f32_16x16x32_bf16 v[24:27], v[176:179], v[208:211], 0
	v_mfma_f32_16x16x32_bf16 v[16:19], v[184:187], v[208:211], 0
	v_mfma_f32_16x16x32_bf16 v[8:11], v[176:179], v[216:219], 0
	v_mfma_f32_16x16x32_bf16 v[0:3], v[184:187], v[216:219], 0
	v_mfma_f32_16x16x32_bf16 v[56:59], v[180:183], v[196:199], v[56:59]
	v_mfma_f32_16x16x32_bf16 v[48:51], v[188:191], v[196:199], v[48:51]
	v_mfma_f32_16x16x32_bf16 v[40:43], v[180:183], v[204:207], v[40:43]
	v_mfma_f32_16x16x32_bf16 v[32:35], v[188:191], v[204:207], v[32:35]
	v_mfma_f32_16x16x32_bf16 v[24:27], v[180:183], v[212:215], v[24:27]
	v_mfma_f32_16x16x32_bf16 v[16:19], v[188:191], v[212:215], v[16:19]
	v_mfma_f32_16x16x32_bf16 v[8:11], v[180:183], v[220:223], v[8:11]
	v_mfma_f32_16x16x32_bf16 v[0:3], v[188:191], v[220:223], v[0:3]
	s_setprio 0
	s_barrier
	s_add_i32 s71, 0, 0x18000
	v_add_u32_e32 v153, s71, v147
	s_add_i32 s72, 0, 0x1c000
	ds_read_b128 v[160:163], v153
	ds_read_b128 v[164:167], v153 offset:1024
	ds_read_b128 v[168:171], v153 offset:2048
	ds_read_b128 v[172:175], v153 offset:3072
	v_add_u32_e32 v153, s72, v147
	ds_read_b128 v[176:179], v153
	ds_read_b128 v[180:183], v153 offset:1024
	ds_read_b128 v[184:187], v153 offset:2048
	ds_read_b128 v[188:191], v153 offset:3072
	s_add_u32 s46, s46, 0x40000
	s_addc_u32 s47, s47, 0
	s_mov_b32 m0, s54
	v_lshl_add_u64 v[230:231], s[46:47], 0, v[134:135]
	ds_read_b128 v[192:195], v150 offset:32768
	ds_read_b128 v[196:199], v150 offset:33792
	ds_read_b128 v[200:203], v150 offset:34816
	ds_read_b128 v[204:207], v150 offset:35840
	ds_read_b128 v[208:211], v150 offset:36864
	ds_read_b128 v[212:215], v150 offset:37888
	ds_read_b128 v[216:219], v150 offset:38912
	ds_read_b128 v[220:223], v150 offset:39936
	global_load_lds_dwordx4 v[230:231], off
	v_lshl_add_u64 v[230:231], s[46:47], 0, v[130:131]
	s_mov_b32 m0, s55
	s_nop 0
	global_load_lds_dwordx4 v[230:231], off
	s_waitcnt vmcnt(8)
	s_waitcnt lgkmcnt(0)
	s_barrier
	s_setprio 1
	s_waitcnt lgkmcnt(0)
	v_mfma_f32_16x16x32_bf16 v[124:127], v[160:163], v[192:195], v[124:127]
	v_mfma_f32_16x16x32_bf16 v[116:119], v[168:171], v[192:195], v[116:119]
	v_mfma_f32_16x16x32_bf16 v[108:111], v[160:163], v[200:203], v[108:111]
	v_mfma_f32_16x16x32_bf16 v[100:103], v[168:171], v[200:203], v[100:103]
	v_mfma_f32_16x16x32_bf16 v[92:95], v[160:163], v[208:211], v[92:95]
	v_mfma_f32_16x16x32_bf16 v[84:87], v[168:171], v[208:211], v[84:87]
	v_mfma_f32_16x16x32_bf16 v[76:79], v[160:163], v[216:219], v[76:79]
	v_mfma_f32_16x16x32_bf16 v[68:71], v[168:171], v[216:219], v[68:71]
	v_mfma_f32_16x16x32_bf16 v[124:127], v[164:167], v[196:199], v[124:127]
	v_mfma_f32_16x16x32_bf16 v[116:119], v[172:175], v[196:199], v[116:119]
	v_mfma_f32_16x16x32_bf16 v[108:111], v[164:167], v[204:207], v[108:111]
	v_mfma_f32_16x16x32_bf16 v[100:103], v[172:175], v[204:207], v[100:103]
	v_mfma_f32_16x16x32_bf16 v[92:95], v[164:167], v[212:215], v[92:95]
	v_mfma_f32_16x16x32_bf16 v[84:87], v[172:175], v[212:215], v[84:87]
	v_mfma_f32_16x16x32_bf16 v[76:79], v[164:167], v[220:223], v[76:79]
	v_mfma_f32_16x16x32_bf16 v[68:71], v[172:175], v[220:223], v[68:71]
	s_setprio 0
	s_setprio 1
	v_mfma_f32_16x16x32_bf16 v[120:123], v[176:179], v[192:195], v[120:123]
	v_mfma_f32_16x16x32_bf16 v[112:115], v[184:187], v[192:195], v[112:115]
	v_mfma_f32_16x16x32_bf16 v[104:107], v[176:179], v[200:203], v[104:107]
	v_mfma_f32_16x16x32_bf16 v[96:99], v[184:187], v[200:203], v[96:99]
	v_mfma_f32_16x16x32_bf16 v[88:91], v[176:179], v[208:211], v[88:91]
	v_mfma_f32_16x16x32_bf16 v[80:83], v[184:187], v[208:211], v[80:83]
	v_mfma_f32_16x16x32_bf16 v[72:75], v[176:179], v[216:219], v[72:75]
	v_mfma_f32_16x16x32_bf16 v[64:67], v[184:187], v[216:219], v[64:67]
	v_mfma_f32_16x16x32_bf16 v[120:123], v[180:183], v[196:199], v[120:123]
	v_mfma_f32_16x16x32_bf16 v[112:115], v[188:191], v[196:199], v[112:115]
	v_mfma_f32_16x16x32_bf16 v[104:107], v[180:183], v[204:207], v[104:107]
	v_mfma_f32_16x16x32_bf16 v[96:99], v[188:191], v[204:207], v[96:99]
	v_mfma_f32_16x16x32_bf16 v[88:91], v[180:183], v[212:215], v[88:91]
	v_mfma_f32_16x16x32_bf16 v[80:83], v[188:191], v[212:215], v[80:83]
	v_mfma_f32_16x16x32_bf16 v[72:75], v[180:183], v[220:223], v[72:75]
	v_mfma_f32_16x16x32_bf16 v[64:67], v[188:191], v[220:223], v[64:67]
	s_setprio 0
	s_barrier
	s_add_i32 s46, s71, s49
	v_lshl_add_u64 v[154:155], v[154:155], 0, s[14:15]
	s_mov_b32 m0, s46
	ds_read_b128 v[192:195], v150 offset:49152
	ds_read_b128 v[196:199], v150 offset:50176
	ds_read_b128 v[200:203], v150 offset:51200
	ds_read_b128 v[204:207], v150 offset:52224
	ds_read_b128 v[208:211], v150 offset:53248
	ds_read_b128 v[212:215], v150 offset:54272
	ds_read_b128 v[216:219], v150 offset:55296
	ds_read_b128 v[220:223], v150 offset:56320
	global_load_lds_dwordx4 v[154:155], off
	s_add_i32 m0, s46, 0x2000
	s_add_u32 s44, s44, 0x40080
	v_lshl_add_u64 v[154:155], v[224:225], 0, s[14:15]
	s_addc_u32 s45, s45, 0
	s_add_i32 s46, s72, s49
	global_load_lds_dwordx4 v[154:155], off
	v_lshl_add_u64 v[154:155], s[44:45], 0, v[132:133]
	s_mov_b32 m0, s46
	s_nop 0
	global_load_lds_dwordx4 v[154:155], off
	v_lshl_add_u64 v[154:155], s[44:45], 0, v[128:129]
	s_add_i32 m0, s46, 0x2000
	s_nop 0
	global_load_lds_dwordx4 v[154:155], off
	v_lshl_add_u64 v[154:155], v[226:227], 0, s[14:15]
	s_mov_b32 m0, s57
	s_nop 0
	global_load_lds_dwordx4 v[154:155], off
	v_lshl_add_u64 v[154:155], v[228:229], 0, s[14:15]
	s_mov_b32 m0, s58
	s_nop 0
	global_load_lds_dwordx4 v[154:155], off
	s_waitcnt vmcnt(8)
	s_waitcnt lgkmcnt(0)
	s_barrier
	s_setprio 1
	s_waitcnt lgkmcnt(0)
	v_mfma_f32_16x16x32_bf16 v[60:63], v[160:163], v[192:195], v[60:63]
	v_mfma_f32_16x16x32_bf16 v[52:55], v[168:171], v[192:195], v[52:55]
	v_mfma_f32_16x16x32_bf16 v[44:47], v[160:163], v[200:203], v[44:47]
	v_mfma_f32_16x16x32_bf16 v[36:39], v[168:171], v[200:203], v[36:39]
	v_mfma_f32_16x16x32_bf16 v[28:31], v[160:163], v[208:211], v[28:31]
	v_mfma_f32_16x16x32_bf16 v[20:23], v[168:171], v[208:211], v[20:23]
	v_mfma_f32_16x16x32_bf16 v[12:15], v[160:163], v[216:219], v[12:15]
	v_mfma_f32_16x16x32_bf16 v[4:7], v[168:171], v[216:219], v[4:7]
	v_mfma_f32_16x16x32_bf16 v[60:63], v[164:167], v[196:199], v[60:63]
	v_mfma_f32_16x16x32_bf16 v[52:55], v[172:175], v[196:199], v[52:55]
	v_mfma_f32_16x16x32_bf16 v[44:47], v[164:167], v[204:207], v[44:47]
	v_mfma_f32_16x16x32_bf16 v[36:39], v[172:175], v[204:207], v[36:39]
	v_mfma_f32_16x16x32_bf16 v[28:31], v[164:167], v[212:215], v[28:31]
	v_mfma_f32_16x16x32_bf16 v[20:23], v[172:175], v[212:215], v[20:23]
	v_mfma_f32_16x16x32_bf16 v[12:15], v[164:167], v[220:223], v[12:15]
	v_mfma_f32_16x16x32_bf16 v[4:7], v[172:175], v[220:223], v[4:7]
	s_setprio 0
	s_setprio 1
	v_mfma_f32_16x16x32_bf16 v[56:59], v[176:179], v[192:195], v[56:59]
	v_mfma_f32_16x16x32_bf16 v[48:51], v[184:187], v[192:195], v[48:51]
	v_mfma_f32_16x16x32_bf16 v[40:43], v[176:179], v[200:203], v[40:43]
	v_mfma_f32_16x16x32_bf16 v[32:35], v[184:187], v[200:203], v[32:35]
	v_mfma_f32_16x16x32_bf16 v[24:27], v[176:179], v[208:211], v[24:27]
	v_mfma_f32_16x16x32_bf16 v[16:19], v[184:187], v[208:211], v[16:19]
	v_mfma_f32_16x16x32_bf16 v[8:11], v[176:179], v[216:219], v[8:11]
	v_mfma_f32_16x16x32_bf16 v[0:3], v[184:187], v[216:219], v[0:3]
	v_mfma_f32_16x16x32_bf16 v[56:59], v[180:183], v[196:199], v[56:59]
	v_mfma_f32_16x16x32_bf16 v[48:51], v[188:191], v[196:199], v[48:51]
	v_mfma_f32_16x16x32_bf16 v[40:43], v[180:183], v[204:207], v[40:43]
	v_mfma_f32_16x16x32_bf16 v[32:35], v[188:191], v[204:207], v[32:35]
	v_mfma_f32_16x16x32_bf16 v[24:27], v[180:183], v[212:215], v[24:27]
	v_mfma_f32_16x16x32_bf16 v[16:19], v[188:191], v[212:215], v[16:19]
	v_mfma_f32_16x16x32_bf16 v[8:11], v[180:183], v[220:223], v[8:11]
	v_mfma_f32_16x16x32_bf16 v[0:3], v[188:191], v[220:223], v[0:3]
	s_setprio 0
	s_barrier
	s_add_i32 s70, s70, 2
	s_add_u32 s68, s68, 0x100
	s_addc_u32 s69, s69, 0
	s_add_u32 s30, s30, 0x100
	s_addc_u32 s31, s31, 0
	s_branch .LBB0_1098
.Lfa_10:
	v_add_u32_e32 v153, s61, v147
	ds_read_b128 v[160:163], v153
	ds_read_b128 v[164:167], v153 offset:1024
	ds_read_b128 v[168:171], v153 offset:2048
	ds_read_b128 v[172:175], v153 offset:3072
	v_add_u32_e32 v153, s62, v147
	ds_read_b128 v[176:179], v153
	ds_read_b128 v[180:183], v153 offset:1024
	ds_read_b128 v[184:187], v153 offset:2048
	ds_read_b128 v[188:191], v153 offset:3072
	s_add_u32 s46, s30, 0xfffc0080
	s_addc_u32 s47, s31, -1
	s_and_b64 s[44:45], s[44:45], exec
	s_cselect_b32 s47, s25, s47
	s_cselect_b32 s46, s65, s46
	s_cselect_b32 s45, s66, s69
	s_cselect_b32 s44, s67, s68
	v_lshl_add_u64 v[154:155], s[30:31], 0, v[138:139]
	s_add_i32 m0, s52, 0xc000
	ds_read_b128 v[192:195], v150
	ds_read_b128 v[196:199], v150 offset:1024
	ds_read_b128 v[200:203], v150 offset:2048
	ds_read_b128 v[204:207], v150 offset:3072
	ds_read_b128 v[208:211], v150 offset:4096
	ds_read_b128 v[212:215], v150 offset:5120
	ds_read_b128 v[216:219], v150 offset:6144
	ds_read_b128 v[220:223], v150 offset:7168
	global_load_lds_dwordx4 v[154:155], off
	v_lshl_add_u64 v[154:155], s[30:31], 0, v[136:137]
	s_add_i32 m0, s52, 0xe000
	s_nop 0
	global_load_lds_dwordx4 v[154:155], off
	s_waitcnt vmcnt(8)
	s_waitcnt lgkmcnt(0)
	s_barrier
	s_setprio 1
	s_waitcnt lgkmcnt(0)
	v_mfma_f32_16x16x32_bf16 v[124:127], v[160:163], v[192:195], 0
	v_mfma_f32_16x16x32_bf16 v[116:119], v[168:171], v[192:195], 0
	v_mfma_f32_16x16x32_bf16 v[108:111], v[160:163], v[200:203], 0
	v_mfma_f32_16x16x32_bf16 v[100:103], v[168:171], v[200:203], 0
	v_mfma_f32_16x16x32_bf16 v[92:95], v[160:163], v[208:211], 0
	v_mfma_f32_16x16x32_bf16 v[84:87], v[168:171], v[208:211], 0
	v_mfma_f32_16x16x32_bf16 v[76:79], v[160:163], v[216:219], 0
	v_mfma_f32_16x16x32_bf16 v[68:71], v[168:171], v[216:219], 0
	v_mfma_f32_16x16x32_bf16 v[124:127], v[164:167], v[196:199], v[124:127]
	v_mfma_f32_16x16x32_bf16 v[116:119], v[172:175], v[196:199], v[116:119]
	v_mfma_f32_16x16x32_bf16 v[108:111], v[164:167], v[204:207], v[108:111]
	v_mfma_f32_16x16x32_bf16 v[100:103], v[172:175], v[204:207], v[100:103]
	v_mfma_f32_16x16x32_bf16 v[92:95], v[164:167], v[212:215], v[92:95]
	v_mfma_f32_16x16x32_bf16 v[84:87], v[172:175], v[212:215], v[84:87]
	v_mfma_f32_16x16x32_bf16 v[76:79], v[164:167], v[220:223], v[76:79]
	v_mfma_f32_16x16x32_bf16 v[68:71], v[172:175], v[220:223], v[68:71]
	s_setprio 0
	s_setprio 1
	v_mfma_f32_16x16x32_bf16 v[120:123], v[176:179], v[192:195], 0
	v_mfma_f32_16x16x32_bf16 v[112:115], v[184:187], v[192:195], 0
	v_mfma_f32_16x16x32_bf16 v[104:107], v[176:179], v[200:203], 0
	v_mfma_f32_16x16x32_bf16 v[96:99], v[184:187], v[200:203], 0
	v_mfma_f32_16x16x32_bf16 v[88:91], v[176:179], v[208:211], 0
	v_mfma_f32_16x16x32_bf16 v[80:83], v[184:187], v[208:211], 0
	v_mfma_f32_16x16x32_bf16 v[72:75], v[176:179], v[216:219], 0
	v_mfma_f32_16x16x32_bf16 v[64:67], v[184:187], v[216:219], 0
	v_mfma_f32_16x16x32_bf16 v[120:123], v[180:183], v[196:199], v[120:123]
	v_mfma_f32_16x16x32_bf16 v[112:115], v[188:191], v[196:199], v[112:115]
	v_mfma_f32_16x16x32_bf16 v[104:107], v[180:183], v[204:207], v[104:107]
	v_mfma_f32_16x16x32_bf16 v[96:99], v[188:191], v[204:207], v[96:99]
	v_mfma_f32_16x16x32_bf16 v[88:91], v[180:183], v[212:215], v[88:91]
	v_mfma_f32_16x16x32_bf16 v[80:83], v[188:191], v[212:215], v[80:83]
	v_mfma_f32_16x16x32_bf16 v[72:75], v[180:183], v[220:223], v[72:75]
	v_mfma_f32_16x16x32_bf16 v[64:67], v[188:191], v[220:223], v[64:67]
	s_setprio 0
	s_barrier
	s_add_i32 s71, s61, s49
	v_lshl_add_u64 v[154:155], s[44:45], 0, v[132:133]
	s_mov_b32 m0, s71
	ds_read_b128 v[192:195], v150 offset:16384
	ds_read_b128 v[196:199], v150 offset:17408
	ds_read_b128 v[200:203], v150 offset:18432
	ds_read_b128 v[204:207], v150 offset:19456
	ds_read_b128 v[208:211], v150 offset:20480
	ds_read_b128 v[212:215], v150 offset:21504
	ds_read_b128 v[216:219], v150 offset:22528
	ds_read_b128 v[220:223], v150 offset:23552
	global_load_lds_dwordx4 v[154:155], off
	s_add_i32 m0, s71, 0x2000
	s_add_u32 s72, s44, 0x40000
	v_lshl_add_u64 v[224:225], s[44:45], 0, v[128:129]
	s_addc_u32 s73, s45, 0
	s_add_i32 s71, s62, s49
	global_load_lds_dwordx4 v[224:225], off
	v_lshl_add_u64 v[226:227], s[72:73], 0, v[132:133]
	s_mov_b32 m0, s71
	v_lshl_add_u64 v[228:229], s[46:47], 0, v[130:131]
	global_load_lds_dwordx4 v[226:227], off
	v_lshl_add_u64 v[226:227], s[72:73], 0, v[128:129]
	s_add_i32 m0, s71, 0x2000
	s_nop 0
	global_load_lds_dwordx4 v[226:227], off
	v_lshl_add_u64 v[226:227], s[46:47], 0, v[134:135]
	s_mov_b32 m0, s52
	s_nop 0
	global_load_lds_dwordx4 v[226:227], off
	s_mov_b32 m0, s53
	s_nop 0
	global_load_lds_dwordx4 v[228:229], off
	s_waitcnt vmcnt(8)
	s_waitcnt lgkmcnt(0)
	s_barrier
	s_setprio 1
	s_waitcnt lgkmcnt(0)
	v_mfma_f32_16x16x32_bf16 v[60:63], v[160:163], v[192:195], 0
	v_mfma_f32_16x16x32_bf16 v[52:55], v[168:171], v[192:195], 0
	v_mfma_f32_16x16x32_bf16 v[44:47], v[160:163], v[200:203], 0
	v_mfma_f32_16x16x32_bf16 v[36:39], v[168:171], v[200:203], 0
	v_mfma_f32_16x16x32_bf16 v[28:31], v[160:163], v[208:211], 0
	v_mfma_f32_16x16x32_bf16 v[20:23], v[168:171], v[208:211], 0
	v_mfma_f32_16x16x32_bf16 v[12:15], v[160:163], v[216:219], 0
	v_mfma_f32_16x16x32_bf16 v[4:7], v[168:171], v[216:219], 0
	v_mfma_f32_16x16x32_bf16 v[60:63], v[164:167], v[196:199], v[60:63]
	v_mfma_f32_16x16x32_bf16 v[52:55], v[172:175], v[196:199], v[52:55]
	v_mfma_f32_16x16x32_bf16 v[44:47], v[164:167], v[204:207], v[44:47]
	v_mfma_f32_16x16x32_bf16 v[36:39], v[172:175], v[204:207], v[36:39]
	v_mfma_f32_16x16x32_bf16 v[28:31], v[164:167], v[212:215], v[28:31]
	v_mfma_f32_16x16x32_bf16 v[20:23], v[172:175], v[212:215], v[20:23]
	v_mfma_f32_16x16x32_bf16 v[12:15], v[164:167], v[220:223], v[12:15]
	v_mfma_f32_16x16x32_bf16 v[4:7], v[172:175], v[220:223], v[4:7]
	s_setprio 0
	s_setprio 1
	v_mfma_f32_16x16x32_bf16 v[56:59], v[176:179], v[192:195], 0
	v_mfma_f32_16x16x32_bf16 v[48:51], v[184:187], v[192:195], 0
	v_mfma_f32_16x16x32_bf16 v[40:43], v[176:179], v[200:203], 0
	v_mfma_f32_16x16x32_bf16 v[32:35], v[184:187], v[200:203], 0
	v_mfma_f32_16x16x32_bf16 v[24:27], v[176:179], v[208:211], 0
	v_mfma_f32_16x16x32_bf16 v[16:19], v[184:187], v[208:211], 0
	v_mfma_f32_16x16x32_bf16 v[8:11], v[176:179], v[216:219], 0
	v_mfma_f32_16x16x32_bf16 v[0:3], v[184:187], v[216:219], 0
	v_mfma_f32_16x16x32_bf16 v[56:59], v[180:183], v[196:199], v[56:59]
	v_mfma_f32_16x16x32_bf16 v[48:51], v[188:191], v[196:199], v[48:51]
	v_mfma_f32_16x16x32_bf16 v[40:43], v[180:183], v[204:207], v[40:43]
	v_mfma_f32_16x16x32_bf16 v[32:35], v[188:191], v[204:207], v[32:35]
	v_mfma_f32_16x16x32_bf16 v[24:27], v[180:183], v[212:215], v[24:27]
	v_mfma_f32_16x16x32_bf16 v[16:19], v[188:191], v[212:215], v[16:19]
	v_mfma_f32_16x16x32_bf16 v[8:11], v[180:183], v[220:223], v[8:11]
	v_mfma_f32_16x16x32_bf16 v[0:3], v[188:191], v[220:223], v[0:3]
	s_setprio 0
	s_barrier
	s_add_i32 s71, 0, 0x18000
	v_add_u32_e32 v153, s71, v147
	s_add_i32 s72, 0, 0x1c000
	ds_read_b128 v[160:163], v153
	ds_read_b128 v[164:167], v153 offset:1024
	ds_read_b128 v[168:171], v153 offset:2048
	ds_read_b128 v[172:175], v153 offset:3072
	v_add_u32_e32 v153, s72, v147
	ds_read_b128 v[176:179], v153
	ds_read_b128 v[180:183], v153 offset:1024
	ds_read_b128 v[184:187], v153 offset:2048
	ds_read_b128 v[188:191], v153 offset:3072
	s_add_u32 s46, s46, 0x40000
	s_addc_u32 s47, s47, 0
	s_mov_b32 m0, s54
	v_lshl_add_u64 v[230:231], s[46:47], 0, v[134:135]
	ds_read_b128 v[192:195], v150 offset:32768
	ds_read_b128 v[196:199], v150 offset:33792
	ds_read_b128 v[200:203], v150 offset:34816
	ds_read_b128 v[204:207], v150 offset:35840
	ds_read_b128 v[208:211], v150 offset:36864
	ds_read_b128 v[212:215], v150 offset:37888
	ds_read_b128 v[216:219], v150 offset:38912
	ds_read_b128 v[220:223], v150 offset:39936
	global_load_lds_dwordx4 v[230:231], off
	v_lshl_add_u64 v[230:231], s[46:47], 0, v[130:131]
	s_mov_b32 m0, s55
	s_nop 0
	global_load_lds_dwordx4 v[230:231], off
	s_waitcnt vmcnt(8)
	s_waitcnt lgkmcnt(0)
	s_barrier
	s_setprio 1
	s_waitcnt lgkmcnt(0)
	v_mfma_f32_16x16x32_bf16 v[124:127], v[160:163], v[192:195], v[124:127]
	v_mfma_f32_16x16x32_bf16 v[116:119], v[168:171], v[192:195], v[116:119]
	v_mfma_f32_16x16x32_bf16 v[108:111], v[160:163], v[200:203], v[108:111]
	v_mfma_f32_16x16x32_bf16 v[100:103], v[168:171], v[200:203], v[100:103]
	v_mfma_f32_16x16x32_bf16 v[92:95], v[160:163], v[208:211], v[92:95]
	v_mfma_f32_16x16x32_bf16 v[84:87], v[168:171], v[208:211], v[84:87]
	v_mfma_f32_16x16x32_bf16 v[76:79], v[160:163], v[216:219], v[76:79]
	v_mfma_f32_16x16x32_bf16 v[68:71], v[168:171], v[216:219], v[68:71]
	v_mfma_f32_16x16x32_bf16 v[124:127], v[164:167], v[196:199], v[124:127]
	v_mfma_f32_16x16x32_bf16 v[116:119], v[172:175], v[196:199], v[116:119]
	v_mfma_f32_16x16x32_bf16 v[108:111], v[164:167], v[204:207], v[108:111]
	v_mfma_f32_16x16x32_bf16 v[100:103], v[172:175], v[204:207], v[100:103]
	v_mfma_f32_16x16x32_bf16 v[92:95], v[164:167], v[212:215], v[92:95]
	v_mfma_f32_16x16x32_bf16 v[84:87], v[172:175], v[212:215], v[84:87]
	v_mfma_f32_16x16x32_bf16 v[76:79], v[164:167], v[220:223], v[76:79]
	v_mfma_f32_16x16x32_bf16 v[68:71], v[172:175], v[220:223], v[68:71]
	s_setprio 0
	s_setprio 1
	v_mfma_f32_16x16x32_bf16 v[120:123], v[176:179], v[192:195], v[120:123]
	v_mfma_f32_16x16x32_bf16 v[112:115], v[184:187], v[192:195], v[112:115]
	v_mfma_f32_16x16x32_bf16 v[104:107], v[176:179], v[200:203], v[104:107]
	v_mfma_f32_16x16x32_bf16 v[96:99], v[184:187], v[200:203], v[96:99]
	v_mfma_f32_16x16x32_bf16 v[88:91], v[176:179], v[208:211], v[88:91]
	v_mfma_f32_16x16x32_bf16 v[80:83], v[184:187], v[208:211], v[80:83]
	v_mfma_f32_16x16x32_bf16 v[72:75], v[176:179], v[216:219], v[72:75]
	v_mfma_f32_16x16x32_bf16 v[64:67], v[184:187], v[216:219], v[64:67]
	v_mfma_f32_16x16x32_bf16 v[120:123], v[180:183], v[196:199], v[120:123]
	v_mfma_f32_16x16x32_bf16 v[112:115], v[188:191], v[196:199], v[112:115]
	v_mfma_f32_16x16x32_bf16 v[104:107], v[180:183], v[204:207], v[104:107]
	v_mfma_f32_16x16x32_bf16 v[96:99], v[188:191], v[204:207], v[96:99]
	v_mfma_f32_16x16x32_bf16 v[88:91], v[180:183], v[212:215], v[88:91]
	v_mfma_f32_16x16x32_bf16 v[80:83], v[188:191], v[212:215], v[80:83]
	v_mfma_f32_16x16x32_bf16 v[72:75], v[180:183], v[220:223], v[72:75]
	v_mfma_f32_16x16x32_bf16 v[64:67], v[188:191], v[220:223], v[64:67]
	s_setprio 0
	s_barrier
	s_add_i32 s46, s71, s49
	v_lshl_add_u64 v[154:155], v[154:155], 0, s[14:15]
	s_mov_b32 m0, s46
	ds_read_b128 v[192:195], v150 offset:49152
	ds_read_b128 v[196:199], v150 offset:50176
	ds_read_b128 v[200:203], v150 offset:51200
	ds_read_b128 v[204:207], v150 offset:52224
	ds_read_b128 v[208:211], v150 offset:53248
	ds_read_b128 v[212:215], v150 offset:54272
	ds_read_b128 v[216:219], v150 offset:55296
	ds_read_b128 v[220:223], v150 offset:56320
	global_load_lds_dwordx4 v[154:155], off
	s_add_i32 m0, s46, 0x2000
	s_add_u32 s44, s44, 0x40080
	v_lshl_add_u64 v[154:155], v[224:225], 0, s[14:15]
	s_addc_u32 s45, s45, 0
	s_add_i32 s46, s72, s49
	global_load_lds_dwordx4 v[154:155], off
	v_lshl_add_u64 v[154:155], s[44:45], 0, v[132:133]
	s_mov_b32 m0, s46
	s_nop 0
	global_load_lds_dwordx4 v[154:155], off
	v_lshl_add_u64 v[154:155], s[44:45], 0, v[128:129]
	s_add_i32 m0, s46, 0x2000
	s_nop 0
	global_load_lds_dwordx4 v[154:155], off
	v_lshl_add_u64 v[154:155], v[226:227], 0, s[14:15]
	s_mov_b32 m0, s57
	s_nop 0
	global_load_lds_dwordx4 v[154:155], off
	v_lshl_add_u64 v[154:155], v[228:229], 0, s[14:15]
	s_mov_b32 m0, s58
	s_nop 0
	global_load_lds_dwordx4 v[154:155], off
	s_waitcnt vmcnt(8)
	s_waitcnt lgkmcnt(0)
	s_barrier
	s_setprio 1
	s_waitcnt lgkmcnt(0)
	v_mfma_f32_16x16x32_bf16 v[60:63], v[160:163], v[192:195], v[60:63]
	v_mfma_f32_16x16x32_bf16 v[52:55], v[168:171], v[192:195], v[52:55]
	v_mfma_f32_16x16x32_bf16 v[44:47], v[160:163], v[200:203], v[44:47]
	v_mfma_f32_16x16x32_bf16 v[36:39], v[168:171], v[200:203], v[36:39]
	v_mfma_f32_16x16x32_bf16 v[28:31], v[160:163], v[208:211], v[28:31]
	v_mfma_f32_16x16x32_bf16 v[20:23], v[168:171], v[208:211], v[20:23]
	v_mfma_f32_16x16x32_bf16 v[12:15], v[160:163], v[216:219], v[12:15]
	v_mfma_f32_16x16x32_bf16 v[4:7], v[168:171], v[216:219], v[4:7]
	v_mfma_f32_16x16x32_bf16 v[60:63], v[164:167], v[196:199], v[60:63]
	v_mfma_f32_16x16x32_bf16 v[52:55], v[172:175], v[196:199], v[52:55]
	v_mfma_f32_16x16x32_bf16 v[44:47], v[164:167], v[204:207], v[44:47]
	v_mfma_f32_16x16x32_bf16 v[36:39], v[172:175], v[204:207], v[36:39]
	v_mfma_f32_16x16x32_bf16 v[28:31], v[164:167], v[212:215], v[28:31]
	v_mfma_f32_16x16x32_bf16 v[20:23], v[172:175], v[212:215], v[20:23]
	v_mfma_f32_16x16x32_bf16 v[12:15], v[164:167], v[220:223], v[12:15]
	v_mfma_f32_16x16x32_bf16 v[4:7], v[172:175], v[220:223], v[4:7]
	s_setprio 0
	s_setprio 1
	v_mfma_f32_16x16x32_bf16 v[56:59], v[176:179], v[192:195], v[56:59]
	v_mfma_f32_16x16x32_bf16 v[48:51], v[184:187], v[192:195], v[48:51]
	v_mfma_f32_16x16x32_bf16 v[40:43], v[176:179], v[200:203], v[40:43]
	v_mfma_f32_16x16x32_bf16 v[32:35], v[184:187], v[200:203], v[32:35]
	v_mfma_f32_16x16x32_bf16 v[24:27], v[176:179], v[208:211], v[24:27]
	v_mfma_f32_16x16x32_bf16 v[16:19], v[184:187], v[208:211], v[16:19]
	v_mfma_f32_16x16x32_bf16 v[8:11], v[176:179], v[216:219], v[8:11]
	v_mfma_f32_16x16x32_bf16 v[0:3], v[184:187], v[216:219], v[0:3]
	v_mfma_f32_16x16x32_bf16 v[56:59], v[180:183], v[196:199], v[56:59]
	v_mfma_f32_16x16x32_bf16 v[48:51], v[188:191], v[196:199], v[48:51]
	v_mfma_f32_16x16x32_bf16 v[40:43], v[180:183], v[204:207], v[40:43]
	v_mfma_f32_16x16x32_bf16 v[32:35], v[188:191], v[204:207], v[32:35]
	v_mfma_f32_16x16x32_bf16 v[24:27], v[180:183], v[212:215], v[24:27]
	v_mfma_f32_16x16x32_bf16 v[16:19], v[188:191], v[212:215], v[16:19]
	v_mfma_f32_16x16x32_bf16 v[8:11], v[180:183], v[220:223], v[8:11]
	v_mfma_f32_16x16x32_bf16 v[0:3], v[188:191], v[220:223], v[0:3]
	s_setprio 0
	s_barrier
	s_add_i32 s70, s70, 2
	s_add_u32 s68, s68, 0x100
	s_addc_u32 s69, s69, 0
	s_add_u32 s30, s30, 0x100
	s_addc_u32 s31, s31, 0
	s_branch .LBB0_1098

.LBB0_1180:
	s_add_u32 s72, s50, 0x100
	s_addc_u32 s73, s51, 0
	s_mov_b32 s74, -2
	s_waitcnt lgkmcnt(0)
	s_cmp_eq_u32 s63, 1
	s_cbranch_scc1 .Lfa_11
	ds_read_b128 v[128:131], v188
	ds_read_b128 v[132:135], v188 offset:1024
	ds_read_b128 v[136:139], v188 offset:2048
	ds_read_b128 v[140:143], v188 offset:3072
	ds_read_b128 v[144:147], v189
	ds_read_b128 v[148:151], v189 offset:1024
	ds_read_b128 v[172:175], v189 offset:2048
	ds_read_b128 v[176:179], v189 offset:3072
	s_add_u32 s50, s48, 0x100
	s_addc_u32 s51, s49, 0
	s_cmp_eq_u32 s74, 40
	s_cselect_b32 s55, s11, s51
	s_cselect_b32 s54, s10, s50
	s_cselect_b32 s53, s47, s73
	s_cselect_b32 s52, s46, s72
	v_lshl_add_u64 v[220:221], s[48:49], 0, v[166:167]
	s_add_i32 m0, s59, 0xc000
	ds_read_b128 v[180:183], v190
	ds_read_b128 v[192:195], v190 offset:1024
	ds_read_b128 v[196:199], v190 offset:2048
	ds_read_b128 v[200:203], v190 offset:3072
	ds_read_b128 v[204:207], v190 offset:4096
	ds_read_b128 v[208:211], v190 offset:5120
	ds_read_b128 v[212:215], v190 offset:6144
	ds_read_b128 v[216:219], v190 offset:7168
	global_load_lds_dwordx4 v[220:221], off
	v_lshl_add_u64 v[220:221], s[48:49], 0, v[164:165]
	s_add_i32 m0, s59, 0xe000
	s_nop 0
	global_load_lds_dwordx4 v[220:221], off
	s_waitcnt vmcnt(24)
	s_waitcnt lgkmcnt(0)
	s_barrier
	s_setprio 1
	s_waitcnt lgkmcnt(0)
	v_mfma_f32_16x16x32_bf16 v[124:127], v[128:131], v[180:183], 0
	v_mfma_f32_16x16x32_bf16 v[120:123], v[136:139], v[180:183], 0
	v_mfma_f32_16x16x32_bf16 v[108:111], v[128:131], v[196:199], 0
	v_mfma_f32_16x16x32_bf16 v[104:107], v[136:139], v[196:199], 0
	v_mfma_f32_16x16x32_bf16 v[92:95], v[128:131], v[204:207], 0
	v_mfma_f32_16x16x32_bf16 v[88:91], v[136:139], v[204:207], 0
	v_mfma_f32_16x16x32_bf16 v[76:79], v[128:131], v[212:215], 0
	v_mfma_f32_16x16x32_bf16 v[72:75], v[136:139], v[212:215], 0
	v_mfma_f32_16x16x32_bf16 v[124:127], v[132:135], v[192:195], v[124:127]
	v_mfma_f32_16x16x32_bf16 v[120:123], v[140:143], v[192:195], v[120:123]
	v_mfma_f32_16x16x32_bf16 v[108:111], v[132:135], v[200:203], v[108:111]
	v_mfma_f32_16x16x32_bf16 v[104:107], v[140:143], v[200:203], v[104:107]
	v_mfma_f32_16x16x32_bf16 v[92:95], v[132:135], v[208:211], v[92:95]
	v_mfma_f32_16x16x32_bf16 v[88:91], v[140:143], v[208:211], v[88:91]
	v_mfma_f32_16x16x32_bf16 v[76:79], v[132:135], v[216:219], v[76:79]
	v_mfma_f32_16x16x32_bf16 v[72:75], v[140:143], v[216:219], v[72:75]
	s_setprio 0
	s_setprio 1
	v_mfma_f32_16x16x32_bf16 v[116:119], v[144:147], v[180:183], 0
	v_mfma_f32_16x16x32_bf16 v[112:115], v[172:175], v[180:183], 0
	v_mfma_f32_16x16x32_bf16 v[100:103], v[144:147], v[196:199], 0
	v_mfma_f32_16x16x32_bf16 v[96:99], v[172:175], v[196:199], 0
	v_mfma_f32_16x16x32_bf16 v[84:87], v[144:147], v[204:207], 0
	v_mfma_f32_16x16x32_bf16 v[80:83], v[172:175], v[204:207], 0
	v_mfma_f32_16x16x32_bf16 v[68:71], v[144:147], v[212:215], 0
	v_mfma_f32_16x16x32_bf16 v[64:67], v[172:175], v[212:215], 0
	v_mfma_f32_16x16x32_bf16 v[116:119], v[148:151], v[192:195], v[116:119]
	v_mfma_f32_16x16x32_bf16 v[112:115], v[176:179], v[192:195], v[112:115]
	v_mfma_f32_16x16x32_bf16 v[100:103], v[148:151], v[200:203], v[100:103]
	v_mfma_f32_16x16x32_bf16 v[96:99], v[176:179], v[200:203], v[96:99]
	v_mfma_f32_16x16x32_bf16 v[84:87], v[148:151], v[208:211], v[84:87]
	v_mfma_f32_16x16x32_bf16 v[80:83], v[176:179], v[208:211], v[80:83]
	v_mfma_f32_16x16x32_bf16 v[68:71], v[148:151], v[216:219], v[68:71]
	v_mfma_f32_16x16x32_bf16 v[64:67], v[176:179], v[216:219], v[64:67]
	s_setprio 0
	s_barrier
	s_add_i32 s48, s68, s58
	v_lshl_add_u64 v[220:221], s[52:53], 0, v[154:155]
	s_mov_b32 m0, s48
	ds_read_b128 v[180:183], v190 offset:16384
	ds_read_b128 v[192:195], v190 offset:17408
	ds_read_b128 v[196:199], v190 offset:18432
	ds_read_b128 v[200:203], v190 offset:19456
	ds_read_b128 v[204:207], v190 offset:20480
	ds_read_b128 v[208:211], v190 offset:21504
	ds_read_b128 v[212:215], v190 offset:22528
	ds_read_b128 v[216:219], v190 offset:23552
	global_load_lds_dwordx4 v[220:221], off
	s_add_i32 m0, s48, 0x2000
	s_add_u32 s48, s52, 0xb0000
	v_lshl_add_u64 v[222:223], s[52:53], 0, v[162:163]
	s_addc_u32 s49, s53, 0
	s_add_i32 s75, s69, s58
	global_load_lds_dwordx4 v[222:223], off
	v_lshl_add_u64 v[224:225], s[48:49], 0, v[154:155]
	s_mov_b32 m0, s75
	v_lshl_add_u64 v[226:227], s[54:55], 0, v[160:161]
	global_load_lds_dwordx4 v[224:225], off
	v_lshl_add_u64 v[224:225], s[48:49], 0, v[162:163]
	s_add_i32 m0, s75, 0x2000
	s_nop 0
	global_load_lds_dwordx4 v[224:225], off
	v_lshl_add_u64 v[224:225], s[54:55], 0, v[152:153]
	s_mov_b32 m0, s59
	s_nop 0
	global_load_lds_dwordx4 v[224:225], off
	s_mov_b32 m0, s60
	s_nop 0
	global_load_lds_dwordx4 v[226:227], off
	s_waitcnt vmcnt(24)
	s_waitcnt lgkmcnt(0)
	s_barrier
	s_setprio 1
	s_waitcnt lgkmcnt(0)
	v_mfma_f32_16x16x32_bf16 v[60:63], v[128:131], v[180:183], 0
	v_mfma_f32_16x16x32_bf16 v[56:59], v[136:139], v[180:183], 0
	v_mfma_f32_16x16x32_bf16 v[44:47], v[128:131], v[196:199], 0
	v_mfma_f32_16x16x32_bf16 v[40:43], v[136:139], v[196:199], 0
	v_mfma_f32_16x16x32_bf16 v[28:31], v[128:131], v[204:207], 0
	v_mfma_f32_16x16x32_bf16 v[24:27], v[136:139], v[204:207], 0
	v_mfma_f32_16x16x32_bf16 v[12:15], v[128:131], v[212:215], 0
	v_mfma_f32_16x16x32_bf16 v[8:11], v[136:139], v[212:215], 0
	v_mfma_f32_16x16x32_bf16 v[60:63], v[132:135], v[192:195], v[60:63]
	v_mfma_f32_16x16x32_bf16 v[56:59], v[140:143], v[192:195], v[56:59]
	v_mfma_f32_16x16x32_bf16 v[44:47], v[132:135], v[200:203], v[44:47]
	v_mfma_f32_16x16x32_bf16 v[40:43], v[140:143], v[200:203], v[40:43]
	v_mfma_f32_16x16x32_bf16 v[28:31], v[132:135], v[208:211], v[28:31]
	v_mfma_f32_16x16x32_bf16 v[24:27], v[140:143], v[208:211], v[24:27]
	v_mfma_f32_16x16x32_bf16 v[12:15], v[132:135], v[216:219], v[12:15]
	v_mfma_f32_16x16x32_bf16 v[8:11], v[140:143], v[216:219], v[8:11]
	s_setprio 0
	s_setprio 1
	v_mfma_f32_16x16x32_bf16 v[52:55], v[144:147], v[180:183], 0
	v_mfma_f32_16x16x32_bf16 v[48:51], v[172:175], v[180:183], 0
	v_mfma_f32_16x16x32_bf16 v[36:39], v[144:147], v[196:199], 0
	v_mfma_f32_16x16x32_bf16 v[32:35], v[172:175], v[196:199], 0
	v_mfma_f32_16x16x32_bf16 v[20:23], v[144:147], v[204:207], 0
	v_mfma_f32_16x16x32_bf16 v[16:19], v[172:175], v[204:207], 0
	v_mfma_f32_16x16x32_bf16 v[4:7], v[144:147], v[212:215], 0
	v_mfma_f32_16x16x32_bf16 v[0:3], v[172:175], v[212:215], 0
	v_mfma_f32_16x16x32_bf16 v[52:55], v[148:151], v[192:195], v[52:55]
	v_mfma_f32_16x16x32_bf16 v[48:51], v[176:179], v[192:195], v[48:51]
	v_mfma_f32_16x16x32_bf16 v[36:39], v[148:151], v[200:203], v[36:39]
	v_mfma_f32_16x16x32_bf16 v[32:35], v[176:179], v[200:203], v[32:35]
	v_mfma_f32_16x16x32_bf16 v[20:23], v[148:151], v[208:211], v[20:23]
	v_mfma_f32_16x16x32_bf16 v[16:19], v[176:179], v[208:211], v[16:19]
	v_mfma_f32_16x16x32_bf16 v[4:7], v[148:151], v[216:219], v[4:7]
	v_mfma_f32_16x16x32_bf16 v[0:3], v[176:179], v[216:219], v[0:3]
	s_setprio 0
	s_barrier
	s_add_i32 s75, 0, 0x18000
	s_add_i32 s76, 0, 0x1c000
	v_add_u32_e32 v140, s75, v185
	v_add_u32_e32 v176, s76, v185
	ds_read_b128 v[128:131], v140
	ds_read_b128 v[132:135], v140 offset:1024
	ds_read_b128 v[136:139], v140 offset:2048
	ds_read_b128 v[140:143], v140 offset:3072
	ds_read_b128 v[144:147], v176
	ds_read_b128 v[148:151], v176 offset:1024
	ds_read_b128 v[172:175], v176 offset:2048
	ds_read_b128 v[176:179], v176 offset:3072
	s_add_u32 s48, s54, 0xb0000
	s_addc_u32 s49, s55, 0
	s_mov_b32 m0, s61
	v_lshl_add_u64 v[228:229], s[48:49], 0, v[152:153]
	ds_read_b128 v[180:183], v190 offset:32768
	ds_read_b128 v[192:195], v190 offset:33792
	ds_read_b128 v[196:199], v190 offset:34816
	ds_read_b128 v[200:203], v190 offset:35840
	ds_read_b128 v[204:207], v190 offset:36864
	ds_read_b128 v[208:211], v190 offset:37888
	ds_read_b128 v[212:215], v190 offset:38912
	ds_read_b128 v[216:219], v190 offset:39936
	global_load_lds_dwordx4 v[228:229], off
	v_lshl_add_u64 v[228:229], s[48:49], 0, v[160:161]
	s_mov_b32 m0, s62
	s_nop 0
	global_load_lds_dwordx4 v[228:229], off
	s_waitcnt vmcnt(8)
	s_waitcnt lgkmcnt(0)
	s_barrier
	s_setprio 1
	s_waitcnt lgkmcnt(0)
	v_mfma_f32_16x16x32_bf16 v[124:127], v[128:131], v[180:183], v[124:127]
	v_mfma_f32_16x16x32_bf16 v[120:123], v[136:139], v[180:183], v[120:123]
	v_mfma_f32_16x16x32_bf16 v[108:111], v[128:131], v[196:199], v[108:111]
	v_mfma_f32_16x16x32_bf16 v[104:107], v[136:139], v[196:199], v[104:107]
	v_mfma_f32_16x16x32_bf16 v[92:95], v[128:131], v[204:207], v[92:95]
	v_mfma_f32_16x16x32_bf16 v[88:91], v[136:139], v[204:207], v[88:91]
	v_mfma_f32_16x16x32_bf16 v[76:79], v[128:131], v[212:215], v[76:79]
	v_mfma_f32_16x16x32_bf16 v[72:75], v[136:139], v[212:215], v[72:75]
	v_mfma_f32_16x16x32_bf16 v[124:127], v[132:135], v[192:195], v[124:127]
	v_mfma_f32_16x16x32_bf16 v[120:123], v[140:143], v[192:195], v[120:123]
	v_mfma_f32_16x16x32_bf16 v[108:111], v[132:135], v[200:203], v[108:111]
	v_mfma_f32_16x16x32_bf16 v[104:107], v[140:143], v[200:203], v[104:107]
	v_mfma_f32_16x16x32_bf16 v[92:95], v[132:135], v[208:211], v[92:95]
	v_mfma_f32_16x16x32_bf16 v[88:91], v[140:143], v[208:211], v[88:91]
	v_mfma_f32_16x16x32_bf16 v[76:79], v[132:135], v[216:219], v[76:79]
	v_mfma_f32_16x16x32_bf16 v[72:75], v[140:143], v[216:219], v[72:75]
	s_setprio 0
	s_setprio 1
	v_mfma_f32_16x16x32_bf16 v[116:119], v[144:147], v[180:183], v[116:119]
	v_mfma_f32_16x16x32_bf16 v[112:115], v[172:175], v[180:183], v[112:115]
	v_mfma_f32_16x16x32_bf16 v[100:103], v[144:147], v[196:199], v[100:103]
	v_mfma_f32_16x16x32_bf16 v[96:99], v[172:175], v[196:199], v[96:99]
	v_mfma_f32_16x16x32_bf16 v[84:87], v[144:147], v[204:207], v[84:87]
	v_mfma_f32_16x16x32_bf16 v[80:83], v[172:175], v[204:207], v[80:83]
	v_mfma_f32_16x16x32_bf16 v[68:71], v[144:147], v[212:215], v[68:71]
	v_mfma_f32_16x16x32_bf16 v[64:67], v[172:175], v[212:215], v[64:67]
	v_mfma_f32_16x16x32_bf16 v[116:119], v[148:151], v[192:195], v[116:119]
	v_mfma_f32_16x16x32_bf16 v[112:115], v[176:179], v[192:195], v[112:115]
	v_mfma_f32_16x16x32_bf16 v[100:103], v[148:151], v[200:203], v[100:103]
	v_mfma_f32_16x16x32_bf16 v[96:99], v[176:179], v[200:203], v[96:99]
	v_mfma_f32_16x16x32_bf16 v[84:87], v[148:151], v[208:211], v[84:87]
	v_mfma_f32_16x16x32_bf16 v[80:83], v[176:179], v[208:211], v[80:83]
	v_mfma_f32_16x16x32_bf16 v[68:71], v[148:151], v[216:219], v[68:71]
	v_mfma_f32_16x16x32_bf16 v[64:67], v[176:179], v[216:219], v[64:67]
	s_setprio 0
	s_barrier
	s_add_i32 s48, s75, s58
	v_lshl_add_u64 v[220:221], v[220:221], 0, s[22:23]
	s_mov_b32 m0, s48
	ds_read_b128 v[180:183], v190 offset:49152
	ds_read_b128 v[192:195], v190 offset:50176
	ds_read_b128 v[196:199], v190 offset:51200
	ds_read_b128 v[200:203], v190 offset:52224
	ds_read_b128 v[204:207], v190 offset:53248
	ds_read_b128 v[208:211], v190 offset:54272
	ds_read_b128 v[212:215], v190 offset:55296
	ds_read_b128 v[216:219], v190 offset:56320
	global_load_lds_dwordx4 v[220:221], off
	s_add_i32 m0, s48, 0x2000
	s_add_u32 s48, s52, 0xb0080
	v_lshl_add_u64 v[220:221], v[222:223], 0, s[22:23]
	s_addc_u32 s49, s53, 0
	s_add_i32 s52, s76, s58
	global_load_lds_dwordx4 v[220:221], off
	v_lshl_add_u64 v[220:221], s[48:49], 0, v[154:155]
	s_mov_b32 m0, s52
	s_nop 0
	global_load_lds_dwordx4 v[220:221], off
	v_lshl_add_u64 v[220:221], s[48:49], 0, v[162:163]
	s_add_i32 m0, s52, 0x2000
	s_nop 0
	global_load_lds_dwordx4 v[220:221], off
	v_lshl_add_u64 v[220:221], v[224:225], 0, s[22:23]
	s_mov_b32 m0, s3
	s_nop 0
	global_load_lds_dwordx4 v[220:221], off
	v_lshl_add_u64 v[220:221], v[226:227], 0, s[22:23]
	s_mov_b32 m0, s64
	s_nop 0
	global_load_lds_dwordx4 v[220:221], off
	s_waitcnt vmcnt(8)
	s_waitcnt lgkmcnt(0)
	s_barrier
	s_setprio 1
	s_waitcnt lgkmcnt(0)
	v_mfma_f32_16x16x32_bf16 v[60:63], v[128:131], v[180:183], v[60:63]
	v_mfma_f32_16x16x32_bf16 v[56:59], v[136:139], v[180:183], v[56:59]
	v_mfma_f32_16x16x32_bf16 v[44:47], v[128:131], v[196:199], v[44:47]
	v_mfma_f32_16x16x32_bf16 v[40:43], v[136:139], v[196:199], v[40:43]
	v_mfma_f32_16x16x32_bf16 v[28:31], v[128:131], v[204:207], v[28:31]
	v_mfma_f32_16x16x32_bf16 v[24:27], v[136:139], v[204:207], v[24:27]
	v_mfma_f32_16x16x32_bf16 v[12:15], v[128:131], v[212:215], v[12:15]
	v_mfma_f32_16x16x32_bf16 v[8:11], v[136:139], v[212:215], v[8:11]
	v_mfma_f32_16x16x32_bf16 v[60:63], v[132:135], v[192:195], v[60:63]
	v_mfma_f32_16x16x32_bf16 v[56:59], v[140:143], v[192:195], v[56:59]
	v_mfma_f32_16x16x32_bf16 v[44:47], v[132:135], v[200:203], v[44:47]
	v_mfma_f32_16x16x32_bf16 v[40:43], v[140:143], v[200:203], v[40:43]
	v_mfma_f32_16x16x32_bf16 v[28:31], v[132:135], v[208:211], v[28:31]
	v_mfma_f32_16x16x32_bf16 v[24:27], v[140:143], v[208:211], v[24:27]
	v_mfma_f32_16x16x32_bf16 v[12:15], v[132:135], v[216:219], v[12:15]
	v_mfma_f32_16x16x32_bf16 v[8:11], v[140:143], v[216:219], v[8:11]
	s_setprio 0
	s_setprio 1
	v_mfma_f32_16x16x32_bf16 v[52:55], v[144:147], v[180:183], v[52:55]
	v_mfma_f32_16x16x32_bf16 v[48:51], v[172:175], v[180:183], v[48:51]
	v_mfma_f32_16x16x32_bf16 v[36:39], v[144:147], v[196:199], v[36:39]
	v_mfma_f32_16x16x32_bf16 v[32:35], v[172:175], v[196:199], v[32:35]
	v_mfma_f32_16x16x32_bf16 v[20:23], v[144:147], v[204:207], v[20:23]
	v_mfma_f32_16x16x32_bf16 v[16:19], v[172:175], v[204:207], v[16:19]
	v_mfma_f32_16x16x32_bf16 v[4:7], v[144:147], v[212:215], v[4:7]
	v_mfma_f32_16x16x32_bf16 v[0:3], v[172:175], v[212:215], v[0:3]
	v_mfma_f32_16x16x32_bf16 v[52:55], v[148:151], v[192:195], v[52:55]
	v_mfma_f32_16x16x32_bf16 v[48:51], v[176:179], v[192:195], v[48:51]
	v_mfma_f32_16x16x32_bf16 v[36:39], v[148:151], v[200:203], v[36:39]
	v_mfma_f32_16x16x32_bf16 v[32:35], v[176:179], v[200:203], v[32:35]
	v_mfma_f32_16x16x32_bf16 v[20:23], v[148:151], v[208:211], v[20:23]
	v_mfma_f32_16x16x32_bf16 v[16:19], v[176:179], v[208:211], v[16:19]
	v_mfma_f32_16x16x32_bf16 v[4:7], v[148:151], v[216:219], v[4:7]
	v_mfma_f32_16x16x32_bf16 v[0:3], v[176:179], v[216:219], v[0:3]
	s_setprio 0
	s_barrier
	s_add_i32 s74, s74, 2
	s_add_u32 s72, s72, 0x100
	s_addc_u32 s73, s73, 0
	s_cmp_gt_u32 s74, 41
	s_mov_b64 s[48:49], s[50:51]
	s_branch .LBB0_1181
.Lfa_11:
	ds_read_b128 v[128:131], v188
	ds_read_b128 v[132:135], v188 offset:1024
	ds_read_b128 v[136:139], v188 offset:2048
	ds_read_b128 v[140:143], v188 offset:3072
	ds_read_b128 v[144:147], v189
	ds_read_b128 v[148:151], v189 offset:1024
	ds_read_b128 v[172:175], v189 offset:2048
	ds_read_b128 v[176:179], v189 offset:3072
	s_add_u32 s50, s48, 0x100
	s_addc_u32 s51, s49, 0
	s_cmp_eq_u32 s74, 40
	s_cselect_b32 s55, s11, s51
	s_cselect_b32 s54, s10, s50
	s_cselect_b32 s53, s47, s73
	s_cselect_b32 s52, s46, s72
	v_lshl_add_u64 v[220:221], s[48:49], 0, v[166:167]
	s_add_i32 m0, s59, 0xc000
	ds_read_b128 v[180:183], v190
	ds_read_b128 v[192:195], v190 offset:1024
	ds_read_b128 v[196:199], v190 offset:2048
	ds_read_b128 v[200:203], v190 offset:3072
	ds_read_b128 v[204:207], v190 offset:4096
	ds_read_b128 v[208:211], v190 offset:5120
	ds_read_b128 v[212:215], v190 offset:6144
	ds_read_b128 v[216:219], v190 offset:7168
	global_load_lds_dwordx4 v[220:221], off
	v_lshl_add_u64 v[220:221], s[48:49], 0, v[164:165]
	s_add_i32 m0, s59, 0xe000
	s_nop 0
	global_load_lds_dwordx4 v[220:221], off
	s_waitcnt vmcnt(8)
	s_waitcnt lgkmcnt(0)
	s_barrier
	s_setprio 1
	s_waitcnt lgkmcnt(0)
	v_mfma_f32_16x16x32_bf16 v[124:127], v[128:131], v[180:183], 0
	v_mfma_f32_16x16x32_bf16 v[120:123], v[136:139], v[180:183], 0
	v_mfma_f32_16x16x32_bf16 v[108:111], v[128:131], v[196:199], 0
	v_mfma_f32_16x16x32_bf16 v[104:107], v[136:139], v[196:199], 0
	v_mfma_f32_16x16x32_bf16 v[92:95], v[128:131], v[204:207], 0
	v_mfma_f32_16x16x32_bf16 v[88:91], v[136:139], v[204:207], 0
	v_mfma_f32_16x16x32_bf16 v[76:79], v[128:131], v[212:215], 0
	v_mfma_f32_16x16x32_bf16 v[72:75], v[136:139], v[212:215], 0
	v_mfma_f32_16x16x32_bf16 v[124:127], v[132:135], v[192:195], v[124:127]
	v_mfma_f32_16x16x32_bf16 v[120:123], v[140:143], v[192:195], v[120:123]
	v_mfma_f32_16x16x32_bf16 v[108:111], v[132:135], v[200:203], v[108:111]
	v_mfma_f32_16x16x32_bf16 v[104:107], v[140:143], v[200:203], v[104:107]
	v_mfma_f32_16x16x32_bf16 v[92:95], v[132:135], v[208:211], v[92:95]
	v_mfma_f32_16x16x32_bf16 v[88:91], v[140:143], v[208:211], v[88:91]
	v_mfma_f32_16x16x32_bf16 v[76:79], v[132:135], v[216:219], v[76:79]
	v_mfma_f32_16x16x32_bf16 v[72:75], v[140:143], v[216:219], v[72:75]
	s_setprio 0
	s_setprio 1
	v_mfma_f32_16x16x32_bf16 v[116:119], v[144:147], v[180:183], 0
	v_mfma_f32_16x16x32_bf16 v[112:115], v[172:175], v[180:183], 0
	v_mfma_f32_16x16x32_bf16 v[100:103], v[144:147], v[196:199], 0
	v_mfma_f32_16x16x32_bf16 v[96:99], v[172:175], v[196:199], 0
	v_mfma_f32_16x16x32_bf16 v[84:87], v[144:147], v[204:207], 0
	v_mfma_f32_16x16x32_bf16 v[80:83], v[172:175], v[204:207], 0
	v_mfma_f32_16x16x32_bf16 v[68:71], v[144:147], v[212:215], 0
	v_mfma_f32_16x16x32_bf16 v[64:67], v[172:175], v[212:215], 0
	v_mfma_f32_16x16x32_bf16 v[116:119], v[148:151], v[192:195], v[116:119]
	v_mfma_f32_16x16x32_bf16 v[112:115], v[176:179], v[192:195], v[112:115]
	v_mfma_f32_16x16x32_bf16 v[100:103], v[148:151], v[200:203], v[100:103]
	v_mfma_f32_16x16x32_bf16 v[96:99], v[176:179], v[200:203], v[96:99]
	v_mfma_f32_16x16x32_bf16 v[84:87], v[148:151], v[208:211], v[84:87]
	v_mfma_f32_16x16x32_bf16 v[80:83], v[176:179], v[208:211], v[80:83]
	v_mfma_f32_16x16x32_bf16 v[68:71], v[148:151], v[216:219], v[68:71]
	v_mfma_f32_16x16x32_bf16 v[64:67], v[176:179], v[216:219], v[64:67]
	s_setprio 0
	s_barrier
	s_add_i32 s48, s68, s58
	v_lshl_add_u64 v[220:221], s[52:53], 0, v[154:155]
	s_mov_b32 m0, s48
	ds_read_b128 v[180:183], v190 offset:16384
	ds_read_b128 v[192:195], v190 offset:17408
	ds_read_b128 v[196:199], v190 offset:18432
	ds_read_b128 v[200:203], v190 offset:19456
	ds_read_b128 v[204:207], v190 offset:20480
	ds_read_b128 v[208:211], v190 offset:21504
	ds_read_b128 v[212:215], v190 offset:22528
	ds_read_b128 v[216:219], v190 offset:23552
	global_load_lds_dwordx4 v[220:221], off
	s_add_i32 m0, s48, 0x2000
	s_add_u32 s48, s52, 0xb0000
	v_lshl_add_u64 v[222:223], s[52:53], 0, v[162:163]
	s_addc_u32 s49, s53, 0
	s_add_i32 s75, s69, s58
	global_load_lds_dwordx4 v[222:223], off
	v_lshl_add_u64 v[224:225], s[48:49], 0, v[154:155]
	s_mov_b32 m0, s75
	v_lshl_add_u64 v[226:227], s[54:55], 0, v[160:161]
	global_load_lds_dwordx4 v[224:225], off
	v_lshl_add_u64 v[224:225], s[48:49], 0, v[162:163]
	s_add_i32 m0, s75, 0x2000
	s_nop 0
	global_load_lds_dwordx4 v[224:225], off
	v_lshl_add_u64 v[224:225], s[54:55], 0, v[152:153]
	s_mov_b32 m0, s59
	s_nop 0
	global_load_lds_dwordx4 v[224:225], off
	s_mov_b32 m0, s60
	s_nop 0
	global_load_lds_dwordx4 v[226:227], off
	s_waitcnt vmcnt(8)
	s_waitcnt lgkmcnt(0)
	s_barrier
	s_setprio 1
	s_waitcnt lgkmcnt(0)
	v_mfma_f32_16x16x32_bf16 v[60:63], v[128:131], v[180:183], 0
	v_mfma_f32_16x16x32_bf16 v[56:59], v[136:139], v[180:183], 0
	v_mfma_f32_16x16x32_bf16 v[44:47], v[128:131], v[196:199], 0
	v_mfma_f32_16x16x32_bf16 v[40:43], v[136:139], v[196:199], 0
	v_mfma_f32_16x16x32_bf16 v[28:31], v[128:131], v[204:207], 0
	v_mfma_f32_16x16x32_bf16 v[24:27], v[136:139], v[204:207], 0
	v_mfma_f32_16x16x32_bf16 v[12:15], v[128:131], v[212:215], 0
	v_mfma_f32_16x16x32_bf16 v[8:11], v[136:139], v[212:215], 0
	v_mfma_f32_16x16x32_bf16 v[60:63], v[132:135], v[192:195], v[60:63]
	v_mfma_f32_16x16x32_bf16 v[56:59], v[140:143], v[192:195], v[56:59]
	v_mfma_f32_16x16x32_bf16 v[44:47], v[132:135], v[200:203], v[44:47]
	v_mfma_f32_16x16x32_bf16 v[40:43], v[140:143], v[200:203], v[40:43]
	v_mfma_f32_16x16x32_bf16 v[28:31], v[132:135], v[208:211], v[28:31]
	v_mfma_f32_16x16x32_bf16 v[24:27], v[140:143], v[208:211], v[24:27]
	v_mfma_f32_16x16x32_bf16 v[12:15], v[132:135], v[216:219], v[12:15]
	v_mfma_f32_16x16x32_bf16 v[8:11], v[140:143], v[216:219], v[8:11]
	s_setprio 0
	s_setprio 1
	v_mfma_f32_16x16x32_bf16 v[52:55], v[144:147], v[180:183], 0
	v_mfma_f32_16x16x32_bf16 v[48:51], v[172:175], v[180:183], 0
	v_mfma_f32_16x16x32_bf16 v[36:39], v[144:147], v[196:199], 0
	v_mfma_f32_16x16x32_bf16 v[32:35], v[172:175], v[196:199], 0
	v_mfma_f32_16x16x32_bf16 v[20:23], v[144:147], v[204:207], 0
	v_mfma_f32_16x16x32_bf16 v[16:19], v[172:175], v[204:207], 0
	v_mfma_f32_16x16x32_bf16 v[4:7], v[144:147], v[212:215], 0
	v_mfma_f32_16x16x32_bf16 v[0:3], v[172:175], v[212:215], 0
	v_mfma_f32_16x16x32_bf16 v[52:55], v[148:151], v[192:195], v[52:55]
	v_mfma_f32_16x16x32_bf16 v[48:51], v[176:179], v[192:195], v[48:51]
	v_mfma_f32_16x16x32_bf16 v[36:39], v[148:151], v[200:203], v[36:39]
	v_mfma_f32_16x16x32_bf16 v[32:35], v[176:179], v[200:203], v[32:35]
	v_mfma_f32_16x16x32_bf16 v[20:23], v[148:151], v[208:211], v[20:23]
	v_mfma_f32_16x16x32_bf16 v[16:19], v[176:179], v[208:211], v[16:19]
	v_mfma_f32_16x16x32_bf16 v[4:7], v[148:151], v[216:219], v[4:7]
	v_mfma_f32_16x16x32_bf16 v[0:3], v[176:179], v[216:219], v[0:3]
	s_setprio 0
	s_barrier
	s_add_i32 s75, 0, 0x18000
	s_add_i32 s76, 0, 0x1c000
	v_add_u32_e32 v140, s75, v185
	v_add_u32_e32 v176, s76, v185
	ds_read_b128 v[128:131], v140
	ds_read_b128 v[132:135], v140 offset:1024
	ds_read_b128 v[136:139], v140 offset:2048
	ds_read_b128 v[140:143], v140 offset:3072
	ds_read_b128 v[144:147], v176
	ds_read_b128 v[148:151], v176 offset:1024
	ds_read_b128 v[172:175], v176 offset:2048
	ds_read_b128 v[176:179], v176 offset:3072
	s_add_u32 s48, s54, 0xb0000
	s_addc_u32 s49, s55, 0
	s_mov_b32 m0, s61
	v_lshl_add_u64 v[228:229], s[48:49], 0, v[152:153]
	ds_read_b128 v[180:183], v190 offset:32768
	ds_read_b128 v[192:195], v190 offset:33792
	ds_read_b128 v[196:199], v190 offset:34816
	ds_read_b128 v[200:203], v190 offset:35840
	ds_read_b128 v[204:207], v190 offset:36864
	ds_read_b128 v[208:211], v190 offset:37888
	ds_read_b128 v[212:215], v190 offset:38912
	ds_read_b128 v[216:219], v190 offset:39936
	global_load_lds_dwordx4 v[228:229], off
	v_lshl_add_u64 v[228:229], s[48:49], 0, v[160:161]
	s_mov_b32 m0, s62
	s_nop 0
	global_load_lds_dwordx4 v[228:229], off
	s_waitcnt vmcnt(8)
	s_waitcnt lgkmcnt(0)
	s_barrier
	s_setprio 1
	s_waitcnt lgkmcnt(0)
	v_mfma_f32_16x16x32_bf16 v[124:127], v[128:131], v[180:183], v[124:127]
	v_mfma_f32_16x16x32_bf16 v[120:123], v[136:139], v[180:183], v[120:123]
	v_mfma_f32_16x16x32_bf16 v[108:111], v[128:131], v[196:199], v[108:111]
	v_mfma_f32_16x16x32_bf16 v[104:107], v[136:139], v[196:199], v[104:107]
	v_mfma_f32_16x16x32_bf16 v[92:95], v[128:131], v[204:207], v[92:95]
	v_mfma_f32_16x16x32_bf16 v[88:91], v[136:139], v[204:207], v[88:91]
	v_mfma_f32_16x16x32_bf16 v[76:79], v[128:131], v[212:215], v[76:79]
	v_mfma_f32_16x16x32_bf16 v[72:75], v[136:139], v[212:215], v[72:75]
	v_mfma_f32_16x16x32_bf16 v[124:127], v[132:135], v[192:195], v[124:127]
	v_mfma_f32_16x16x32_bf16 v[120:123], v[140:143], v[192:195], v[120:123]
	v_mfma_f32_16x16x32_bf16 v[108:111], v[132:135], v[200:203], v[108:111]
	v_mfma_f32_16x16x32_bf16 v[104:107], v[140:143], v[200:203], v[104:107]
	v_mfma_f32_16x16x32_bf16 v[92:95], v[132:135], v[208:211], v[92:95]
	v_mfma_f32_16x16x32_bf16 v[88:91], v[140:143], v[208:211], v[88:91]
	v_mfma_f32_16x16x32_bf16 v[76:79], v[132:135], v[216:219], v[76:79]
	v_mfma_f32_16x16x32_bf16 v[72:75], v[140:143], v[216:219], v[72:75]
	s_setprio 0
	s_setprio 1
	v_mfma_f32_16x16x32_bf16 v[116:119], v[144:147], v[180:183], v[116:119]
	v_mfma_f32_16x16x32_bf16 v[112:115], v[172:175], v[180:183], v[112:115]
	v_mfma_f32_16x16x32_bf16 v[100:103], v[144:147], v[196:199], v[100:103]
	v_mfma_f32_16x16x32_bf16 v[96:99], v[172:175], v[196:199], v[96:99]
	v_mfma_f32_16x16x32_bf16 v[84:87], v[144:147], v[204:207], v[84:87]
	v_mfma_f32_16x16x32_bf16 v[80:83], v[172:175], v[204:207], v[80:83]
	v_mfma_f32_16x16x32_bf16 v[68:71], v[144:147], v[212:215], v[68:71]
	v_mfma_f32_16x16x32_bf16 v[64:67], v[172:175], v[212:215], v[64:67]
	v_mfma_f32_16x16x32_bf16 v[116:119], v[148:151], v[192:195], v[116:119]
	v_mfma_f32_16x16x32_bf16 v[112:115], v[176:179], v[192:195], v[112:115]
	v_mfma_f32_16x16x32_bf16 v[100:103], v[148:151], v[200:203], v[100:103]
	v_mfma_f32_16x16x32_bf16 v[96:99], v[176:179], v[200:203], v[96:99]
	v_mfma_f32_16x16x32_bf16 v[84:87], v[148:151], v[208:211], v[84:87]
	v_mfma_f32_16x16x32_bf16 v[80:83], v[176:179], v[208:211], v[80:83]
	v_mfma_f32_16x16x32_bf16 v[68:71], v[148:151], v[216:219], v[68:71]
	v_mfma_f32_16x16x32_bf16 v[64:67], v[176:179], v[216:219], v[64:67]
	s_setprio 0
	s_barrier
	s_add_i32 s48, s75, s58
	v_lshl_add_u64 v[220:221], v[220:221], 0, s[22:23]
	s_mov_b32 m0, s48
	ds_read_b128 v[180:183], v190 offset:49152
	ds_read_b128 v[192:195], v190 offset:50176
	ds_read_b128 v[196:199], v190 offset:51200
	ds_read_b128 v[200:203], v190 offset:52224
	ds_read_b128 v[204:207], v190 offset:53248
	ds_read_b128 v[208:211], v190 offset:54272
	ds_read_b128 v[212:215], v190 offset:55296
	ds_read_b128 v[216:219], v190 offset:56320
	global_load_lds_dwordx4 v[220:221], off
	s_add_i32 m0, s48, 0x2000
	s_add_u32 s48, s52, 0xb0080
	v_lshl_add_u64 v[220:221], v[222:223], 0, s[22:23]
	s_addc_u32 s49, s53, 0
	s_add_i32 s52, s76, s58
	global_load_lds_dwordx4 v[220:221], off
	v_lshl_add_u64 v[220:221], s[48:49], 0, v[154:155]
	s_mov_b32 m0, s52
	s_nop 0
	global_load_lds_dwordx4 v[220:221], off
	v_lshl_add_u64 v[220:221], s[48:49], 0, v[162:163]
	s_add_i32 m0, s52, 0x2000
	s_nop 0
	global_load_lds_dwordx4 v[220:221], off
	v_lshl_add_u64 v[220:221], v[224:225], 0, s[22:23]
	s_mov_b32 m0, s3
	s_nop 0
	global_load_lds_dwordx4 v[220:221], off
	v_lshl_add_u64 v[220:221], v[226:227], 0, s[22:23]
	s_mov_b32 m0, s64
	s_nop 0
	global_load_lds_dwordx4 v[220:221], off
	s_waitcnt vmcnt(8)
	s_waitcnt lgkmcnt(0)
	s_barrier
	s_setprio 1
	s_waitcnt lgkmcnt(0)
	v_mfma_f32_16x16x32_bf16 v[60:63], v[128:131], v[180:183], v[60:63]
	v_mfma_f32_16x16x32_bf16 v[56:59], v[136:139], v[180:183], v[56:59]
	v_mfma_f32_16x16x32_bf16 v[44:47], v[128:131], v[196:199], v[44:47]
	v_mfma_f32_16x16x32_bf16 v[40:43], v[136:139], v[196:199], v[40:43]
	v_mfma_f32_16x16x32_bf16 v[28:31], v[128:131], v[204:207], v[28:31]
	v_mfma_f32_16x16x32_bf16 v[24:27], v[136:139], v[204:207], v[24:27]
	v_mfma_f32_16x16x32_bf16 v[12:15], v[128:131], v[212:215], v[12:15]
	v_mfma_f32_16x16x32_bf16 v[8:11], v[136:139], v[212:215], v[8:11]
	v_mfma_f32_16x16x32_bf16 v[60:63], v[132:135], v[192:195], v[60:63]
	v_mfma_f32_16x16x32_bf16 v[56:59], v[140:143], v[192:195], v[56:59]
	v_mfma_f32_16x16x32_bf16 v[44:47], v[132:135], v[200:203], v[44:47]
	v_mfma_f32_16x16x32_bf16 v[40:43], v[140:143], v[200:203], v[40:43]
	v_mfma_f32_16x16x32_bf16 v[28:31], v[132:135], v[208:211], v[28:31]
	v_mfma_f32_16x16x32_bf16 v[24:27], v[140:143], v[208:211], v[24:27]
	v_mfma_f32_16x16x32_bf16 v[12:15], v[132:135], v[216:219], v[12:15]
	v_mfma_f32_16x16x32_bf16 v[8:11], v[140:143], v[216:219], v[8:11]
	s_setprio 0
	s_setprio 1
	v_mfma_f32_16x16x32_bf16 v[52:55], v[144:147], v[180:183], v[52:55]
	v_mfma_f32_16x16x32_bf16 v[48:51], v[172:175], v[180:183], v[48:51]
	v_mfma_f32_16x16x32_bf16 v[36:39], v[144:147], v[196:199], v[36:39]
	v_mfma_f32_16x16x32_bf16 v[32:35], v[172:175], v[196:199], v[32:35]
	v_mfma_f32_16x16x32_bf16 v[20:23], v[144:147], v[204:207], v[20:23]
	v_mfma_f32_16x16x32_bf16 v[16:19], v[172:175], v[204:207], v[16:19]
	v_mfma_f32_16x16x32_bf16 v[4:7], v[144:147], v[212:215], v[4:7]
	v_mfma_f32_16x16x32_bf16 v[0:3], v[172:175], v[212:215], v[0:3]
	v_mfma_f32_16x16x32_bf16 v[52:55], v[148:151], v[192:195], v[52:55]
	v_mfma_f32_16x16x32_bf16 v[48:51], v[176:179], v[192:195], v[48:51]
	v_mfma_f32_16x16x32_bf16 v[36:39], v[148:151], v[200:203], v[36:39]
	v_mfma_f32_16x16x32_bf16 v[32:35], v[176:179], v[200:203], v[32:35]
	v_mfma_f32_16x16x32_bf16 v[20:23], v[148:151], v[208:211], v[20:23]
	v_mfma_f32_16x16x32_bf16 v[16:19], v[176:179], v[208:211], v[16:19]
	v_mfma_f32_16x16x32_bf16 v[4:7], v[148:151], v[216:219], v[4:7]
	v_mfma_f32_16x16x32_bf16 v[0:3], v[176:179], v[216:219], v[0:3]
	s_setprio 0
	s_barrier
	s_add_i32 s74, s74, 2
	s_add_u32 s72, s72, 0x100
	s_addc_u32 s73, s73, 0
	s_cmp_gt_u32 s74, 41
	s_mov_b64 s[48:49], s[50:51]
